# all deleted instructions in the epilogue and priority edits replaced by s_nop 0 so every compiler wait-state distance is preserved; P0 bias dot products spread over all workgroups; P2 gelu epilogue lo
# baseline (speedup 1.0000x reference)
; __global__ void __launch_bounds__(512, 2) hymba_fwd(Args a) {
;     ...
;         if (gw < 256) {
;             const int which = gw >> 7, n = gw & 127;
;             const float* pe = which ? a.in[12] : a.in[8]; const float* w1 = which ? a.in[13] : a.in[9]; const float* b1 = which ? a.in[14] : a.in[10];
;             float s = 0.f;
;             for (int k = lane; k < 2048; k += 64) s += pe[k] * w1[(size_t)k * 128 + n];
;             s = wave_sum(s);
;             if (lane == 0) { BIAS1[which * 256 + n] = s + b1[n]; BIAS1[which * 256 + 128 + n] = 0.f; }
;         }
;     ...
;         f32x4 vn[4];
;         if (gw < NTOK) { const f32x4* xr0 = (const f32x4*)(a.in[0] + (size_t)gw * DM) + lane;
; #pragma unroll
;             for (int j = 0; j < 4; ++j) vn[j] = xr0[64 * j]; }
;         for (int m = gw; m < NTOK; m += NGW) {
;             f32x4 v[4]; float s = 0.f;
; #pragma unroll
;             for (int j = 0; j < 4; ++j) v[j] = vn[j];
;             if (m + NGW < NTOK) { const f32x4* xr1 = (const f32x4*)(a.in[0] + (size_t)(m + NGW) * DM) + lane;
; #pragma unroll
;                 for (int j = 0; j < 4; ++j) vn[j] = xr1[64 * j]; }
.LBB0_272:
	s_or_b64 exec, exec, s[4:5]
	v_and_b32_e32 v0, 63, v156
	v_lshrrev_b32_e32 v1, 6, v156
	v_lshl_add_u32 v2, v1, 8, v0
	v_lshlrev_b32_e32 v3, 9, v2
	v_lshlrev_b32_e32 v2, 2, v2
	s_and_b32 s3, s2, 0x7f
	s_cmpk_lt_u32 s2, 0x80
	s_cselect_b32 s5, s53, s61
	s_cselect_b32 s4, s52, s60
	s_cselect_b32 s7, s55, s63
	s_cselect_b32 s6, s54, s62
	s_cselect_b32 s13, s57, s65
	s_cselect_b32 s12, s56, s64
	s_cselect_b32 s26, 0, 0x400
	s_lshl_b32 s0, s3, 2
	s_add_u32 s6, s6, s0
	s_addc_u32 s7, s7, 0
	s_add_u32 s12, s12, s0
	s_addc_u32 s13, s13, 0
	s_add_u32 s26, s26, s0
	s_add_u32 s26, s24, s26
	s_addc_u32 s27, s25, 0
	global_load_dword v8, v2, s[4:5]
	global_load_dword v9, v2, s[4:5] offset:256
	global_load_dword v10, v2, s[4:5] offset:512
	global_load_dword v11, v2, s[4:5] offset:768
	v_add_u32_e32 v4, 0x8000, v3
	v_add_u32_e32 v5, 0x10000, v3
	v_add_u32_e32 v6, 0x18000, v3
	global_load_dword v12, v3, s[6:7]
	global_load_dword v13, v4, s[6:7]
	global_load_dword v14, v5, s[6:7]
	global_load_dword v15, v6, s[6:7]
	v_mov_b32_e32 v7, 0
	s_waitcnt vmcnt(3)
	v_fmac_f32_e32 v7, v8, v12
	s_waitcnt vmcnt(2)
	v_fmac_f32_e32 v7, v9, v13
	s_waitcnt vmcnt(1)
	v_fmac_f32_e32 v7, v10, v14
	s_waitcnt vmcnt(0)
	v_fmac_f32_e32 v7, v11, v15
	v_mbcnt_lo_u32_b32 v16, -1, 0
	v_mbcnt_hi_u32_b32 v16, -1, v16
	v_xor_b32_e32 v17, 1, v16
	v_lshlrev_b32_e32 v17, 2, v17
	ds_bpermute_b32 v18, v17, v7
	s_waitcnt lgkmcnt(0)
	v_add_f32_e32 v7, v7, v18
	v_xor_b32_e32 v17, 2, v16
	v_lshlrev_b32_e32 v17, 2, v17
	ds_bpermute_b32 v18, v17, v7
	s_waitcnt lgkmcnt(0)
	v_add_f32_e32 v7, v7, v18
	v_xor_b32_e32 v17, 4, v16
	v_lshlrev_b32_e32 v17, 2, v17
	ds_bpermute_b32 v18, v17, v7
	s_waitcnt lgkmcnt(0)
	v_add_f32_e32 v7, v7, v18
	v_xor_b32_e32 v17, 8, v16
	v_lshlrev_b32_e32 v17, 2, v17
	ds_bpermute_b32 v18, v17, v7
	s_waitcnt lgkmcnt(0)
	v_add_f32_e32 v7, v7, v18
	v_xor_b32_e32 v17, 16, v16
	v_lshlrev_b32_e32 v17, 2, v17
	ds_bpermute_b32 v18, v17, v7
	s_waitcnt lgkmcnt(0)
	v_add_f32_e32 v7, v7, v18
	v_xor_b32_e32 v17, 32, v16
	v_lshlrev_b32_e32 v17, 2, v17
	ds_bpermute_b32 v18, v17, v7
	s_waitcnt lgkmcnt(0)
	v_add_f32_e32 v7, v7, v18
	v_mov_b32_e32 v19, 0x25f00
	v_lshl_add_u32 v19, v1, 2, v19
	v_cmp_eq_u32_e32 vcc, 0, v0
	s_and_saveexec_b64 s[0:1], vcc
	ds_write_b32 v19, v7
	s_or_b64 exec, exec, s[0:1]
	s_waitcnt lgkmcnt(0)
	s_barrier
	v_cmp_eq_u32_e32 vcc, 0, v156
	s_and_saveexec_b64 s[0:1], vcc
	s_cbranch_execz .Lbias_done
	v_mov_b32_e32 v19, 0x25f00
	ds_read_b128 v[8:11], v19
	ds_read_b128 v[12:15], v19 offset:16
	v_mov_b32_e32 v20, 0
	global_load_dword v21, v20, s[12:13]
	s_waitcnt lgkmcnt(0)
	v_add_f32_e32 v8, v8, v9
	v_add_f32_e32 v8, v8, v10
	v_add_f32_e32 v8, v8, v11
	v_add_f32_e32 v8, v8, v12
	v_add_f32_e32 v8, v8, v13
	v_add_f32_e32 v8, v8, v14
	v_add_f32_e32 v8, v8, v15
	s_waitcnt vmcnt(0)
	v_add_f32_e32 v8, v8, v21
	global_store_dword v20, v8, s[26:27]
	global_store_dword v20, v20, s[26:27] offset:512
.Lbias_done:
	s_or_b64 exec, exec, s[0:1]
.LBB0_278:
	v_readlane_b32 s0, v247, 39
	s_cmp_gt_i32 s0, 0xffff
	v_readlane_b32 s1, v247, 40
	s_cbranch_scc1 .LBB0_287
	v_readlane_b32 s12, v247, 39
	v_readlane_b32 s13, v247, 40
	s_ashr_i32 s13, s12, 31
	s_lshl_b64 s[0:1], s[12:13], 12
	s_add_u32 s0, s36, s0
	s_addc_u32 s1, s37, s1
	v_lshlrev_b32_e32 v32, 4, v158
	global_load_dwordx4 v[12:15], v32, s[0:1]
	global_load_dwordx4 v[8:11], v32, s[0:1] offset:1024
	global_load_dwordx4 v[4:7], v32, s[0:1] offset:2048
	s_waitcnt lgkmcnt(0)
	global_load_dwordx4 v[0:3], v32, s[0:1] offset:3072
	v_mbcnt_lo_u32_b32 v17, -1, 0
	v_mov_b32_e32 v33, 0
	v_mbcnt_hi_u32_b32 v18, -1, v17
	v_lshlrev_b32_e32 v16, 3, v158
	v_mov_b32_e32 v17, v33
	v_and_b32_e32 v19, 64, v18
	v_xor_b32_e32 v20, 1, v18
	v_lshl_add_u64 v[34:35], s[96:97], 0, v[16:17]
	v_add_u32_e32 v16, 64, v19
	s_ashr_i32 s95, s94, 31
	s_lshl_b64 s[6:7], s[12:13], 2
	v_xor_b32_e32 v21, 2, v18
	v_cmp_lt_i32_e32 vcc, v20, v16
	s_add_u32 s6, s86, s6
	v_xor_b32_e32 v22, 4, v18
	v_cndmask_b32_e32 v17, v18, v20, vcc
	v_cmp_lt_i32_e32 vcc, v21, v16
	s_addc_u32 s7, s87, s7
	v_xor_b32_e32 v23, 8, v18
	v_cndmask_b32_e32 v19, v18, v21, vcc
	v_cmp_lt_i32_e32 vcc, v22, v16
	s_add_u32 s6, s6, 0x2300000
	s_mov_b32 s28, s12
	v_xor_b32_e32 v24, 16, v18
	v_cndmask_b32_e32 v20, v18, v22, vcc
	v_cmp_lt_i32_e32 vcc, v23, v16
	s_addc_u32 s7, s7, 0
	v_writelane_b32 v247, s12, 39
	s_add_i32 s26, s12, s94
	v_xor_b32_e32 v25, 32, v18
	v_cndmask_b32_e32 v21, v18, v23, vcc
	v_cmp_lt_i32_e32 vcc, v24, v16
	s_ashr_i32 s27, s26, 31
	s_lshl_b64 s[20:21], s[94:95], 2
	v_cndmask_b32_e32 v22, v18, v24, vcc
	v_cmp_lt_i32_e32 vcc, v25, v16
	s_lshl_b64 s[26:27], s[26:27], 12
	s_add_u32 s30, s36, s26
	v_cndmask_b32_e32 v16, v18, v25, vcc
	v_lshlrev_b32_e32 v41, 2, v17
	v_lshlrev_b32_e32 v42, 2, v19
	v_lshlrev_b32_e32 v43, 2, v20
	v_lshlrev_b32_e32 v44, 2, v21
	v_lshlrev_b32_e32 v45, 2, v22
	v_lshlrev_b32_e32 v46, 2, v16
	s_addc_u32 s31, s37, s27
	v_cmp_ne_u32_e64 s[4:5], 0, v158
	s_mov_b64 s[0:1], 0
	v_mov_b32_e32 v40, 0x358637bd
	s_mov_b32 s3, 0x800000
	s_lshl_b64 s[26:27], s[94:95], 12
	v_lshl_add_u64 v[36:37], s[30:31], 0, v[32:33]
	v_writelane_b32 v247, s13, 40
	s_waitcnt vmcnt(3)
	v_mov_b64_e32 v[18:19], v[14:15]
	s_waitcnt vmcnt(2)
	v_mov_b64_e32 v[22:23], v[10:11]
	s_waitcnt vmcnt(1)
	v_mov_b64_e32 v[26:27], v[6:7]
	s_waitcnt vmcnt(0)
	v_mov_b64_e32 v[30:31], v[2:3]
	v_mov_b64_e32 v[16:17], v[12:13]
	v_mov_b64_e32 v[20:21], v[8:9]
	v_mov_b64_e32 v[24:25], v[4:5]
	v_mov_b64_e32 v[28:29], v[0:1]
	s_branch .LBB0_281

; __device__ __forceinline__ bf16_t f2bf(float x) { return (bf16_t)(pk2(x, 0.f) & 0xffffu); }
; __device__ __forceinline__ u32x4 pack8(const float (&f)[8]) { u32x4 w; w.x = pk2(f[0], f[1]); w.y = pk2(f[2], f[3]); w.z = pk2(f[4], f[5]); w.w = pk2(f[6], f[7]); return w; }
;     __device__ __forceinline__ void operator()(const f32x4 (&acc)[2][2][4][2], const pg8::Unit& u, int wr, int wc, int fr, int fq) const {
;     ...
;                 const int r = u.pm * 256 + ai * 128 + wr * 64 + m * 16 + fr;
;                 float rs = 1.f;
;                 if (MODE == 0 || MODE == 5) rs = rowscale[r];
;                 float ssq = 0.f;
; #pragma unroll
;                 for (int bj = 0; bj < 2; ++bj) {
;                     const int c0 = u.pn * 256 + bj * 128 + wc * 32 + 8 * fq;
;                     const f32x4 a0 = acc[ai][bj][m][0], a1 = acc[ai][bj][m][1];
;                     float v[8] = {a0[0], a0[1], a0[2], a0[3], a1[0], a1[1], a1[2], a1[3]};
;                     if (MODE == 0) {
; #pragma unroll
;                         for (int j = 0; j < 8; ++j) v[j] *= rs;
;                         if (u.pn == 4) {
;                             const int b = r >> 12, t = r & 4095, cc = wc * 32 + 8 * fq;
;                             bf16_t* vt = OT + (size_t)bj * ((size_t)16 * 128 * 4096) + ((size_t)(b * 128 + cc)) * 4096 + t;
; #pragma unroll
;                             for (int j = 0; j < 8; ++j) vt[(size_t)j * 4096] = f2bf(v[j]);
;                         } else {
;                             *(u32x4*)(O + (size_t)r * ldc + c0) = pack8(v);
.LBB0_368:
	v_or_b32_e32 v114, 16, v148
	v_ashrrev_i32_e32 v115, 31, v114
	v_lshl_add_u64 v[116:117], v[114:115], 2, s[20:21]
	v_mov_b32_e32 v116, v249
	s_and_b64 vcc, exec, s[6:7]
	s_mov_b64 s[52:53], -1
	s_nop 0
	v_pk_mul_f32 v[118:119], v[108:109], v[116:117] op_sel_hi:[1,0]
	v_pk_mul_f32 v[110:111], v[110:111], v[116:117] op_sel_hi:[1,0]
	v_pk_mul_f32 v[108:109], v[104:105], v[116:117] op_sel_hi:[1,0]
	v_pk_mul_f32 v[104:105], v[106:107], v[116:117] op_sel_hi:[1,0]
	s_cbranch_vccnz .LBB0_370
	v_mov_b64_e32 v[106:107], s[38:39]
	v_mad_i64_i32 v[106:107], s[52:53], v114, s71, v[106:107]
	v_cvt_pk_bf16_f32 v122, v118, v119
	v_cvt_pk_bf16_f32 v123, v110, v111
	v_cvt_pk_bf16_f32 v124, v108, v109
	v_cvt_pk_bf16_f32 v125, v104, v105
	v_lshl_add_u64 v[106:107], v[146:147], 1, v[106:107]
	s_mov_b64 s[52:53], 0
	global_store_dwordx4 v[106:107], v[122:125], off

; __device__ __forceinline__ bf16_t f2bf(float x) { return (bf16_t)(pk2(x, 0.f) & 0xffffu); }
; __device__ __forceinline__ u32x4 pack8(const float (&f)[8]) { u32x4 w; w.x = pk2(f[0], f[1]); w.y = pk2(f[2], f[3]); w.z = pk2(f[4], f[5]); w.w = pk2(f[6], f[7]); return w; }
;     __device__ __forceinline__ void operator()(const f32x4 (&acc)[2][2][4][2], const pg8::Unit& u, int wr, int wc, int fr, int fq) const {
;     ...
;                 const int r = u.pm * 256 + ai * 128 + wr * 64 + m * 16 + fr;
;                 float rs = 1.f;
;                 if (MODE == 0 || MODE == 5) rs = rowscale[r];
;                 float ssq = 0.f;
; #pragma unroll
;                 for (int bj = 0; bj < 2; ++bj) {
;                     const int c0 = u.pn * 256 + bj * 128 + wc * 32 + 8 * fq;
;                     const f32x4 a0 = acc[ai][bj][m][0], a1 = acc[ai][bj][m][1];
;                     float v[8] = {a0[0], a0[1], a0[2], a0[3], a1[0], a1[1], a1[2], a1[3]};
;                     if (MODE == 0) {
; #pragma unroll
;                         for (int j = 0; j < 8; ++j) v[j] *= rs;
;                         if (u.pn == 4) {
;                             const int b = r >> 12, t = r & 4095, cc = wc * 32 + 8 * fq;
;                             bf16_t* vt = OT + (size_t)bj * ((size_t)16 * 128 * 4096) + ((size_t)(b * 128 + cc)) * 4096 + t;
; #pragma unroll
;                             for (int j = 0; j < 8; ++j) vt[(size_t)j * 4096] = f2bf(v[j]);
;                         } else {
;                             *(u32x4*)(O + (size_t)r * ldc + c0) = pack8(v);
.LBB0_376:
	v_or_b32_e32 v96, 32, v148
	v_ashrrev_i32_e32 v97, 31, v96
	v_lshl_add_u64 v[98:99], v[96:97], 2, s[20:21]
	v_mov_b32_e32 v98, v250
	s_and_b64 vcc, exec, s[6:7]
	s_mov_b64 s[52:53], -1
	s_nop 0
	v_pk_mul_f32 v[100:101], v[92:93], v[98:99] op_sel_hi:[1,0]
	v_pk_mul_f32 v[94:95], v[94:95], v[98:99] op_sel_hi:[1,0]
	v_pk_mul_f32 v[92:93], v[88:89], v[98:99] op_sel_hi:[1,0]
	v_pk_mul_f32 v[88:89], v[90:91], v[98:99] op_sel_hi:[1,0]
	s_cbranch_vccnz .LBB0_378
	v_mov_b64_e32 v[90:91], s[38:39]
	v_mad_i64_i32 v[90:91], s[52:53], v96, s71, v[90:91]
	v_cvt_pk_bf16_f32 v102, v100, v101
	v_cvt_pk_bf16_f32 v103, v94, v95
	v_cvt_pk_bf16_f32 v104, v92, v93
	v_cvt_pk_bf16_f32 v105, v88, v89
	v_lshl_add_u64 v[90:91], v[146:147], 1, v[90:91]
	s_mov_b64 s[52:53], 0
	global_store_dwordx4 v[90:91], v[102:105], off

; __device__ __forceinline__ bf16_t f2bf(float x) { return (bf16_t)(pk2(x, 0.f) & 0xffffu); }
; __device__ __forceinline__ u32x4 pack8(const float (&f)[8]) { u32x4 w; w.x = pk2(f[0], f[1]); w.y = pk2(f[2], f[3]); w.z = pk2(f[4], f[5]); w.w = pk2(f[6], f[7]); return w; }
;     __device__ __forceinline__ void operator()(const f32x4 (&acc)[2][2][4][2], const pg8::Unit& u, int wr, int wc, int fr, int fq) const {
;     ...
;                 const int r = u.pm * 256 + ai * 128 + wr * 64 + m * 16 + fr;
;                 float rs = 1.f;
;                 if (MODE == 0 || MODE == 5) rs = rowscale[r];
;                 float ssq = 0.f;
; #pragma unroll
;                 for (int bj = 0; bj < 2; ++bj) {
;                     const int c0 = u.pn * 256 + bj * 128 + wc * 32 + 8 * fq;
;                     const f32x4 a0 = acc[ai][bj][m][0], a1 = acc[ai][bj][m][1];
;                     float v[8] = {a0[0], a0[1], a0[2], a0[3], a1[0], a1[1], a1[2], a1[3]};
;                     if (MODE == 0) {
; #pragma unroll
;                         for (int j = 0; j < 8; ++j) v[j] *= rs;
;                         if (u.pn == 4) {
;                             const int b = r >> 12, t = r & 4095, cc = wc * 32 + 8 * fq;
;                             bf16_t* vt = OT + (size_t)bj * ((size_t)16 * 128 * 4096) + ((size_t)(b * 128 + cc)) * 4096 + t;
; #pragma unroll
;                             for (int j = 0; j < 8; ++j) vt[(size_t)j * 4096] = f2bf(v[j]);
;                         } else {
;                             *(u32x4*)(O + (size_t)r * ldc + c0) = pack8(v);
.LBB0_384:
	v_or_b32_e32 v80, 48, v148
	v_ashrrev_i32_e32 v81, 31, v80
	v_lshl_add_u64 v[82:83], v[80:81], 2, s[20:21]
	v_mov_b32_e32 v82, v251
	s_and_b64 vcc, exec, s[6:7]
	s_mov_b64 s[52:53], -1
	s_nop 0
	v_pk_mul_f32 v[84:85], v[76:77], v[82:83] op_sel_hi:[1,0]
	v_pk_mul_f32 v[78:79], v[78:79], v[82:83] op_sel_hi:[1,0]
	v_pk_mul_f32 v[76:77], v[72:73], v[82:83] op_sel_hi:[1,0]
	v_pk_mul_f32 v[72:73], v[74:75], v[82:83] op_sel_hi:[1,0]
	s_cbranch_vccnz .LBB0_386
	v_mov_b64_e32 v[74:75], s[38:39]
	v_mad_i64_i32 v[74:75], s[52:53], v80, s71, v[74:75]
	v_cvt_pk_bf16_f32 v86, v84, v85
	v_cvt_pk_bf16_f32 v87, v78, v79
	v_cvt_pk_bf16_f32 v88, v76, v77
	v_cvt_pk_bf16_f32 v89, v72, v73
	v_lshl_add_u64 v[74:75], v[146:147], 1, v[74:75]
	s_mov_b64 s[52:53], 0
	global_store_dwordx4 v[74:75], v[86:89], off

; __device__ __forceinline__ bf16_t f2bf(float x) { return (bf16_t)(pk2(x, 0.f) & 0xffffu); }
; __device__ __forceinline__ u32x4 pack8(const float (&f)[8]) { u32x4 w; w.x = pk2(f[0], f[1]); w.y = pk2(f[2], f[3]); w.z = pk2(f[4], f[5]); w.w = pk2(f[6], f[7]); return w; }
;     __device__ __forceinline__ void operator()(const f32x4 (&acc)[2][2][4][2], const pg8::Unit& u, int wr, int wc, int fr, int fq) const {
;     ...
;                 const int r = u.pm * 256 + ai * 128 + wr * 64 + m * 16 + fr;
;                 float rs = 1.f;
;                 if (MODE == 0 || MODE == 5) rs = rowscale[r];
;                 float ssq = 0.f;
; #pragma unroll
;                 for (int bj = 0; bj < 2; ++bj) {
;                     const int c0 = u.pn * 256 + bj * 128 + wc * 32 + 8 * fq;
;                     const f32x4 a0 = acc[ai][bj][m][0], a1 = acc[ai][bj][m][1];
;                     float v[8] = {a0[0], a0[1], a0[2], a0[3], a1[0], a1[1], a1[2], a1[3]};
;                     if (MODE == 0) {
; #pragma unroll
;                         for (int j = 0; j < 8; ++j) v[j] *= rs;
;                         if (u.pn == 4) {
;                             const int b = r >> 12, t = r & 4095, cc = wc * 32 + 8 * fq;
;                             bf16_t* vt = OT + (size_t)bj * ((size_t)16 * 128 * 4096) + ((size_t)(b * 128 + cc)) * 4096 + t;
; #pragma unroll
;                             for (int j = 0; j < 8; ++j) vt[(size_t)j * 4096] = f2bf(v[j]);
;                         } else {
;                             *(u32x4*)(O + (size_t)r * ldc + c0) = pack8(v);
.LBB0_392:
	s_addk_i32 s31, 0x80
	v_or_b32_e32 v64, s31, v157
	v_ashrrev_i32_e32 v65, 31, v64
	v_lshl_add_u64 v[66:67], v[64:65], 2, s[20:21]
	v_mov_b32_e32 v66, v252
	s_and_b64 vcc, exec, s[6:7]
	s_mov_b64 s[52:53], -1
	s_nop 0
	v_pk_mul_f32 v[70:71], v[60:61], v[66:67] op_sel_hi:[1,0]
	v_pk_mul_f32 v[68:69], v[62:63], v[66:67] op_sel_hi:[1,0]
	v_pk_mul_f32 v[62:63], v[56:57], v[66:67] op_sel_hi:[1,0]
	v_pk_mul_f32 v[60:61], v[58:59], v[66:67] op_sel_hi:[1,0]
	s_cbranch_vccnz .LBB0_394
	v_mov_b64_e32 v[72:73], s[38:39]
	v_mad_i64_i32 v[72:73], s[52:53], v64, s71, v[72:73]
	v_cvt_pk_bf16_f32 v56, v70, v71
	v_cvt_pk_bf16_f32 v57, v68, v69
	v_cvt_pk_bf16_f32 v58, v62, v63
	v_cvt_pk_bf16_f32 v59, v60, v61
	v_lshl_add_u64 v[72:73], v[146:147], 1, v[72:73]
	s_mov_b64 s[52:53], 0
	global_store_dwordx4 v[72:73], v[56:59], off

; __device__ __forceinline__ bf16_t f2bf(float x) { return (bf16_t)(pk2(x, 0.f) & 0xffffu); }
; __device__ __forceinline__ u32x4 pack8(const float (&f)[8]) { u32x4 w; w.x = pk2(f[0], f[1]); w.y = pk2(f[2], f[3]); w.z = pk2(f[4], f[5]); w.w = pk2(f[6], f[7]); return w; }
;     __device__ __forceinline__ void operator()(const f32x4 (&acc)[2][2][4][2], const pg8::Unit& u, int wr, int wc, int fr, int fq) const {
;     ...
;                 const int r = u.pm * 256 + ai * 128 + wr * 64 + m * 16 + fr;
;                 float rs = 1.f;
;                 if (MODE == 0 || MODE == 5) rs = rowscale[r];
;                 float ssq = 0.f;
; #pragma unroll
;                 for (int bj = 0; bj < 2; ++bj) {
;                     const int c0 = u.pn * 256 + bj * 128 + wc * 32 + 8 * fq;
;                     const f32x4 a0 = acc[ai][bj][m][0], a1 = acc[ai][bj][m][1];
;                     float v[8] = {a0[0], a0[1], a0[2], a0[3], a1[0], a1[1], a1[2], a1[3]};
;                     if (MODE == 0) {
; #pragma unroll
;                         for (int j = 0; j < 8; ++j) v[j] *= rs;
;                         if (u.pn == 4) {
;                             const int b = r >> 12, t = r & 4095, cc = wc * 32 + 8 * fq;
;                             bf16_t* vt = OT + (size_t)bj * ((size_t)16 * 128 * 4096) + ((size_t)(b * 128 + cc)) * 4096 + t;
; #pragma unroll
;                             for (int j = 0; j < 8; ++j) vt[(size_t)j * 4096] = f2bf(v[j]);
;                         } else {
;                             *(u32x4*)(O + (size_t)r * ldc + c0) = pack8(v);
.LBB0_400:
	v_or_b32_e32 v50, 16, v64
	v_ashrrev_i32_e32 v51, 31, v50
	v_lshl_add_u64 v[52:53], v[50:51], 2, s[20:21]
	v_mov_b32_e32 v52, v253
	s_and_b64 vcc, exec, s[6:7]
	s_mov_b64 s[52:53], -1
	s_nop 0
	v_pk_mul_f32 v[54:55], v[44:45], v[52:53] op_sel_hi:[1,0]
	v_pk_mul_f32 v[46:47], v[46:47], v[52:53] op_sel_hi:[1,0]
	v_pk_mul_f32 v[44:45], v[40:41], v[52:53] op_sel_hi:[1,0]
	v_pk_mul_f32 v[40:41], v[42:43], v[52:53] op_sel_hi:[1,0]
	s_cbranch_vccnz .LBB0_402
	v_mov_b64_e32 v[42:43], s[38:39]
	v_mad_i64_i32 v[42:43], s[52:53], v50, s71, v[42:43]
	v_cvt_pk_bf16_f32 v58, v54, v55
	v_cvt_pk_bf16_f32 v59, v46, v47
	v_cvt_pk_bf16_f32 v60, v44, v45
	v_cvt_pk_bf16_f32 v61, v40, v41
	v_lshl_add_u64 v[42:43], v[146:147], 1, v[42:43]
	s_mov_b64 s[52:53], 0
	global_store_dwordx4 v[42:43], v[58:61], off

; __device__ __forceinline__ bf16_t f2bf(float x) { return (bf16_t)(pk2(x, 0.f) & 0xffffu); }
; __device__ __forceinline__ u32x4 pack8(const float (&f)[8]) { u32x4 w; w.x = pk2(f[0], f[1]); w.y = pk2(f[2], f[3]); w.z = pk2(f[4], f[5]); w.w = pk2(f[6], f[7]); return w; }
;     __device__ __forceinline__ void operator()(const f32x4 (&acc)[2][2][4][2], const pg8::Unit& u, int wr, int wc, int fr, int fq) const {
;     ...
;                 const int r = u.pm * 256 + ai * 128 + wr * 64 + m * 16 + fr;
;                 float rs = 1.f;
;                 if (MODE == 0 || MODE == 5) rs = rowscale[r];
;                 float ssq = 0.f;
; #pragma unroll
;                 for (int bj = 0; bj < 2; ++bj) {
;                     const int c0 = u.pn * 256 + bj * 128 + wc * 32 + 8 * fq;
;                     const f32x4 a0 = acc[ai][bj][m][0], a1 = acc[ai][bj][m][1];
;                     float v[8] = {a0[0], a0[1], a0[2], a0[3], a1[0], a1[1], a1[2], a1[3]};
;                     if (MODE == 0) {
; #pragma unroll
;                         for (int j = 0; j < 8; ++j) v[j] *= rs;
;                         if (u.pn == 4) {
;                             const int b = r >> 12, t = r & 4095, cc = wc * 32 + 8 * fq;
;                             bf16_t* vt = OT + (size_t)bj * ((size_t)16 * 128 * 4096) + ((size_t)(b * 128 + cc)) * 4096 + t;
; #pragma unroll
;                             for (int j = 0; j < 8; ++j) vt[(size_t)j * 4096] = f2bf(v[j]);
;                         } else {
;                             *(u32x4*)(O + (size_t)r * ldc + c0) = pack8(v);
.LBB0_408:
	v_or_b32_e32 v32, 32, v64
	v_ashrrev_i32_e32 v33, 31, v32
	v_lshl_add_u64 v[34:35], v[32:33], 2, s[20:21]
	v_mov_b32_e32 v34, v254
	s_and_b64 vcc, exec, s[6:7]
	s_mov_b64 s[52:53], -1
	s_nop 0
	v_pk_mul_f32 v[36:37], v[28:29], v[34:35] op_sel_hi:[1,0]
	v_pk_mul_f32 v[30:31], v[30:31], v[34:35] op_sel_hi:[1,0]
	v_pk_mul_f32 v[28:29], v[24:25], v[34:35] op_sel_hi:[1,0]
	v_pk_mul_f32 v[24:25], v[26:27], v[34:35] op_sel_hi:[1,0]
	s_cbranch_vccnz .LBB0_410
	v_mov_b64_e32 v[26:27], s[38:39]
	v_mad_i64_i32 v[26:27], s[52:53], v32, s71, v[26:27]
	v_cvt_pk_bf16_f32 v38, v36, v37
	v_cvt_pk_bf16_f32 v39, v30, v31
	v_cvt_pk_bf16_f32 v40, v28, v29
	v_cvt_pk_bf16_f32 v41, v24, v25
	v_lshl_add_u64 v[26:27], v[146:147], 1, v[26:27]
	s_mov_b64 s[52:53], 0
	global_store_dwordx4 v[26:27], v[38:41], off

; __device__ __forceinline__ bf16_t f2bf(float x) { return (bf16_t)(pk2(x, 0.f) & 0xffffu); }
; __device__ __forceinline__ u32x4 pack8(const float (&f)[8]) { u32x4 w; w.x = pk2(f[0], f[1]); w.y = pk2(f[2], f[3]); w.z = pk2(f[4], f[5]); w.w = pk2(f[6], f[7]); return w; }
;     __device__ __forceinline__ void operator()(const f32x4 (&acc)[2][2][4][2], const pg8::Unit& u, int wr, int wc, int fr, int fq) const {
;     ...
;                 const int r = u.pm * 256 + ai * 128 + wr * 64 + m * 16 + fr;
;                 float rs = 1.f;
;                 if (MODE == 0 || MODE == 5) rs = rowscale[r];
;                 float ssq = 0.f;
; #pragma unroll
;                 for (int bj = 0; bj < 2; ++bj) {
;                     const int c0 = u.pn * 256 + bj * 128 + wc * 32 + 8 * fq;
;                     const f32x4 a0 = acc[ai][bj][m][0], a1 = acc[ai][bj][m][1];
;                     float v[8] = {a0[0], a0[1], a0[2], a0[3], a1[0], a1[1], a1[2], a1[3]};
;                     if (MODE == 0) {
; #pragma unroll
;                         for (int j = 0; j < 8; ++j) v[j] *= rs;
;                         if (u.pn == 4) {
;                             const int b = r >> 12, t = r & 4095, cc = wc * 32 + 8 * fq;
;                             bf16_t* vt = OT + (size_t)bj * ((size_t)16 * 128 * 4096) + ((size_t)(b * 128 + cc)) * 4096 + t;
; #pragma unroll
;                             for (int j = 0; j < 8; ++j) vt[(size_t)j * 4096] = f2bf(v[j]);
;                         } else {
;                             *(u32x4*)(O + (size_t)r * ldc + c0) = pack8(v);
.LBB0_416:
	v_or_b32_e32 v16, 48, v64
	v_ashrrev_i32_e32 v17, 31, v16
	v_lshl_add_u64 v[18:19], v[16:17], 2, s[20:21]
	v_mov_b32_e32 v18, v255
	s_and_b64 vcc, exec, s[6:7]
	s_mov_b64 s[52:53], -1
	s_nop 0
	v_pk_mul_f32 v[20:21], v[12:13], v[18:19] op_sel_hi:[1,0]
	v_pk_mul_f32 v[14:15], v[14:15], v[18:19] op_sel_hi:[1,0]
	v_pk_mul_f32 v[12:13], v[8:9], v[18:19] op_sel_hi:[1,0]
	v_pk_mul_f32 v[8:9], v[10:11], v[18:19] op_sel_hi:[1,0]
	s_cbranch_vccnz .LBB0_418
	v_mov_b64_e32 v[10:11], s[38:39]
	v_mad_i64_i32 v[10:11], s[52:53], v16, s71, v[10:11]
	v_cvt_pk_bf16_f32 v22, v20, v21
	v_cvt_pk_bf16_f32 v23, v14, v15
	v_cvt_pk_bf16_f32 v24, v12, v13
	v_cvt_pk_bf16_f32 v25, v8, v9
	v_lshl_add_u64 v[10:11], v[146:147], 1, v[10:11]
	s_mov_b64 s[52:53], 0
	global_store_dwordx4 v[10:11], v[22:25], off

; __device__ __forceinline__ bf16_t f2bf(float x) { return (bf16_t)(pk2(x, 0.f) & 0xffffu); }
; __device__ __forceinline__ float sigm(float x) { return __builtin_amdgcn_rcpf(1.f + __expf(-x)); }
; __device__ __forceinline__ u32x4 pack8(const float (&f)[8]) { u32x4 w; w.x = pk2(f[0], f[1]); w.y = pk2(f[2], f[3]); w.z = pk2(f[4], f[5]); w.w = pk2(f[6], f[7]); return w; }
;     __device__ __forceinline__ void operator()(const f32x4 (&acc)[2][2][4][2], const pg8::Unit& u, int wr, int wc, int fr, int fq) const {
;     ...
;         for (int ai = 0; ai < 2; ++ai)
; #pragma unroll
;             for (int m = 0; m < 4; ++m) {
;                 const int r = u.pm * 256 + ai * 128 + wr * 64 + m * 16 + fr;
;                 float rs = 1.f;
;                 if (MODE == 0 || MODE == 5) rs = rowscale[r];
;                 float ssq = 0.f;
; #pragma unroll
;                 for (int bj = 0; bj < 2; ++bj) {
;                     const int c0 = u.pn * 256 + bj * 128 + wc * 32 + 8 * fq;
;                     const f32x4 a0 = acc[ai][bj][m][0], a1 = acc[ai][bj][m][1];
;                     float v[8] = {a0[0], a0[1], a0[2], a0[3], a1[0], a1[1], a1[2], a1[3]};
;                     if (MODE == 0) {
; #pragma unroll
;                         for (int j = 0; j < 8; ++j) v[j] *= rs;
;                         if (u.pn == 4) {
;                             const int b = r >> 12, t = r & 4095, cc = wc * 32 + 8 * fq;
;                             bf16_t* vt = OT + (size_t)bj * ((size_t)16 * 128 * 4096) + ((size_t)(b * 128 + cc)) * 4096 + t;
; #pragma unroll
;                             for (int j = 0; j < 8; ++j) vt[(size_t)j * 4096] = f2bf(v[j]);
;                         } else {
;                             *(u32x4*)(O + (size_t)r * ldc + c0) = pack8(v);
;                         }
;                     } else if (MODE == 1) {
;                         const f32x4 b0 = *(const f32x4*)(bias + c0), b1 = *(const f32x4*)(bias + c0 + 4);
;                         const float bb[8] = {b0[0], b0[1], b0[2], b0[3], b1[0], b1[1], b1[2], b1[3]};
; #pragma unroll
;                         for (int j = 0; j < 8; ++j) { const float x = v[j] + bb[j]; const float uu = 0.7978845608028654f * (x + 0.044715f * x * x * x); v[j] = x * sigm(2.f * uu); }
;                         *(u32x4*)(O + (size_t)r * ldc + c0) = pack8(v);
.LBB0_505:
	v_lshl_or_b32 v146, s34, 8, v160
	v_ashrrev_i32_e32 v147, 31, v146
	v_lshl_add_u64 v[142:143], v[146:147], 2, s[24:25]
	global_load_dwordx4 v[164:167], v[142:143], off offset:16
	global_load_dwordx4 v[168:171], v[142:143], off
	global_load_dwordx4 v[228:231], v[142:143], off offset:528
	global_load_dwordx4 v[232:235], v[142:143], off offset:512
	v_lshl_add_u32 v140, s33, 8, v157
	v_ashrrev_i32_e32 v141, 31, v140
	s_mov_b64 s[20:21], -1
	s_and_b64 vcc, exec, s[4:5]
	s_waitcnt vmcnt(0)
	v_mov_b64_e32 v[220:221], v[164:165]
	v_mov_b64_e32 v[222:223], v[166:167]
	v_mov_b64_e32 v[224:225], v[168:169]
	v_mov_b64_e32 v[226:227], v[170:171]
	v_pk_add_f32 v[120:121], v[120:121], v[164:165]
	v_pk_add_f32 v[124:125], v[124:125], v[168:169]
	v_pk_add_f32 v[126:127], v[126:127], v[170:171]
	v_mul_f32_e32 v144, 0x3d372713, v124
	v_mul_f32_e32 v145, 0x3d372713, v125
	v_mul_f32_e32 v144, v124, v144
	v_mul_f32_e32 v145, v125, v145
	v_fma_f32 v144, v124, v144, v124
	v_fma_f32 v145, v125, v145, v125
	v_mul_f32_e32 v144, 0x3f4c422a, v144
	v_mul_f32_e32 v145, 0x3f4c422a, v145
	v_add_f32_e32 v144, v144, v144
	v_add_f32_e32 v145, v145, v145
	v_mul_f32_e32 v144, 0xbfb8aa3b, v144
	v_mul_f32_e32 v145, 0xbfb8aa3b, v145
	v_exp_f32_e32 v144, v144
	v_exp_f32_e32 v145, v145
	v_pk_add_f32 v[122:123], v[122:123], v[166:167]
	v_add_f32_e32 v144, 1.0, v144
	v_add_f32_e32 v145, 1.0, v145
	v_rcp_f32_e32 v144, v144
	v_rcp_f32_e32 v145, v145
	s_nop 0
	v_pk_mul_f32 v[124:125], v[124:125], v[144:145]
	v_mul_f32_e32 v144, 0x3d372713, v126
	v_mul_f32_e32 v145, 0x3d372713, v127
	v_mul_f32_e32 v144, v126, v144
	v_mul_f32_e32 v145, v127, v145
	v_fma_f32 v144, v126, v144, v126
	v_fma_f32 v145, v127, v145, v127
	v_mul_f32_e32 v144, 0x3f4c422a, v144
	v_mul_f32_e32 v145, 0x3f4c422a, v145
	v_add_f32_e32 v144, v144, v144
	v_add_f32_e32 v145, v145, v145
	v_mul_f32_e32 v144, 0xbfb8aa3b, v144
	v_mul_f32_e32 v145, 0xbfb8aa3b, v145
	v_exp_f32_e32 v144, v144
	v_exp_f32_e32 v145, v145
	v_add_f32_e32 v144, 1.0, v144
	v_add_f32_e32 v145, 1.0, v145
	v_rcp_f32_e32 v144, v144
	v_rcp_f32_e32 v145, v145
	s_nop 0
	v_pk_mul_f32 v[126:127], v[126:127], v[144:145]
	v_mul_f32_e32 v144, 0x3d372713, v120
	v_mul_f32_e32 v145, 0x3d372713, v121
	v_mul_f32_e32 v144, v120, v144
	v_mul_f32_e32 v145, v121, v145
	v_fma_f32 v144, v120, v144, v120
	v_fma_f32 v145, v121, v145, v121
	v_mul_f32_e32 v144, 0x3f4c422a, v144
	v_mul_f32_e32 v145, 0x3f4c422a, v145
	v_add_f32_e32 v144, v144, v144
	v_add_f32_e32 v145, v145, v145
	v_mul_f32_e32 v144, 0xbfb8aa3b, v144
	v_mul_f32_e32 v145, 0xbfb8aa3b, v145
	v_exp_f32_e32 v144, v144
	v_exp_f32_e32 v145, v145
	v_add_f32_e32 v144, 1.0, v144
	v_add_f32_e32 v145, 1.0, v145
	v_rcp_f32_e32 v144, v144
	v_rcp_f32_e32 v145, v145
	s_nop 0
	v_pk_mul_f32 v[144:145], v[120:121], v[144:145]
	v_mul_f32_e32 v120, 0x3d372713, v122
	v_mul_f32_e32 v121, 0x3d372713, v123
	v_mul_f32_e32 v120, v122, v120
	v_mul_f32_e32 v121, v123, v121
	v_fma_f32 v120, v122, v120, v122
	v_fma_f32 v121, v123, v121, v123
	v_mul_f32_e32 v120, 0x3f4c422a, v120
	v_mul_f32_e32 v121, 0x3f4c422a, v121
	v_add_f32_e32 v120, v120, v120
	v_add_f32_e32 v121, v121, v121
	v_mul_f32_e32 v120, 0xbfb8aa3b, v120
	v_mul_f32_e32 v121, 0xbfb8aa3b, v121
	v_exp_f32_e32 v120, v120
	v_exp_f32_e32 v121, v121
	v_add_f32_e32 v120, 1.0, v120
	v_add_f32_e32 v121, 1.0, v121
	v_rcp_f32_e32 v120, v120
	v_rcp_f32_e32 v121, v121
	s_nop 0
	v_pk_mul_f32 v[164:165], v[122:123], v[120:121]
	v_cvt_pk_bf16_f32 v120, v124, v125
	v_lshlrev_b64 v[124:125], 9, v[140:141]
	v_cvt_pk_bf16_f32 v121, v126, v127
	v_lshl_add_u64 v[126:127], s[18:19], 0, v[124:125]
	v_lshlrev_b64 v[124:125], 1, v[146:147]
	v_cvt_pk_bf16_f32 v122, v144, v145
	v_cvt_pk_bf16_f32 v123, v164, v165
	v_lshl_add_u64 v[144:145], v[126:127], 0, v[124:125]
	global_store_dwordx4 v[144:145], v[120:123], off
	s_nop 1
	v_or_b32_e32 v120, 0x80, v146
	v_ashrrev_i32_e32 v121, 31, v120
	v_lshl_add_u64 v[126:127], v[120:121], 2, s[24:25]
	s_nop 0
	s_nop 0
	v_mov_b64_e32 v[120:121], v[228:229]
	v_mov_b64_e32 v[122:123], v[230:231]
	v_mov_b64_e32 v[164:165], v[232:233]
	v_mov_b64_e32 v[166:167], v[234:235]
	v_pk_add_f32 v[112:113], v[112:113], v[120:121]
	s_nop 0
	v_pk_add_f32 v[116:117], v[116:117], v[164:165]
	v_mul_f32_e32 v120, 0x3d372713, v112
	v_mul_f32_e32 v141, 0x3d372713, v116
	v_mul_f32_e32 v141, v116, v141
	v_fma_f32 v141, v116, v141, v116
	v_mul_f32_e32 v141, 0x3f4c422a, v141
	v_add_f32_e32 v141, v141, v141
	v_mul_f32_e32 v141, 0xbfb8aa3b, v141
	v_exp_f32_e32 v141, v141
	v_mul_f32_e32 v121, 0x3d372713, v113
	v_mul_f32_e32 v120, v112, v120
	v_mul_f32_e32 v121, v113, v121
	v_add_f32_e32 v141, 1.0, v141
	v_rcp_f32_e32 v146, v141
	v_mul_f32_e32 v141, 0x3d372713, v117
	v_mul_f32_e32 v141, v117, v141
	v_fma_f32 v141, v117, v141, v117
	v_mul_f32_e32 v141, 0x3f4c422a, v141
	v_add_f32_e32 v141, v141, v141
	v_mul_f32_e32 v141, 0xbfb8aa3b, v141
	v_exp_f32_e32 v141, v141
	v_fma_f32 v120, v112, v120, v112
	v_fma_f32 v121, v113, v121, v113
	v_pk_add_f32 v[118:119], v[118:119], v[166:167]
	v_add_f32_e32 v141, 1.0, v141
	v_mul_f32_e32 v120, 0x3f4c422a, v120
	v_mul_f32_e32 v121, 0x3f4c422a, v121
	v_rcp_f32_e32 v147, v141
	v_mul_f32_e32 v141, 0x3d372713, v118
	v_add_f32_e32 v120, v120, v120
	v_add_f32_e32 v121, v121, v121
	v_mul_f32_e32 v141, v118, v141
	v_mul_f32_e32 v120, 0xbfb8aa3b, v120
	v_mul_f32_e32 v121, 0xbfb8aa3b, v121
	v_fma_f32 v141, v118, v141, v118
	v_exp_f32_e32 v120, v120
	v_exp_f32_e32 v121, v121
	v_mul_f32_e32 v141, 0x3f4c422a, v141
	v_add_f32_e32 v141, v141, v141
	v_mul_f32_e32 v141, 0xbfb8aa3b, v141
	v_exp_f32_e32 v141, v141
	v_add_f32_e32 v120, 1.0, v120
	v_add_f32_e32 v121, 1.0, v121
; __device__ __forceinline__ bf16_t f2bf(float x) { return (bf16_t)(pk2(x, 0.f) & 0xffffu); }
; __device__ __forceinline__ float sigm(float x) { return __builtin_amdgcn_rcpf(1.f + __expf(-x)); }
; __device__ __forceinline__ u32x4 pack8(const float (&f)[8]) { u32x4 w; w.x = pk2(f[0], f[1]); w.y = pk2(f[2], f[3]); w.z = pk2(f[4], f[5]); w.w = pk2(f[6], f[7]); return w; }
;     __device__ __forceinline__ void operator()(const f32x4 (&acc)[2][2][4][2], const pg8::Unit& u, int wr, int wc, int fr, int fq) const {
;     ...
;                     const int c0 = u.pn * 256 + bj * 128 + wc * 32 + 8 * fq;
;                     const f32x4 a0 = acc[ai][bj][m][0], a1 = acc[ai][bj][m][1];
;                     float v[8] = {a0[0], a0[1], a0[2], a0[3], a1[0], a1[1], a1[2], a1[3]};
;                     if (MODE == 0) {
; #pragma unroll
;                         for (int j = 0; j < 8; ++j) v[j] *= rs;
;                         if (u.pn == 4) {
;                             const int b = r >> 12, t = r & 4095, cc = wc * 32 + 8 * fq;
;                             bf16_t* vt = OT + (size_t)bj * ((size_t)16 * 128 * 4096) + ((size_t)(b * 128 + cc)) * 4096 + t;
; #pragma unroll
;                             for (int j = 0; j < 8; ++j) vt[(size_t)j * 4096] = f2bf(v[j]);
;                         } else {
;                             *(u32x4*)(O + (size_t)r * ldc + c0) = pack8(v);
;                         }
;                     } else if (MODE == 1) {
;                         const f32x4 b0 = *(const f32x4*)(bias + c0), b1 = *(const f32x4*)(bias + c0 + 4);
;                         const float bb[8] = {b0[0], b0[1], b0[2], b0[3], b1[0], b1[1], b1[2], b1[3]};
; #pragma unroll
;                         for (int j = 0; j < 8; ++j) { const float x = v[j] + bb[j]; const float uu = 0.7978845608028654f * (x + 0.044715f * x * x * x); v[j] = x * sigm(2.f * uu); }
;                         *(u32x4*)(O + (size_t)r * ldc + c0) = pack8(v);
	v_rcp_f32_e32 v120, v120
	v_rcp_f32_e32 v121, v121
	v_add_f32_e32 v141, 1.0, v141
	v_pk_add_f32 v[114:115], v[114:115], v[122:123]
	v_pk_mul_f32 v[116:117], v[116:117], v[146:147]
	v_rcp_f32_e32 v146, v141
	v_mul_f32_e32 v141, 0x3d372713, v119
	v_pk_mul_f32 v[120:121], v[112:113], v[120:121]
	v_mul_f32_e32 v112, 0x3d372713, v114
	v_mul_f32_e32 v113, 0x3d372713, v115
	v_mul_f32_e32 v141, v119, v141
	v_mul_f32_e32 v112, v114, v112
	v_mul_f32_e32 v113, v115, v113
	v_fma_f32 v141, v119, v141, v119
	v_fma_f32 v112, v114, v112, v114
	v_fma_f32 v113, v115, v113, v115
	v_mul_f32_e32 v141, 0x3f4c422a, v141
	v_mul_f32_e32 v112, 0x3f4c422a, v112
	v_mul_f32_e32 v113, 0x3f4c422a, v113
	v_add_f32_e32 v141, v141, v141
	v_add_f32_e32 v112, v112, v112
	v_add_f32_e32 v113, v113, v113
	v_mul_f32_e32 v141, 0xbfb8aa3b, v141
	v_mul_f32_e32 v112, 0xbfb8aa3b, v112
	v_mul_f32_e32 v113, 0xbfb8aa3b, v113
	v_exp_f32_e32 v141, v141
	v_exp_f32_e32 v112, v112
	v_exp_f32_e32 v113, v113
	v_add_f32_e32 v141, 1.0, v141
	v_add_f32_e32 v112, 1.0, v112
	v_add_f32_e32 v113, 1.0, v113
	v_rcp_f32_e32 v147, v141
	v_rcp_f32_e32 v112, v112
	v_rcp_f32_e32 v113, v113
	v_pk_mul_f32 v[118:119], v[118:119], v[146:147]
	v_pk_mul_f32 v[122:123], v[114:115], v[112:113]
	v_cvt_pk_bf16_f32 v112, v116, v117
	v_cvt_pk_bf16_f32 v113, v118, v119
	v_cvt_pk_bf16_f32 v114, v120, v121
	v_cvt_pk_bf16_f32 v115, v122, v123
	global_store_dwordx4 v[144:145], v[112:115], off offset:256
	s_nop 0
	s_nop 0
	v_or_b32_e32 v112, 16, v140
	v_ashrrev_i32_e32 v113, 31, v112
	v_mov_b64_e32 v[114:115], v[220:221]
	v_mov_b64_e32 v[116:117], v[222:223]
	v_mov_b64_e32 v[118:119], v[224:225]
	v_mov_b64_e32 v[120:121], v[226:227]
	v_pk_add_f32 v[104:105], v[104:105], v[114:115]
	s_nop 0
	v_pk_add_f32 v[108:109], v[108:109], v[118:119]
	v_mul_f32_e32 v114, 0x3d372713, v104
	v_mul_f32_e32 v115, 0x3d372713, v105
	v_mul_f32_e32 v118, 0x3d372713, v108
	v_mul_f32_e32 v119, 0x3d372713, v109
	v_mul_f32_e32 v114, v104, v114
	v_mul_f32_e32 v115, v105, v115
	v_mul_f32_e32 v118, v108, v118
	v_mul_f32_e32 v119, v109, v119
	v_fma_f32 v114, v104, v114, v104
	v_fma_f32 v115, v105, v115, v105
	v_fma_f32 v118, v108, v118, v108
	v_fma_f32 v119, v109, v119, v109
	v_mul_f32_e32 v114, 0x3f4c422a, v114
	v_mul_f32_e32 v115, 0x3f4c422a, v115
	v_mul_f32_e32 v118, 0x3f4c422a, v118
	v_mul_f32_e32 v119, 0x3f4c422a, v119
	v_add_f32_e32 v114, v114, v114
	v_add_f32_e32 v115, v115, v115
	v_add_f32_e32 v118, v118, v118
	v_add_f32_e32 v119, v119, v119
	v_mul_f32_e32 v114, 0xbfb8aa3b, v114
	v_mul_f32_e32 v115, 0xbfb8aa3b, v115
	v_mul_f32_e32 v118, 0xbfb8aa3b, v118
	v_mul_f32_e32 v119, 0xbfb8aa3b, v119
	v_exp_f32_e32 v114, v114
	v_exp_f32_e32 v115, v115
	v_exp_f32_e32 v118, v118
	v_exp_f32_e32 v119, v119
	v_add_f32_e32 v114, 1.0, v114
	v_add_f32_e32 v115, 1.0, v115
	v_add_f32_e32 v118, 1.0, v118
	v_add_f32_e32 v119, 1.0, v119
	v_rcp_f32_e32 v114, v114
	v_rcp_f32_e32 v115, v115
	v_rcp_f32_e32 v118, v118
	v_rcp_f32_e32 v119, v119
	v_pk_add_f32 v[106:107], v[106:107], v[116:117]
	v_pk_add_f32 v[110:111], v[110:111], v[120:121]
	v_pk_mul_f32 v[114:115], v[104:105], v[114:115]
	v_mul_f32_e32 v104, 0x3d372713, v106
	v_mul_f32_e32 v105, 0x3d372713, v107
	v_pk_mul_f32 v[108:109], v[108:109], v[118:119]
	v_mul_f32_e32 v118, 0x3d372713, v110
	v_mul_f32_e32 v119, 0x3d372713, v111
	v_mul_f32_e32 v104, v106, v104
	v_mul_f32_e32 v105, v107, v105
	v_mul_f32_e32 v118, v110, v118
	v_mul_f32_e32 v119, v111, v119
	v_fma_f32 v104, v106, v104, v106
	v_fma_f32 v105, v107, v105, v107
	v_fma_f32 v118, v110, v118, v110
	v_fma_f32 v119, v111, v119, v111
	v_mul_f32_e32 v104, 0x3f4c422a, v104
	v_mul_f32_e32 v105, 0x3f4c422a, v105
	v_mul_f32_e32 v118, 0x3f4c422a, v118
	v_mul_f32_e32 v119, 0x3f4c422a, v119
	v_add_f32_e32 v104, v104, v104
	v_add_f32_e32 v105, v105, v105
	v_add_f32_e32 v118, v118, v118
	v_add_f32_e32 v119, v119, v119
	v_mul_f32_e32 v104, 0xbfb8aa3b, v104
	v_mul_f32_e32 v105, 0xbfb8aa3b, v105
	v_mul_f32_e32 v118, 0xbfb8aa3b, v118
	v_mul_f32_e32 v119, 0xbfb8aa3b, v119
	v_exp_f32_e32 v104, v104
	v_exp_f32_e32 v105, v105
	v_exp_f32_e32 v118, v118
	v_exp_f32_e32 v119, v119
	v_add_f32_e32 v104, 1.0, v104
	v_add_f32_e32 v105, 1.0, v105
	v_add_f32_e32 v118, 1.0, v118
	v_add_f32_e32 v119, 1.0, v119
	v_rcp_f32_e32 v104, v104
	v_rcp_f32_e32 v105, v105
	v_rcp_f32_e32 v118, v118
	v_rcp_f32_e32 v119, v119
	v_pk_mul_f32 v[116:117], v[106:107], v[104:105]
	v_cvt_pk_bf16_f32 v104, v108, v109
	v_lshlrev_b64 v[108:109], 9, v[112:113]
	v_pk_mul_f32 v[110:111], v[110:111], v[118:119]
	v_lshl_add_u64 v[108:109], s[18:19], 0, v[108:109]
	v_cvt_pk_bf16_f32 v105, v110, v111
	v_cvt_pk_bf16_f32 v106, v114, v115
	v_cvt_pk_bf16_f32 v107, v116, v117
	v_lshl_add_u64 v[108:109], v[108:109], 0, v[124:125]
	global_store_dwordx4 v[108:109], v[104:107], off
	s_nop 0
	s_nop 0
	s_nop 0
	v_mov_b64_e32 v[104:105], v[228:229]
	v_mov_b64_e32 v[106:107], v[230:231]
	v_mov_b64_e32 v[110:111], v[232:233]
	v_mov_b64_e32 v[112:113], v[234:235]
	v_pk_add_f32 v[96:97], v[96:97], v[104:105]
	s_nop 0
	v_pk_add_f32 v[100:101], v[100:101], v[110:111]
	v_mul_f32_e32 v104, 0x3d372713, v96
	v_mul_f32_e32 v110, 0x3d372713, v100
	v_mul_f32_e32 v111, 0x3d372713, v101
	v_mul_f32_e32 v105, 0x3d372713, v97
	v_mul_f32_e32 v110, v100, v110
	v_mul_f32_e32 v111, v101, v111
	v_mul_f32_e32 v104, v96, v104
	v_mul_f32_e32 v105, v97, v105
	v_fma_f32 v110, v100, v110, v100
	v_fma_f32 v111, v101, v111, v101
	v_fma_f32 v104, v96, v104, v96
	v_fma_f32 v105, v97, v105, v97
	v_mul_f32_e32 v110, 0x3f4c422a, v110
	v_mul_f32_e32 v111, 0x3f4c422a, v111
	v_mul_f32_e32 v104, 0x3f4c422a, v104
	v_mul_f32_e32 v105, 0x3f4c422a, v105
	v_add_f32_e32 v110, v110, v110
; __device__ __forceinline__ bf16_t f2bf(float x) { return (bf16_t)(pk2(x, 0.f) & 0xffffu); }
; __device__ __forceinline__ float sigm(float x) { return __builtin_amdgcn_rcpf(1.f + __expf(-x)); }
; __device__ __forceinline__ u32x4 pack8(const float (&f)[8]) { u32x4 w; w.x = pk2(f[0], f[1]); w.y = pk2(f[2], f[3]); w.z = pk2(f[4], f[5]); w.w = pk2(f[6], f[7]); return w; }
;     __device__ __forceinline__ void operator()(const f32x4 (&acc)[2][2][4][2], const pg8::Unit& u, int wr, int wc, int fr, int fq) const {
;     ...
;                     const int c0 = u.pn * 256 + bj * 128 + wc * 32 + 8 * fq;
;                     const f32x4 a0 = acc[ai][bj][m][0], a1 = acc[ai][bj][m][1];
;                     float v[8] = {a0[0], a0[1], a0[2], a0[3], a1[0], a1[1], a1[2], a1[3]};
;                     if (MODE == 0) {
; #pragma unroll
;                         for (int j = 0; j < 8; ++j) v[j] *= rs;
;                         if (u.pn == 4) {
;                             const int b = r >> 12, t = r & 4095, cc = wc * 32 + 8 * fq;
;                             bf16_t* vt = OT + (size_t)bj * ((size_t)16 * 128 * 4096) + ((size_t)(b * 128 + cc)) * 4096 + t;
; #pragma unroll
;                             for (int j = 0; j < 8; ++j) vt[(size_t)j * 4096] = f2bf(v[j]);
;                         } else {
;                             *(u32x4*)(O + (size_t)r * ldc + c0) = pack8(v);
;                         }
;                     } else if (MODE == 1) {
;                         const f32x4 b0 = *(const f32x4*)(bias + c0), b1 = *(const f32x4*)(bias + c0 + 4);
;                         const float bb[8] = {b0[0], b0[1], b0[2], b0[3], b1[0], b1[1], b1[2], b1[3]};
; #pragma unroll
;                         for (int j = 0; j < 8; ++j) { const float x = v[j] + bb[j]; const float uu = 0.7978845608028654f * (x + 0.044715f * x * x * x); v[j] = x * sigm(2.f * uu); }
;                         *(u32x4*)(O + (size_t)r * ldc + c0) = pack8(v);
	v_add_f32_e32 v111, v111, v111
	v_add_f32_e32 v104, v104, v104
	v_add_f32_e32 v105, v105, v105
	v_mul_f32_e32 v110, 0xbfb8aa3b, v110
	v_mul_f32_e32 v111, 0xbfb8aa3b, v111
	v_mul_f32_e32 v104, 0xbfb8aa3b, v104
	v_mul_f32_e32 v105, 0xbfb8aa3b, v105
	v_exp_f32_e32 v110, v110
	v_exp_f32_e32 v111, v111
	v_exp_f32_e32 v104, v104
	v_exp_f32_e32 v105, v105
	v_add_f32_e32 v110, 1.0, v110
	v_add_f32_e32 v111, 1.0, v111
	v_add_f32_e32 v104, 1.0, v104
	v_add_f32_e32 v105, 1.0, v105
	v_rcp_f32_e32 v110, v110
	v_rcp_f32_e32 v111, v111
	v_rcp_f32_e32 v104, v104
	v_rcp_f32_e32 v105, v105
	v_pk_add_f32 v[102:103], v[102:103], v[112:113]
	v_pk_add_f32 v[98:99], v[98:99], v[106:107]
	v_pk_mul_f32 v[100:101], v[100:101], v[110:111]
	v_mul_f32_e32 v110, 0x3d372713, v102
	v_mul_f32_e32 v111, 0x3d372713, v103
	v_pk_mul_f32 v[104:105], v[96:97], v[104:105]
	v_mul_f32_e32 v96, 0x3d372713, v98
	v_mul_f32_e32 v97, 0x3d372713, v99
	v_mul_f32_e32 v110, v102, v110
	v_mul_f32_e32 v111, v103, v111
	v_mul_f32_e32 v96, v98, v96
	v_mul_f32_e32 v97, v99, v97
	v_fma_f32 v110, v102, v110, v102
	v_fma_f32 v111, v103, v111, v103
	v_fma_f32 v96, v98, v96, v98
	v_fma_f32 v97, v99, v97, v99
	v_mul_f32_e32 v110, 0x3f4c422a, v110
	v_mul_f32_e32 v111, 0x3f4c422a, v111
	v_mul_f32_e32 v96, 0x3f4c422a, v96
	v_mul_f32_e32 v97, 0x3f4c422a, v97
	v_add_f32_e32 v110, v110, v110
	v_add_f32_e32 v111, v111, v111
	v_add_f32_e32 v96, v96, v96
	v_add_f32_e32 v97, v97, v97
	v_mul_f32_e32 v110, 0xbfb8aa3b, v110
	v_mul_f32_e32 v111, 0xbfb8aa3b, v111
	v_mul_f32_e32 v96, 0xbfb8aa3b, v96
	v_mul_f32_e32 v97, 0xbfb8aa3b, v97
	v_exp_f32_e32 v110, v110
	v_exp_f32_e32 v111, v111
	v_exp_f32_e32 v96, v96
	v_exp_f32_e32 v97, v97
	v_add_f32_e32 v110, 1.0, v110
	v_add_f32_e32 v111, 1.0, v111
	v_add_f32_e32 v96, 1.0, v96
	v_add_f32_e32 v97, 1.0, v97
	v_rcp_f32_e32 v110, v110
	v_rcp_f32_e32 v111, v111
	v_rcp_f32_e32 v96, v96
	v_rcp_f32_e32 v97, v97
	v_pk_mul_f32 v[102:103], v[102:103], v[110:111]
	v_pk_mul_f32 v[106:107], v[98:99], v[96:97]
	v_cvt_pk_bf16_f32 v96, v100, v101
	v_cvt_pk_bf16_f32 v97, v102, v103
	v_cvt_pk_bf16_f32 v98, v104, v105
	v_cvt_pk_bf16_f32 v99, v106, v107
	global_store_dwordx4 v[108:109], v[96:99], off offset:256
	s_nop 0
	s_nop 0
	v_or_b32_e32 v96, 32, v140
	v_ashrrev_i32_e32 v97, 31, v96
	v_mov_b64_e32 v[98:99], v[220:221]
	v_mov_b64_e32 v[100:101], v[222:223]
	v_mov_b64_e32 v[102:103], v[224:225]
	v_mov_b64_e32 v[104:105], v[226:227]
	v_pk_add_f32 v[88:89], v[88:89], v[98:99]
	s_nop 0
	v_pk_add_f32 v[92:93], v[92:93], v[102:103]
	v_mul_f32_e32 v98, 0x3d372713, v88
	v_mul_f32_e32 v99, 0x3d372713, v89
	v_mul_f32_e32 v102, 0x3d372713, v92
	v_mul_f32_e32 v103, 0x3d372713, v93
	v_mul_f32_e32 v98, v88, v98
	v_mul_f32_e32 v99, v89, v99
	v_mul_f32_e32 v102, v92, v102
	v_mul_f32_e32 v103, v93, v103
	v_fma_f32 v98, v88, v98, v88
	v_fma_f32 v99, v89, v99, v89
	v_fma_f32 v102, v92, v102, v92
	v_fma_f32 v103, v93, v103, v93
	v_mul_f32_e32 v98, 0x3f4c422a, v98
	v_mul_f32_e32 v99, 0x3f4c422a, v99
	v_mul_f32_e32 v102, 0x3f4c422a, v102
	v_mul_f32_e32 v103, 0x3f4c422a, v103
	v_add_f32_e32 v98, v98, v98
	v_add_f32_e32 v99, v99, v99
	v_add_f32_e32 v102, v102, v102
	v_add_f32_e32 v103, v103, v103
	v_mul_f32_e32 v98, 0xbfb8aa3b, v98
	v_mul_f32_e32 v99, 0xbfb8aa3b, v99
	v_mul_f32_e32 v102, 0xbfb8aa3b, v102
	v_mul_f32_e32 v103, 0xbfb8aa3b, v103
	v_exp_f32_e32 v98, v98
	v_exp_f32_e32 v99, v99
	v_exp_f32_e32 v102, v102
	v_exp_f32_e32 v103, v103
	v_add_f32_e32 v98, 1.0, v98
	v_add_f32_e32 v99, 1.0, v99
	v_add_f32_e32 v102, 1.0, v102
	v_add_f32_e32 v103, 1.0, v103
	v_rcp_f32_e32 v98, v98
	v_rcp_f32_e32 v99, v99
	v_rcp_f32_e32 v102, v102
	v_rcp_f32_e32 v103, v103
	v_pk_add_f32 v[90:91], v[90:91], v[100:101]
	v_pk_add_f32 v[94:95], v[94:95], v[104:105]
	v_pk_mul_f32 v[98:99], v[88:89], v[98:99]
	v_mul_f32_e32 v88, 0x3d372713, v90
	v_mul_f32_e32 v89, 0x3d372713, v91
	v_pk_mul_f32 v[92:93], v[92:93], v[102:103]
	v_mul_f32_e32 v102, 0x3d372713, v94
	v_mul_f32_e32 v103, 0x3d372713, v95
	v_mul_f32_e32 v88, v90, v88
	v_mul_f32_e32 v89, v91, v89
	v_mul_f32_e32 v102, v94, v102
	v_mul_f32_e32 v103, v95, v103
	v_fma_f32 v88, v90, v88, v90
	v_fma_f32 v89, v91, v89, v91
	v_fma_f32 v102, v94, v102, v94
	v_fma_f32 v103, v95, v103, v95
	v_mul_f32_e32 v88, 0x3f4c422a, v88
	v_mul_f32_e32 v89, 0x3f4c422a, v89
	v_mul_f32_e32 v102, 0x3f4c422a, v102
	v_mul_f32_e32 v103, 0x3f4c422a, v103
	v_add_f32_e32 v88, v88, v88
	v_add_f32_e32 v89, v89, v89
	v_add_f32_e32 v102, v102, v102
	v_add_f32_e32 v103, v103, v103
	v_mul_f32_e32 v88, 0xbfb8aa3b, v88
	v_mul_f32_e32 v89, 0xbfb8aa3b, v89
	v_mul_f32_e32 v102, 0xbfb8aa3b, v102
	v_mul_f32_e32 v103, 0xbfb8aa3b, v103
	v_exp_f32_e32 v88, v88
	v_exp_f32_e32 v89, v89
	v_exp_f32_e32 v102, v102
	v_exp_f32_e32 v103, v103
	v_add_f32_e32 v88, 1.0, v88
	v_add_f32_e32 v89, 1.0, v89
	v_add_f32_e32 v102, 1.0, v102
	v_add_f32_e32 v103, 1.0, v103
	v_rcp_f32_e32 v88, v88
	v_rcp_f32_e32 v89, v89
	v_rcp_f32_e32 v102, v102
	v_rcp_f32_e32 v103, v103
	v_pk_mul_f32 v[100:101], v[90:91], v[88:89]
	v_cvt_pk_bf16_f32 v88, v92, v93
	v_lshlrev_b64 v[92:93], 9, v[96:97]
	v_pk_mul_f32 v[94:95], v[94:95], v[102:103]
	v_lshl_add_u64 v[92:93], s[18:19], 0, v[92:93]
	v_cvt_pk_bf16_f32 v89, v94, v95
	v_cvt_pk_bf16_f32 v90, v98, v99
	v_cvt_pk_bf16_f32 v91, v100, v101
	v_lshl_add_u64 v[92:93], v[92:93], 0, v[124:125]
	global_store_dwordx4 v[92:93], v[88:91], off
	s_nop 0
	s_nop 0
	s_nop 0
	v_mov_b64_e32 v[88:89], v[228:229]
	v_mov_b64_e32 v[90:91], v[230:231]
	v_mov_b64_e32 v[94:95], v[232:233]
	v_mov_b64_e32 v[96:97], v[234:235]
	v_pk_add_f32 v[80:81], v[80:81], v[88:89]
	s_nop 0
	v_pk_add_f32 v[84:85], v[84:85], v[94:95]
; __device__ __forceinline__ bf16_t f2bf(float x) { return (bf16_t)(pk2(x, 0.f) & 0xffffu); }
; __device__ __forceinline__ float sigm(float x) { return __builtin_amdgcn_rcpf(1.f + __expf(-x)); }
; __device__ __forceinline__ u32x4 pack8(const float (&f)[8]) { u32x4 w; w.x = pk2(f[0], f[1]); w.y = pk2(f[2], f[3]); w.z = pk2(f[4], f[5]); w.w = pk2(f[6], f[7]); return w; }
;     __device__ __forceinline__ void operator()(const f32x4 (&acc)[2][2][4][2], const pg8::Unit& u, int wr, int wc, int fr, int fq) const {
;     ...
;                     const int c0 = u.pn * 256 + bj * 128 + wc * 32 + 8 * fq;
;                     const f32x4 a0 = acc[ai][bj][m][0], a1 = acc[ai][bj][m][1];
;                     float v[8] = {a0[0], a0[1], a0[2], a0[3], a1[0], a1[1], a1[2], a1[3]};
;                     if (MODE == 0) {
; #pragma unroll
;                         for (int j = 0; j < 8; ++j) v[j] *= rs;
;                         if (u.pn == 4) {
;                             const int b = r >> 12, t = r & 4095, cc = wc * 32 + 8 * fq;
;                             bf16_t* vt = OT + (size_t)bj * ((size_t)16 * 128 * 4096) + ((size_t)(b * 128 + cc)) * 4096 + t;
; #pragma unroll
;                             for (int j = 0; j < 8; ++j) vt[(size_t)j * 4096] = f2bf(v[j]);
;                         } else {
;                             *(u32x4*)(O + (size_t)r * ldc + c0) = pack8(v);
;                         }
;                     } else if (MODE == 1) {
;                         const f32x4 b0 = *(const f32x4*)(bias + c0), b1 = *(const f32x4*)(bias + c0 + 4);
;                         const float bb[8] = {b0[0], b0[1], b0[2], b0[3], b1[0], b1[1], b1[2], b1[3]};
; #pragma unroll
;                         for (int j = 0; j < 8; ++j) { const float x = v[j] + bb[j]; const float uu = 0.7978845608028654f * (x + 0.044715f * x * x * x); v[j] = x * sigm(2.f * uu); }
;                         *(u32x4*)(O + (size_t)r * ldc + c0) = pack8(v);
	v_mul_f32_e32 v88, 0x3d372713, v80
	v_mul_f32_e32 v94, 0x3d372713, v84
	v_mul_f32_e32 v95, 0x3d372713, v85
	v_mul_f32_e32 v89, 0x3d372713, v81
	v_mul_f32_e32 v94, v84, v94
	v_mul_f32_e32 v95, v85, v95
	v_mul_f32_e32 v88, v80, v88
	v_mul_f32_e32 v89, v81, v89
	v_fma_f32 v94, v84, v94, v84
	v_fma_f32 v95, v85, v95, v85
	v_fma_f32 v88, v80, v88, v80
	v_fma_f32 v89, v81, v89, v81
	v_mul_f32_e32 v94, 0x3f4c422a, v94
	v_mul_f32_e32 v95, 0x3f4c422a, v95
	v_mul_f32_e32 v88, 0x3f4c422a, v88
	v_mul_f32_e32 v89, 0x3f4c422a, v89
	v_add_f32_e32 v94, v94, v94
	v_add_f32_e32 v95, v95, v95
	v_add_f32_e32 v88, v88, v88
	v_add_f32_e32 v89, v89, v89
	v_mul_f32_e32 v94, 0xbfb8aa3b, v94
	v_mul_f32_e32 v95, 0xbfb8aa3b, v95
	v_mul_f32_e32 v88, 0xbfb8aa3b, v88
	v_mul_f32_e32 v89, 0xbfb8aa3b, v89
	v_exp_f32_e32 v94, v94
	v_exp_f32_e32 v95, v95
	v_exp_f32_e32 v88, v88
	v_exp_f32_e32 v89, v89
	v_add_f32_e32 v94, 1.0, v94
	v_add_f32_e32 v95, 1.0, v95
	v_add_f32_e32 v88, 1.0, v88
	v_add_f32_e32 v89, 1.0, v89
	v_rcp_f32_e32 v94, v94
	v_rcp_f32_e32 v95, v95
	v_rcp_f32_e32 v88, v88
	v_rcp_f32_e32 v89, v89
	v_pk_add_f32 v[86:87], v[86:87], v[96:97]
	v_pk_add_f32 v[82:83], v[82:83], v[90:91]
	v_pk_mul_f32 v[84:85], v[84:85], v[94:95]
	v_mul_f32_e32 v94, 0x3d372713, v86
	v_mul_f32_e32 v95, 0x3d372713, v87
	v_pk_mul_f32 v[88:89], v[80:81], v[88:89]
	v_mul_f32_e32 v80, 0x3d372713, v82
	v_mul_f32_e32 v81, 0x3d372713, v83
	v_mul_f32_e32 v94, v86, v94
	v_mul_f32_e32 v95, v87, v95
	v_mul_f32_e32 v80, v82, v80
	v_mul_f32_e32 v81, v83, v81
	v_fma_f32 v94, v86, v94, v86
	v_fma_f32 v95, v87, v95, v87
	v_fma_f32 v80, v82, v80, v82
	v_fma_f32 v81, v83, v81, v83
	v_mul_f32_e32 v94, 0x3f4c422a, v94
	v_mul_f32_e32 v95, 0x3f4c422a, v95
	v_mul_f32_e32 v80, 0x3f4c422a, v80
	v_mul_f32_e32 v81, 0x3f4c422a, v81
	v_add_f32_e32 v94, v94, v94
	v_add_f32_e32 v95, v95, v95
	v_add_f32_e32 v80, v80, v80
	v_add_f32_e32 v81, v81, v81
	v_mul_f32_e32 v94, 0xbfb8aa3b, v94
	v_mul_f32_e32 v95, 0xbfb8aa3b, v95
	v_mul_f32_e32 v80, 0xbfb8aa3b, v80
	v_mul_f32_e32 v81, 0xbfb8aa3b, v81
	v_exp_f32_e32 v94, v94
	v_exp_f32_e32 v95, v95
	v_exp_f32_e32 v80, v80
	v_exp_f32_e32 v81, v81
	v_add_f32_e32 v94, 1.0, v94
	v_add_f32_e32 v95, 1.0, v95
	v_add_f32_e32 v80, 1.0, v80
	v_add_f32_e32 v81, 1.0, v81
	v_rcp_f32_e32 v94, v94
	v_rcp_f32_e32 v95, v95
	v_rcp_f32_e32 v80, v80
	v_rcp_f32_e32 v81, v81
	v_pk_mul_f32 v[86:87], v[86:87], v[94:95]
	v_pk_mul_f32 v[90:91], v[82:83], v[80:81]
	v_cvt_pk_bf16_f32 v80, v84, v85
	v_cvt_pk_bf16_f32 v81, v86, v87
	v_cvt_pk_bf16_f32 v82, v88, v89
	v_cvt_pk_bf16_f32 v83, v90, v91
	global_store_dwordx4 v[92:93], v[80:83], off offset:256
	s_nop 0
	s_nop 0
	v_or_b32_e32 v80, 48, v140
	v_ashrrev_i32_e32 v81, 31, v80
	v_mov_b64_e32 v[82:83], v[220:221]
	v_mov_b64_e32 v[84:85], v[222:223]
	v_mov_b64_e32 v[86:87], v[224:225]
	v_mov_b64_e32 v[88:89], v[226:227]
	v_pk_add_f32 v[72:73], v[72:73], v[82:83]
	s_nop 0
	v_pk_add_f32 v[76:77], v[76:77], v[86:87]
	v_mul_f32_e32 v82, 0x3d372713, v72
	v_mul_f32_e32 v83, 0x3d372713, v73
	v_mul_f32_e32 v86, 0x3d372713, v76
	v_mul_f32_e32 v87, 0x3d372713, v77
	v_mul_f32_e32 v82, v72, v82
	v_mul_f32_e32 v83, v73, v83
	v_mul_f32_e32 v86, v76, v86
	v_mul_f32_e32 v87, v77, v87
	v_fma_f32 v82, v72, v82, v72
	v_fma_f32 v83, v73, v83, v73
	v_fma_f32 v86, v76, v86, v76
	v_fma_f32 v87, v77, v87, v77
	v_mul_f32_e32 v82, 0x3f4c422a, v82
	v_mul_f32_e32 v83, 0x3f4c422a, v83
	v_mul_f32_e32 v86, 0x3f4c422a, v86
	v_mul_f32_e32 v87, 0x3f4c422a, v87
	v_add_f32_e32 v82, v82, v82
	v_add_f32_e32 v83, v83, v83
	v_add_f32_e32 v86, v86, v86
	v_add_f32_e32 v87, v87, v87
	v_mul_f32_e32 v82, 0xbfb8aa3b, v82
	v_mul_f32_e32 v83, 0xbfb8aa3b, v83
	v_mul_f32_e32 v86, 0xbfb8aa3b, v86
	v_mul_f32_e32 v87, 0xbfb8aa3b, v87
	v_exp_f32_e32 v82, v82
	v_exp_f32_e32 v83, v83
	v_exp_f32_e32 v86, v86
	v_exp_f32_e32 v87, v87
	v_add_f32_e32 v82, 1.0, v82
	v_add_f32_e32 v83, 1.0, v83
	v_add_f32_e32 v86, 1.0, v86
	v_add_f32_e32 v87, 1.0, v87
	v_rcp_f32_e32 v82, v82
	v_rcp_f32_e32 v83, v83
	v_rcp_f32_e32 v86, v86
	v_rcp_f32_e32 v87, v87
	v_pk_add_f32 v[74:75], v[74:75], v[84:85]
	v_pk_add_f32 v[78:79], v[78:79], v[88:89]
	v_pk_mul_f32 v[82:83], v[72:73], v[82:83]
	v_mul_f32_e32 v72, 0x3d372713, v74
	v_mul_f32_e32 v73, 0x3d372713, v75
	v_pk_mul_f32 v[76:77], v[76:77], v[86:87]
	v_mul_f32_e32 v86, 0x3d372713, v78
	v_mul_f32_e32 v87, 0x3d372713, v79
	v_mul_f32_e32 v72, v74, v72
	v_mul_f32_e32 v73, v75, v73
	v_mul_f32_e32 v86, v78, v86
	v_mul_f32_e32 v87, v79, v87
	v_fma_f32 v72, v74, v72, v74
	v_fma_f32 v73, v75, v73, v75
	v_fma_f32 v86, v78, v86, v78
	v_fma_f32 v87, v79, v87, v79
	v_mul_f32_e32 v72, 0x3f4c422a, v72
	v_mul_f32_e32 v73, 0x3f4c422a, v73
	v_mul_f32_e32 v86, 0x3f4c422a, v86
	v_mul_f32_e32 v87, 0x3f4c422a, v87
	v_add_f32_e32 v72, v72, v72
	v_add_f32_e32 v73, v73, v73
	v_add_f32_e32 v86, v86, v86
	v_add_f32_e32 v87, v87, v87
	v_mul_f32_e32 v72, 0xbfb8aa3b, v72
	v_mul_f32_e32 v73, 0xbfb8aa3b, v73
	v_mul_f32_e32 v86, 0xbfb8aa3b, v86
	v_mul_f32_e32 v87, 0xbfb8aa3b, v87
	v_exp_f32_e32 v72, v72
	v_exp_f32_e32 v73, v73
	v_exp_f32_e32 v86, v86
	v_exp_f32_e32 v87, v87
	v_add_f32_e32 v72, 1.0, v72
	v_add_f32_e32 v73, 1.0, v73
	v_add_f32_e32 v86, 1.0, v86
	v_add_f32_e32 v87, 1.0, v87
	v_rcp_f32_e32 v72, v72
	v_rcp_f32_e32 v73, v73
	v_rcp_f32_e32 v86, v86
	v_rcp_f32_e32 v87, v87
	v_pk_mul_f32 v[84:85], v[74:75], v[72:73]
	v_cvt_pk_bf16_f32 v72, v76, v77
	v_lshlrev_b64 v[76:77], 9, v[80:81]
	v_pk_mul_f32 v[78:79], v[78:79], v[86:87]
	v_lshl_add_u64 v[76:77], s[18:19], 0, v[76:77]
	v_cvt_pk_bf16_f32 v73, v78, v79
	v_cvt_pk_bf16_f32 v74, v82, v83
	v_cvt_pk_bf16_f32 v75, v84, v85
	v_lshl_add_u64 v[76:77], v[76:77], 0, v[124:125]
; __device__ __forceinline__ bf16_t f2bf(float x) { return (bf16_t)(pk2(x, 0.f) & 0xffffu); }
; __device__ __forceinline__ float sigm(float x) { return __builtin_amdgcn_rcpf(1.f + __expf(-x)); }
; __device__ __forceinline__ u32x4 pack8(const float (&f)[8]) { u32x4 w; w.x = pk2(f[0], f[1]); w.y = pk2(f[2], f[3]); w.z = pk2(f[4], f[5]); w.w = pk2(f[6], f[7]); return w; }
;     __device__ __forceinline__ void operator()(const f32x4 (&acc)[2][2][4][2], const pg8::Unit& u, int wr, int wc, int fr, int fq) const {
;     ...
;                     const int c0 = u.pn * 256 + bj * 128 + wc * 32 + 8 * fq;
;                     const f32x4 a0 = acc[ai][bj][m][0], a1 = acc[ai][bj][m][1];
;                     float v[8] = {a0[0], a0[1], a0[2], a0[3], a1[0], a1[1], a1[2], a1[3]};
;                     if (MODE == 0) {
; #pragma unroll
;                         for (int j = 0; j < 8; ++j) v[j] *= rs;
;                         if (u.pn == 4) {
;                             const int b = r >> 12, t = r & 4095, cc = wc * 32 + 8 * fq;
;                             bf16_t* vt = OT + (size_t)bj * ((size_t)16 * 128 * 4096) + ((size_t)(b * 128 + cc)) * 4096 + t;
; #pragma unroll
;                             for (int j = 0; j < 8; ++j) vt[(size_t)j * 4096] = f2bf(v[j]);
;                         } else {
;                             *(u32x4*)(O + (size_t)r * ldc + c0) = pack8(v);
;                         }
;                     } else if (MODE == 1) {
;                         const f32x4 b0 = *(const f32x4*)(bias + c0), b1 = *(const f32x4*)(bias + c0 + 4);
;                         const float bb[8] = {b0[0], b0[1], b0[2], b0[3], b1[0], b1[1], b1[2], b1[3]};
; #pragma unroll
;                         for (int j = 0; j < 8; ++j) { const float x = v[j] + bb[j]; const float uu = 0.7978845608028654f * (x + 0.044715f * x * x * x); v[j] = x * sigm(2.f * uu); }
;                         *(u32x4*)(O + (size_t)r * ldc + c0) = pack8(v);
	global_store_dwordx4 v[76:77], v[72:75], off
	s_nop 0
	s_nop 0
	s_nop 0
	v_mov_b64_e32 v[72:73], v[228:229]
	v_mov_b64_e32 v[74:75], v[230:231]
	v_mov_b64_e32 v[78:79], v[232:233]
	v_mov_b64_e32 v[80:81], v[234:235]
	v_pk_add_f32 v[64:65], v[64:65], v[72:73]
	s_nop 0
	v_pk_add_f32 v[68:69], v[68:69], v[78:79]
	v_mul_f32_e32 v72, 0x3d372713, v64
	v_mul_f32_e32 v78, 0x3d372713, v68
	v_mul_f32_e32 v79, 0x3d372713, v69
	v_mul_f32_e32 v73, 0x3d372713, v65
	v_mul_f32_e32 v78, v68, v78
	v_mul_f32_e32 v79, v69, v79
	v_mul_f32_e32 v72, v64, v72
	v_mul_f32_e32 v73, v65, v73
	v_fma_f32 v78, v68, v78, v68
	v_fma_f32 v79, v69, v79, v69
	v_fma_f32 v72, v64, v72, v64
	v_fma_f32 v73, v65, v73, v65
	v_mul_f32_e32 v78, 0x3f4c422a, v78
	v_mul_f32_e32 v79, 0x3f4c422a, v79
	v_mul_f32_e32 v72, 0x3f4c422a, v72
	v_mul_f32_e32 v73, 0x3f4c422a, v73
	v_add_f32_e32 v78, v78, v78
	v_add_f32_e32 v79, v79, v79
	v_add_f32_e32 v72, v72, v72
	v_add_f32_e32 v73, v73, v73
	v_mul_f32_e32 v78, 0xbfb8aa3b, v78
	v_mul_f32_e32 v79, 0xbfb8aa3b, v79
	v_mul_f32_e32 v72, 0xbfb8aa3b, v72
	v_mul_f32_e32 v73, 0xbfb8aa3b, v73
	v_exp_f32_e32 v78, v78
	v_exp_f32_e32 v79, v79
	v_exp_f32_e32 v72, v72
	v_exp_f32_e32 v73, v73
	v_add_f32_e32 v78, 1.0, v78
	v_add_f32_e32 v79, 1.0, v79
	v_add_f32_e32 v72, 1.0, v72
	v_add_f32_e32 v73, 1.0, v73
	v_rcp_f32_e32 v78, v78
	v_rcp_f32_e32 v79, v79
	v_rcp_f32_e32 v72, v72
	v_rcp_f32_e32 v73, v73
	v_pk_add_f32 v[70:71], v[70:71], v[80:81]
	v_pk_add_f32 v[66:67], v[66:67], v[74:75]
	v_pk_mul_f32 v[68:69], v[68:69], v[78:79]
	v_mul_f32_e32 v78, 0x3d372713, v70
	v_mul_f32_e32 v79, 0x3d372713, v71
	v_pk_mul_f32 v[72:73], v[64:65], v[72:73]
	v_mul_f32_e32 v64, 0x3d372713, v66
	v_mul_f32_e32 v65, 0x3d372713, v67
	v_mul_f32_e32 v78, v70, v78
	v_mul_f32_e32 v79, v71, v79
	v_mul_f32_e32 v64, v66, v64
	v_mul_f32_e32 v65, v67, v65
	v_fma_f32 v78, v70, v78, v70
	v_fma_f32 v79, v71, v79, v71
	v_fma_f32 v64, v66, v64, v66
	v_fma_f32 v65, v67, v65, v67
	v_mul_f32_e32 v78, 0x3f4c422a, v78
	v_mul_f32_e32 v79, 0x3f4c422a, v79
	v_mul_f32_e32 v64, 0x3f4c422a, v64
	v_mul_f32_e32 v65, 0x3f4c422a, v65
	v_add_f32_e32 v78, v78, v78
	v_add_f32_e32 v79, v79, v79
	v_add_f32_e32 v64, v64, v64
	v_add_f32_e32 v65, v65, v65
	v_mul_f32_e32 v78, 0xbfb8aa3b, v78
	v_mul_f32_e32 v79, 0xbfb8aa3b, v79
	v_mul_f32_e32 v64, 0xbfb8aa3b, v64
	v_mul_f32_e32 v65, 0xbfb8aa3b, v65
	v_exp_f32_e32 v78, v78
	v_exp_f32_e32 v79, v79
	v_exp_f32_e32 v64, v64
	v_exp_f32_e32 v65, v65
	v_add_f32_e32 v78, 1.0, v78
	v_add_f32_e32 v79, 1.0, v79
	v_add_f32_e32 v64, 1.0, v64
	v_add_f32_e32 v65, 1.0, v65
	v_rcp_f32_e32 v78, v78
	v_rcp_f32_e32 v79, v79
	v_rcp_f32_e32 v64, v64
	v_rcp_f32_e32 v65, v65
	v_pk_mul_f32 v[70:71], v[70:71], v[78:79]
	v_pk_mul_f32 v[74:75], v[66:67], v[64:65]
	v_cvt_pk_bf16_f32 v64, v68, v69
	v_cvt_pk_bf16_f32 v65, v70, v71
	v_cvt_pk_bf16_f32 v66, v72, v73
	v_cvt_pk_bf16_f32 v67, v74, v75
	global_store_dwordx4 v[76:77], v[64:67], off offset:256
	s_nop 0
	s_nop 0
	v_add_u32_e32 v64, 0x80, v140
	v_ashrrev_i32_e32 v65, 31, v64
	v_mov_b64_e32 v[66:67], v[220:221]
	v_mov_b64_e32 v[68:69], v[222:223]
	v_mov_b64_e32 v[70:71], v[224:225]
	v_mov_b64_e32 v[72:73], v[226:227]
	v_pk_add_f32 v[56:57], v[56:57], v[66:67]
	s_nop 0
	v_pk_add_f32 v[60:61], v[60:61], v[70:71]
	v_mul_f32_e32 v66, 0x3d372713, v56
	v_mul_f32_e32 v67, 0x3d372713, v57
	v_mul_f32_e32 v70, 0x3d372713, v60
	v_mul_f32_e32 v71, 0x3d372713, v61
	v_mul_f32_e32 v66, v56, v66
	v_mul_f32_e32 v67, v57, v67
	v_mul_f32_e32 v70, v60, v70
	v_mul_f32_e32 v71, v61, v71
	v_fma_f32 v66, v56, v66, v56
	v_fma_f32 v67, v57, v67, v57
	v_fma_f32 v70, v60, v70, v60
	v_fma_f32 v71, v61, v71, v61
	v_mul_f32_e32 v66, 0x3f4c422a, v66
	v_mul_f32_e32 v67, 0x3f4c422a, v67
	v_mul_f32_e32 v70, 0x3f4c422a, v70
	v_mul_f32_e32 v71, 0x3f4c422a, v71
	v_add_f32_e32 v66, v66, v66
	v_add_f32_e32 v67, v67, v67
	v_add_f32_e32 v70, v70, v70
	v_add_f32_e32 v71, v71, v71
	v_mul_f32_e32 v66, 0xbfb8aa3b, v66
	v_mul_f32_e32 v67, 0xbfb8aa3b, v67
	v_mul_f32_e32 v70, 0xbfb8aa3b, v70
	v_mul_f32_e32 v71, 0xbfb8aa3b, v71
	v_exp_f32_e32 v66, v66
	v_exp_f32_e32 v67, v67
	v_exp_f32_e32 v70, v70
	v_exp_f32_e32 v71, v71
	v_add_f32_e32 v66, 1.0, v66
	v_add_f32_e32 v67, 1.0, v67
	v_add_f32_e32 v70, 1.0, v70
	v_add_f32_e32 v71, 1.0, v71
	v_rcp_f32_e32 v66, v66
	v_rcp_f32_e32 v67, v67
	v_rcp_f32_e32 v70, v70
	v_rcp_f32_e32 v71, v71
	v_pk_add_f32 v[58:59], v[58:59], v[68:69]
	v_pk_add_f32 v[62:63], v[62:63], v[72:73]
	v_pk_mul_f32 v[66:67], v[56:57], v[66:67]
	v_mul_f32_e32 v56, 0x3d372713, v58
	v_mul_f32_e32 v57, 0x3d372713, v59
	v_pk_mul_f32 v[60:61], v[60:61], v[70:71]
	v_mul_f32_e32 v70, 0x3d372713, v62
	v_mul_f32_e32 v71, 0x3d372713, v63
	v_mul_f32_e32 v56, v58, v56
	v_mul_f32_e32 v57, v59, v57
	v_mul_f32_e32 v70, v62, v70
	v_mul_f32_e32 v71, v63, v71
	v_fma_f32 v56, v58, v56, v58
	v_fma_f32 v57, v59, v57, v59
	v_fma_f32 v70, v62, v70, v62
	v_fma_f32 v71, v63, v71, v63
	v_mul_f32_e32 v56, 0x3f4c422a, v56
	v_mul_f32_e32 v57, 0x3f4c422a, v57
	v_mul_f32_e32 v70, 0x3f4c422a, v70
	v_mul_f32_e32 v71, 0x3f4c422a, v71
	v_add_f32_e32 v56, v56, v56
	v_add_f32_e32 v57, v57, v57
	v_add_f32_e32 v70, v70, v70
	v_add_f32_e32 v71, v71, v71
	v_mul_f32_e32 v56, 0xbfb8aa3b, v56
	v_mul_f32_e32 v57, 0xbfb8aa3b, v57
	v_mul_f32_e32 v70, 0xbfb8aa3b, v70
	v_mul_f32_e32 v71, 0xbfb8aa3b, v71
	v_exp_f32_e32 v56, v56
	v_exp_f32_e32 v57, v57
	v_exp_f32_e32 v70, v70
	v_exp_f32_e32 v71, v71
	v_add_f32_e32 v56, 1.0, v56
	v_add_f32_e32 v57, 1.0, v57
	v_add_f32_e32 v70, 1.0, v70
	v_add_f32_e32 v71, 1.0, v71
	v_rcp_f32_e32 v56, v56
	v_rcp_f32_e32 v57, v57
	v_rcp_f32_e32 v70, v70
	v_rcp_f32_e32 v71, v71
; __device__ __forceinline__ bf16_t f2bf(float x) { return (bf16_t)(pk2(x, 0.f) & 0xffffu); }
; __device__ __forceinline__ float sigm(float x) { return __builtin_amdgcn_rcpf(1.f + __expf(-x)); }
; __device__ __forceinline__ u32x4 pack8(const float (&f)[8]) { u32x4 w; w.x = pk2(f[0], f[1]); w.y = pk2(f[2], f[3]); w.z = pk2(f[4], f[5]); w.w = pk2(f[6], f[7]); return w; }
;     __device__ __forceinline__ void operator()(const f32x4 (&acc)[2][2][4][2], const pg8::Unit& u, int wr, int wc, int fr, int fq) const {
;     ...
;                     const int c0 = u.pn * 256 + bj * 128 + wc * 32 + 8 * fq;
;                     const f32x4 a0 = acc[ai][bj][m][0], a1 = acc[ai][bj][m][1];
;                     float v[8] = {a0[0], a0[1], a0[2], a0[3], a1[0], a1[1], a1[2], a1[3]};
;                     if (MODE == 0) {
; #pragma unroll
;                         for (int j = 0; j < 8; ++j) v[j] *= rs;
;                         if (u.pn == 4) {
;                             const int b = r >> 12, t = r & 4095, cc = wc * 32 + 8 * fq;
;                             bf16_t* vt = OT + (size_t)bj * ((size_t)16 * 128 * 4096) + ((size_t)(b * 128 + cc)) * 4096 + t;
; #pragma unroll
;                             for (int j = 0; j < 8; ++j) vt[(size_t)j * 4096] = f2bf(v[j]);
;                         } else {
;                             *(u32x4*)(O + (size_t)r * ldc + c0) = pack8(v);
;                         }
;                     } else if (MODE == 1) {
;                         const f32x4 b0 = *(const f32x4*)(bias + c0), b1 = *(const f32x4*)(bias + c0 + 4);
;                         const float bb[8] = {b0[0], b0[1], b0[2], b0[3], b1[0], b1[1], b1[2], b1[3]};
; #pragma unroll
;                         for (int j = 0; j < 8; ++j) { const float x = v[j] + bb[j]; const float uu = 0.7978845608028654f * (x + 0.044715f * x * x * x); v[j] = x * sigm(2.f * uu); }
;                         *(u32x4*)(O + (size_t)r * ldc + c0) = pack8(v);
	v_pk_mul_f32 v[68:69], v[58:59], v[56:57]
	v_cvt_pk_bf16_f32 v56, v60, v61
	v_lshlrev_b64 v[60:61], 9, v[64:65]
	v_pk_mul_f32 v[62:63], v[62:63], v[70:71]
	v_lshl_add_u64 v[60:61], s[18:19], 0, v[60:61]
	v_cvt_pk_bf16_f32 v57, v62, v63
	v_cvt_pk_bf16_f32 v58, v66, v67
	v_cvt_pk_bf16_f32 v59, v68, v69
	v_lshl_add_u64 v[60:61], v[60:61], 0, v[124:125]
	global_store_dwordx4 v[60:61], v[56:59], off
	s_nop 0
	s_nop 0
	s_nop 0
	v_mov_b64_e32 v[56:57], v[228:229]
	v_mov_b64_e32 v[58:59], v[230:231]
	v_mov_b64_e32 v[62:63], v[232:233]
	v_mov_b64_e32 v[64:65], v[234:235]
	v_pk_add_f32 v[48:49], v[48:49], v[56:57]
	s_nop 0
	v_pk_add_f32 v[52:53], v[52:53], v[62:63]
	v_mul_f32_e32 v56, 0x3d372713, v48
	v_mul_f32_e32 v62, 0x3d372713, v52
	v_mul_f32_e32 v63, 0x3d372713, v53
	v_mul_f32_e32 v57, 0x3d372713, v49
	v_mul_f32_e32 v62, v52, v62
	v_mul_f32_e32 v63, v53, v63
	v_mul_f32_e32 v56, v48, v56
	v_mul_f32_e32 v57, v49, v57
	v_fma_f32 v62, v52, v62, v52
	v_fma_f32 v63, v53, v63, v53
	v_fma_f32 v56, v48, v56, v48
	v_fma_f32 v57, v49, v57, v49
	v_mul_f32_e32 v62, 0x3f4c422a, v62
	v_mul_f32_e32 v63, 0x3f4c422a, v63
	v_mul_f32_e32 v56, 0x3f4c422a, v56
	v_mul_f32_e32 v57, 0x3f4c422a, v57
	v_add_f32_e32 v62, v62, v62
	v_add_f32_e32 v63, v63, v63
	v_add_f32_e32 v56, v56, v56
	v_add_f32_e32 v57, v57, v57
	v_mul_f32_e32 v62, 0xbfb8aa3b, v62
	v_mul_f32_e32 v63, 0xbfb8aa3b, v63
	v_mul_f32_e32 v56, 0xbfb8aa3b, v56
	v_mul_f32_e32 v57, 0xbfb8aa3b, v57
	v_exp_f32_e32 v62, v62
	v_exp_f32_e32 v63, v63
	v_exp_f32_e32 v56, v56
	v_exp_f32_e32 v57, v57
	v_add_f32_e32 v62, 1.0, v62
	v_add_f32_e32 v63, 1.0, v63
	v_add_f32_e32 v56, 1.0, v56
	v_add_f32_e32 v57, 1.0, v57
	v_rcp_f32_e32 v62, v62
	v_rcp_f32_e32 v63, v63
	v_rcp_f32_e32 v56, v56
	v_rcp_f32_e32 v57, v57
	v_pk_add_f32 v[54:55], v[54:55], v[64:65]
	v_pk_add_f32 v[50:51], v[50:51], v[58:59]
	v_pk_mul_f32 v[52:53], v[52:53], v[62:63]
	v_mul_f32_e32 v62, 0x3d372713, v54
	v_mul_f32_e32 v63, 0x3d372713, v55
	v_pk_mul_f32 v[56:57], v[48:49], v[56:57]
	v_mul_f32_e32 v48, 0x3d372713, v50
	v_mul_f32_e32 v49, 0x3d372713, v51
	v_mul_f32_e32 v62, v54, v62
	v_mul_f32_e32 v63, v55, v63
	v_mul_f32_e32 v48, v50, v48
	v_mul_f32_e32 v49, v51, v49
	v_fma_f32 v62, v54, v62, v54
	v_fma_f32 v63, v55, v63, v55
	v_fma_f32 v48, v50, v48, v50
	v_fma_f32 v49, v51, v49, v51
	v_mul_f32_e32 v62, 0x3f4c422a, v62
	v_mul_f32_e32 v63, 0x3f4c422a, v63
	v_mul_f32_e32 v48, 0x3f4c422a, v48
	v_mul_f32_e32 v49, 0x3f4c422a, v49
	v_add_f32_e32 v62, v62, v62
	v_add_f32_e32 v63, v63, v63
	v_add_f32_e32 v48, v48, v48
	v_add_f32_e32 v49, v49, v49
	v_mul_f32_e32 v62, 0xbfb8aa3b, v62
	v_mul_f32_e32 v63, 0xbfb8aa3b, v63
	v_mul_f32_e32 v48, 0xbfb8aa3b, v48
	v_mul_f32_e32 v49, 0xbfb8aa3b, v49
	v_exp_f32_e32 v62, v62
	v_exp_f32_e32 v63, v63
	v_exp_f32_e32 v48, v48
	v_exp_f32_e32 v49, v49
	v_add_f32_e32 v62, 1.0, v62
	v_add_f32_e32 v63, 1.0, v63
	v_add_f32_e32 v48, 1.0, v48
	v_add_f32_e32 v49, 1.0, v49
	v_rcp_f32_e32 v62, v62
	v_rcp_f32_e32 v63, v63
	v_rcp_f32_e32 v48, v48
	v_rcp_f32_e32 v49, v49
	v_pk_mul_f32 v[54:55], v[54:55], v[62:63]
	v_pk_mul_f32 v[58:59], v[50:51], v[48:49]
	v_cvt_pk_bf16_f32 v48, v52, v53
	v_cvt_pk_bf16_f32 v49, v54, v55
	v_cvt_pk_bf16_f32 v50, v56, v57
	v_cvt_pk_bf16_f32 v51, v58, v59
	global_store_dwordx4 v[60:61], v[48:51], off offset:256
	s_nop 0
	s_nop 0
	v_add_u32_e32 v48, 0x90, v140
	v_ashrrev_i32_e32 v49, 31, v48
	v_mov_b64_e32 v[50:51], v[220:221]
	v_mov_b64_e32 v[52:53], v[222:223]
	v_mov_b64_e32 v[54:55], v[224:225]
	v_mov_b64_e32 v[56:57], v[226:227]
	v_pk_add_f32 v[40:41], v[40:41], v[50:51]
	s_nop 0
	v_pk_add_f32 v[44:45], v[44:45], v[54:55]
	v_mul_f32_e32 v50, 0x3d372713, v40
	v_mul_f32_e32 v51, 0x3d372713, v41
	v_mul_f32_e32 v54, 0x3d372713, v44
	v_mul_f32_e32 v55, 0x3d372713, v45
	v_mul_f32_e32 v50, v40, v50
	v_mul_f32_e32 v51, v41, v51
	v_mul_f32_e32 v54, v44, v54
	v_mul_f32_e32 v55, v45, v55
	v_fma_f32 v50, v40, v50, v40
	v_fma_f32 v51, v41, v51, v41
	v_fma_f32 v54, v44, v54, v44
	v_fma_f32 v55, v45, v55, v45
	v_mul_f32_e32 v50, 0x3f4c422a, v50
	v_mul_f32_e32 v51, 0x3f4c422a, v51
	v_mul_f32_e32 v54, 0x3f4c422a, v54
	v_mul_f32_e32 v55, 0x3f4c422a, v55
	v_add_f32_e32 v50, v50, v50
	v_add_f32_e32 v51, v51, v51
	v_add_f32_e32 v54, v54, v54
	v_add_f32_e32 v55, v55, v55
	v_mul_f32_e32 v50, 0xbfb8aa3b, v50
	v_mul_f32_e32 v51, 0xbfb8aa3b, v51
	v_mul_f32_e32 v54, 0xbfb8aa3b, v54
	v_mul_f32_e32 v55, 0xbfb8aa3b, v55
	v_exp_f32_e32 v50, v50
	v_exp_f32_e32 v51, v51
	v_exp_f32_e32 v54, v54
	v_exp_f32_e32 v55, v55
	v_add_f32_e32 v50, 1.0, v50
	v_add_f32_e32 v51, 1.0, v51
	v_add_f32_e32 v54, 1.0, v54
	v_add_f32_e32 v55, 1.0, v55
	v_rcp_f32_e32 v50, v50
	v_rcp_f32_e32 v51, v51
	v_rcp_f32_e32 v54, v54
	v_rcp_f32_e32 v55, v55
	v_pk_add_f32 v[42:43], v[42:43], v[52:53]
	v_pk_add_f32 v[46:47], v[46:47], v[56:57]
	v_pk_mul_f32 v[50:51], v[40:41], v[50:51]
	v_mul_f32_e32 v40, 0x3d372713, v42
	v_mul_f32_e32 v41, 0x3d372713, v43
	v_pk_mul_f32 v[44:45], v[44:45], v[54:55]
	v_mul_f32_e32 v54, 0x3d372713, v46
	v_mul_f32_e32 v55, 0x3d372713, v47
	v_mul_f32_e32 v40, v42, v40
	v_mul_f32_e32 v41, v43, v41
	v_mul_f32_e32 v54, v46, v54
	v_mul_f32_e32 v55, v47, v55
	v_fma_f32 v40, v42, v40, v42
	v_fma_f32 v41, v43, v41, v43
	v_fma_f32 v54, v46, v54, v46
	v_fma_f32 v55, v47, v55, v47
	v_mul_f32_e32 v40, 0x3f4c422a, v40
	v_mul_f32_e32 v41, 0x3f4c422a, v41
	v_mul_f32_e32 v54, 0x3f4c422a, v54
	v_mul_f32_e32 v55, 0x3f4c422a, v55
	v_add_f32_e32 v40, v40, v40
	v_add_f32_e32 v41, v41, v41
	v_add_f32_e32 v54, v54, v54
	v_add_f32_e32 v55, v55, v55
	v_mul_f32_e32 v40, 0xbfb8aa3b, v40
	v_mul_f32_e32 v41, 0xbfb8aa3b, v41
	v_mul_f32_e32 v54, 0xbfb8aa3b, v54
; __device__ __forceinline__ bf16_t f2bf(float x) { return (bf16_t)(pk2(x, 0.f) & 0xffffu); }
; __device__ __forceinline__ float sigm(float x) { return __builtin_amdgcn_rcpf(1.f + __expf(-x)); }
; __device__ __forceinline__ u32x4 pack8(const float (&f)[8]) { u32x4 w; w.x = pk2(f[0], f[1]); w.y = pk2(f[2], f[3]); w.z = pk2(f[4], f[5]); w.w = pk2(f[6], f[7]); return w; }
;     __device__ __forceinline__ void operator()(const f32x4 (&acc)[2][2][4][2], const pg8::Unit& u, int wr, int wc, int fr, int fq) const {
;     ...
;                     const int c0 = u.pn * 256 + bj * 128 + wc * 32 + 8 * fq;
;                     const f32x4 a0 = acc[ai][bj][m][0], a1 = acc[ai][bj][m][1];
;                     float v[8] = {a0[0], a0[1], a0[2], a0[3], a1[0], a1[1], a1[2], a1[3]};
;                     if (MODE == 0) {
; #pragma unroll
;                         for (int j = 0; j < 8; ++j) v[j] *= rs;
;                         if (u.pn == 4) {
;                             const int b = r >> 12, t = r & 4095, cc = wc * 32 + 8 * fq;
;                             bf16_t* vt = OT + (size_t)bj * ((size_t)16 * 128 * 4096) + ((size_t)(b * 128 + cc)) * 4096 + t;
; #pragma unroll
;                             for (int j = 0; j < 8; ++j) vt[(size_t)j * 4096] = f2bf(v[j]);
;                         } else {
;                             *(u32x4*)(O + (size_t)r * ldc + c0) = pack8(v);
;                         }
;                     } else if (MODE == 1) {
;                         const f32x4 b0 = *(const f32x4*)(bias + c0), b1 = *(const f32x4*)(bias + c0 + 4);
;                         const float bb[8] = {b0[0], b0[1], b0[2], b0[3], b1[0], b1[1], b1[2], b1[3]};
; #pragma unroll
;                         for (int j = 0; j < 8; ++j) { const float x = v[j] + bb[j]; const float uu = 0.7978845608028654f * (x + 0.044715f * x * x * x); v[j] = x * sigm(2.f * uu); }
;                         *(u32x4*)(O + (size_t)r * ldc + c0) = pack8(v);
	v_mul_f32_e32 v55, 0xbfb8aa3b, v55
	v_exp_f32_e32 v40, v40
	v_exp_f32_e32 v41, v41
	v_exp_f32_e32 v54, v54
	v_exp_f32_e32 v55, v55
	v_add_f32_e32 v40, 1.0, v40
	v_add_f32_e32 v41, 1.0, v41
	v_add_f32_e32 v54, 1.0, v54
	v_add_f32_e32 v55, 1.0, v55
	v_rcp_f32_e32 v40, v40
	v_rcp_f32_e32 v41, v41
	v_rcp_f32_e32 v54, v54
	v_rcp_f32_e32 v55, v55
	v_pk_mul_f32 v[52:53], v[42:43], v[40:41]
	v_cvt_pk_bf16_f32 v40, v44, v45
	v_lshlrev_b64 v[44:45], 9, v[48:49]
	v_pk_mul_f32 v[46:47], v[46:47], v[54:55]
	v_lshl_add_u64 v[44:45], s[18:19], 0, v[44:45]
	v_cvt_pk_bf16_f32 v41, v46, v47
	v_cvt_pk_bf16_f32 v42, v50, v51
	v_cvt_pk_bf16_f32 v43, v52, v53
	v_lshl_add_u64 v[44:45], v[44:45], 0, v[124:125]
	global_store_dwordx4 v[44:45], v[40:43], off
	s_nop 0
	s_nop 0
	s_nop 0
	v_mov_b64_e32 v[40:41], v[228:229]
	v_mov_b64_e32 v[42:43], v[230:231]
	v_mov_b64_e32 v[46:47], v[232:233]
	v_mov_b64_e32 v[48:49], v[234:235]
	v_pk_add_f32 v[32:33], v[32:33], v[40:41]
	s_nop 0
	v_pk_add_f32 v[36:37], v[36:37], v[46:47]
	v_mul_f32_e32 v40, 0x3d372713, v32
	v_mul_f32_e32 v46, 0x3d372713, v36
	v_mul_f32_e32 v47, 0x3d372713, v37
	v_mul_f32_e32 v41, 0x3d372713, v33
	v_mul_f32_e32 v46, v36, v46
	v_mul_f32_e32 v47, v37, v47
	v_mul_f32_e32 v40, v32, v40
	v_mul_f32_e32 v41, v33, v41
	v_fma_f32 v46, v36, v46, v36
	v_fma_f32 v47, v37, v47, v37
	v_fma_f32 v40, v32, v40, v32
	v_fma_f32 v41, v33, v41, v33
	v_mul_f32_e32 v46, 0x3f4c422a, v46
	v_mul_f32_e32 v47, 0x3f4c422a, v47
	v_mul_f32_e32 v40, 0x3f4c422a, v40
	v_mul_f32_e32 v41, 0x3f4c422a, v41
	v_add_f32_e32 v46, v46, v46
	v_add_f32_e32 v47, v47, v47
	v_add_f32_e32 v40, v40, v40
	v_add_f32_e32 v41, v41, v41
	v_mul_f32_e32 v46, 0xbfb8aa3b, v46
	v_mul_f32_e32 v47, 0xbfb8aa3b, v47
	v_mul_f32_e32 v40, 0xbfb8aa3b, v40
	v_mul_f32_e32 v41, 0xbfb8aa3b, v41
	v_exp_f32_e32 v46, v46
	v_exp_f32_e32 v47, v47
	v_exp_f32_e32 v40, v40
	v_exp_f32_e32 v41, v41
	v_add_f32_e32 v46, 1.0, v46
	v_add_f32_e32 v47, 1.0, v47
	v_add_f32_e32 v40, 1.0, v40
	v_add_f32_e32 v41, 1.0, v41
	v_rcp_f32_e32 v46, v46
	v_rcp_f32_e32 v47, v47
	v_rcp_f32_e32 v40, v40
	v_rcp_f32_e32 v41, v41
	v_pk_add_f32 v[38:39], v[38:39], v[48:49]
	v_pk_add_f32 v[34:35], v[34:35], v[42:43]
	v_pk_mul_f32 v[36:37], v[36:37], v[46:47]
	v_mul_f32_e32 v46, 0x3d372713, v38
	v_mul_f32_e32 v47, 0x3d372713, v39
	v_pk_mul_f32 v[40:41], v[32:33], v[40:41]
	v_mul_f32_e32 v32, 0x3d372713, v34
	v_mul_f32_e32 v33, 0x3d372713, v35
	v_mul_f32_e32 v46, v38, v46
	v_mul_f32_e32 v47, v39, v47
	v_mul_f32_e32 v32, v34, v32
	v_mul_f32_e32 v33, v35, v33
	v_fma_f32 v46, v38, v46, v38
	v_fma_f32 v47, v39, v47, v39
	v_fma_f32 v32, v34, v32, v34
	v_fma_f32 v33, v35, v33, v35
	v_mul_f32_e32 v46, 0x3f4c422a, v46
	v_mul_f32_e32 v47, 0x3f4c422a, v47
	v_mul_f32_e32 v32, 0x3f4c422a, v32
	v_mul_f32_e32 v33, 0x3f4c422a, v33
	v_add_f32_e32 v46, v46, v46
	v_add_f32_e32 v47, v47, v47
	v_add_f32_e32 v32, v32, v32
	v_add_f32_e32 v33, v33, v33
	v_mul_f32_e32 v46, 0xbfb8aa3b, v46
	v_mul_f32_e32 v47, 0xbfb8aa3b, v47
	v_mul_f32_e32 v32, 0xbfb8aa3b, v32
	v_mul_f32_e32 v33, 0xbfb8aa3b, v33
	v_exp_f32_e32 v46, v46
	v_exp_f32_e32 v47, v47
	v_exp_f32_e32 v32, v32
	v_exp_f32_e32 v33, v33
	v_add_f32_e32 v46, 1.0, v46
	v_add_f32_e32 v47, 1.0, v47
	v_add_f32_e32 v32, 1.0, v32
	v_add_f32_e32 v33, 1.0, v33
	v_rcp_f32_e32 v46, v46
	v_rcp_f32_e32 v47, v47
	v_rcp_f32_e32 v32, v32
	v_rcp_f32_e32 v33, v33
	v_pk_mul_f32 v[38:39], v[38:39], v[46:47]
	v_pk_mul_f32 v[42:43], v[34:35], v[32:33]
	v_cvt_pk_bf16_f32 v32, v36, v37
	v_cvt_pk_bf16_f32 v33, v38, v39
	v_cvt_pk_bf16_f32 v34, v40, v41
	v_cvt_pk_bf16_f32 v35, v42, v43
	global_store_dwordx4 v[44:45], v[32:35], off offset:256
	s_nop 0
	s_nop 0
	v_add_u32_e32 v32, 0xa0, v140
	v_ashrrev_i32_e32 v33, 31, v32
	v_mov_b64_e32 v[34:35], v[220:221]
	v_mov_b64_e32 v[36:37], v[222:223]
	v_mov_b64_e32 v[38:39], v[224:225]
	v_mov_b64_e32 v[40:41], v[226:227]
	v_pk_add_f32 v[24:25], v[24:25], v[34:35]
	s_nop 0
	v_pk_add_f32 v[28:29], v[28:29], v[38:39]
	v_mul_f32_e32 v34, 0x3d372713, v24
	v_mul_f32_e32 v35, 0x3d372713, v25
	v_mul_f32_e32 v38, 0x3d372713, v28
	v_mul_f32_e32 v39, 0x3d372713, v29
	v_mul_f32_e32 v34, v24, v34
	v_mul_f32_e32 v35, v25, v35
	v_mul_f32_e32 v38, v28, v38
	v_mul_f32_e32 v39, v29, v39
	v_fma_f32 v34, v24, v34, v24
	v_fma_f32 v35, v25, v35, v25
	v_fma_f32 v38, v28, v38, v28
	v_fma_f32 v39, v29, v39, v29
	v_mul_f32_e32 v34, 0x3f4c422a, v34
	v_mul_f32_e32 v35, 0x3f4c422a, v35
	v_mul_f32_e32 v38, 0x3f4c422a, v38
	v_mul_f32_e32 v39, 0x3f4c422a, v39
	v_add_f32_e32 v34, v34, v34
	v_add_f32_e32 v35, v35, v35
	v_add_f32_e32 v38, v38, v38
	v_add_f32_e32 v39, v39, v39
	v_mul_f32_e32 v34, 0xbfb8aa3b, v34
	v_mul_f32_e32 v35, 0xbfb8aa3b, v35
	v_mul_f32_e32 v38, 0xbfb8aa3b, v38
	v_mul_f32_e32 v39, 0xbfb8aa3b, v39
	v_exp_f32_e32 v34, v34
	v_exp_f32_e32 v35, v35
	v_exp_f32_e32 v38, v38
	v_exp_f32_e32 v39, v39
	v_add_f32_e32 v34, 1.0, v34
	v_add_f32_e32 v35, 1.0, v35
	v_add_f32_e32 v38, 1.0, v38
	v_add_f32_e32 v39, 1.0, v39
	v_rcp_f32_e32 v34, v34
	v_rcp_f32_e32 v35, v35
	v_rcp_f32_e32 v38, v38
	v_rcp_f32_e32 v39, v39
	v_pk_add_f32 v[26:27], v[26:27], v[36:37]
	v_pk_add_f32 v[30:31], v[30:31], v[40:41]
	v_pk_mul_f32 v[34:35], v[24:25], v[34:35]
	v_mul_f32_e32 v24, 0x3d372713, v26
	v_mul_f32_e32 v25, 0x3d372713, v27
	v_pk_mul_f32 v[28:29], v[28:29], v[38:39]
	v_mul_f32_e32 v38, 0x3d372713, v30
	v_mul_f32_e32 v39, 0x3d372713, v31
	v_mul_f32_e32 v24, v26, v24
	v_mul_f32_e32 v25, v27, v25
	v_mul_f32_e32 v38, v30, v38
	v_mul_f32_e32 v39, v31, v39
	v_fma_f32 v24, v26, v24, v26
	v_fma_f32 v25, v27, v25, v27
	v_fma_f32 v38, v30, v38, v30
	v_fma_f32 v39, v31, v39, v31
	v_mul_f32_e32 v24, 0x3f4c422a, v24
; __device__ __forceinline__ bf16_t f2bf(float x) { return (bf16_t)(pk2(x, 0.f) & 0xffffu); }
; __device__ __forceinline__ float sigm(float x) { return __builtin_amdgcn_rcpf(1.f + __expf(-x)); }
; __device__ __forceinline__ u32x4 pack8(const float (&f)[8]) { u32x4 w; w.x = pk2(f[0], f[1]); w.y = pk2(f[2], f[3]); w.z = pk2(f[4], f[5]); w.w = pk2(f[6], f[7]); return w; }
;     __device__ __forceinline__ void operator()(const f32x4 (&acc)[2][2][4][2], const pg8::Unit& u, int wr, int wc, int fr, int fq) const {
;     ...
;                     const int c0 = u.pn * 256 + bj * 128 + wc * 32 + 8 * fq;
;                     const f32x4 a0 = acc[ai][bj][m][0], a1 = acc[ai][bj][m][1];
;                     float v[8] = {a0[0], a0[1], a0[2], a0[3], a1[0], a1[1], a1[2], a1[3]};
;                     if (MODE == 0) {
; #pragma unroll
;                         for (int j = 0; j < 8; ++j) v[j] *= rs;
;                         if (u.pn == 4) {
;                             const int b = r >> 12, t = r & 4095, cc = wc * 32 + 8 * fq;
;                             bf16_t* vt = OT + (size_t)bj * ((size_t)16 * 128 * 4096) + ((size_t)(b * 128 + cc)) * 4096 + t;
; #pragma unroll
;                             for (int j = 0; j < 8; ++j) vt[(size_t)j * 4096] = f2bf(v[j]);
;                         } else {
;                             *(u32x4*)(O + (size_t)r * ldc + c0) = pack8(v);
;                         }
;                     } else if (MODE == 1) {
;                         const f32x4 b0 = *(const f32x4*)(bias + c0), b1 = *(const f32x4*)(bias + c0 + 4);
;                         const float bb[8] = {b0[0], b0[1], b0[2], b0[3], b1[0], b1[1], b1[2], b1[3]};
; #pragma unroll
;                         for (int j = 0; j < 8; ++j) { const float x = v[j] + bb[j]; const float uu = 0.7978845608028654f * (x + 0.044715f * x * x * x); v[j] = x * sigm(2.f * uu); }
;                         *(u32x4*)(O + (size_t)r * ldc + c0) = pack8(v);
	v_mul_f32_e32 v25, 0x3f4c422a, v25
	v_mul_f32_e32 v38, 0x3f4c422a, v38
	v_mul_f32_e32 v39, 0x3f4c422a, v39
	v_add_f32_e32 v24, v24, v24
	v_add_f32_e32 v25, v25, v25
	v_add_f32_e32 v38, v38, v38
	v_add_f32_e32 v39, v39, v39
	v_mul_f32_e32 v24, 0xbfb8aa3b, v24
	v_mul_f32_e32 v25, 0xbfb8aa3b, v25
	v_mul_f32_e32 v38, 0xbfb8aa3b, v38
	v_mul_f32_e32 v39, 0xbfb8aa3b, v39
	v_exp_f32_e32 v24, v24
	v_exp_f32_e32 v25, v25
	v_exp_f32_e32 v38, v38
	v_exp_f32_e32 v39, v39
	v_add_f32_e32 v24, 1.0, v24
	v_add_f32_e32 v25, 1.0, v25
	v_add_f32_e32 v38, 1.0, v38
	v_add_f32_e32 v39, 1.0, v39
	v_rcp_f32_e32 v24, v24
	v_rcp_f32_e32 v25, v25
	v_rcp_f32_e32 v38, v38
	v_rcp_f32_e32 v39, v39
	v_pk_mul_f32 v[36:37], v[26:27], v[24:25]
	v_cvt_pk_bf16_f32 v24, v28, v29
	v_lshlrev_b64 v[28:29], 9, v[32:33]
	v_pk_mul_f32 v[30:31], v[30:31], v[38:39]
	v_lshl_add_u64 v[28:29], s[18:19], 0, v[28:29]
	v_cvt_pk_bf16_f32 v25, v30, v31
	v_cvt_pk_bf16_f32 v26, v34, v35
	v_cvt_pk_bf16_f32 v27, v36, v37
	v_lshl_add_u64 v[28:29], v[28:29], 0, v[124:125]
	global_store_dwordx4 v[28:29], v[24:27], off
	s_nop 0
	s_nop 0
	s_nop 0
	v_mov_b64_e32 v[24:25], v[228:229]
	v_mov_b64_e32 v[26:27], v[230:231]
	v_mov_b64_e32 v[30:31], v[232:233]
	v_mov_b64_e32 v[32:33], v[234:235]
	v_pk_add_f32 v[16:17], v[16:17], v[24:25]
	s_nop 0
	v_pk_add_f32 v[20:21], v[20:21], v[30:31]
	v_mul_f32_e32 v24, 0x3d372713, v16
	v_mul_f32_e32 v30, 0x3d372713, v20
	v_mul_f32_e32 v31, 0x3d372713, v21
	v_mul_f32_e32 v25, 0x3d372713, v17
	v_mul_f32_e32 v30, v20, v30
	v_mul_f32_e32 v31, v21, v31
	v_mul_f32_e32 v24, v16, v24
	v_mul_f32_e32 v25, v17, v25
	v_fma_f32 v30, v20, v30, v20
	v_fma_f32 v31, v21, v31, v21
	v_fma_f32 v24, v16, v24, v16
	v_fma_f32 v25, v17, v25, v17
	v_mul_f32_e32 v30, 0x3f4c422a, v30
	v_mul_f32_e32 v31, 0x3f4c422a, v31
	v_mul_f32_e32 v24, 0x3f4c422a, v24
	v_mul_f32_e32 v25, 0x3f4c422a, v25
	v_add_f32_e32 v30, v30, v30
	v_add_f32_e32 v31, v31, v31
	v_add_f32_e32 v24, v24, v24
	v_add_f32_e32 v25, v25, v25
	v_mul_f32_e32 v30, 0xbfb8aa3b, v30
	v_mul_f32_e32 v31, 0xbfb8aa3b, v31
	v_mul_f32_e32 v24, 0xbfb8aa3b, v24
	v_mul_f32_e32 v25, 0xbfb8aa3b, v25
	v_exp_f32_e32 v30, v30
	v_exp_f32_e32 v31, v31
	v_exp_f32_e32 v24, v24
	v_exp_f32_e32 v25, v25
	v_add_f32_e32 v30, 1.0, v30
	v_add_f32_e32 v31, 1.0, v31
	v_add_f32_e32 v24, 1.0, v24
	v_add_f32_e32 v25, 1.0, v25
	v_rcp_f32_e32 v30, v30
	v_rcp_f32_e32 v31, v31
	v_rcp_f32_e32 v24, v24
	v_rcp_f32_e32 v25, v25
	v_pk_add_f32 v[22:23], v[22:23], v[32:33]
	v_pk_add_f32 v[18:19], v[18:19], v[26:27]
	v_pk_mul_f32 v[20:21], v[20:21], v[30:31]
	v_mul_f32_e32 v30, 0x3d372713, v22
	v_mul_f32_e32 v31, 0x3d372713, v23
	v_pk_mul_f32 v[24:25], v[16:17], v[24:25]
	v_mul_f32_e32 v16, 0x3d372713, v18
	v_mul_f32_e32 v17, 0x3d372713, v19
	v_mul_f32_e32 v30, v22, v30
	v_mul_f32_e32 v31, v23, v31
	v_mul_f32_e32 v16, v18, v16
	v_mul_f32_e32 v17, v19, v17
	v_fma_f32 v30, v22, v30, v22
	v_fma_f32 v31, v23, v31, v23
	v_fma_f32 v16, v18, v16, v18
	v_fma_f32 v17, v19, v17, v19
	v_mul_f32_e32 v30, 0x3f4c422a, v30
	v_mul_f32_e32 v31, 0x3f4c422a, v31
	v_mul_f32_e32 v16, 0x3f4c422a, v16
	v_mul_f32_e32 v17, 0x3f4c422a, v17
	v_add_f32_e32 v30, v30, v30
	v_add_f32_e32 v31, v31, v31
	v_add_f32_e32 v16, v16, v16
	v_add_f32_e32 v17, v17, v17
	v_mul_f32_e32 v30, 0xbfb8aa3b, v30
	v_mul_f32_e32 v31, 0xbfb8aa3b, v31
	v_mul_f32_e32 v16, 0xbfb8aa3b, v16
	v_mul_f32_e32 v17, 0xbfb8aa3b, v17
	v_exp_f32_e32 v30, v30
	v_exp_f32_e32 v31, v31
	v_exp_f32_e32 v16, v16
	v_exp_f32_e32 v17, v17
	v_add_f32_e32 v30, 1.0, v30
	v_add_f32_e32 v31, 1.0, v31
	v_add_f32_e32 v16, 1.0, v16
	v_add_f32_e32 v17, 1.0, v17
	v_rcp_f32_e32 v30, v30
	v_rcp_f32_e32 v31, v31
	v_rcp_f32_e32 v16, v16
	v_rcp_f32_e32 v17, v17
	v_pk_mul_f32 v[22:23], v[22:23], v[30:31]
	v_pk_mul_f32 v[26:27], v[18:19], v[16:17]
	v_cvt_pk_bf16_f32 v16, v20, v21
	v_cvt_pk_bf16_f32 v17, v22, v23
	v_cvt_pk_bf16_f32 v18, v24, v25
	v_cvt_pk_bf16_f32 v19, v26, v27
	global_store_dwordx4 v[28:29], v[16:19], off offset:256
	s_nop 0
	s_nop 0
	v_add_u32_e32 v16, 0xb0, v140
	v_ashrrev_i32_e32 v17, 31, v16
	v_mov_b64_e32 v[18:19], v[220:221]
	v_mov_b64_e32 v[20:21], v[222:223]
	v_mov_b64_e32 v[22:23], v[224:225]
	v_mov_b64_e32 v[24:25], v[226:227]
	v_pk_add_f32 v[8:9], v[8:9], v[18:19]
	s_nop 0
	v_pk_add_f32 v[12:13], v[12:13], v[22:23]
	v_mul_f32_e32 v18, 0x3d372713, v8
	v_mul_f32_e32 v19, 0x3d372713, v9
	v_mul_f32_e32 v22, 0x3d372713, v12
	v_mul_f32_e32 v23, 0x3d372713, v13
	v_mul_f32_e32 v18, v8, v18
	v_mul_f32_e32 v19, v9, v19
	v_mul_f32_e32 v22, v12, v22
	v_mul_f32_e32 v23, v13, v23
	v_fma_f32 v18, v8, v18, v8
	v_fma_f32 v19, v9, v19, v9
	v_fma_f32 v22, v12, v22, v12
	v_fma_f32 v23, v13, v23, v13
	v_mul_f32_e32 v18, 0x3f4c422a, v18
	v_mul_f32_e32 v19, 0x3f4c422a, v19
	v_mul_f32_e32 v22, 0x3f4c422a, v22
	v_mul_f32_e32 v23, 0x3f4c422a, v23
	v_add_f32_e32 v18, v18, v18
	v_add_f32_e32 v19, v19, v19
	v_add_f32_e32 v22, v22, v22
	v_add_f32_e32 v23, v23, v23
; __device__ __forceinline__ bf16_t f2bf(float x) { return (bf16_t)(pk2(x, 0.f) & 0xffffu); }
; template <class Epi, class Sched, bool ALIGN_EPI = true, bool SP2 = true>
; __device__ __forceinline__ void gemm_phase(LAS unsigned char* lds, const Gemm g, const Sched& S, const Epi& E) {
;     ...
;         if constexpr (ALIGN_EPI) { if (wr == 0) PG8_BAR; }
;         E(acc, cur, wr, wc, fr, fq);
;         if (!has_next) break;
; #pragma unroll
;         for (int a = 0; a < 2; ++a)
; #pragma unroll
;             for (int b = 0; b < 2; ++b)
; #pragma unroll
;                 for (int m = 0; m < 4; ++m)
; #pragma unroll
;                     for (int n = 0; n < 2; ++n) acc[a][b][m][n] = (f32x4){0.f, 0.f, 0.f, 0.f};
;         cur = nxt; cA = nA; cB = nB; ++ui;
;         if constexpr (ALIGN_EPI) { if (wr == 1) PG8_BAR; }
;     __device__ __forceinline__ void operator()(const f32x4 (&acc)[2][2][4][2], const pg8::Unit& u, int wr, int wc, int fr, int fq) const {
;     ...
;                     const int c0 = u.pn * 256 + bj * 128 + wc * 32 + 8 * fq;
;                     const f32x4 a0 = acc[ai][bj][m][0], a1 = acc[ai][bj][m][1];
;                     float v[8] = {a0[0], a0[1], a0[2], a0[3], a1[0], a1[1], a1[2], a1[3]};
;                     if (MODE == 0) {
; #pragma unroll
;                         for (int j = 0; j < 8; ++j) v[j] *= rs;
;                         if (u.pn == 4) {
;                             const int b = r >> 12, t = r & 4095, cc = wc * 32 + 8 * fq;
;                             bf16_t* vt = OT + (size_t)bj * ((size_t)16 * 128 * 4096) + ((size_t)(b * 128 + cc)) * 4096 + t;
; #pragma unroll
;                             for (int j = 0; j < 8; ++j) vt[(size_t)j * 4096] = f2bf(v[j]);
;                         } else {
;                             *(u32x4*)(O + (size_t)r * ldc + c0) = pack8(v);
;                         }
;                     } else if (MODE == 1) {
;                         const f32x4 b0 = *(const f32x4*)(bias + c0), b1 = *(const f32x4*)(bias + c0 + 4);
;                         const float bb[8] = {b0[0], b0[1], b0[2], b0[3], b1[0], b1[1], b1[2], b1[3]};
; #pragma unroll
;                         for (int j = 0; j < 8; ++j) { const float x = v[j] + bb[j]; const float uu = 0.7978845608028654f * (x + 0.044715f * x * x * x); v[j] = x * sigm(2.f * uu); }
;                         *(u32x4*)(O + (size_t)r * ldc + c0) = pack8(v);
	v_mul_f32_e32 v18, 0xbfb8aa3b, v18
	v_mul_f32_e32 v19, 0xbfb8aa3b, v19
	v_mul_f32_e32 v22, 0xbfb8aa3b, v22
	v_mul_f32_e32 v23, 0xbfb8aa3b, v23
	v_exp_f32_e32 v18, v18
	v_exp_f32_e32 v19, v19
	v_exp_f32_e32 v22, v22
	v_exp_f32_e32 v23, v23
	v_add_f32_e32 v18, 1.0, v18
	v_add_f32_e32 v19, 1.0, v19
	v_add_f32_e32 v22, 1.0, v22
	v_add_f32_e32 v23, 1.0, v23
	v_rcp_f32_e32 v18, v18
	v_rcp_f32_e32 v19, v19
	v_rcp_f32_e32 v22, v22
	v_rcp_f32_e32 v23, v23
	v_pk_add_f32 v[10:11], v[10:11], v[20:21]
	v_pk_add_f32 v[14:15], v[14:15], v[24:25]
	v_pk_mul_f32 v[18:19], v[8:9], v[18:19]
	v_mul_f32_e32 v8, 0x3d372713, v10
	v_mul_f32_e32 v9, 0x3d372713, v11
	v_pk_mul_f32 v[12:13], v[12:13], v[22:23]
	v_mul_f32_e32 v22, 0x3d372713, v14
	v_mul_f32_e32 v23, 0x3d372713, v15
	v_mul_f32_e32 v8, v10, v8
	v_mul_f32_e32 v9, v11, v9
	v_mul_f32_e32 v22, v14, v22
	v_mul_f32_e32 v23, v15, v23
	v_fma_f32 v8, v10, v8, v10
	v_fma_f32 v9, v11, v9, v11
	v_fma_f32 v22, v14, v22, v14
	v_fma_f32 v23, v15, v23, v15
	v_mul_f32_e32 v8, 0x3f4c422a, v8
	v_mul_f32_e32 v9, 0x3f4c422a, v9
	v_mul_f32_e32 v22, 0x3f4c422a, v22
	v_mul_f32_e32 v23, 0x3f4c422a, v23
	v_add_f32_e32 v8, v8, v8
	v_add_f32_e32 v9, v9, v9
	v_add_f32_e32 v22, v22, v22
	v_add_f32_e32 v23, v23, v23
	v_mul_f32_e32 v8, 0xbfb8aa3b, v8
	v_mul_f32_e32 v9, 0xbfb8aa3b, v9
	v_mul_f32_e32 v22, 0xbfb8aa3b, v22
	v_mul_f32_e32 v23, 0xbfb8aa3b, v23
	v_exp_f32_e32 v8, v8
	v_exp_f32_e32 v9, v9
	v_exp_f32_e32 v22, v22
	v_exp_f32_e32 v23, v23
	v_add_f32_e32 v8, 1.0, v8
	v_add_f32_e32 v9, 1.0, v9
	v_add_f32_e32 v22, 1.0, v22
	v_add_f32_e32 v23, 1.0, v23
	v_rcp_f32_e32 v8, v8
	v_rcp_f32_e32 v9, v9
	v_rcp_f32_e32 v22, v22
	v_rcp_f32_e32 v23, v23
	v_pk_mul_f32 v[20:21], v[10:11], v[8:9]
	v_cvt_pk_bf16_f32 v8, v12, v13
	v_lshlrev_b64 v[12:13], 9, v[16:17]
	v_pk_mul_f32 v[14:15], v[14:15], v[22:23]
	v_lshl_add_u64 v[12:13], s[18:19], 0, v[12:13]
	v_cvt_pk_bf16_f32 v9, v14, v15
	v_cvt_pk_bf16_f32 v10, v18, v19
	v_cvt_pk_bf16_f32 v11, v20, v21
	v_lshl_add_u64 v[12:13], v[12:13], 0, v[124:125]
	global_store_dwordx4 v[12:13], v[8:11], off
	s_nop 0
	s_nop 0
	s_nop 0
	v_mov_b64_e32 v[8:9], v[228:229]
	v_mov_b64_e32 v[10:11], v[230:231]
	v_mov_b64_e32 v[14:15], v[232:233]
	v_mov_b64_e32 v[16:17], v[234:235]
	v_pk_add_f32 v[0:1], v[0:1], v[8:9]
	s_nop 0
	v_pk_add_f32 v[4:5], v[4:5], v[14:15]
	v_mul_f32_e32 v8, 0x3d372713, v0
	v_mul_f32_e32 v14, 0x3d372713, v4
	v_mul_f32_e32 v15, 0x3d372713, v5
	v_mul_f32_e32 v9, 0x3d372713, v1
	v_mul_f32_e32 v14, v4, v14
	v_mul_f32_e32 v15, v5, v15
	v_mul_f32_e32 v8, v0, v8
	v_mul_f32_e32 v9, v1, v9
	v_fma_f32 v14, v4, v14, v4
	v_fma_f32 v15, v5, v15, v5
	v_fma_f32 v8, v0, v8, v0
	v_fma_f32 v9, v1, v9, v1
	v_mul_f32_e32 v14, 0x3f4c422a, v14
	v_mul_f32_e32 v15, 0x3f4c422a, v15
	v_mul_f32_e32 v8, 0x3f4c422a, v8
	v_mul_f32_e32 v9, 0x3f4c422a, v9
	v_add_f32_e32 v14, v14, v14
	v_add_f32_e32 v15, v15, v15
	v_add_f32_e32 v8, v8, v8
	v_add_f32_e32 v9, v9, v9
	v_mul_f32_e32 v14, 0xbfb8aa3b, v14
	v_mul_f32_e32 v15, 0xbfb8aa3b, v15
	v_mul_f32_e32 v8, 0xbfb8aa3b, v8
	v_mul_f32_e32 v9, 0xbfb8aa3b, v9
	v_exp_f32_e32 v14, v14
	v_exp_f32_e32 v15, v15
	v_exp_f32_e32 v8, v8
	v_exp_f32_e32 v9, v9
	v_add_f32_e32 v14, 1.0, v14
	v_add_f32_e32 v15, 1.0, v15
	v_add_f32_e32 v8, 1.0, v8
	v_add_f32_e32 v9, 1.0, v9
	v_rcp_f32_e32 v14, v14
	v_rcp_f32_e32 v15, v15
	v_rcp_f32_e32 v8, v8
	v_rcp_f32_e32 v9, v9
	v_pk_add_f32 v[6:7], v[6:7], v[16:17]
	v_pk_add_f32 v[2:3], v[2:3], v[10:11]
	v_pk_mul_f32 v[4:5], v[4:5], v[14:15]
	v_mul_f32_e32 v14, 0x3d372713, v6
	v_mul_f32_e32 v15, 0x3d372713, v7
	v_pk_mul_f32 v[8:9], v[0:1], v[8:9]
	v_mul_f32_e32 v0, 0x3d372713, v2
	v_mul_f32_e32 v1, 0x3d372713, v3
	v_mul_f32_e32 v14, v6, v14
	v_mul_f32_e32 v15, v7, v15
	v_mul_f32_e32 v0, v2, v0
	v_mul_f32_e32 v1, v3, v1
	v_fma_f32 v14, v6, v14, v6
	v_fma_f32 v15, v7, v15, v7
	v_fma_f32 v0, v2, v0, v2
	v_fma_f32 v1, v3, v1, v3
	v_mul_f32_e32 v14, 0x3f4c422a, v14
	v_mul_f32_e32 v15, 0x3f4c422a, v15
	v_mul_f32_e32 v0, 0x3f4c422a, v0
	v_mul_f32_e32 v1, 0x3f4c422a, v1
	v_add_f32_e32 v14, v14, v14
	v_add_f32_e32 v15, v15, v15
	v_add_f32_e32 v0, v0, v0
	v_add_f32_e32 v1, v1, v1
	v_mul_f32_e32 v14, 0xbfb8aa3b, v14
	v_mul_f32_e32 v15, 0xbfb8aa3b, v15
	v_mul_f32_e32 v0, 0xbfb8aa3b, v0
	v_mul_f32_e32 v1, 0xbfb8aa3b, v1
	v_exp_f32_e32 v14, v14
	v_exp_f32_e32 v15, v15
	v_exp_f32_e32 v0, v0
	v_exp_f32_e32 v1, v1
	v_add_f32_e32 v14, 1.0, v14
	v_add_f32_e32 v15, 1.0, v15
	v_add_f32_e32 v0, 1.0, v0
	v_add_f32_e32 v1, 1.0, v1
	v_rcp_f32_e32 v14, v14
	v_rcp_f32_e32 v15, v15
	v_rcp_f32_e32 v0, v0
	v_rcp_f32_e32 v1, v1
	v_pk_mul_f32 v[6:7], v[6:7], v[14:15]
	v_pk_mul_f32 v[10:11], v[2:3], v[0:1]
	v_cvt_pk_bf16_f32 v0, v4, v5
	v_cvt_pk_bf16_f32 v1, v6, v7
	v_cvt_pk_bf16_f32 v2, v8, v9
	v_cvt_pk_bf16_f32 v3, v10, v11
	global_store_dwordx4 v[12:13], v[0:3], off offset:256
	s_cbranch_vccnz .LBB0_492
	s_andn2_b64 vcc, exec, s[28:29]
	s_cbranch_vccnz .LBB0_491
	s_barrier
	s_branch .LBB0_491

; __device__ __forceinline__ bf16_t f2bf(float x) { return (bf16_t)(pk2(x, 0.f) & 0xffffu); }
; __device__ __forceinline__ float sigm(float x) { return __builtin_amdgcn_rcpf(1.f + __expf(-x)); }
; __device__ __forceinline__ u32x4 pack8(const float (&f)[8]) { u32x4 w; w.x = pk2(f[0], f[1]); w.y = pk2(f[2], f[3]); w.z = pk2(f[4], f[5]); w.w = pk2(f[6], f[7]); return w; }
;     __device__ __forceinline__ void operator()(const f32x4 (&acc)[2][2][4][2], const pg8::Unit& u, int wr, int wc, int fr, int fq) const {
;     ...
;         for (int ai = 0; ai < 2; ++ai)
; #pragma unroll
;             for (int m = 0; m < 4; ++m) {
;                 const int r = u.pm * 256 + ai * 128 + wr * 64 + m * 16 + fr;
;                 float rs = 1.f;
;                 if (MODE == 0 || MODE == 5) rs = rowscale[r];
;                 float ssq = 0.f;
; #pragma unroll
;                 for (int bj = 0; bj < 2; ++bj) {
;                     const int c0 = u.pn * 256 + bj * 128 + wc * 32 + 8 * fq;
;                     const f32x4 a0 = acc[ai][bj][m][0], a1 = acc[ai][bj][m][1];
;                     float v[8] = {a0[0], a0[1], a0[2], a0[3], a1[0], a1[1], a1[2], a1[3]};
;                     if (MODE == 0) {
; #pragma unroll
;                         for (int j = 0; j < 8; ++j) v[j] *= rs;
;                         if (u.pn == 4) {
;                             const int b = r >> 12, t = r & 4095, cc = wc * 32 + 8 * fq;
;                             bf16_t* vt = OT + (size_t)bj * ((size_t)16 * 128 * 4096) + ((size_t)(b * 128 + cc)) * 4096 + t;
; #pragma unroll
;                             for (int j = 0; j < 8; ++j) vt[(size_t)j * 4096] = f2bf(v[j]);
;                         } else {
;                             *(u32x4*)(O + (size_t)r * ldc + c0) = pack8(v);
;                         }
;                     } else if (MODE == 1) {
;                         const f32x4 b0 = *(const f32x4*)(bias + c0), b1 = *(const f32x4*)(bias + c0 + 4);
;                         const float bb[8] = {b0[0], b0[1], b0[2], b0[3], b1[0], b1[1], b1[2], b1[3]};
; #pragma unroll
;                         for (int j = 0; j < 8; ++j) { const float x = v[j] + bb[j]; const float uu = 0.7978845608028654f * (x + 0.044715f * x * x * x); v[j] = x * sigm(2.f * uu); }
;                         *(u32x4*)(O + (size_t)r * ldc + c0) = pack8(v);
.LBB0_531:
	v_lshl_or_b32 v146, s34, 8, v150
	v_ashrrev_i32_e32 v147, 31, v146
	v_lshl_add_u64 v[142:143], v[146:147], 2, s[24:25]
	global_load_dwordx4 v[160:163], v[142:143], off offset:16
	global_load_dwordx4 v[164:167], v[142:143], off
	global_load_dwordx4 v[228:231], v[142:143], off offset:528
	global_load_dwordx4 v[232:235], v[142:143], off offset:512
	v_lshl_add_u32 v140, s33, 8, v157
	v_ashrrev_i32_e32 v141, 31, v140
	s_mov_b64 s[20:21], -1
	s_and_b64 vcc, exec, s[4:5]
	s_waitcnt vmcnt(0)
	v_mov_b64_e32 v[220:221], v[160:161]
	v_mov_b64_e32 v[222:223], v[162:163]
	v_mov_b64_e32 v[224:225], v[164:165]
	v_mov_b64_e32 v[226:227], v[166:167]
	v_pk_add_f32 v[120:121], v[120:121], v[160:161]
	v_pk_add_f32 v[124:125], v[124:125], v[164:165]
	v_pk_add_f32 v[126:127], v[126:127], v[166:167]
	v_mul_f32_e32 v144, 0x3d372713, v124
	v_mul_f32_e32 v145, 0x3d372713, v125
	v_mul_f32_e32 v144, v124, v144
	v_mul_f32_e32 v145, v125, v145
	v_fma_f32 v144, v124, v144, v124
	v_fma_f32 v145, v125, v145, v125
	v_mul_f32_e32 v144, 0x3f4c422a, v144
	v_mul_f32_e32 v145, 0x3f4c422a, v145
	v_add_f32_e32 v144, v144, v144
	v_add_f32_e32 v145, v145, v145
	v_mul_f32_e32 v144, 0xbfb8aa3b, v144
	v_mul_f32_e32 v145, 0xbfb8aa3b, v145
	v_exp_f32_e32 v144, v144
	v_exp_f32_e32 v145, v145
	v_pk_add_f32 v[122:123], v[122:123], v[162:163]
	v_add_f32_e32 v144, 1.0, v144
	v_add_f32_e32 v145, 1.0, v145
	v_rcp_f32_e32 v144, v144
	v_rcp_f32_e32 v145, v145
	s_nop 0
	v_pk_mul_f32 v[124:125], v[124:125], v[144:145]
	v_mul_f32_e32 v144, 0x3d372713, v126
	v_mul_f32_e32 v145, 0x3d372713, v127
	v_mul_f32_e32 v144, v126, v144
	v_mul_f32_e32 v145, v127, v145
	v_fma_f32 v144, v126, v144, v126
	v_fma_f32 v145, v127, v145, v127
	v_mul_f32_e32 v144, 0x3f4c422a, v144
	v_mul_f32_e32 v145, 0x3f4c422a, v145
	v_add_f32_e32 v144, v144, v144
	v_add_f32_e32 v145, v145, v145
	v_mul_f32_e32 v144, 0xbfb8aa3b, v144
	v_mul_f32_e32 v145, 0xbfb8aa3b, v145
	v_exp_f32_e32 v144, v144
	v_exp_f32_e32 v145, v145
	v_add_f32_e32 v144, 1.0, v144
	v_add_f32_e32 v145, 1.0, v145
	v_rcp_f32_e32 v144, v144
	v_rcp_f32_e32 v145, v145
	s_nop 0
	v_pk_mul_f32 v[126:127], v[126:127], v[144:145]
	v_mul_f32_e32 v144, 0x3d372713, v120
	v_mul_f32_e32 v145, 0x3d372713, v121
	v_mul_f32_e32 v144, v120, v144
	v_mul_f32_e32 v145, v121, v145
	v_fma_f32 v144, v120, v144, v120
	v_fma_f32 v145, v121, v145, v121
	v_mul_f32_e32 v144, 0x3f4c422a, v144
	v_mul_f32_e32 v145, 0x3f4c422a, v145
	v_add_f32_e32 v144, v144, v144
	v_add_f32_e32 v145, v145, v145
	v_mul_f32_e32 v144, 0xbfb8aa3b, v144
	v_mul_f32_e32 v145, 0xbfb8aa3b, v145
	v_exp_f32_e32 v144, v144
	v_exp_f32_e32 v145, v145
	v_add_f32_e32 v144, 1.0, v144
	v_add_f32_e32 v145, 1.0, v145
	v_rcp_f32_e32 v144, v144
	v_rcp_f32_e32 v145, v145
	s_nop 0
	v_pk_mul_f32 v[144:145], v[120:121], v[144:145]
	v_mul_f32_e32 v120, 0x3d372713, v122
	v_mul_f32_e32 v121, 0x3d372713, v123
	v_mul_f32_e32 v120, v122, v120
	v_mul_f32_e32 v121, v123, v121
	v_fma_f32 v120, v122, v120, v122
	v_fma_f32 v121, v123, v121, v123
	v_mul_f32_e32 v120, 0x3f4c422a, v120
	v_mul_f32_e32 v121, 0x3f4c422a, v121
	v_add_f32_e32 v120, v120, v120
	v_add_f32_e32 v121, v121, v121
	v_mul_f32_e32 v120, 0xbfb8aa3b, v120
	v_mul_f32_e32 v121, 0xbfb8aa3b, v121
	v_exp_f32_e32 v120, v120
	v_exp_f32_e32 v121, v121
	v_add_f32_e32 v120, 1.0, v120
	v_add_f32_e32 v121, 1.0, v121
	v_rcp_f32_e32 v120, v120
	v_rcp_f32_e32 v121, v121
	s_nop 0
	v_pk_mul_f32 v[154:155], v[122:123], v[120:121]
	v_cvt_pk_bf16_f32 v120, v124, v125
	v_lshlrev_b64 v[124:125], 9, v[140:141]
	v_cvt_pk_bf16_f32 v121, v126, v127
	v_lshl_add_u64 v[126:127], s[16:17], 0, v[124:125]
	v_lshlrev_b64 v[124:125], 1, v[146:147]
	v_cvt_pk_bf16_f32 v122, v144, v145
	v_cvt_pk_bf16_f32 v123, v154, v155
	v_lshl_add_u64 v[144:145], v[126:127], 0, v[124:125]
	global_store_dwordx4 v[144:145], v[120:123], off
	s_nop 1
	v_or_b32_e32 v120, 0x80, v146
	v_ashrrev_i32_e32 v121, 31, v120
	v_lshl_add_u64 v[126:127], v[120:121], 2, s[24:25]
	s_nop 0
	s_nop 0
	v_mov_b64_e32 v[120:121], v[228:229]
	v_mov_b64_e32 v[122:123], v[230:231]
	v_mov_b64_e32 v[160:161], v[232:233]
	v_mov_b64_e32 v[162:163], v[234:235]
	v_pk_add_f32 v[112:113], v[112:113], v[120:121]
	s_nop 0
	v_pk_add_f32 v[116:117], v[116:117], v[160:161]
	v_mul_f32_e32 v120, 0x3d372713, v112
	v_mul_f32_e32 v141, 0x3d372713, v116
	v_mul_f32_e32 v141, v116, v141
	v_fma_f32 v141, v116, v141, v116
	v_mul_f32_e32 v141, 0x3f4c422a, v141
	v_add_f32_e32 v141, v141, v141
	v_mul_f32_e32 v141, 0xbfb8aa3b, v141
	v_exp_f32_e32 v141, v141
	v_mul_f32_e32 v121, 0x3d372713, v113
	v_mul_f32_e32 v120, v112, v120
	v_mul_f32_e32 v121, v113, v121
	v_add_f32_e32 v141, 1.0, v141
	v_rcp_f32_e32 v146, v141
	v_mul_f32_e32 v141, 0x3d372713, v117
	v_mul_f32_e32 v141, v117, v141
	v_fma_f32 v141, v117, v141, v117
	v_mul_f32_e32 v141, 0x3f4c422a, v141
	v_add_f32_e32 v141, v141, v141
	v_mul_f32_e32 v141, 0xbfb8aa3b, v141
	v_exp_f32_e32 v141, v141
	v_fma_f32 v120, v112, v120, v112
	v_fma_f32 v121, v113, v121, v113
	v_pk_add_f32 v[118:119], v[118:119], v[162:163]
	v_add_f32_e32 v141, 1.0, v141
	v_mul_f32_e32 v120, 0x3f4c422a, v120
	v_mul_f32_e32 v121, 0x3f4c422a, v121
	v_rcp_f32_e32 v147, v141
	v_mul_f32_e32 v141, 0x3d372713, v118
	v_add_f32_e32 v120, v120, v120
	v_add_f32_e32 v121, v121, v121
	v_mul_f32_e32 v141, v118, v141
	v_mul_f32_e32 v120, 0xbfb8aa3b, v120
	v_mul_f32_e32 v121, 0xbfb8aa3b, v121
	v_fma_f32 v141, v118, v141, v118
	v_exp_f32_e32 v120, v120
	v_exp_f32_e32 v121, v121
	v_mul_f32_e32 v141, 0x3f4c422a, v141
	v_add_f32_e32 v141, v141, v141
	v_mul_f32_e32 v141, 0xbfb8aa3b, v141
	v_exp_f32_e32 v141, v141
	v_add_f32_e32 v120, 1.0, v120
	v_add_f32_e32 v121, 1.0, v121
; __device__ __forceinline__ bf16_t f2bf(float x) { return (bf16_t)(pk2(x, 0.f) & 0xffffu); }
; __device__ __forceinline__ float sigm(float x) { return __builtin_amdgcn_rcpf(1.f + __expf(-x)); }
; __device__ __forceinline__ u32x4 pack8(const float (&f)[8]) { u32x4 w; w.x = pk2(f[0], f[1]); w.y = pk2(f[2], f[3]); w.z = pk2(f[4], f[5]); w.w = pk2(f[6], f[7]); return w; }
;     __device__ __forceinline__ void operator()(const f32x4 (&acc)[2][2][4][2], const pg8::Unit& u, int wr, int wc, int fr, int fq) const {
;     ...
;                     const int c0 = u.pn * 256 + bj * 128 + wc * 32 + 8 * fq;
;                     const f32x4 a0 = acc[ai][bj][m][0], a1 = acc[ai][bj][m][1];
;                     float v[8] = {a0[0], a0[1], a0[2], a0[3], a1[0], a1[1], a1[2], a1[3]};
;                     if (MODE == 0) {
; #pragma unroll
;                         for (int j = 0; j < 8; ++j) v[j] *= rs;
;                         if (u.pn == 4) {
;                             const int b = r >> 12, t = r & 4095, cc = wc * 32 + 8 * fq;
;                             bf16_t* vt = OT + (size_t)bj * ((size_t)16 * 128 * 4096) + ((size_t)(b * 128 + cc)) * 4096 + t;
; #pragma unroll
;                             for (int j = 0; j < 8; ++j) vt[(size_t)j * 4096] = f2bf(v[j]);
;                         } else {
;                             *(u32x4*)(O + (size_t)r * ldc + c0) = pack8(v);
;                         }
;                     } else if (MODE == 1) {
;                         const f32x4 b0 = *(const f32x4*)(bias + c0), b1 = *(const f32x4*)(bias + c0 + 4);
;                         const float bb[8] = {b0[0], b0[1], b0[2], b0[3], b1[0], b1[1], b1[2], b1[3]};
; #pragma unroll
;                         for (int j = 0; j < 8; ++j) { const float x = v[j] + bb[j]; const float uu = 0.7978845608028654f * (x + 0.044715f * x * x * x); v[j] = x * sigm(2.f * uu); }
;                         *(u32x4*)(O + (size_t)r * ldc + c0) = pack8(v);
	v_rcp_f32_e32 v120, v120
	v_rcp_f32_e32 v121, v121
	v_add_f32_e32 v141, 1.0, v141
	v_pk_add_f32 v[114:115], v[114:115], v[122:123]
	v_pk_mul_f32 v[116:117], v[116:117], v[146:147]
	v_rcp_f32_e32 v146, v141
	v_mul_f32_e32 v141, 0x3d372713, v119
	v_pk_mul_f32 v[120:121], v[112:113], v[120:121]
	v_mul_f32_e32 v112, 0x3d372713, v114
	v_mul_f32_e32 v113, 0x3d372713, v115
	v_mul_f32_e32 v141, v119, v141
	v_mul_f32_e32 v112, v114, v112
	v_mul_f32_e32 v113, v115, v113
	v_fma_f32 v141, v119, v141, v119
	v_fma_f32 v112, v114, v112, v114
	v_fma_f32 v113, v115, v113, v115
	v_mul_f32_e32 v141, 0x3f4c422a, v141
	v_mul_f32_e32 v112, 0x3f4c422a, v112
	v_mul_f32_e32 v113, 0x3f4c422a, v113
	v_add_f32_e32 v141, v141, v141
	v_add_f32_e32 v112, v112, v112
	v_add_f32_e32 v113, v113, v113
	v_mul_f32_e32 v141, 0xbfb8aa3b, v141
	v_mul_f32_e32 v112, 0xbfb8aa3b, v112
	v_mul_f32_e32 v113, 0xbfb8aa3b, v113
	v_exp_f32_e32 v141, v141
	v_exp_f32_e32 v112, v112
	v_exp_f32_e32 v113, v113
	v_add_f32_e32 v141, 1.0, v141
	v_add_f32_e32 v112, 1.0, v112
	v_add_f32_e32 v113, 1.0, v113
	v_rcp_f32_e32 v147, v141
	v_rcp_f32_e32 v112, v112
	v_rcp_f32_e32 v113, v113
	v_pk_mul_f32 v[118:119], v[118:119], v[146:147]
	v_pk_mul_f32 v[122:123], v[114:115], v[112:113]
	v_cvt_pk_bf16_f32 v112, v116, v117
	v_cvt_pk_bf16_f32 v113, v118, v119
	v_cvt_pk_bf16_f32 v114, v120, v121
	v_cvt_pk_bf16_f32 v115, v122, v123
	global_store_dwordx4 v[144:145], v[112:115], off offset:256
	s_nop 0
	s_nop 0
	v_or_b32_e32 v112, 16, v140
	v_ashrrev_i32_e32 v113, 31, v112
	v_mov_b64_e32 v[114:115], v[220:221]
	v_mov_b64_e32 v[116:117], v[222:223]
	v_mov_b64_e32 v[118:119], v[224:225]
	v_mov_b64_e32 v[120:121], v[226:227]
	v_pk_add_f32 v[104:105], v[104:105], v[114:115]
	s_nop 0
	v_pk_add_f32 v[108:109], v[108:109], v[118:119]
	v_mul_f32_e32 v114, 0x3d372713, v104
	v_mul_f32_e32 v115, 0x3d372713, v105
	v_mul_f32_e32 v118, 0x3d372713, v108
	v_mul_f32_e32 v119, 0x3d372713, v109
	v_mul_f32_e32 v114, v104, v114
	v_mul_f32_e32 v115, v105, v115
	v_mul_f32_e32 v118, v108, v118
	v_mul_f32_e32 v119, v109, v119
	v_fma_f32 v114, v104, v114, v104
	v_fma_f32 v115, v105, v115, v105
	v_fma_f32 v118, v108, v118, v108
	v_fma_f32 v119, v109, v119, v109
	v_mul_f32_e32 v114, 0x3f4c422a, v114
	v_mul_f32_e32 v115, 0x3f4c422a, v115
	v_mul_f32_e32 v118, 0x3f4c422a, v118
	v_mul_f32_e32 v119, 0x3f4c422a, v119
	v_add_f32_e32 v114, v114, v114
	v_add_f32_e32 v115, v115, v115
	v_add_f32_e32 v118, v118, v118
	v_add_f32_e32 v119, v119, v119
	v_mul_f32_e32 v114, 0xbfb8aa3b, v114
	v_mul_f32_e32 v115, 0xbfb8aa3b, v115
	v_mul_f32_e32 v118, 0xbfb8aa3b, v118
	v_mul_f32_e32 v119, 0xbfb8aa3b, v119
	v_exp_f32_e32 v114, v114
	v_exp_f32_e32 v115, v115
	v_exp_f32_e32 v118, v118
	v_exp_f32_e32 v119, v119
	v_add_f32_e32 v114, 1.0, v114
	v_add_f32_e32 v115, 1.0, v115
	v_add_f32_e32 v118, 1.0, v118
	v_add_f32_e32 v119, 1.0, v119
	v_rcp_f32_e32 v114, v114
	v_rcp_f32_e32 v115, v115
	v_rcp_f32_e32 v118, v118
	v_rcp_f32_e32 v119, v119
	v_pk_add_f32 v[106:107], v[106:107], v[116:117]
	v_pk_add_f32 v[110:111], v[110:111], v[120:121]
	v_pk_mul_f32 v[114:115], v[104:105], v[114:115]
	v_mul_f32_e32 v104, 0x3d372713, v106
	v_mul_f32_e32 v105, 0x3d372713, v107
	v_pk_mul_f32 v[108:109], v[108:109], v[118:119]
	v_mul_f32_e32 v118, 0x3d372713, v110
	v_mul_f32_e32 v119, 0x3d372713, v111
	v_mul_f32_e32 v104, v106, v104
	v_mul_f32_e32 v105, v107, v105
	v_mul_f32_e32 v118, v110, v118
	v_mul_f32_e32 v119, v111, v119
	v_fma_f32 v104, v106, v104, v106
	v_fma_f32 v105, v107, v105, v107
	v_fma_f32 v118, v110, v118, v110
	v_fma_f32 v119, v111, v119, v111
	v_mul_f32_e32 v104, 0x3f4c422a, v104
	v_mul_f32_e32 v105, 0x3f4c422a, v105
	v_mul_f32_e32 v118, 0x3f4c422a, v118
	v_mul_f32_e32 v119, 0x3f4c422a, v119
	v_add_f32_e32 v104, v104, v104
	v_add_f32_e32 v105, v105, v105
	v_add_f32_e32 v118, v118, v118
	v_add_f32_e32 v119, v119, v119
	v_mul_f32_e32 v104, 0xbfb8aa3b, v104
	v_mul_f32_e32 v105, 0xbfb8aa3b, v105
	v_mul_f32_e32 v118, 0xbfb8aa3b, v118
	v_mul_f32_e32 v119, 0xbfb8aa3b, v119
	v_exp_f32_e32 v104, v104
	v_exp_f32_e32 v105, v105
	v_exp_f32_e32 v118, v118
	v_exp_f32_e32 v119, v119
	v_add_f32_e32 v104, 1.0, v104
	v_add_f32_e32 v105, 1.0, v105
	v_add_f32_e32 v118, 1.0, v118
	v_add_f32_e32 v119, 1.0, v119
	v_rcp_f32_e32 v104, v104
	v_rcp_f32_e32 v105, v105
	v_rcp_f32_e32 v118, v118
	v_rcp_f32_e32 v119, v119
	v_pk_mul_f32 v[116:117], v[106:107], v[104:105]
	v_cvt_pk_bf16_f32 v104, v108, v109
	v_lshlrev_b64 v[108:109], 9, v[112:113]
	v_pk_mul_f32 v[110:111], v[110:111], v[118:119]
	v_lshl_add_u64 v[108:109], s[16:17], 0, v[108:109]
	v_cvt_pk_bf16_f32 v105, v110, v111
	v_cvt_pk_bf16_f32 v106, v114, v115
	v_cvt_pk_bf16_f32 v107, v116, v117
	v_lshl_add_u64 v[108:109], v[108:109], 0, v[124:125]
	global_store_dwordx4 v[108:109], v[104:107], off
	s_nop 0
	s_nop 0
	s_nop 0
	v_mov_b64_e32 v[104:105], v[228:229]
	v_mov_b64_e32 v[106:107], v[230:231]
	v_mov_b64_e32 v[110:111], v[232:233]
	v_mov_b64_e32 v[112:113], v[234:235]
	v_pk_add_f32 v[96:97], v[96:97], v[104:105]
	s_nop 0
	v_pk_add_f32 v[100:101], v[100:101], v[110:111]
	v_mul_f32_e32 v104, 0x3d372713, v96
	v_mul_f32_e32 v110, 0x3d372713, v100
	v_mul_f32_e32 v111, 0x3d372713, v101
	v_mul_f32_e32 v105, 0x3d372713, v97
	v_mul_f32_e32 v110, v100, v110
	v_mul_f32_e32 v111, v101, v111
	v_mul_f32_e32 v104, v96, v104
	v_mul_f32_e32 v105, v97, v105
	v_fma_f32 v110, v100, v110, v100
	v_fma_f32 v111, v101, v111, v101
	v_fma_f32 v104, v96, v104, v96
	v_fma_f32 v105, v97, v105, v97
	v_mul_f32_e32 v110, 0x3f4c422a, v110
	v_mul_f32_e32 v111, 0x3f4c422a, v111
	v_mul_f32_e32 v104, 0x3f4c422a, v104
	v_mul_f32_e32 v105, 0x3f4c422a, v105
	v_add_f32_e32 v110, v110, v110
; __device__ __forceinline__ bf16_t f2bf(float x) { return (bf16_t)(pk2(x, 0.f) & 0xffffu); }
; __device__ __forceinline__ float sigm(float x) { return __builtin_amdgcn_rcpf(1.f + __expf(-x)); }
; __device__ __forceinline__ u32x4 pack8(const float (&f)[8]) { u32x4 w; w.x = pk2(f[0], f[1]); w.y = pk2(f[2], f[3]); w.z = pk2(f[4], f[5]); w.w = pk2(f[6], f[7]); return w; }
;     __device__ __forceinline__ void operator()(const f32x4 (&acc)[2][2][4][2], const pg8::Unit& u, int wr, int wc, int fr, int fq) const {
;     ...
;                     const int c0 = u.pn * 256 + bj * 128 + wc * 32 + 8 * fq;
;                     const f32x4 a0 = acc[ai][bj][m][0], a1 = acc[ai][bj][m][1];
;                     float v[8] = {a0[0], a0[1], a0[2], a0[3], a1[0], a1[1], a1[2], a1[3]};
;                     if (MODE == 0) {
; #pragma unroll
;                         for (int j = 0; j < 8; ++j) v[j] *= rs;
;                         if (u.pn == 4) {
;                             const int b = r >> 12, t = r & 4095, cc = wc * 32 + 8 * fq;
;                             bf16_t* vt = OT + (size_t)bj * ((size_t)16 * 128 * 4096) + ((size_t)(b * 128 + cc)) * 4096 + t;
; #pragma unroll
;                             for (int j = 0; j < 8; ++j) vt[(size_t)j * 4096] = f2bf(v[j]);
;                         } else {
;                             *(u32x4*)(O + (size_t)r * ldc + c0) = pack8(v);
;                         }
;                     } else if (MODE == 1) {
;                         const f32x4 b0 = *(const f32x4*)(bias + c0), b1 = *(const f32x4*)(bias + c0 + 4);
;                         const float bb[8] = {b0[0], b0[1], b0[2], b0[3], b1[0], b1[1], b1[2], b1[3]};
; #pragma unroll
;                         for (int j = 0; j < 8; ++j) { const float x = v[j] + bb[j]; const float uu = 0.7978845608028654f * (x + 0.044715f * x * x * x); v[j] = x * sigm(2.f * uu); }
;                         *(u32x4*)(O + (size_t)r * ldc + c0) = pack8(v);
	v_add_f32_e32 v111, v111, v111
	v_add_f32_e32 v104, v104, v104
	v_add_f32_e32 v105, v105, v105
	v_mul_f32_e32 v110, 0xbfb8aa3b, v110
	v_mul_f32_e32 v111, 0xbfb8aa3b, v111
	v_mul_f32_e32 v104, 0xbfb8aa3b, v104
	v_mul_f32_e32 v105, 0xbfb8aa3b, v105
	v_exp_f32_e32 v110, v110
	v_exp_f32_e32 v111, v111
	v_exp_f32_e32 v104, v104
	v_exp_f32_e32 v105, v105
	v_add_f32_e32 v110, 1.0, v110
	v_add_f32_e32 v111, 1.0, v111
	v_add_f32_e32 v104, 1.0, v104
	v_add_f32_e32 v105, 1.0, v105
	v_rcp_f32_e32 v110, v110
	v_rcp_f32_e32 v111, v111
	v_rcp_f32_e32 v104, v104
	v_rcp_f32_e32 v105, v105
	v_pk_add_f32 v[102:103], v[102:103], v[112:113]
	v_pk_add_f32 v[98:99], v[98:99], v[106:107]
	v_pk_mul_f32 v[100:101], v[100:101], v[110:111]
	v_mul_f32_e32 v110, 0x3d372713, v102
	v_mul_f32_e32 v111, 0x3d372713, v103
	v_pk_mul_f32 v[104:105], v[96:97], v[104:105]
	v_mul_f32_e32 v96, 0x3d372713, v98
	v_mul_f32_e32 v97, 0x3d372713, v99
	v_mul_f32_e32 v110, v102, v110
	v_mul_f32_e32 v111, v103, v111
	v_mul_f32_e32 v96, v98, v96
	v_mul_f32_e32 v97, v99, v97
	v_fma_f32 v110, v102, v110, v102
	v_fma_f32 v111, v103, v111, v103
	v_fma_f32 v96, v98, v96, v98
	v_fma_f32 v97, v99, v97, v99
	v_mul_f32_e32 v110, 0x3f4c422a, v110
	v_mul_f32_e32 v111, 0x3f4c422a, v111
	v_mul_f32_e32 v96, 0x3f4c422a, v96
	v_mul_f32_e32 v97, 0x3f4c422a, v97
	v_add_f32_e32 v110, v110, v110
	v_add_f32_e32 v111, v111, v111
	v_add_f32_e32 v96, v96, v96
	v_add_f32_e32 v97, v97, v97
	v_mul_f32_e32 v110, 0xbfb8aa3b, v110
	v_mul_f32_e32 v111, 0xbfb8aa3b, v111
	v_mul_f32_e32 v96, 0xbfb8aa3b, v96
	v_mul_f32_e32 v97, 0xbfb8aa3b, v97
	v_exp_f32_e32 v110, v110
	v_exp_f32_e32 v111, v111
	v_exp_f32_e32 v96, v96
	v_exp_f32_e32 v97, v97
	v_add_f32_e32 v110, 1.0, v110
	v_add_f32_e32 v111, 1.0, v111
	v_add_f32_e32 v96, 1.0, v96
	v_add_f32_e32 v97, 1.0, v97
	v_rcp_f32_e32 v110, v110
	v_rcp_f32_e32 v111, v111
	v_rcp_f32_e32 v96, v96
	v_rcp_f32_e32 v97, v97
	v_pk_mul_f32 v[102:103], v[102:103], v[110:111]
	v_pk_mul_f32 v[106:107], v[98:99], v[96:97]
	v_cvt_pk_bf16_f32 v96, v100, v101
	v_cvt_pk_bf16_f32 v97, v102, v103
	v_cvt_pk_bf16_f32 v98, v104, v105
	v_cvt_pk_bf16_f32 v99, v106, v107
	global_store_dwordx4 v[108:109], v[96:99], off offset:256
	s_nop 0
	s_nop 0
	v_or_b32_e32 v96, 32, v140
	v_ashrrev_i32_e32 v97, 31, v96
	v_mov_b64_e32 v[98:99], v[220:221]
	v_mov_b64_e32 v[100:101], v[222:223]
	v_mov_b64_e32 v[102:103], v[224:225]
	v_mov_b64_e32 v[104:105], v[226:227]
	v_pk_add_f32 v[88:89], v[88:89], v[98:99]
	s_nop 0
	v_pk_add_f32 v[92:93], v[92:93], v[102:103]
	v_mul_f32_e32 v98, 0x3d372713, v88
	v_mul_f32_e32 v99, 0x3d372713, v89
	v_mul_f32_e32 v102, 0x3d372713, v92
	v_mul_f32_e32 v103, 0x3d372713, v93
	v_mul_f32_e32 v98, v88, v98
	v_mul_f32_e32 v99, v89, v99
	v_mul_f32_e32 v102, v92, v102
	v_mul_f32_e32 v103, v93, v103
	v_fma_f32 v98, v88, v98, v88
	v_fma_f32 v99, v89, v99, v89
	v_fma_f32 v102, v92, v102, v92
	v_fma_f32 v103, v93, v103, v93
	v_mul_f32_e32 v98, 0x3f4c422a, v98
	v_mul_f32_e32 v99, 0x3f4c422a, v99
	v_mul_f32_e32 v102, 0x3f4c422a, v102
	v_mul_f32_e32 v103, 0x3f4c422a, v103
	v_add_f32_e32 v98, v98, v98
	v_add_f32_e32 v99, v99, v99
	v_add_f32_e32 v102, v102, v102
	v_add_f32_e32 v103, v103, v103
	v_mul_f32_e32 v98, 0xbfb8aa3b, v98
	v_mul_f32_e32 v99, 0xbfb8aa3b, v99
	v_mul_f32_e32 v102, 0xbfb8aa3b, v102
	v_mul_f32_e32 v103, 0xbfb8aa3b, v103
	v_exp_f32_e32 v98, v98
	v_exp_f32_e32 v99, v99
	v_exp_f32_e32 v102, v102
	v_exp_f32_e32 v103, v103
	v_add_f32_e32 v98, 1.0, v98
	v_add_f32_e32 v99, 1.0, v99
	v_add_f32_e32 v102, 1.0, v102
	v_add_f32_e32 v103, 1.0, v103
	v_rcp_f32_e32 v98, v98
	v_rcp_f32_e32 v99, v99
	v_rcp_f32_e32 v102, v102
	v_rcp_f32_e32 v103, v103
	v_pk_add_f32 v[90:91], v[90:91], v[100:101]
	v_pk_add_f32 v[94:95], v[94:95], v[104:105]
	v_pk_mul_f32 v[98:99], v[88:89], v[98:99]
	v_mul_f32_e32 v88, 0x3d372713, v90
	v_mul_f32_e32 v89, 0x3d372713, v91
	v_pk_mul_f32 v[92:93], v[92:93], v[102:103]
	v_mul_f32_e32 v102, 0x3d372713, v94
	v_mul_f32_e32 v103, 0x3d372713, v95
	v_mul_f32_e32 v88, v90, v88
	v_mul_f32_e32 v89, v91, v89
	v_mul_f32_e32 v102, v94, v102
	v_mul_f32_e32 v103, v95, v103
	v_fma_f32 v88, v90, v88, v90
	v_fma_f32 v89, v91, v89, v91
	v_fma_f32 v102, v94, v102, v94
	v_fma_f32 v103, v95, v103, v95
	v_mul_f32_e32 v88, 0x3f4c422a, v88
	v_mul_f32_e32 v89, 0x3f4c422a, v89
	v_mul_f32_e32 v102, 0x3f4c422a, v102
	v_mul_f32_e32 v103, 0x3f4c422a, v103
	v_add_f32_e32 v88, v88, v88
	v_add_f32_e32 v89, v89, v89
	v_add_f32_e32 v102, v102, v102
	v_add_f32_e32 v103, v103, v103
	v_mul_f32_e32 v88, 0xbfb8aa3b, v88
	v_mul_f32_e32 v89, 0xbfb8aa3b, v89
	v_mul_f32_e32 v102, 0xbfb8aa3b, v102
	v_mul_f32_e32 v103, 0xbfb8aa3b, v103
	v_exp_f32_e32 v88, v88
	v_exp_f32_e32 v89, v89
	v_exp_f32_e32 v102, v102
	v_exp_f32_e32 v103, v103
	v_add_f32_e32 v88, 1.0, v88
	v_add_f32_e32 v89, 1.0, v89
	v_add_f32_e32 v102, 1.0, v102
	v_add_f32_e32 v103, 1.0, v103
	v_rcp_f32_e32 v88, v88
	v_rcp_f32_e32 v89, v89
	v_rcp_f32_e32 v102, v102
	v_rcp_f32_e32 v103, v103
	v_pk_mul_f32 v[100:101], v[90:91], v[88:89]
	v_cvt_pk_bf16_f32 v88, v92, v93
	v_lshlrev_b64 v[92:93], 9, v[96:97]
	v_pk_mul_f32 v[94:95], v[94:95], v[102:103]
	v_lshl_add_u64 v[92:93], s[16:17], 0, v[92:93]
	v_cvt_pk_bf16_f32 v89, v94, v95
	v_cvt_pk_bf16_f32 v90, v98, v99
	v_cvt_pk_bf16_f32 v91, v100, v101
	v_lshl_add_u64 v[92:93], v[92:93], 0, v[124:125]
	global_store_dwordx4 v[92:93], v[88:91], off
	s_nop 0
	s_nop 0
	s_nop 0
	v_mov_b64_e32 v[88:89], v[228:229]
	v_mov_b64_e32 v[90:91], v[230:231]
	v_mov_b64_e32 v[94:95], v[232:233]
	v_mov_b64_e32 v[96:97], v[234:235]
	v_pk_add_f32 v[80:81], v[80:81], v[88:89]
	s_nop 0
	v_pk_add_f32 v[84:85], v[84:85], v[94:95]
; __device__ __forceinline__ bf16_t f2bf(float x) { return (bf16_t)(pk2(x, 0.f) & 0xffffu); }
; __device__ __forceinline__ float sigm(float x) { return __builtin_amdgcn_rcpf(1.f + __expf(-x)); }
; __device__ __forceinline__ u32x4 pack8(const float (&f)[8]) { u32x4 w; w.x = pk2(f[0], f[1]); w.y = pk2(f[2], f[3]); w.z = pk2(f[4], f[5]); w.w = pk2(f[6], f[7]); return w; }
;     __device__ __forceinline__ void operator()(const f32x4 (&acc)[2][2][4][2], const pg8::Unit& u, int wr, int wc, int fr, int fq) const {
;     ...
;                     const int c0 = u.pn * 256 + bj * 128 + wc * 32 + 8 * fq;
;                     const f32x4 a0 = acc[ai][bj][m][0], a1 = acc[ai][bj][m][1];
;                     float v[8] = {a0[0], a0[1], a0[2], a0[3], a1[0], a1[1], a1[2], a1[3]};
;                     if (MODE == 0) {
; #pragma unroll
;                         for (int j = 0; j < 8; ++j) v[j] *= rs;
;                         if (u.pn == 4) {
;                             const int b = r >> 12, t = r & 4095, cc = wc * 32 + 8 * fq;
;                             bf16_t* vt = OT + (size_t)bj * ((size_t)16 * 128 * 4096) + ((size_t)(b * 128 + cc)) * 4096 + t;
; #pragma unroll
;                             for (int j = 0; j < 8; ++j) vt[(size_t)j * 4096] = f2bf(v[j]);
;                         } else {
;                             *(u32x4*)(O + (size_t)r * ldc + c0) = pack8(v);
;                         }
;                     } else if (MODE == 1) {
;                         const f32x4 b0 = *(const f32x4*)(bias + c0), b1 = *(const f32x4*)(bias + c0 + 4);
;                         const float bb[8] = {b0[0], b0[1], b0[2], b0[3], b1[0], b1[1], b1[2], b1[3]};
; #pragma unroll
;                         for (int j = 0; j < 8; ++j) { const float x = v[j] + bb[j]; const float uu = 0.7978845608028654f * (x + 0.044715f * x * x * x); v[j] = x * sigm(2.f * uu); }
;                         *(u32x4*)(O + (size_t)r * ldc + c0) = pack8(v);
	v_mul_f32_e32 v88, 0x3d372713, v80
	v_mul_f32_e32 v94, 0x3d372713, v84
	v_mul_f32_e32 v95, 0x3d372713, v85
	v_mul_f32_e32 v89, 0x3d372713, v81
	v_mul_f32_e32 v94, v84, v94
	v_mul_f32_e32 v95, v85, v95
	v_mul_f32_e32 v88, v80, v88
	v_mul_f32_e32 v89, v81, v89
	v_fma_f32 v94, v84, v94, v84
	v_fma_f32 v95, v85, v95, v85
	v_fma_f32 v88, v80, v88, v80
	v_fma_f32 v89, v81, v89, v81
	v_mul_f32_e32 v94, 0x3f4c422a, v94
	v_mul_f32_e32 v95, 0x3f4c422a, v95
	v_mul_f32_e32 v88, 0x3f4c422a, v88
	v_mul_f32_e32 v89, 0x3f4c422a, v89
	v_add_f32_e32 v94, v94, v94
	v_add_f32_e32 v95, v95, v95
	v_add_f32_e32 v88, v88, v88
	v_add_f32_e32 v89, v89, v89
	v_mul_f32_e32 v94, 0xbfb8aa3b, v94
	v_mul_f32_e32 v95, 0xbfb8aa3b, v95
	v_mul_f32_e32 v88, 0xbfb8aa3b, v88
	v_mul_f32_e32 v89, 0xbfb8aa3b, v89
	v_exp_f32_e32 v94, v94
	v_exp_f32_e32 v95, v95
	v_exp_f32_e32 v88, v88
	v_exp_f32_e32 v89, v89
	v_add_f32_e32 v94, 1.0, v94
	v_add_f32_e32 v95, 1.0, v95
	v_add_f32_e32 v88, 1.0, v88
	v_add_f32_e32 v89, 1.0, v89
	v_rcp_f32_e32 v94, v94
	v_rcp_f32_e32 v95, v95
	v_rcp_f32_e32 v88, v88
	v_rcp_f32_e32 v89, v89
	v_pk_add_f32 v[86:87], v[86:87], v[96:97]
	v_pk_add_f32 v[82:83], v[82:83], v[90:91]
	v_pk_mul_f32 v[84:85], v[84:85], v[94:95]
	v_mul_f32_e32 v94, 0x3d372713, v86
	v_mul_f32_e32 v95, 0x3d372713, v87
	v_pk_mul_f32 v[88:89], v[80:81], v[88:89]
	v_mul_f32_e32 v80, 0x3d372713, v82
	v_mul_f32_e32 v81, 0x3d372713, v83
	v_mul_f32_e32 v94, v86, v94
	v_mul_f32_e32 v95, v87, v95
	v_mul_f32_e32 v80, v82, v80
	v_mul_f32_e32 v81, v83, v81
	v_fma_f32 v94, v86, v94, v86
	v_fma_f32 v95, v87, v95, v87
	v_fma_f32 v80, v82, v80, v82
	v_fma_f32 v81, v83, v81, v83
	v_mul_f32_e32 v94, 0x3f4c422a, v94
	v_mul_f32_e32 v95, 0x3f4c422a, v95
	v_mul_f32_e32 v80, 0x3f4c422a, v80
	v_mul_f32_e32 v81, 0x3f4c422a, v81
	v_add_f32_e32 v94, v94, v94
	v_add_f32_e32 v95, v95, v95
	v_add_f32_e32 v80, v80, v80
	v_add_f32_e32 v81, v81, v81
	v_mul_f32_e32 v94, 0xbfb8aa3b, v94
	v_mul_f32_e32 v95, 0xbfb8aa3b, v95
	v_mul_f32_e32 v80, 0xbfb8aa3b, v80
	v_mul_f32_e32 v81, 0xbfb8aa3b, v81
	v_exp_f32_e32 v94, v94
	v_exp_f32_e32 v95, v95
	v_exp_f32_e32 v80, v80
	v_exp_f32_e32 v81, v81
	v_add_f32_e32 v94, 1.0, v94
	v_add_f32_e32 v95, 1.0, v95
	v_add_f32_e32 v80, 1.0, v80
	v_add_f32_e32 v81, 1.0, v81
	v_rcp_f32_e32 v94, v94
	v_rcp_f32_e32 v95, v95
	v_rcp_f32_e32 v80, v80
	v_rcp_f32_e32 v81, v81
	v_pk_mul_f32 v[86:87], v[86:87], v[94:95]
	v_pk_mul_f32 v[90:91], v[82:83], v[80:81]
	v_cvt_pk_bf16_f32 v80, v84, v85
	v_cvt_pk_bf16_f32 v81, v86, v87
	v_cvt_pk_bf16_f32 v82, v88, v89
	v_cvt_pk_bf16_f32 v83, v90, v91
	global_store_dwordx4 v[92:93], v[80:83], off offset:256
	s_nop 0
	s_nop 0
	v_or_b32_e32 v80, 48, v140
	v_ashrrev_i32_e32 v81, 31, v80
	v_mov_b64_e32 v[82:83], v[220:221]
	v_mov_b64_e32 v[84:85], v[222:223]
	v_mov_b64_e32 v[86:87], v[224:225]
	v_mov_b64_e32 v[88:89], v[226:227]
	v_pk_add_f32 v[72:73], v[72:73], v[82:83]
	s_nop 0
	v_pk_add_f32 v[76:77], v[76:77], v[86:87]
	v_mul_f32_e32 v82, 0x3d372713, v72
	v_mul_f32_e32 v83, 0x3d372713, v73
	v_mul_f32_e32 v86, 0x3d372713, v76
	v_mul_f32_e32 v87, 0x3d372713, v77
	v_mul_f32_e32 v82, v72, v82
	v_mul_f32_e32 v83, v73, v83
	v_mul_f32_e32 v86, v76, v86
	v_mul_f32_e32 v87, v77, v87
	v_fma_f32 v82, v72, v82, v72
	v_fma_f32 v83, v73, v83, v73
	v_fma_f32 v86, v76, v86, v76
	v_fma_f32 v87, v77, v87, v77
	v_mul_f32_e32 v82, 0x3f4c422a, v82
	v_mul_f32_e32 v83, 0x3f4c422a, v83
	v_mul_f32_e32 v86, 0x3f4c422a, v86
	v_mul_f32_e32 v87, 0x3f4c422a, v87
	v_add_f32_e32 v82, v82, v82
	v_add_f32_e32 v83, v83, v83
	v_add_f32_e32 v86, v86, v86
	v_add_f32_e32 v87, v87, v87
	v_mul_f32_e32 v82, 0xbfb8aa3b, v82
	v_mul_f32_e32 v83, 0xbfb8aa3b, v83
	v_mul_f32_e32 v86, 0xbfb8aa3b, v86
	v_mul_f32_e32 v87, 0xbfb8aa3b, v87
	v_exp_f32_e32 v82, v82
	v_exp_f32_e32 v83, v83
	v_exp_f32_e32 v86, v86
	v_exp_f32_e32 v87, v87
	v_add_f32_e32 v82, 1.0, v82
	v_add_f32_e32 v83, 1.0, v83
	v_add_f32_e32 v86, 1.0, v86
	v_add_f32_e32 v87, 1.0, v87
	v_rcp_f32_e32 v82, v82
	v_rcp_f32_e32 v83, v83
	v_rcp_f32_e32 v86, v86
	v_rcp_f32_e32 v87, v87
	v_pk_add_f32 v[74:75], v[74:75], v[84:85]
	v_pk_add_f32 v[78:79], v[78:79], v[88:89]
	v_pk_mul_f32 v[82:83], v[72:73], v[82:83]
	v_mul_f32_e32 v72, 0x3d372713, v74
	v_mul_f32_e32 v73, 0x3d372713, v75
	v_pk_mul_f32 v[76:77], v[76:77], v[86:87]
	v_mul_f32_e32 v86, 0x3d372713, v78
	v_mul_f32_e32 v87, 0x3d372713, v79
	v_mul_f32_e32 v72, v74, v72
	v_mul_f32_e32 v73, v75, v73
	v_mul_f32_e32 v86, v78, v86
	v_mul_f32_e32 v87, v79, v87
	v_fma_f32 v72, v74, v72, v74
	v_fma_f32 v73, v75, v73, v75
	v_fma_f32 v86, v78, v86, v78
	v_fma_f32 v87, v79, v87, v79
	v_mul_f32_e32 v72, 0x3f4c422a, v72
	v_mul_f32_e32 v73, 0x3f4c422a, v73
	v_mul_f32_e32 v86, 0x3f4c422a, v86
	v_mul_f32_e32 v87, 0x3f4c422a, v87
	v_add_f32_e32 v72, v72, v72
	v_add_f32_e32 v73, v73, v73
	v_add_f32_e32 v86, v86, v86
	v_add_f32_e32 v87, v87, v87
	v_mul_f32_e32 v72, 0xbfb8aa3b, v72
	v_mul_f32_e32 v73, 0xbfb8aa3b, v73
	v_mul_f32_e32 v86, 0xbfb8aa3b, v86
	v_mul_f32_e32 v87, 0xbfb8aa3b, v87
	v_exp_f32_e32 v72, v72
	v_exp_f32_e32 v73, v73
	v_exp_f32_e32 v86, v86
	v_exp_f32_e32 v87, v87
	v_add_f32_e32 v72, 1.0, v72
	v_add_f32_e32 v73, 1.0, v73
	v_add_f32_e32 v86, 1.0, v86
	v_add_f32_e32 v87, 1.0, v87
	v_rcp_f32_e32 v72, v72
	v_rcp_f32_e32 v73, v73
	v_rcp_f32_e32 v86, v86
	v_rcp_f32_e32 v87, v87
	v_pk_mul_f32 v[84:85], v[74:75], v[72:73]
	v_cvt_pk_bf16_f32 v72, v76, v77
	v_lshlrev_b64 v[76:77], 9, v[80:81]
	v_pk_mul_f32 v[78:79], v[78:79], v[86:87]
	v_lshl_add_u64 v[76:77], s[16:17], 0, v[76:77]
	v_cvt_pk_bf16_f32 v73, v78, v79
	v_cvt_pk_bf16_f32 v74, v82, v83
	v_cvt_pk_bf16_f32 v75, v84, v85
	v_lshl_add_u64 v[76:77], v[76:77], 0, v[124:125]
; __device__ __forceinline__ float sigm(float x) { return __builtin_amdgcn_rcpf(1.f + __expf(-x)); }
; __device__ __forceinline__ u32x4 pack8(const float (&f)[8]) { u32x4 w; w.x = pk2(f[0], f[1]); w.y = pk2(f[2], f[3]); w.z = pk2(f[4], f[5]); w.w = pk2(f[6], f[7]); return w; }
;     __device__ __forceinline__ void operator()(const f32x4 (&acc)[2][2][4][2], const pg8::Unit& u, int wr, int wc, int fr, int fq) const {
;     ...
;                         const f32x4 b0 = *(const f32x4*)(bias + c0), b1 = *(const f32x4*)(bias + c0 + 4);
;                         const float bb[8] = {b0[0], b0[1], b0[2], b0[3], b1[0], b1[1], b1[2], b1[3]};
; #pragma unroll
;                         for (int j = 0; j < 8; ++j) { const float x = v[j] + bb[j]; const float uu = 0.7978845608028654f * (x + 0.044715f * x * x * x); v[j] = x * sigm(2.f * uu); }
;                         *(u32x4*)(O + (size_t)r * ldc + c0) = pack8(v);
	global_store_dwordx4 v[76:77], v[72:75], off
	s_nop 0
	s_nop 0
	s_nop 0
	v_mov_b64_e32 v[72:73], v[228:229]
	v_mov_b64_e32 v[74:75], v[230:231]
	v_mov_b64_e32 v[78:79], v[232:233]
	v_mov_b64_e32 v[80:81], v[234:235]
	v_pk_add_f32 v[64:65], v[64:65], v[72:73]
	s_nop 0
	v_pk_add_f32 v[68:69], v[68:69], v[78:79]
	v_mul_f32_e32 v72, 0x3d372713, v64
	v_mul_f32_e32 v78, 0x3d372713, v68
	v_mul_f32_e32 v79, 0x3d372713, v69
	v_mul_f32_e32 v73, 0x3d372713, v65
	v_mul_f32_e32 v78, v68, v78
	v_mul_f32_e32 v79, v69, v79
	v_mul_f32_e32 v72, v64, v72
	v_mul_f32_e32 v73, v65, v73
	v_fma_f32 v78, v68, v78, v68
	v_fma_f32 v79, v69, v79, v69
	v_fma_f32 v72, v64, v72, v64
	v_fma_f32 v73, v65, v73, v65
	v_mul_f32_e32 v78, 0x3f4c422a, v78
	v_mul_f32_e32 v79, 0x3f4c422a, v79
	v_mul_f32_e32 v72, 0x3f4c422a, v72
	v_mul_f32_e32 v73, 0x3f4c422a, v73
	v_add_f32_e32 v78, v78, v78
	v_add_f32_e32 v79, v79, v79
	v_add_f32_e32 v72, v72, v72
	v_add_f32_e32 v73, v73, v73
	v_mul_f32_e32 v78, 0xbfb8aa3b, v78
	v_mul_f32_e32 v79, 0xbfb8aa3b, v79
	v_mul_f32_e32 v72, 0xbfb8aa3b, v72
	v_mul_f32_e32 v73, 0xbfb8aa3b, v73
	v_exp_f32_e32 v78, v78
	v_exp_f32_e32 v79, v79
	v_exp_f32_e32 v72, v72
	v_exp_f32_e32 v73, v73
	v_add_f32_e32 v78, 1.0, v78
	v_add_f32_e32 v79, 1.0, v79
	v_add_f32_e32 v72, 1.0, v72
	v_add_f32_e32 v73, 1.0, v73
	v_rcp_f32_e32 v78, v78
	v_rcp_f32_e32 v79, v79
	v_rcp_f32_e32 v72, v72
	v_rcp_f32_e32 v73, v73
	v_pk_add_f32 v[70:71], v[70:71], v[80:81]
	v_pk_add_f32 v[66:67], v[66:67], v[74:75]
	v_pk_mul_f32 v[68:69], v[68:69], v[78:79]
	v_mul_f32_e32 v78, 0x3d372713, v70
	v_mul_f32_e32 v79, 0x3d372713, v71
	v_pk_mul_f32 v[72:73], v[64:65], v[72:73]
	v_mul_f32_e32 v64, 0x3d372713, v66
	v_mul_f32_e32 v65, 0x3d372713, v67
	v_mul_f32_e32 v78, v70, v78
	v_mul_f32_e32 v79, v71, v79
	v_mul_f32_e32 v64, v66, v64
	v_mul_f32_e32 v65, v67, v65
	v_fma_f32 v78, v70, v78, v70
	v_fma_f32 v79, v71, v79, v71
	v_fma_f32 v64, v66, v64, v66
	v_fma_f32 v65, v67, v65, v67
	v_mul_f32_e32 v78, 0x3f4c422a, v78
	v_mul_f32_e32 v79, 0x3f4c422a, v79
	v_mul_f32_e32 v64, 0x3f4c422a, v64
	v_mul_f32_e32 v65, 0x3f4c422a, v65
	v_add_f32_e32 v78, v78, v78
	v_add_f32_e32 v79, v79, v79
	v_add_f32_e32 v64, v64, v64
	v_add_f32_e32 v65, v65, v65
	v_mul_f32_e32 v78, 0xbfb8aa3b, v78
	v_mul_f32_e32 v79, 0xbfb8aa3b, v79
	v_mul_f32_e32 v64, 0xbfb8aa3b, v64
	v_mul_f32_e32 v65, 0xbfb8aa3b, v65
	v_exp_f32_e32 v78, v78
	v_exp_f32_e32 v79, v79
	v_exp_f32_e32 v64, v64
	v_exp_f32_e32 v65, v65
	v_add_f32_e32 v78, 1.0, v78
	v_add_f32_e32 v79, 1.0, v79
	v_add_f32_e32 v64, 1.0, v64
	v_add_f32_e32 v65, 1.0, v65
	v_rcp_f32_e32 v78, v78
	v_rcp_f32_e32 v79, v79
	v_rcp_f32_e32 v64, v64
	v_rcp_f32_e32 v65, v65
	v_pk_mul_f32 v[70:71], v[70:71], v[78:79]
	v_pk_mul_f32 v[74:75], v[66:67], v[64:65]
	v_cvt_pk_bf16_f32 v64, v68, v69
	v_cvt_pk_bf16_f32 v65, v70, v71
	v_cvt_pk_bf16_f32 v66, v72, v73
	v_cvt_pk_bf16_f32 v67, v74, v75
	global_store_dwordx4 v[76:77], v[64:67], off offset:256
	s_nop 0
	s_nop 0
	v_add_u32_e32 v64, 0x80, v140
	v_ashrrev_i32_e32 v65, 31, v64
	v_mov_b64_e32 v[66:67], v[220:221]
	v_mov_b64_e32 v[68:69], v[222:223]
	v_mov_b64_e32 v[70:71], v[224:225]
	v_mov_b64_e32 v[72:73], v[226:227]
	v_pk_add_f32 v[56:57], v[56:57], v[66:67]
	s_nop 0
	v_pk_add_f32 v[60:61], v[60:61], v[70:71]
	v_mul_f32_e32 v66, 0x3d372713, v56
	v_mul_f32_e32 v67, 0x3d372713, v57
	v_mul_f32_e32 v70, 0x3d372713, v60
	v_mul_f32_e32 v71, 0x3d372713, v61
	v_mul_f32_e32 v66, v56, v66
	v_mul_f32_e32 v67, v57, v67
	v_mul_f32_e32 v70, v60, v70
	v_mul_f32_e32 v71, v61, v71
	v_fma_f32 v66, v56, v66, v56
	v_fma_f32 v67, v57, v67, v57
	v_fma_f32 v70, v60, v70, v60
	v_fma_f32 v71, v61, v71, v61
	v_mul_f32_e32 v66, 0x3f4c422a, v66
	v_mul_f32_e32 v67, 0x3f4c422a, v67
	v_mul_f32_e32 v70, 0x3f4c422a, v70
	v_mul_f32_e32 v71, 0x3f4c422a, v71
	v_add_f32_e32 v66, v66, v66
	v_add_f32_e32 v67, v67, v67
	v_add_f32_e32 v70, v70, v70
	v_add_f32_e32 v71, v71, v71
	v_mul_f32_e32 v66, 0xbfb8aa3b, v66
	v_mul_f32_e32 v67, 0xbfb8aa3b, v67
	v_mul_f32_e32 v70, 0xbfb8aa3b, v70
	v_mul_f32_e32 v71, 0xbfb8aa3b, v71
	v_exp_f32_e32 v66, v66
	v_exp_f32_e32 v67, v67
	v_exp_f32_e32 v70, v70
	v_exp_f32_e32 v71, v71
	v_add_f32_e32 v66, 1.0, v66
	v_add_f32_e32 v67, 1.0, v67
	v_add_f32_e32 v70, 1.0, v70
	v_add_f32_e32 v71, 1.0, v71
	v_rcp_f32_e32 v66, v66
	v_rcp_f32_e32 v67, v67
	v_rcp_f32_e32 v70, v70
	v_rcp_f32_e32 v71, v71
	v_pk_add_f32 v[58:59], v[58:59], v[68:69]
	v_pk_add_f32 v[62:63], v[62:63], v[72:73]
	v_pk_mul_f32 v[66:67], v[56:57], v[66:67]
	v_mul_f32_e32 v56, 0x3d372713, v58
	v_mul_f32_e32 v57, 0x3d372713, v59
	v_pk_mul_f32 v[60:61], v[60:61], v[70:71]
	v_mul_f32_e32 v70, 0x3d372713, v62
	v_mul_f32_e32 v71, 0x3d372713, v63
	v_mul_f32_e32 v56, v58, v56
	v_mul_f32_e32 v57, v59, v57
	v_mul_f32_e32 v70, v62, v70
	v_mul_f32_e32 v71, v63, v71
	v_fma_f32 v56, v58, v56, v58
	v_fma_f32 v57, v59, v57, v59
	v_fma_f32 v70, v62, v70, v62
	v_fma_f32 v71, v63, v71, v63
	v_mul_f32_e32 v56, 0x3f4c422a, v56
	v_mul_f32_e32 v57, 0x3f4c422a, v57
	v_mul_f32_e32 v70, 0x3f4c422a, v70
	v_mul_f32_e32 v71, 0x3f4c422a, v71
	v_add_f32_e32 v56, v56, v56
	v_add_f32_e32 v57, v57, v57
	v_add_f32_e32 v70, v70, v70
	v_add_f32_e32 v71, v71, v71
	v_mul_f32_e32 v56, 0xbfb8aa3b, v56
	v_mul_f32_e32 v57, 0xbfb8aa3b, v57
	v_mul_f32_e32 v70, 0xbfb8aa3b, v70
	v_mul_f32_e32 v71, 0xbfb8aa3b, v71
	v_exp_f32_e32 v56, v56
	v_exp_f32_e32 v57, v57
	v_exp_f32_e32 v70, v70
	v_exp_f32_e32 v71, v71
	v_add_f32_e32 v56, 1.0, v56
	v_add_f32_e32 v57, 1.0, v57
	v_add_f32_e32 v70, 1.0, v70
	v_add_f32_e32 v71, 1.0, v71
	v_rcp_f32_e32 v56, v56
	v_rcp_f32_e32 v57, v57
	v_rcp_f32_e32 v70, v70
	v_rcp_f32_e32 v71, v71
; __device__ __forceinline__ float sigm(float x) { return __builtin_amdgcn_rcpf(1.f + __expf(-x)); }
; __device__ __forceinline__ u32x4 pack8(const float (&f)[8]) { u32x4 w; w.x = pk2(f[0], f[1]); w.y = pk2(f[2], f[3]); w.z = pk2(f[4], f[5]); w.w = pk2(f[6], f[7]); return w; }
;     __device__ __forceinline__ void operator()(const f32x4 (&acc)[2][2][4][2], const pg8::Unit& u, int wr, int wc, int fr, int fq) const {
;     ...
;                         const f32x4 b0 = *(const f32x4*)(bias + c0), b1 = *(const f32x4*)(bias + c0 + 4);
;                         const float bb[8] = {b0[0], b0[1], b0[2], b0[3], b1[0], b1[1], b1[2], b1[3]};
; #pragma unroll
;                         for (int j = 0; j < 8; ++j) { const float x = v[j] + bb[j]; const float uu = 0.7978845608028654f * (x + 0.044715f * x * x * x); v[j] = x * sigm(2.f * uu); }
;                         *(u32x4*)(O + (size_t)r * ldc + c0) = pack8(v);
	v_pk_mul_f32 v[68:69], v[58:59], v[56:57]
	v_cvt_pk_bf16_f32 v56, v60, v61
	v_lshlrev_b64 v[60:61], 9, v[64:65]
	v_pk_mul_f32 v[62:63], v[62:63], v[70:71]
	v_lshl_add_u64 v[60:61], s[16:17], 0, v[60:61]
	v_cvt_pk_bf16_f32 v57, v62, v63
	v_cvt_pk_bf16_f32 v58, v66, v67
	v_cvt_pk_bf16_f32 v59, v68, v69
	v_lshl_add_u64 v[60:61], v[60:61], 0, v[124:125]
	global_store_dwordx4 v[60:61], v[56:59], off
	s_nop 0
	s_nop 0
	s_nop 0
	v_mov_b64_e32 v[56:57], v[228:229]
	v_mov_b64_e32 v[58:59], v[230:231]
	v_mov_b64_e32 v[62:63], v[232:233]
	v_mov_b64_e32 v[64:65], v[234:235]
	v_pk_add_f32 v[48:49], v[48:49], v[56:57]
	s_nop 0
	v_pk_add_f32 v[52:53], v[52:53], v[62:63]
	v_mul_f32_e32 v56, 0x3d372713, v48
	v_mul_f32_e32 v62, 0x3d372713, v52
	v_mul_f32_e32 v63, 0x3d372713, v53
	v_mul_f32_e32 v57, 0x3d372713, v49
	v_mul_f32_e32 v62, v52, v62
	v_mul_f32_e32 v63, v53, v63
	v_mul_f32_e32 v56, v48, v56
	v_mul_f32_e32 v57, v49, v57
	v_fma_f32 v62, v52, v62, v52
	v_fma_f32 v63, v53, v63, v53
	v_fma_f32 v56, v48, v56, v48
	v_fma_f32 v57, v49, v57, v49
	v_mul_f32_e32 v62, 0x3f4c422a, v62
	v_mul_f32_e32 v63, 0x3f4c422a, v63
	v_mul_f32_e32 v56, 0x3f4c422a, v56
	v_mul_f32_e32 v57, 0x3f4c422a, v57
	v_add_f32_e32 v62, v62, v62
	v_add_f32_e32 v63, v63, v63
	v_add_f32_e32 v56, v56, v56
	v_add_f32_e32 v57, v57, v57
	v_mul_f32_e32 v62, 0xbfb8aa3b, v62
	v_mul_f32_e32 v63, 0xbfb8aa3b, v63
	v_mul_f32_e32 v56, 0xbfb8aa3b, v56
	v_mul_f32_e32 v57, 0xbfb8aa3b, v57
	v_exp_f32_e32 v62, v62
	v_exp_f32_e32 v63, v63
	v_exp_f32_e32 v56, v56
	v_exp_f32_e32 v57, v57
	v_add_f32_e32 v62, 1.0, v62
	v_add_f32_e32 v63, 1.0, v63
	v_add_f32_e32 v56, 1.0, v56
	v_add_f32_e32 v57, 1.0, v57
	v_rcp_f32_e32 v62, v62
	v_rcp_f32_e32 v63, v63
	v_rcp_f32_e32 v56, v56
	v_rcp_f32_e32 v57, v57
	v_pk_add_f32 v[54:55], v[54:55], v[64:65]
	v_pk_add_f32 v[50:51], v[50:51], v[58:59]
	v_pk_mul_f32 v[52:53], v[52:53], v[62:63]
	v_mul_f32_e32 v62, 0x3d372713, v54
	v_mul_f32_e32 v63, 0x3d372713, v55
	v_pk_mul_f32 v[56:57], v[48:49], v[56:57]
	v_mul_f32_e32 v48, 0x3d372713, v50
	v_mul_f32_e32 v49, 0x3d372713, v51
	v_mul_f32_e32 v62, v54, v62
	v_mul_f32_e32 v63, v55, v63
	v_mul_f32_e32 v48, v50, v48
	v_mul_f32_e32 v49, v51, v49
	v_fma_f32 v62, v54, v62, v54
	v_fma_f32 v63, v55, v63, v55
	v_fma_f32 v48, v50, v48, v50
	v_fma_f32 v49, v51, v49, v51
	v_mul_f32_e32 v62, 0x3f4c422a, v62
	v_mul_f32_e32 v63, 0x3f4c422a, v63
	v_mul_f32_e32 v48, 0x3f4c422a, v48
	v_mul_f32_e32 v49, 0x3f4c422a, v49
	v_add_f32_e32 v62, v62, v62
	v_add_f32_e32 v63, v63, v63
	v_add_f32_e32 v48, v48, v48
	v_add_f32_e32 v49, v49, v49
	v_mul_f32_e32 v62, 0xbfb8aa3b, v62
	v_mul_f32_e32 v63, 0xbfb8aa3b, v63
	v_mul_f32_e32 v48, 0xbfb8aa3b, v48
	v_mul_f32_e32 v49, 0xbfb8aa3b, v49
	v_exp_f32_e32 v62, v62
	v_exp_f32_e32 v63, v63
	v_exp_f32_e32 v48, v48
	v_exp_f32_e32 v49, v49
	v_add_f32_e32 v62, 1.0, v62
	v_add_f32_e32 v63, 1.0, v63
	v_add_f32_e32 v48, 1.0, v48
	v_add_f32_e32 v49, 1.0, v49
	v_rcp_f32_e32 v62, v62
	v_rcp_f32_e32 v63, v63
	v_rcp_f32_e32 v48, v48
	v_rcp_f32_e32 v49, v49
	v_pk_mul_f32 v[54:55], v[54:55], v[62:63]
	v_pk_mul_f32 v[58:59], v[50:51], v[48:49]
	v_cvt_pk_bf16_f32 v48, v52, v53
	v_cvt_pk_bf16_f32 v49, v54, v55
	v_cvt_pk_bf16_f32 v50, v56, v57
	v_cvt_pk_bf16_f32 v51, v58, v59
	global_store_dwordx4 v[60:61], v[48:51], off offset:256
	s_nop 0
	s_nop 0
	v_add_u32_e32 v48, 0x90, v140
	v_ashrrev_i32_e32 v49, 31, v48
	v_mov_b64_e32 v[50:51], v[220:221]
	v_mov_b64_e32 v[52:53], v[222:223]
	v_mov_b64_e32 v[54:55], v[224:225]
	v_mov_b64_e32 v[56:57], v[226:227]
	v_pk_add_f32 v[40:41], v[40:41], v[50:51]
	s_nop 0
	v_pk_add_f32 v[44:45], v[44:45], v[54:55]
	v_mul_f32_e32 v50, 0x3d372713, v40
	v_mul_f32_e32 v51, 0x3d372713, v41
	v_mul_f32_e32 v54, 0x3d372713, v44
	v_mul_f32_e32 v55, 0x3d372713, v45
	v_mul_f32_e32 v50, v40, v50
	v_mul_f32_e32 v51, v41, v51
	v_mul_f32_e32 v54, v44, v54
	v_mul_f32_e32 v55, v45, v55
	v_fma_f32 v50, v40, v50, v40
	v_fma_f32 v51, v41, v51, v41
	v_fma_f32 v54, v44, v54, v44
	v_fma_f32 v55, v45, v55, v45
	v_mul_f32_e32 v50, 0x3f4c422a, v50
	v_mul_f32_e32 v51, 0x3f4c422a, v51
	v_mul_f32_e32 v54, 0x3f4c422a, v54
	v_mul_f32_e32 v55, 0x3f4c422a, v55
	v_add_f32_e32 v50, v50, v50
	v_add_f32_e32 v51, v51, v51
	v_add_f32_e32 v54, v54, v54
	v_add_f32_e32 v55, v55, v55
	v_mul_f32_e32 v50, 0xbfb8aa3b, v50
	v_mul_f32_e32 v51, 0xbfb8aa3b, v51
	v_mul_f32_e32 v54, 0xbfb8aa3b, v54
	v_mul_f32_e32 v55, 0xbfb8aa3b, v55
	v_exp_f32_e32 v50, v50
	v_exp_f32_e32 v51, v51
	v_exp_f32_e32 v54, v54
	v_exp_f32_e32 v55, v55
	v_add_f32_e32 v50, 1.0, v50
	v_add_f32_e32 v51, 1.0, v51
	v_add_f32_e32 v54, 1.0, v54
	v_add_f32_e32 v55, 1.0, v55
	v_rcp_f32_e32 v50, v50
	v_rcp_f32_e32 v51, v51
	v_rcp_f32_e32 v54, v54
	v_rcp_f32_e32 v55, v55
	v_pk_add_f32 v[42:43], v[42:43], v[52:53]
	v_pk_add_f32 v[46:47], v[46:47], v[56:57]
	v_pk_mul_f32 v[50:51], v[40:41], v[50:51]
	v_mul_f32_e32 v40, 0x3d372713, v42
	v_mul_f32_e32 v41, 0x3d372713, v43
	v_pk_mul_f32 v[44:45], v[44:45], v[54:55]
	v_mul_f32_e32 v54, 0x3d372713, v46
	v_mul_f32_e32 v55, 0x3d372713, v47
	v_mul_f32_e32 v40, v42, v40
	v_mul_f32_e32 v41, v43, v41
	v_mul_f32_e32 v54, v46, v54
	v_mul_f32_e32 v55, v47, v55
	v_fma_f32 v40, v42, v40, v42
	v_fma_f32 v41, v43, v41, v43
	v_fma_f32 v54, v46, v54, v46
	v_fma_f32 v55, v47, v55, v47
	v_mul_f32_e32 v40, 0x3f4c422a, v40
	v_mul_f32_e32 v41, 0x3f4c422a, v41
	v_mul_f32_e32 v54, 0x3f4c422a, v54
	v_mul_f32_e32 v55, 0x3f4c422a, v55
	v_add_f32_e32 v40, v40, v40
	v_add_f32_e32 v41, v41, v41
	v_add_f32_e32 v54, v54, v54
	v_add_f32_e32 v55, v55, v55
	v_mul_f32_e32 v40, 0xbfb8aa3b, v40
	v_mul_f32_e32 v41, 0xbfb8aa3b, v41
	v_mul_f32_e32 v54, 0xbfb8aa3b, v54
; __device__ __forceinline__ float sigm(float x) { return __builtin_amdgcn_rcpf(1.f + __expf(-x)); }
; __device__ __forceinline__ u32x4 pack8(const float (&f)[8]) { u32x4 w; w.x = pk2(f[0], f[1]); w.y = pk2(f[2], f[3]); w.z = pk2(f[4], f[5]); w.w = pk2(f[6], f[7]); return w; }
;     __device__ __forceinline__ void operator()(const f32x4 (&acc)[2][2][4][2], const pg8::Unit& u, int wr, int wc, int fr, int fq) const {
;     ...
;                         const f32x4 b0 = *(const f32x4*)(bias + c0), b1 = *(const f32x4*)(bias + c0 + 4);
;                         const float bb[8] = {b0[0], b0[1], b0[2], b0[3], b1[0], b1[1], b1[2], b1[3]};
; #pragma unroll
;                         for (int j = 0; j < 8; ++j) { const float x = v[j] + bb[j]; const float uu = 0.7978845608028654f * (x + 0.044715f * x * x * x); v[j] = x * sigm(2.f * uu); }
;                         *(u32x4*)(O + (size_t)r * ldc + c0) = pack8(v);
	v_mul_f32_e32 v55, 0xbfb8aa3b, v55
	v_exp_f32_e32 v40, v40
	v_exp_f32_e32 v41, v41
	v_exp_f32_e32 v54, v54
	v_exp_f32_e32 v55, v55
	v_add_f32_e32 v40, 1.0, v40
	v_add_f32_e32 v41, 1.0, v41
	v_add_f32_e32 v54, 1.0, v54
	v_add_f32_e32 v55, 1.0, v55
	v_rcp_f32_e32 v40, v40
	v_rcp_f32_e32 v41, v41
	v_rcp_f32_e32 v54, v54
	v_rcp_f32_e32 v55, v55
	v_pk_mul_f32 v[52:53], v[42:43], v[40:41]
	v_cvt_pk_bf16_f32 v40, v44, v45
	v_lshlrev_b64 v[44:45], 9, v[48:49]
	v_pk_mul_f32 v[46:47], v[46:47], v[54:55]
	v_lshl_add_u64 v[44:45], s[16:17], 0, v[44:45]
	v_cvt_pk_bf16_f32 v41, v46, v47
	v_cvt_pk_bf16_f32 v42, v50, v51
	v_cvt_pk_bf16_f32 v43, v52, v53
	v_lshl_add_u64 v[44:45], v[44:45], 0, v[124:125]
	global_store_dwordx4 v[44:45], v[40:43], off
	s_nop 0
	s_nop 0
	s_nop 0
	v_mov_b64_e32 v[40:41], v[228:229]
	v_mov_b64_e32 v[42:43], v[230:231]
	v_mov_b64_e32 v[46:47], v[232:233]
	v_mov_b64_e32 v[48:49], v[234:235]
	v_pk_add_f32 v[32:33], v[32:33], v[40:41]
	s_nop 0
	v_pk_add_f32 v[36:37], v[36:37], v[46:47]
	v_mul_f32_e32 v40, 0x3d372713, v32
	v_mul_f32_e32 v46, 0x3d372713, v36
	v_mul_f32_e32 v47, 0x3d372713, v37
	v_mul_f32_e32 v41, 0x3d372713, v33
	v_mul_f32_e32 v46, v36, v46
	v_mul_f32_e32 v47, v37, v47
	v_mul_f32_e32 v40, v32, v40
	v_mul_f32_e32 v41, v33, v41
	v_fma_f32 v46, v36, v46, v36
	v_fma_f32 v47, v37, v47, v37
	v_fma_f32 v40, v32, v40, v32
	v_fma_f32 v41, v33, v41, v33
	v_mul_f32_e32 v46, 0x3f4c422a, v46
	v_mul_f32_e32 v47, 0x3f4c422a, v47
	v_mul_f32_e32 v40, 0x3f4c422a, v40
	v_mul_f32_e32 v41, 0x3f4c422a, v41
	v_add_f32_e32 v46, v46, v46
	v_add_f32_e32 v47, v47, v47
	v_add_f32_e32 v40, v40, v40
	v_add_f32_e32 v41, v41, v41
	v_mul_f32_e32 v46, 0xbfb8aa3b, v46
	v_mul_f32_e32 v47, 0xbfb8aa3b, v47
	v_mul_f32_e32 v40, 0xbfb8aa3b, v40
	v_mul_f32_e32 v41, 0xbfb8aa3b, v41
	v_exp_f32_e32 v46, v46
	v_exp_f32_e32 v47, v47
	v_exp_f32_e32 v40, v40
	v_exp_f32_e32 v41, v41
	v_add_f32_e32 v46, 1.0, v46
	v_add_f32_e32 v47, 1.0, v47
	v_add_f32_e32 v40, 1.0, v40
	v_add_f32_e32 v41, 1.0, v41
	v_rcp_f32_e32 v46, v46
	v_rcp_f32_e32 v47, v47
	v_rcp_f32_e32 v40, v40
	v_rcp_f32_e32 v41, v41
	v_pk_add_f32 v[38:39], v[38:39], v[48:49]
	v_pk_add_f32 v[34:35], v[34:35], v[42:43]
	v_pk_mul_f32 v[36:37], v[36:37], v[46:47]
	v_mul_f32_e32 v46, 0x3d372713, v38
	v_mul_f32_e32 v47, 0x3d372713, v39
	v_pk_mul_f32 v[40:41], v[32:33], v[40:41]
	v_mul_f32_e32 v32, 0x3d372713, v34
	v_mul_f32_e32 v33, 0x3d372713, v35
	v_mul_f32_e32 v46, v38, v46
	v_mul_f32_e32 v47, v39, v47
	v_mul_f32_e32 v32, v34, v32
	v_mul_f32_e32 v33, v35, v33
	v_fma_f32 v46, v38, v46, v38
	v_fma_f32 v47, v39, v47, v39
	v_fma_f32 v32, v34, v32, v34
	v_fma_f32 v33, v35, v33, v35
	v_mul_f32_e32 v46, 0x3f4c422a, v46
	v_mul_f32_e32 v47, 0x3f4c422a, v47
	v_mul_f32_e32 v32, 0x3f4c422a, v32
	v_mul_f32_e32 v33, 0x3f4c422a, v33
	v_add_f32_e32 v46, v46, v46
	v_add_f32_e32 v47, v47, v47
	v_add_f32_e32 v32, v32, v32
	v_add_f32_e32 v33, v33, v33
	v_mul_f32_e32 v46, 0xbfb8aa3b, v46
	v_mul_f32_e32 v47, 0xbfb8aa3b, v47
	v_mul_f32_e32 v32, 0xbfb8aa3b, v32
	v_mul_f32_e32 v33, 0xbfb8aa3b, v33
	v_exp_f32_e32 v46, v46
	v_exp_f32_e32 v47, v47
	v_exp_f32_e32 v32, v32
	v_exp_f32_e32 v33, v33
	v_add_f32_e32 v46, 1.0, v46
	v_add_f32_e32 v47, 1.0, v47
	v_add_f32_e32 v32, 1.0, v32
	v_add_f32_e32 v33, 1.0, v33
	v_rcp_f32_e32 v46, v46
	v_rcp_f32_e32 v47, v47
	v_rcp_f32_e32 v32, v32
	v_rcp_f32_e32 v33, v33
	v_pk_mul_f32 v[38:39], v[38:39], v[46:47]
	v_pk_mul_f32 v[42:43], v[34:35], v[32:33]
	v_cvt_pk_bf16_f32 v32, v36, v37
	v_cvt_pk_bf16_f32 v33, v38, v39
	v_cvt_pk_bf16_f32 v34, v40, v41
	v_cvt_pk_bf16_f32 v35, v42, v43
	global_store_dwordx4 v[44:45], v[32:35], off offset:256
	s_nop 0
	s_nop 0
	v_add_u32_e32 v32, 0xa0, v140
	v_ashrrev_i32_e32 v33, 31, v32
	v_mov_b64_e32 v[34:35], v[220:221]
	v_mov_b64_e32 v[36:37], v[222:223]
	v_mov_b64_e32 v[38:39], v[224:225]
	v_mov_b64_e32 v[40:41], v[226:227]
	v_pk_add_f32 v[24:25], v[24:25], v[34:35]
	s_nop 0
	v_pk_add_f32 v[28:29], v[28:29], v[38:39]
	v_mul_f32_e32 v34, 0x3d372713, v24
	v_mul_f32_e32 v35, 0x3d372713, v25
	v_mul_f32_e32 v38, 0x3d372713, v28
	v_mul_f32_e32 v39, 0x3d372713, v29
	v_mul_f32_e32 v34, v24, v34
	v_mul_f32_e32 v35, v25, v35
	v_mul_f32_e32 v38, v28, v38
	v_mul_f32_e32 v39, v29, v39
	v_fma_f32 v34, v24, v34, v24
	v_fma_f32 v35, v25, v35, v25
	v_fma_f32 v38, v28, v38, v28
	v_fma_f32 v39, v29, v39, v29
	v_mul_f32_e32 v34, 0x3f4c422a, v34
	v_mul_f32_e32 v35, 0x3f4c422a, v35
	v_mul_f32_e32 v38, 0x3f4c422a, v38
	v_mul_f32_e32 v39, 0x3f4c422a, v39
	v_add_f32_e32 v34, v34, v34
	v_add_f32_e32 v35, v35, v35
	v_add_f32_e32 v38, v38, v38
	v_add_f32_e32 v39, v39, v39
	v_mul_f32_e32 v34, 0xbfb8aa3b, v34
	v_mul_f32_e32 v35, 0xbfb8aa3b, v35
	v_mul_f32_e32 v38, 0xbfb8aa3b, v38
	v_mul_f32_e32 v39, 0xbfb8aa3b, v39
	v_exp_f32_e32 v34, v34
	v_exp_f32_e32 v35, v35
	v_exp_f32_e32 v38, v38
	v_exp_f32_e32 v39, v39
	v_add_f32_e32 v34, 1.0, v34
	v_add_f32_e32 v35, 1.0, v35
	v_add_f32_e32 v38, 1.0, v38
	v_add_f32_e32 v39, 1.0, v39
	v_rcp_f32_e32 v34, v34
	v_rcp_f32_e32 v35, v35
	v_rcp_f32_e32 v38, v38
	v_rcp_f32_e32 v39, v39
	v_pk_add_f32 v[26:27], v[26:27], v[36:37]
	v_pk_add_f32 v[30:31], v[30:31], v[40:41]
	v_pk_mul_f32 v[34:35], v[24:25], v[34:35]
	v_mul_f32_e32 v24, 0x3d372713, v26
	v_mul_f32_e32 v25, 0x3d372713, v27
	v_pk_mul_f32 v[28:29], v[28:29], v[38:39]
	v_mul_f32_e32 v38, 0x3d372713, v30
	v_mul_f32_e32 v39, 0x3d372713, v31
	v_mul_f32_e32 v24, v26, v24
	v_mul_f32_e32 v25, v27, v25
	v_mul_f32_e32 v38, v30, v38
	v_mul_f32_e32 v39, v31, v39
	v_fma_f32 v24, v26, v24, v26
	v_fma_f32 v25, v27, v25, v27
	v_fma_f32 v38, v30, v38, v30
	v_fma_f32 v39, v31, v39, v31
	v_mul_f32_e32 v24, 0x3f4c422a, v24
; __device__ __forceinline__ float sigm(float x) { return __builtin_amdgcn_rcpf(1.f + __expf(-x)); }
; __device__ __forceinline__ u32x4 pack8(const float (&f)[8]) { u32x4 w; w.x = pk2(f[0], f[1]); w.y = pk2(f[2], f[3]); w.z = pk2(f[4], f[5]); w.w = pk2(f[6], f[7]); return w; }
;     __device__ __forceinline__ void operator()(const f32x4 (&acc)[2][2][4][2], const pg8::Unit& u, int wr, int wc, int fr, int fq) const {
;     ...
;                         const f32x4 b0 = *(const f32x4*)(bias + c0), b1 = *(const f32x4*)(bias + c0 + 4);
;                         const float bb[8] = {b0[0], b0[1], b0[2], b0[3], b1[0], b1[1], b1[2], b1[3]};
; #pragma unroll
;                         for (int j = 0; j < 8; ++j) { const float x = v[j] + bb[j]; const float uu = 0.7978845608028654f * (x + 0.044715f * x * x * x); v[j] = x * sigm(2.f * uu); }
;                         *(u32x4*)(O + (size_t)r * ldc + c0) = pack8(v);
	v_mul_f32_e32 v25, 0x3f4c422a, v25
	v_mul_f32_e32 v38, 0x3f4c422a, v38
	v_mul_f32_e32 v39, 0x3f4c422a, v39
	v_add_f32_e32 v24, v24, v24
	v_add_f32_e32 v25, v25, v25
	v_add_f32_e32 v38, v38, v38
	v_add_f32_e32 v39, v39, v39
	v_mul_f32_e32 v24, 0xbfb8aa3b, v24
	v_mul_f32_e32 v25, 0xbfb8aa3b, v25
	v_mul_f32_e32 v38, 0xbfb8aa3b, v38
	v_mul_f32_e32 v39, 0xbfb8aa3b, v39
	v_exp_f32_e32 v24, v24
	v_exp_f32_e32 v25, v25
	v_exp_f32_e32 v38, v38
	v_exp_f32_e32 v39, v39
	v_add_f32_e32 v24, 1.0, v24
	v_add_f32_e32 v25, 1.0, v25
	v_add_f32_e32 v38, 1.0, v38
	v_add_f32_e32 v39, 1.0, v39
	v_rcp_f32_e32 v24, v24
	v_rcp_f32_e32 v25, v25
	v_rcp_f32_e32 v38, v38
	v_rcp_f32_e32 v39, v39
	v_pk_mul_f32 v[36:37], v[26:27], v[24:25]
	v_cvt_pk_bf16_f32 v24, v28, v29
	v_lshlrev_b64 v[28:29], 9, v[32:33]
	v_pk_mul_f32 v[30:31], v[30:31], v[38:39]
	v_lshl_add_u64 v[28:29], s[16:17], 0, v[28:29]
	v_cvt_pk_bf16_f32 v25, v30, v31
	v_cvt_pk_bf16_f32 v26, v34, v35
	v_cvt_pk_bf16_f32 v27, v36, v37
	v_lshl_add_u64 v[28:29], v[28:29], 0, v[124:125]
	global_store_dwordx4 v[28:29], v[24:27], off
	s_nop 0
	s_nop 0
	s_nop 0
	v_mov_b64_e32 v[24:25], v[228:229]
	v_mov_b64_e32 v[26:27], v[230:231]
	v_mov_b64_e32 v[30:31], v[232:233]
	v_mov_b64_e32 v[32:33], v[234:235]
	v_pk_add_f32 v[16:17], v[16:17], v[24:25]
	s_nop 0
	v_pk_add_f32 v[20:21], v[20:21], v[30:31]
	v_mul_f32_e32 v24, 0x3d372713, v16
	v_mul_f32_e32 v30, 0x3d372713, v20
	v_mul_f32_e32 v31, 0x3d372713, v21
	v_mul_f32_e32 v25, 0x3d372713, v17
	v_mul_f32_e32 v30, v20, v30
	v_mul_f32_e32 v31, v21, v31
	v_mul_f32_e32 v24, v16, v24
	v_mul_f32_e32 v25, v17, v25
	v_fma_f32 v30, v20, v30, v20
	v_fma_f32 v31, v21, v31, v21
	v_fma_f32 v24, v16, v24, v16
	v_fma_f32 v25, v17, v25, v17
	v_mul_f32_e32 v30, 0x3f4c422a, v30
	v_mul_f32_e32 v31, 0x3f4c422a, v31
	v_mul_f32_e32 v24, 0x3f4c422a, v24
	v_mul_f32_e32 v25, 0x3f4c422a, v25
	v_add_f32_e32 v30, v30, v30
	v_add_f32_e32 v31, v31, v31
	v_add_f32_e32 v24, v24, v24
	v_add_f32_e32 v25, v25, v25
	v_mul_f32_e32 v30, 0xbfb8aa3b, v30
	v_mul_f32_e32 v31, 0xbfb8aa3b, v31
	v_mul_f32_e32 v24, 0xbfb8aa3b, v24
	v_mul_f32_e32 v25, 0xbfb8aa3b, v25
	v_exp_f32_e32 v30, v30
	v_exp_f32_e32 v31, v31
	v_exp_f32_e32 v24, v24
	v_exp_f32_e32 v25, v25
	v_add_f32_e32 v30, 1.0, v30
	v_add_f32_e32 v31, 1.0, v31
	v_add_f32_e32 v24, 1.0, v24
	v_add_f32_e32 v25, 1.0, v25
	v_rcp_f32_e32 v30, v30
	v_rcp_f32_e32 v31, v31
	v_rcp_f32_e32 v24, v24
	v_rcp_f32_e32 v25, v25
	v_pk_add_f32 v[22:23], v[22:23], v[32:33]
	v_pk_add_f32 v[18:19], v[18:19], v[26:27]
	v_pk_mul_f32 v[20:21], v[20:21], v[30:31]
	v_mul_f32_e32 v30, 0x3d372713, v22
	v_mul_f32_e32 v31, 0x3d372713, v23
	v_pk_mul_f32 v[24:25], v[16:17], v[24:25]
	v_mul_f32_e32 v16, 0x3d372713, v18
	v_mul_f32_e32 v17, 0x3d372713, v19
	v_mul_f32_e32 v30, v22, v30
	v_mul_f32_e32 v31, v23, v31
	v_mul_f32_e32 v16, v18, v16
	v_mul_f32_e32 v17, v19, v17
	v_fma_f32 v30, v22, v30, v22
	v_fma_f32 v31, v23, v31, v23
	v_fma_f32 v16, v18, v16, v18
	v_fma_f32 v17, v19, v17, v19
	v_mul_f32_e32 v30, 0x3f4c422a, v30
	v_mul_f32_e32 v31, 0x3f4c422a, v31
	v_mul_f32_e32 v16, 0x3f4c422a, v16
	v_mul_f32_e32 v17, 0x3f4c422a, v17
	v_add_f32_e32 v30, v30, v30
	v_add_f32_e32 v31, v31, v31
	v_add_f32_e32 v16, v16, v16
	v_add_f32_e32 v17, v17, v17
	v_mul_f32_e32 v30, 0xbfb8aa3b, v30
	v_mul_f32_e32 v31, 0xbfb8aa3b, v31
	v_mul_f32_e32 v16, 0xbfb8aa3b, v16
	v_mul_f32_e32 v17, 0xbfb8aa3b, v17
	v_exp_f32_e32 v30, v30
	v_exp_f32_e32 v31, v31
	v_exp_f32_e32 v16, v16
	v_exp_f32_e32 v17, v17
	v_add_f32_e32 v30, 1.0, v30
	v_add_f32_e32 v31, 1.0, v31
	v_add_f32_e32 v16, 1.0, v16
	v_add_f32_e32 v17, 1.0, v17
	v_rcp_f32_e32 v30, v30
	v_rcp_f32_e32 v31, v31
	v_rcp_f32_e32 v16, v16
	v_rcp_f32_e32 v17, v17
	v_pk_mul_f32 v[22:23], v[22:23], v[30:31]
	v_pk_mul_f32 v[26:27], v[18:19], v[16:17]
	v_cvt_pk_bf16_f32 v16, v20, v21
	v_cvt_pk_bf16_f32 v17, v22, v23
	v_cvt_pk_bf16_f32 v18, v24, v25
	v_cvt_pk_bf16_f32 v19, v26, v27
	global_store_dwordx4 v[28:29], v[16:19], off offset:256
	s_nop 0
	s_nop 0
	v_add_u32_e32 v16, 0xb0, v140
	v_ashrrev_i32_e32 v17, 31, v16
	v_mov_b64_e32 v[18:19], v[220:221]
	v_mov_b64_e32 v[20:21], v[222:223]
	v_mov_b64_e32 v[22:23], v[224:225]
	v_mov_b64_e32 v[24:25], v[226:227]
	v_pk_add_f32 v[8:9], v[8:9], v[18:19]
	s_nop 0
	v_pk_add_f32 v[12:13], v[12:13], v[22:23]
	v_mul_f32_e32 v18, 0x3d372713, v8
	v_mul_f32_e32 v19, 0x3d372713, v9
	v_mul_f32_e32 v22, 0x3d372713, v12
	v_mul_f32_e32 v23, 0x3d372713, v13
	v_mul_f32_e32 v18, v8, v18
	v_mul_f32_e32 v19, v9, v19
	v_mul_f32_e32 v22, v12, v22
	v_mul_f32_e32 v23, v13, v23
	v_fma_f32 v18, v8, v18, v8
	v_fma_f32 v19, v9, v19, v9
	v_fma_f32 v22, v12, v22, v12
	v_fma_f32 v23, v13, v23, v13
	v_mul_f32_e32 v18, 0x3f4c422a, v18
	v_mul_f32_e32 v19, 0x3f4c422a, v19
	v_mul_f32_e32 v22, 0x3f4c422a, v22
	v_mul_f32_e32 v23, 0x3f4c422a, v23
	v_add_f32_e32 v18, v18, v18
	v_add_f32_e32 v19, v19, v19
	v_add_f32_e32 v22, v22, v22
	v_add_f32_e32 v23, v23, v23
; __device__ __forceinline__ float sigm(float x) { return __builtin_amdgcn_rcpf(1.f + __expf(-x)); }
; __device__ __forceinline__ u32x4 pack8(const float (&f)[8]) { u32x4 w; w.x = pk2(f[0], f[1]); w.y = pk2(f[2], f[3]); w.z = pk2(f[4], f[5]); w.w = pk2(f[6], f[7]); return w; }
; #define PG8_BAR __builtin_amdgcn_s_barrier()
; template <class Epi, class Sched, bool ALIGN_EPI = true, bool SP2 = true>
; __device__ __forceinline__ void gemm_phase(LAS unsigned char* lds, const Gemm g, const Sched& S, const Epi& E) {
;     ...
;         cur = nxt; cA = nA; cB = nB; ++ui;
;         if constexpr (ALIGN_EPI) { if (wr == 1) PG8_BAR; }
;     __device__ __forceinline__ void operator()(const f32x4 (&acc)[2][2][4][2], const pg8::Unit& u, int wr, int wc, int fr, int fq) const {
;     ...
;                         const f32x4 b0 = *(const f32x4*)(bias + c0), b1 = *(const f32x4*)(bias + c0 + 4);
;                         const float bb[8] = {b0[0], b0[1], b0[2], b0[3], b1[0], b1[1], b1[2], b1[3]};
; #pragma unroll
;                         for (int j = 0; j < 8; ++j) { const float x = v[j] + bb[j]; const float uu = 0.7978845608028654f * (x + 0.044715f * x * x * x); v[j] = x * sigm(2.f * uu); }
;                         *(u32x4*)(O + (size_t)r * ldc + c0) = pack8(v);
	v_mul_f32_e32 v18, 0xbfb8aa3b, v18
	v_mul_f32_e32 v19, 0xbfb8aa3b, v19
	v_mul_f32_e32 v22, 0xbfb8aa3b, v22
	v_mul_f32_e32 v23, 0xbfb8aa3b, v23
	v_exp_f32_e32 v18, v18
	v_exp_f32_e32 v19, v19
	v_exp_f32_e32 v22, v22
	v_exp_f32_e32 v23, v23
	v_add_f32_e32 v18, 1.0, v18
	v_add_f32_e32 v19, 1.0, v19
	v_add_f32_e32 v22, 1.0, v22
	v_add_f32_e32 v23, 1.0, v23
	v_rcp_f32_e32 v18, v18
	v_rcp_f32_e32 v19, v19
	v_rcp_f32_e32 v22, v22
	v_rcp_f32_e32 v23, v23
	v_pk_add_f32 v[10:11], v[10:11], v[20:21]
	v_pk_add_f32 v[14:15], v[14:15], v[24:25]
	v_pk_mul_f32 v[18:19], v[8:9], v[18:19]
	v_mul_f32_e32 v8, 0x3d372713, v10
	v_mul_f32_e32 v9, 0x3d372713, v11
	v_pk_mul_f32 v[12:13], v[12:13], v[22:23]
	v_mul_f32_e32 v22, 0x3d372713, v14
	v_mul_f32_e32 v23, 0x3d372713, v15
	v_mul_f32_e32 v8, v10, v8
	v_mul_f32_e32 v9, v11, v9
	v_mul_f32_e32 v22, v14, v22
	v_mul_f32_e32 v23, v15, v23
	v_fma_f32 v8, v10, v8, v10
	v_fma_f32 v9, v11, v9, v11
	v_fma_f32 v22, v14, v22, v14
	v_fma_f32 v23, v15, v23, v15
	v_mul_f32_e32 v8, 0x3f4c422a, v8
	v_mul_f32_e32 v9, 0x3f4c422a, v9
	v_mul_f32_e32 v22, 0x3f4c422a, v22
	v_mul_f32_e32 v23, 0x3f4c422a, v23
	v_add_f32_e32 v8, v8, v8
	v_add_f32_e32 v9, v9, v9
	v_add_f32_e32 v22, v22, v22
	v_add_f32_e32 v23, v23, v23
	v_mul_f32_e32 v8, 0xbfb8aa3b, v8
	v_mul_f32_e32 v9, 0xbfb8aa3b, v9
	v_mul_f32_e32 v22, 0xbfb8aa3b, v22
	v_mul_f32_e32 v23, 0xbfb8aa3b, v23
	v_exp_f32_e32 v8, v8
	v_exp_f32_e32 v9, v9
	v_exp_f32_e32 v22, v22
	v_exp_f32_e32 v23, v23
	v_add_f32_e32 v8, 1.0, v8
	v_add_f32_e32 v9, 1.0, v9
	v_add_f32_e32 v22, 1.0, v22
	v_add_f32_e32 v23, 1.0, v23
	v_rcp_f32_e32 v8, v8
	v_rcp_f32_e32 v9, v9
	v_rcp_f32_e32 v22, v22
	v_rcp_f32_e32 v23, v23
	v_pk_mul_f32 v[20:21], v[10:11], v[8:9]
	v_cvt_pk_bf16_f32 v8, v12, v13
	v_lshlrev_b64 v[12:13], 9, v[16:17]
	v_pk_mul_f32 v[14:15], v[14:15], v[22:23]
	v_lshl_add_u64 v[12:13], s[16:17], 0, v[12:13]
	v_cvt_pk_bf16_f32 v9, v14, v15
	v_cvt_pk_bf16_f32 v10, v18, v19
	v_cvt_pk_bf16_f32 v11, v20, v21
	v_lshl_add_u64 v[12:13], v[12:13], 0, v[124:125]
	global_store_dwordx4 v[12:13], v[8:11], off
	s_nop 0
	s_nop 0
	s_nop 0
	v_mov_b64_e32 v[8:9], v[228:229]
	v_mov_b64_e32 v[10:11], v[230:231]
	v_mov_b64_e32 v[14:15], v[232:233]
	v_mov_b64_e32 v[16:17], v[234:235]
	v_pk_add_f32 v[0:1], v[0:1], v[8:9]
	s_nop 0
	v_pk_add_f32 v[4:5], v[4:5], v[14:15]
	v_mul_f32_e32 v8, 0x3d372713, v0
	v_mul_f32_e32 v14, 0x3d372713, v4
	v_mul_f32_e32 v15, 0x3d372713, v5
	v_mul_f32_e32 v9, 0x3d372713, v1
	v_mul_f32_e32 v14, v4, v14
	v_mul_f32_e32 v15, v5, v15
	v_mul_f32_e32 v8, v0, v8
	v_mul_f32_e32 v9, v1, v9
	v_fma_f32 v14, v4, v14, v4
	v_fma_f32 v15, v5, v15, v5
	v_fma_f32 v8, v0, v8, v0
	v_fma_f32 v9, v1, v9, v1
	v_mul_f32_e32 v14, 0x3f4c422a, v14
	v_mul_f32_e32 v15, 0x3f4c422a, v15
	v_mul_f32_e32 v8, 0x3f4c422a, v8
	v_mul_f32_e32 v9, 0x3f4c422a, v9
	v_add_f32_e32 v14, v14, v14
	v_add_f32_e32 v15, v15, v15
	v_add_f32_e32 v8, v8, v8
	v_add_f32_e32 v9, v9, v9
	v_mul_f32_e32 v14, 0xbfb8aa3b, v14
	v_mul_f32_e32 v15, 0xbfb8aa3b, v15
	v_mul_f32_e32 v8, 0xbfb8aa3b, v8
	v_mul_f32_e32 v9, 0xbfb8aa3b, v9
	v_exp_f32_e32 v14, v14
	v_exp_f32_e32 v15, v15
	v_exp_f32_e32 v8, v8
	v_exp_f32_e32 v9, v9
	v_add_f32_e32 v14, 1.0, v14
	v_add_f32_e32 v15, 1.0, v15
	v_add_f32_e32 v8, 1.0, v8
	v_add_f32_e32 v9, 1.0, v9
	v_rcp_f32_e32 v14, v14
	v_rcp_f32_e32 v15, v15
	v_rcp_f32_e32 v8, v8
	v_rcp_f32_e32 v9, v9
	v_pk_add_f32 v[6:7], v[6:7], v[16:17]
	v_pk_add_f32 v[2:3], v[2:3], v[10:11]
	v_pk_mul_f32 v[4:5], v[4:5], v[14:15]
	v_mul_f32_e32 v14, 0x3d372713, v6
	v_mul_f32_e32 v15, 0x3d372713, v7
	v_pk_mul_f32 v[8:9], v[0:1], v[8:9]
	v_mul_f32_e32 v0, 0x3d372713, v2
	v_mul_f32_e32 v1, 0x3d372713, v3
	v_mul_f32_e32 v14, v6, v14
	v_mul_f32_e32 v15, v7, v15
	v_mul_f32_e32 v0, v2, v0
	v_mul_f32_e32 v1, v3, v1
	v_fma_f32 v14, v6, v14, v6
	v_fma_f32 v15, v7, v15, v7
	v_fma_f32 v0, v2, v0, v2
	v_fma_f32 v1, v3, v1, v3
	v_mul_f32_e32 v14, 0x3f4c422a, v14
	v_mul_f32_e32 v15, 0x3f4c422a, v15
	v_mul_f32_e32 v0, 0x3f4c422a, v0
	v_mul_f32_e32 v1, 0x3f4c422a, v1
	v_add_f32_e32 v14, v14, v14
	v_add_f32_e32 v15, v15, v15
	v_add_f32_e32 v0, v0, v0
	v_add_f32_e32 v1, v1, v1
	v_mul_f32_e32 v14, 0xbfb8aa3b, v14
	v_mul_f32_e32 v15, 0xbfb8aa3b, v15
	v_mul_f32_e32 v0, 0xbfb8aa3b, v0
	v_mul_f32_e32 v1, 0xbfb8aa3b, v1
	v_exp_f32_e32 v14, v14
	v_exp_f32_e32 v15, v15
	v_exp_f32_e32 v0, v0
	v_exp_f32_e32 v1, v1
	v_add_f32_e32 v14, 1.0, v14
	v_add_f32_e32 v15, 1.0, v15
	v_add_f32_e32 v0, 1.0, v0
	v_add_f32_e32 v1, 1.0, v1
	v_rcp_f32_e32 v14, v14
	v_rcp_f32_e32 v15, v15
	v_rcp_f32_e32 v0, v0
	v_rcp_f32_e32 v1, v1
	v_pk_mul_f32 v[6:7], v[6:7], v[14:15]
	v_pk_mul_f32 v[10:11], v[2:3], v[0:1]
	v_cvt_pk_bf16_f32 v0, v4, v5
	v_cvt_pk_bf16_f32 v1, v6, v7
	v_cvt_pk_bf16_f32 v2, v8, v9
	v_cvt_pk_bf16_f32 v3, v10, v11
	global_store_dwordx4 v[12:13], v[0:3], off offset:256
	s_cbranch_vccnz .LBB0_518
	s_andn2_b64 vcc, exec, s[22:23]
	s_cbranch_vccnz .LBB0_517
	s_barrier
	s_branch .LBB0_517

; #define LAS __attribute__((address_space(3)))
; #define MFMA16(a, b, c) __builtin_amdgcn_mfma_f32_16x16x32_bf16(a, b, c, 0, 0, 0)
; template <int MODE> ...
;     ...
;     for (int qs = 0; qs < 2; ++qs) cb[qs] = slope * (float)(key0 + 4 * g4 - tq[qs]) + ((MODE == 1 && !selb[qs]) ? -1e30f : 0.f);
;     __builtin_amdgcn_s_setprio(1);
; #pragma unroll
;     for (int s = 0; s < 4; ++s) {
;         const LAS unsigned char* kp = KT + (s * 16) * 144;
;         const bf16x8 k0 = *(const LAS bf16x8*)kp, k1 = *(const LAS bf16x8*)(kp + 64);
; #pragma unroll
;         for (int qs = 0; qs < 2; ++qs) {
;             f32x4 zz;
; #pragma unroll
;             for (int i = 0; i < 4; ++i) zz[i] = fmaf(slope, (float)(s * 16 + i), cb[qs]);
;             zz = MFMA16(k0, Qf[qs][0], zz);
;             sc[s][qs] = MFMA16(k1, Qf[qs][1], zz);
;         }
;         __builtin_amdgcn_sched_barrier(0);
;     }
;     __builtin_amdgcn_s_setprio(0);
;     if (!full) {
; #pragma unroll
;         for (int qs = 0; qs < 2; ++qs)
; #pragma unroll
;             for (int s = 0; s < 4; ++s)
; #pragma unroll
;                 for (int i = 0; i < 4; ++i) {
;                     const int dist = (tq[qs] - key0 - 4 * g4) - (s * 16 + i);
;                     const bool ok = (MODE == 1) ? (dist >= 0) : (dist >= 0 && dist < 512);
;                     sc[s][qs][i] = ok ? sc[s][qs][i] : -1e30f;
;                 }
.LBB0_1104:
	v_lshrrev_b64 v[92:93], s9, v[124:125]
	v_and_b32_e32 v94, 1, v92
	v_lshrrev_b64 v[92:93], s9, v[128:129]
	s_lshl_b32 s6, s9, 6
	v_mov_b32_e32 v147, v203
	v_mov_b32_e32 v93, v1
	v_add_u32_e32 v148, s6, v141
	v_add_u32_e32 v149, 0, v93
	v_sub_u32_e32 v93, v148, v138
	v_cmp_eq_u32_e32 vcc, 1, v94
	v_sub_u32_e32 v94, v148, v139
	v_cvt_f32_i32_e32 v93, v93
	v_cvt_f32_i32_e32 v94, v94
	v_and_b32_e32 v92, 1, v92
	v_cndmask_b32_e64 v150, v194, 0, vcc
	v_cmp_eq_u32_e32 vcc, 1, v92
	s_cmp_lt_i32 s9, s63
	v_fmac_f32_e32 v150, v160, v93
	v_cndmask_b32_e64 v154, v194, 0, vcc
	v_fmac_f32_e32 v154, v160, v94
	s_nop 0
	ds_read_b128 v[92:95], v149
	v_fma_f32 v96, 0, v160, v150
	v_add_f32_e32 v97, v160, v150
	v_pk_fma_f32 v[98:99], v[162:163], s[56:57], v[150:151] op_sel_hi:[1,1,0]
	v_fma_f32 v100, 0, v160, v154
	v_add_f32_e32 v101, v160, v154
	v_pk_fma_f32 v[102:103], v[162:163], s[56:57], v[154:155] op_sel_hi:[1,1,0]
	s_waitcnt lgkmcnt(0)
	v_mfma_f32_16x16x32_bf16 v[96:99], v[92:95], v[4:7], v[96:99]
	v_mfma_f32_16x16x32_bf16 v[92:95], v[92:95], v[12:15], v[100:103]
	s_nop 2
	ds_read_b128 v[100:103], v149 offset:64
	s_waitcnt lgkmcnt(0)
	v_mfma_f32_16x16x32_bf16 v[104:107], v[100:103], v[8:11], v[96:99]
	v_mfma_f32_16x16x32_bf16 v[92:95], v[100:103], v[16:19], v[92:95]
	s_nop 1
	ds_read_b128 v[96:99], v149 offset:2304
	v_mov_b32_e32 v161, v160
	v_pk_fma_f32 v[100:101], v[164:165], s[88:89], v[150:151] op_sel_hi:[1,1,0]
	v_pk_fma_f32 v[102:103], v[160:161], s[20:21], v[150:151] op_sel_hi:[1,1,0]
	v_pk_fma_f32 v[108:109], v[164:165], s[88:89], v[154:155] op_sel_hi:[1,1,0]
	v_pk_fma_f32 v[110:111], v[160:161], s[20:21], v[154:155] op_sel_hi:[1,1,0]
	s_waitcnt lgkmcnt(0)
	v_mfma_f32_16x16x32_bf16 v[100:103], v[96:99], v[4:7], v[100:103]
	v_mfma_f32_16x16x32_bf16 v[96:99], v[96:99], v[12:15], v[108:111]
	s_nop 2
	ds_read_b128 v[108:111], v149 offset:2368
	s_waitcnt lgkmcnt(0)
	v_mfma_f32_16x16x32_bf16 v[112:115], v[108:111], v[8:11], v[100:103]
	v_mfma_f32_16x16x32_bf16 v[96:99], v[108:111], v[16:19], v[96:99]
	s_nop 1
	ds_read_b128 v[100:103], v149 offset:4608
	ds_read_b128 v[120:123], v149 offset:4672
	v_pk_fma_f32 v[110:111], v[160:161], s[54:55], v[150:151] op_sel_hi:[1,1,0]
	v_pk_fma_f32 v[108:109], v[164:165], s[80:81], v[150:151] op_sel_hi:[1,1,0]
	v_pk_fma_f32 v[118:119], v[160:161], s[54:55], v[154:155] op_sel_hi:[1,1,0]
	v_pk_fma_f32 v[116:117], v[164:165], s[80:81], v[154:155] op_sel_hi:[1,1,0]
	s_waitcnt lgkmcnt(1)
	v_mfma_f32_16x16x32_bf16 v[108:111], v[100:103], v[4:7], v[108:111]
	v_mfma_f32_16x16x32_bf16 v[100:103], v[100:103], v[12:15], v[116:119]
	s_waitcnt lgkmcnt(0)
	v_mfma_f32_16x16x32_bf16 v[116:119], v[120:123], v[8:11], v[108:111]
	v_mfma_f32_16x16x32_bf16 v[100:103], v[120:123], v[16:19], v[100:103]
	s_nop 3
	ds_read_b128 v[108:111], v149 offset:6912
	v_pk_fma_f32 v[122:123], v[160:161], s[44:45], v[150:151] op_sel_hi:[1,1,0]
	v_pk_fma_f32 v[120:121], v[164:165], s[40:41], v[150:151] op_sel_hi:[1,1,0]
	v_pk_fma_f32 v[152:153], v[160:161], s[44:45], v[154:155] op_sel_hi:[1,1,0]
	v_pk_fma_f32 v[150:151], v[164:165], s[40:41], v[154:155] op_sel_hi:[1,1,0]
	s_waitcnt lgkmcnt(0)
	v_mfma_f32_16x16x32_bf16 v[120:123], v[108:111], v[4:7], v[120:123]
	v_mfma_f32_16x16x32_bf16 v[108:111], v[108:111], v[12:15], v[150:153]
	s_nop 2
	ds_read_b128 v[150:153], v149 offset:6976
	s_waitcnt lgkmcnt(0)
	v_mfma_f32_16x16x32_bf16 v[120:123], v[150:153], v[8:11], v[120:123]
	v_mfma_f32_16x16x32_bf16 v[108:111], v[150:153], v[16:19], v[108:111]
	s_nop 0
	s_cbranch_scc1 .LBB0_1106
	v_sub_u32_e32 v149, v138, v148
	v_cmp_lt_i32_e32 vcc, -1, v149
	v_or_b32_e32 v149, 1, v148
	v_sub_u32_e32 v150, v138, v149
	v_cndmask_b32_e32 v104, v194, v104, vcc
	v_cmp_lt_i32_e32 vcc, -1, v150
	v_or_b32_e32 v150, 2, v148
	v_sub_u32_e32 v151, v138, v150
	v_cndmask_b32_e32 v105, v194, v105, vcc
	v_cmp_lt_i32_e32 vcc, -1, v151
	v_or_b32_e32 v151, 3, v148
	v_sub_u32_e32 v152, v138, v151
	v_cndmask_b32_e32 v106, v194, v106, vcc
	v_cmp_lt_i32_e32 vcc, -1, v152
	v_add_u32_e32 v152, 16, v148
	v_sub_u32_e32 v153, v138, v152
	v_cndmask_b32_e32 v107, v194, v107, vcc
	v_cmp_lt_i32_e32 vcc, -1, v153
	v_add_u32_e32 v153, 17, v148
	v_sub_u32_e32 v154, v138, v153
	v_cndmask_b32_e32 v112, v194, v112, vcc
	v_cmp_lt_i32_e32 vcc, -1, v154
	v_add_u32_e32 v154, 18, v148
	v_sub_u32_e32 v155, v138, v154
	v_cndmask_b32_e32 v113, v194, v113, vcc
	v_cmp_lt_i32_e32 vcc, -1, v155
	v_add_u32_e32 v155, 19, v148
	v_sub_u32_e32 v161, v138, v155
	v_cndmask_b32_e32 v114, v194, v114, vcc
	v_cmp_lt_i32_e32 vcc, -1, v161
	v_add_u32_e32 v161, 32, v148
	v_sub_u32_e32 v176, v138, v161
	v_cndmask_b32_e32 v115, v194, v115, vcc
	v_cmp_lt_i32_e32 vcc, -1, v176
	v_add_u32_e32 v176, 33, v148
	v_sub_u32_e32 v177, v138, v176
	v_cndmask_b32_e32 v116, v194, v116, vcc
	v_cmp_lt_i32_e32 vcc, -1, v177
	v_add_u32_e32 v177, 34, v148
	v_sub_u32_e32 v178, v138, v177
	v_cndmask_b32_e32 v117, v194, v117, vcc
	v_cmp_lt_i32_e32 vcc, -1, v178
	v_add_u32_e32 v178, 35, v148
	v_sub_u32_e32 v179, v138, v178
	v_cndmask_b32_e32 v118, v194, v118, vcc
	v_cmp_lt_i32_e32 vcc, -1, v179
	v_add_u32_e32 v179, 48, v148
	v_sub_u32_e32 v180, v138, v179
	v_cndmask_b32_e32 v119, v194, v119, vcc
	v_cmp_lt_i32_e32 vcc, -1, v180
	v_add_u32_e32 v180, 49, v148
	v_sub_u32_e32 v181, v138, v180
	v_cndmask_b32_e32 v120, v194, v120, vcc
	v_cmp_lt_i32_e32 vcc, -1, v181
	v_add_u32_e32 v181, 50, v148
	v_sub_u32_e32 v182, v138, v181
	v_cndmask_b32_e32 v121, v194, v121, vcc
	v_cmp_lt_i32_e32 vcc, -1, v182
	v_add_u32_e32 v182, 51, v148
	v_sub_u32_e32 v183, v138, v182
	v_cndmask_b32_e32 v122, v194, v122, vcc
	v_cmp_lt_i32_e32 vcc, -1, v183
	v_sub_u32_e32 v148, v139, v148
; template <int MODE> ...
;     ...
;     if (!full) {
; #pragma unroll
;         for (int qs = 0; qs < 2; ++qs)
; #pragma unroll
;             for (int s = 0; s < 4; ++s)
; #pragma unroll
;                 for (int i = 0; i < 4; ++i) {
;                     const int dist = (tq[qs] - key0 - 4 * g4) - (s * 16 + i);
;                     const bool ok = (MODE == 1) ? (dist >= 0) : (dist >= 0 && dist < 512);
;                     sc[s][qs][i] = ok ? sc[s][qs][i] : -1e30f;
;                 }
;     }
; #pragma unroll
;     for (int qs = 0; qs < 2; ++qs) {
;         float mx = -1e30f;
; #pragma unroll
;         for (int s = 0; s < 4; ++s)
; #pragma unroll
;             for (int i = 0; i < 4; ++i) mx = fmaxf(mx, sc[s][qs][i]);
;         mx = fmaxf(mx, __shfl_xor(mx, 16)); mx = fmaxf(mx, __shfl_xor(mx, 32));
;         const float mn = fmaxf(mrun[qs], mx);
;         const float alpha = __builtin_amdgcn_exp2f(mrun[qs] - mn);
;         mrun[qs] = mn;
;         const float mnx = fmaxf(mn, -1e29f);
;         float ps = 0.f;
; #pragma unroll
;         for (int s = 0; s < 4; ++s)
; #pragma unroll
;             for (int i = 0; i < 4; ++i) { const float p = __builtin_amdgcn_exp2f(sc[s][qs][i] - mnx); sc[s][qs][i] = p; ps += p; }
;         lrun[qs] = lrun[qs] * alpha + ps;
; #pragma unroll
;         for (int d = 0; d < 4; ++d) O[d][qs] = O[d][qs] * alpha;
;     }
	s_nop 0
	v_cndmask_b32_e32 v123, v194, v123, vcc
	v_cmp_lt_i32_e32 vcc, -1, v148
	v_sub_u32_e32 v148, v139, v149
	s_nop 0
	v_cndmask_b32_e32 v92, v194, v92, vcc
	v_cmp_lt_i32_e32 vcc, -1, v148
	v_sub_u32_e32 v148, v139, v150
	s_nop 0
	v_cndmask_b32_e32 v93, v194, v93, vcc
	v_cmp_lt_i32_e32 vcc, -1, v148
	v_sub_u32_e32 v148, v139, v151
	s_nop 0
	v_cndmask_b32_e32 v94, v194, v94, vcc
	v_cmp_lt_i32_e32 vcc, -1, v148
	v_sub_u32_e32 v148, v139, v152
	s_nop 0
	v_cndmask_b32_e32 v95, v194, v95, vcc
	v_cmp_lt_i32_e32 vcc, -1, v148
	v_sub_u32_e32 v148, v139, v153
	s_nop 0
	v_cndmask_b32_e32 v96, v194, v96, vcc
	v_cmp_lt_i32_e32 vcc, -1, v148
	v_sub_u32_e32 v148, v139, v154
	s_nop 0
	v_cndmask_b32_e32 v97, v194, v97, vcc
	v_cmp_lt_i32_e32 vcc, -1, v148
	v_sub_u32_e32 v148, v139, v155
	s_nop 0
	v_cndmask_b32_e32 v98, v194, v98, vcc
	v_cmp_lt_i32_e32 vcc, -1, v148
	v_sub_u32_e32 v148, v139, v161
	s_nop 0
	v_cndmask_b32_e32 v99, v194, v99, vcc
	v_cmp_lt_i32_e32 vcc, -1, v148
	v_sub_u32_e32 v148, v139, v176
	s_nop 0
	v_cndmask_b32_e32 v100, v194, v100, vcc
	v_cmp_lt_i32_e32 vcc, -1, v148
	v_sub_u32_e32 v148, v139, v177
	s_nop 0
	v_cndmask_b32_e32 v101, v194, v101, vcc
	v_cmp_lt_i32_e32 vcc, -1, v148
	v_sub_u32_e32 v148, v139, v178
	s_nop 0
	v_cndmask_b32_e32 v102, v194, v102, vcc
	v_cmp_lt_i32_e32 vcc, -1, v148
	v_sub_u32_e32 v148, v139, v179
	s_nop 0
	v_cndmask_b32_e32 v103, v194, v103, vcc
	v_cmp_lt_i32_e32 vcc, -1, v148
	v_sub_u32_e32 v148, v139, v180
	s_nop 0
	v_cndmask_b32_e32 v108, v194, v108, vcc
	v_cmp_lt_i32_e32 vcc, -1, v148
	v_sub_u32_e32 v148, v139, v181
	s_nop 0
	v_cndmask_b32_e32 v109, v194, v109, vcc
	v_cmp_lt_i32_e32 vcc, -1, v148
	v_sub_u32_e32 v148, v139, v182
	s_nop 0
	v_cndmask_b32_e32 v110, v194, v110, vcc
	v_cmp_lt_i32_e32 vcc, -1, v148
	s_nop 1
	v_cndmask_b32_e32 v111, v194, v111, vcc
.LBB0_1106:
	v_max3_f32 v148, v104, s92, v105
	v_max3_f32 v148, v148, v106, v107
	v_max3_f32 v148, v148, v112, v113
	v_max3_f32 v148, v148, v114, v115
	v_max3_f32 v148, v148, v116, v117
	v_max3_f32 v148, v148, v118, v119
	v_max3_f32 v148, v148, v120, v121
	v_max3_f32 v148, v148, v122, v123
	ds_bpermute_b32 v149, v201, v148
	v_add_u32_e32 v161, 0, v147
	s_waitcnt lgkmcnt(0)
	v_max_f32_e32 v149, v149, v149
	v_max_f32_e32 v148, v148, v149
	ds_bpermute_b32 v149, v202, v148
	s_waitcnt lgkmcnt(0)
	v_max3_f32 v147, v146, v148, v149
	v_max_f32_e32 v148, 0xefa18f08, v147
	v_sub_f32_e32 v106, v106, v148
	v_exp_f32_e32 v153, v106
	v_max3_f32 v106, v92, s92, v93
	v_max3_f32 v106, v106, v94, v95
	v_max3_f32 v106, v106, v96, v97
	v_max3_f32 v106, v106, v98, v99
	v_max3_f32 v106, v106, v100, v101
	v_max3_f32 v106, v106, v102, v103
	v_max3_f32 v106, v106, v108, v109
	v_sub_f32_e32 v104, v104, v148
	v_max3_f32 v106, v106, v110, v111
	v_exp_f32_e32 v149, v104
	v_sub_f32_e32 v104, v112, v148
	ds_bpermute_b32 v112, v201, v106
	v_exp_f32_e32 v177, v104
	v_sub_f32_e32 v104, v113, v148
	v_exp_f32_e32 v179, v104
	v_sub_f32_e32 v104, v114, v148
	s_waitcnt lgkmcnt(0)
	v_max_f32_e32 v112, v112, v112
	v_exp_f32_e32 v181, v104
	v_sub_f32_e32 v104, v115, v148
	v_max_f32_e32 v106, v106, v112
	v_sub_f32_e32 v105, v105, v148
	v_exp_f32_e32 v183, v104
	v_sub_f32_e32 v104, v116, v148
	ds_bpermute_b32 v112, v202, v106
	v_sub_f32_e32 v107, v107, v148
	v_exp_f32_e32 v151, v105
	v_exp_f32_e32 v105, v104
	v_sub_f32_e32 v104, v117, v148
	v_exp_f32_e32 v155, v107
	v_exp_f32_e32 v107, v104
	v_sub_f32_e32 v104, v118, v148
	v_exp_f32_e32 v113, v104
	v_sub_f32_e32 v104, v119, v148
	v_sub_f32_e32 v146, v146, v147
	v_exp_f32_e32 v115, v104
	v_sub_f32_e32 v104, v120, v148
	v_exp_f32_e32 v117, v104
	v_sub_f32_e32 v104, v121, v148
	v_exp_f32_e32 v185, v146
	s_waitcnt lgkmcnt(0)
; template <int MODE> ...
;     ...
;         const float alpha = __builtin_amdgcn_exp2f(mrun[qs] - mn);
;         mrun[qs] = mn;
;         const float mnx = fmaxf(mn, -1e29f);
;         float ps = 0.f;
; #pragma unroll
;         for (int s = 0; s < 4; ++s)
; #pragma unroll
;             for (int i = 0; i < 4; ++i) { const float p = __builtin_amdgcn_exp2f(sc[s][qs][i] - mnx); sc[s][qs][i] = p; ps += p; }
;         lrun[qs] = lrun[qs] * alpha + ps;
; #pragma unroll
;         for (int d = 0; d < 4; ++d) O[d][qs] = O[d][qs] * alpha;
;     }
;     __builtin_amdgcn_s_setprio(1);
; #pragma unroll
;     for (int kk = 0; kk < 2; ++kk) {
;         bf16x8 Pf[2];
; #pragma unroll
;         for (int qs = 0; qs < 2; ++qs) { u32x4 w; w.x = pk2(sc[2 * kk][qs][0], sc[2 * kk][qs][1]); w.y = pk2(sc[2 * kk][qs][2], sc[2 * kk][qs][3]);
;             w.z = pk2(sc[2 * kk + 1][qs][0], sc[2 * kk + 1][qs][1]); w.w = pk2(sc[2 * kk + 1][qs][2], sc[2 * kk + 1][qs][3]); Pf[qs] = __builtin_bit_cast(bf16x8, w); }
; #pragma unroll
;         for (int d = 0; d < 4; ++d) {
;             const LAS unsigned char* vp = VT + (d * 16) * 144 + (kk * 32) * 2;
;             const s16x4 lo = *(const LAS s16x4*)vp, hi = *(const LAS s16x4*)(vp + 32);
;             const bf16x8 Vf = {lo[0], lo[1], lo[2], lo[3], hi[0], hi[1], hi[2], hi[3]};
; #pragma unroll
;             for (int qs = 0; qs < 2; ++qs) O[d][qs] = MFMA16(Vf, Pf[qs], O[d][qs]);
;             __builtin_amdgcn_sched_barrier(0);
;         }
;     }
; __device__ __forceinline__ void nsa_phase(LAS unsigned char* lds, const Args& a, const bf16_t* z, const bf16_t* KC, const bf16_t* VCT, const bf16_t* VST, const bf16_t* VWT, bf16_t* A2, int ldo, bool merged) {
;     ...
;             while (j >= 0) {
;                 __syncthreads();
;                 nsa_commit(lds, pkv, pvv, tidv);
;                 __syncthreads();
;                 const int jc = j;
;                 if (rem) { j = __builtin_ctzll(rem); rem &= rem - 1ull;
;                     nsa_fetch(pkv, pvv, z + ((size_t)b * SEQ + j * 64) * ZLD + ZKS + g * 64, ZLD, VST + ((size_t)(b * 128 + g * 64)) * SEQ + j * 64, SEQ, tidv); }
;                 else j = -1;
;                 const bool selb[2] = {(bool)((msk[0] >> jc) & 1ull), (bool)((msk[1] >> jc) & 1ull)};
;                 flash_tile<1>(lds, kt_off, vt_off, Qf, O, mrun, lrun, slope, tq, jc * 64, selb, l15, g4, jc < cur);
;             }
	v_max3_f32 v146, v145, v106, v112
	v_exp_f32_e32 v119, v104
	v_sub_f32_e32 v104, v122, v148
	v_max_f32_e32 v122, 0xefa18f08, v146
	v_sub_f32_e32 v92, v92, v122
	v_exp_f32_e32 v121, v104
	v_sub_f32_e32 v104, v123, v148
	v_exp_f32_e32 v148, v92
	v_sub_f32_e32 v92, v93, v122
	v_exp_f32_e32 v150, v92
	v_sub_f32_e32 v92, v94, v122
	v_exp_f32_e32 v152, v92
	v_sub_f32_e32 v92, v95, v122
	v_exp_f32_e32 v154, v92
	v_sub_f32_e32 v92, v96, v122
	v_exp_f32_e32 v176, v92
	v_sub_f32_e32 v92, v97, v122
	v_exp_f32_e32 v178, v92
	v_pk_add_f32 v[92:93], v[148:149], 0 op_sel_hi:[1,0]
	v_sub_f32_e32 v94, v98, v122
	v_pk_add_f32 v[92:93], v[150:151], v[92:93]
	v_exp_f32_e32 v180, v94
	v_pk_add_f32 v[92:93], v[152:153], v[92:93]
	v_sub_f32_e32 v94, v99, v122
	v_pk_add_f32 v[92:93], v[154:155], v[92:93]
	v_exp_f32_e32 v182, v94
	v_sub_f32_e32 v94, v100, v122
	v_exp_f32_e32 v123, v104
	v_pk_add_f32 v[92:93], v[176:177], v[92:93]
	v_exp_f32_e32 v104, v94
	v_sub_f32_e32 v94, v101, v122
	v_pk_add_f32 v[92:93], v[178:179], v[92:93]
	v_exp_f32_e32 v106, v94
	v_sub_f32_e32 v94, v102, v122
	v_exp_f32_e32 v112, v94
	v_sub_f32_e32 v94, v103, v122
	v_pk_add_f32 v[92:93], v[180:181], v[92:93]
	v_exp_f32_e32 v114, v94
	v_sub_f32_e32 v94, v108, v122
	v_pk_add_f32 v[92:93], v[182:183], v[92:93]
	v_exp_f32_e32 v116, v94
	v_sub_f32_e32 v94, v109, v122
	v_pk_add_f32 v[92:93], v[104:105], v[92:93]
	v_exp_f32_e32 v118, v94
	v_sub_f32_e32 v94, v110, v122
	v_pk_add_f32 v[92:93], v[106:107], v[92:93]
	v_exp_f32_e32 v120, v94
	v_sub_f32_e32 v94, v111, v122
	v_pk_add_f32 v[92:93], v[112:113], v[92:93]
	v_sub_f32_e32 v145, v145, v146
	v_exp_f32_e32 v122, v94
	v_pk_add_f32 v[92:93], v[114:115], v[92:93]
	v_exp_f32_e32 v184, v145
	v_pk_add_f32 v[92:93], v[116:117], v[92:93]
	v_mov_b32_e32 v94, v185
	v_pk_add_f32 v[92:93], v[118:119], v[92:93]
	v_pk_mul_f32 v[78:79], v[78:79], v[94:95] op_sel_hi:[1,0]
	v_pk_add_f32 v[92:93], v[120:121], v[92:93]
	v_pk_mul_f32 v[76:77], v[76:77], v[94:95] op_sel_hi:[1,0]
	v_pk_add_f32 v[92:93], v[122:123], v[92:93]
	v_pk_mul_f32 v[82:83], v[82:83], v[94:95] op_sel_hi:[1,0]
	v_pk_mul_f32 v[80:81], v[80:81], v[94:95] op_sel_hi:[1,0]
	v_pk_mul_f32 v[74:75], v[74:75], v[94:95] op_sel_hi:[1,0]
	v_pk_mul_f32 v[72:73], v[72:73], v[94:95] op_sel_hi:[1,0]
	v_pk_mul_f32 v[70:71], v[70:71], v[94:95] op_sel_hi:[1,0]
	v_pk_mul_f32 v[68:69], v[68:69], v[94:95] op_sel_hi:[1,0]
	v_pk_fma_f32 v[134:135], v[134:135], v[184:185], v[92:93]
	v_pk_mul_f32 v[66:67], v[66:67], v[184:185] op_sel_hi:[1,0]
	v_pk_mul_f32 v[64:65], v[64:65], v[184:185] op_sel_hi:[1,0]
	v_pk_mul_f32 v[62:63], v[62:63], v[184:185] op_sel_hi:[1,0]
	v_pk_mul_f32 v[60:61], v[60:61], v[184:185] op_sel_hi:[1,0]
	v_pk_mul_f32 v[58:59], v[58:59], v[184:185] op_sel_hi:[1,0]
	v_pk_mul_f32 v[56:57], v[56:57], v[184:185] op_sel_hi:[1,0]
	v_pk_mul_f32 v[54:55], v[54:55], v[184:185] op_sel_hi:[1,0]
	v_pk_mul_f32 v[52:53], v[52:53], v[184:185] op_sel_hi:[1,0]
	s_nop 0
	ds_read2_b64 v[100:103], v161 offset1:4
	v_cvt_pk_bf16_f32 v92, v149, v151
	v_cvt_pk_bf16_f32 v93, v153, v155
	v_cvt_pk_bf16_f32 v94, v177, v179
	v_cvt_pk_bf16_f32 v95, v181, v183
	v_cvt_pk_bf16_f32 v96, v148, v150
	v_cvt_pk_bf16_f32 v97, v152, v154
	v_cvt_pk_bf16_f32 v98, v176, v178
	v_cvt_pk_bf16_f32 v99, v180, v182
	s_waitcnt lgkmcnt(0)
	v_mfma_f32_16x16x32_bf16 v[76:79], v[100:103], v[92:95], v[76:79]
	v_mfma_f32_16x16x32_bf16 v[64:67], v[100:103], v[96:99], v[64:67]
	v_add_u32_e32 v108, 0x800, v161
	ds_read2_b64 v[100:103], v108 offset0:32 offset1:36
	s_waitcnt lgkmcnt(0)
	v_mfma_f32_16x16x32_bf16 v[80:83], v[100:103], v[92:95], v[80:83]
	v_mfma_f32_16x16x32_bf16 v[60:63], v[100:103], v[96:99], v[60:63]
	v_add_u32_e32 v109, 0x1000, v161
	ds_read2_b64 v[100:103], v109 offset0:64 offset1:68
	s_waitcnt lgkmcnt(0)
	v_mfma_f32_16x16x32_bf16 v[72:75], v[100:103], v[92:95], v[72:75]
	v_mfma_f32_16x16x32_bf16 v[56:59], v[100:103], v[96:99], v[56:59]
	v_add_u32_e32 v110, 0x1800, v161
	ds_read2_b64 v[100:103], v110 offset0:96 offset1:100
	s_waitcnt lgkmcnt(0)
	v_mfma_f32_16x16x32_bf16 v[68:71], v[100:103], v[92:95], v[68:71]
	v_mfma_f32_16x16x32_bf16 v[52:55], v[100:103], v[96:99], v[52:55]
	ds_read2_b64 v[100:103], v161 offset0:8 offset1:12
	v_cvt_pk_bf16_f32 v92, v105, v107
	v_cvt_pk_bf16_f32 v93, v113, v115
	v_cvt_pk_bf16_f32 v94, v117, v119
	v_cvt_pk_bf16_f32 v95, v121, v123
	v_cvt_pk_bf16_f32 v96, v104, v106
	v_cvt_pk_bf16_f32 v97, v112, v114
	v_cvt_pk_bf16_f32 v98, v116, v118
	v_cvt_pk_bf16_f32 v99, v120, v122
	s_waitcnt lgkmcnt(0)
	v_mfma_f32_16x16x32_bf16 v[76:79], v[100:103], v[92:95], v[76:79]
	v_mfma_f32_16x16x32_bf16 v[64:67], v[100:103], v[96:99], v[64:67]
	ds_read2_b64 v[100:103], v108 offset0:40 offset1:44
	s_waitcnt lgkmcnt(0)
	v_mfma_f32_16x16x32_bf16 v[80:83], v[100:103], v[92:95], v[80:83]
	v_mfma_f32_16x16x32_bf16 v[60:63], v[100:103], v[96:99], v[60:63]
	ds_read2_b64 v[100:103], v109 offset0:72 offset1:76
	s_waitcnt lgkmcnt(0)
	v_mfma_f32_16x16x32_bf16 v[72:75], v[100:103], v[92:95], v[72:75]
	v_mfma_f32_16x16x32_bf16 v[56:59], v[100:103], v[96:99], v[56:59]
	ds_read2_b64 v[100:103], v110 offset0:104 offset1:108
	s_waitcnt lgkmcnt(0)
	v_mfma_f32_16x16x32_bf16 v[68:71], v[100:103], v[92:95], v[68:71]
	v_mfma_f32_16x16x32_bf16 v[52:55], v[100:103], v[96:99], v[52:55]
	s_nop 0
	s_cmp_lt_i32 s8, 0
	s_cbranch_scc1 .LBB0_1113
	s_mov_b32 s9, s8
	s_mov_b64 s[6:7], s[0:1]
	v_mov_b32_e32 v145, v146
	v_mov_b32_e32 v146, v147
	s_branch .LBB0_1101

; __device__ __forceinline__ unsigned pk2(float lo, float hi) { f32x2 v = {lo, hi}; bf16x2_t b = __builtin_convertvector(v, bf16x2_t); return __builtin_bit_cast(unsigned, b); }
; template <int MODE> ...
;     ...
; #pragma unroll
;     for (int qs = 0; qs < 2; ++qs) {
;         float mx = -1e30f;
; #pragma unroll
;         for (int s = 0; s < 4; ++s)
; #pragma unroll
;             for (int i = 0; i < 4; ++i) mx = fmaxf(mx, sc[s][qs][i]);
;         mx = fmaxf(mx, __shfl_xor(mx, 16)); mx = fmaxf(mx, __shfl_xor(mx, 32));
;         const float mn = fmaxf(mrun[qs], mx);
;         const float alpha = __builtin_amdgcn_exp2f(mrun[qs] - mn);
;         mrun[qs] = mn;
;         const float mnx = fmaxf(mn, -1e29f);
;         float ps = 0.f;
; #pragma unroll
;         for (int s = 0; s < 4; ++s)
; #pragma unroll
;             for (int i = 0; i < 4; ++i) { const float p = __builtin_amdgcn_exp2f(sc[s][qs][i] - mnx); sc[s][qs][i] = p; ps += p; }
;         lrun[qs] = lrun[qs] * alpha + ps;
; #pragma unroll
;         for (int d = 0; d < 4; ++d) O[d][qs] = O[d][qs] * alpha;
;     }
;     __builtin_amdgcn_s_setprio(1);
; #pragma unroll
;     for (int kk = 0; kk < 2; ++kk) {
;         bf16x8 Pf[2];
; #pragma unroll
;         for (int qs = 0; qs < 2; ++qs) { u32x4 w; w.x = pk2(sc[2 * kk][qs][0], sc[2 * kk][qs][1]); w.y = pk2(sc[2 * kk][qs][2], sc[2 * kk][qs][3]);
;             w.z = pk2(sc[2 * kk + 1][qs][0], sc[2 * kk + 1][qs][1]); w.w = pk2(sc[2 * kk + 1][qs][2], sc[2 * kk + 1][qs][3]); Pf[qs] = __builtin_bit_cast(bf16x8, w); }
.LBB0_1115:
	v_max3_f32 v161, v136, s92, v137
	v_max3_f32 v161, v161, v138, v139
	v_max3_f32 v161, v161, v144, v145
	v_max3_f32 v161, v161, v146, v147
	v_max3_f32 v161, v161, v148, v149
	v_max3_f32 v161, v161, v150, v151
	v_max3_f32 v161, v161, v152, v153
	v_max3_f32 v161, v161, v154, v155
	ds_bpermute_b32 v210, v201, v161
	v_add_u32_e32 v226, 0, v209
	s_waitcnt lgkmcnt(0)
	v_max_f32_e32 v210, v210, v210
	v_max_f32_e32 v161, v161, v210
	ds_bpermute_b32 v210, v202, v161
	s_waitcnt lgkmcnt(0)
	v_max3_f32 v161, v208, v161, v210
	v_max_f32_e32 v210, 0xefa18f08, v161
	v_sub_f32_e32 v138, v138, v210
	v_exp_f32_e32 v213, v138
	v_max3_f32 v138, v124, s92, v125
	v_max3_f32 v138, v138, v126, v127
	v_max3_f32 v138, v138, v128, v129
	v_max3_f32 v138, v138, v130, v131
	v_max3_f32 v138, v138, v132, v133
	v_max3_f32 v138, v138, v134, v135
	v_max3_f32 v138, v138, v140, v141
	v_sub_f32_e32 v136, v136, v210
	v_max3_f32 v138, v138, v142, v143
	v_exp_f32_e32 v209, v136
	v_sub_f32_e32 v136, v144, v210
	ds_bpermute_b32 v144, v201, v138
	v_exp_f32_e32 v217, v136
	v_sub_f32_e32 v136, v145, v210
	v_exp_f32_e32 v219, v136
	v_sub_f32_e32 v136, v146, v210
	s_waitcnt lgkmcnt(0)
	v_max_f32_e32 v144, v144, v144
	v_exp_f32_e32 v221, v136
	v_sub_f32_e32 v136, v147, v210
	v_max_f32_e32 v138, v138, v144
	v_sub_f32_e32 v137, v137, v210
	v_exp_f32_e32 v223, v136
	v_sub_f32_e32 v136, v148, v210
	ds_bpermute_b32 v144, v202, v138
	v_sub_f32_e32 v139, v139, v210
	v_exp_f32_e32 v211, v137
	v_exp_f32_e32 v137, v136
	v_sub_f32_e32 v136, v149, v210
	v_exp_f32_e32 v215, v139
	v_exp_f32_e32 v139, v136
	v_sub_f32_e32 v136, v150, v210
	v_exp_f32_e32 v145, v136
	v_sub_f32_e32 v136, v151, v210
	v_exp_f32_e32 v147, v136
	v_sub_f32_e32 v136, v152, v210
	v_exp_f32_e32 v149, v136
	v_sub_f32_e32 v136, v153, v210
	s_waitcnt lgkmcnt(0)
	v_max3_f32 v227, v207, v138, v144
	v_exp_f32_e32 v151, v136
	v_sub_f32_e32 v136, v154, v210
	v_max_f32_e32 v154, 0xefa18f08, v227
	v_sub_f32_e32 v208, v208, v161
	v_sub_f32_e32 v124, v124, v154
	v_exp_f32_e32 v225, v208
	v_exp_f32_e32 v208, v124
	v_sub_f32_e32 v124, v125, v154
	v_exp_f32_e32 v153, v136
	v_sub_f32_e32 v136, v155, v210
	v_exp_f32_e32 v210, v124
	v_sub_f32_e32 v124, v126, v154
	v_exp_f32_e32 v212, v124
	v_sub_f32_e32 v124, v127, v154
	v_exp_f32_e32 v214, v124
	v_sub_f32_e32 v124, v128, v154
	v_exp_f32_e32 v216, v124
	v_sub_f32_e32 v124, v129, v154
	v_exp_f32_e32 v218, v124
	v_sub_f32_e32 v124, v130, v154
	v_exp_f32_e32 v220, v124
	v_sub_f32_e32 v124, v131, v154
	v_exp_f32_e32 v222, v124
	v_pk_add_f32 v[124:125], v[208:209], 0 op_sel_hi:[1,0]
	v_sub_f32_e32 v126, v132, v154
	v_pk_add_f32 v[124:125], v[210:211], v[124:125]
	v_exp_f32_e32 v155, v136
	v_pk_add_f32 v[124:125], v[212:213], v[124:125]
	v_exp_f32_e32 v136, v126
	v_pk_add_f32 v[124:125], v[214:215], v[124:125]
	v_sub_f32_e32 v126, v133, v154
	v_pk_add_f32 v[124:125], v[216:217], v[124:125]
	v_exp_f32_e32 v138, v126
	v_pk_add_f32 v[124:125], v[218:219], v[124:125]
	v_sub_f32_e32 v126, v134, v154
	v_pk_add_f32 v[124:125], v[220:221], v[124:125]
	v_exp_f32_e32 v144, v126
	v_sub_f32_e32 v126, v135, v154
	v_pk_add_f32 v[124:125], v[222:223], v[124:125]
	v_exp_f32_e32 v146, v126
	v_sub_f32_e32 v126, v140, v154
	v_exp_f32_e32 v148, v126
	v_sub_f32_e32 v126, v141, v154
	v_pk_add_f32 v[124:125], v[136:137], v[124:125]
	v_exp_f32_e32 v150, v126
	v_sub_f32_e32 v126, v142, v154
	v_pk_add_f32 v[124:125], v[138:139], v[124:125]
	v_exp_f32_e32 v152, v126
	v_sub_f32_e32 v126, v143, v154
	v_pk_add_f32 v[124:125], v[144:145], v[124:125]
	v_sub_f32_e32 v207, v207, v227
	v_exp_f32_e32 v154, v126
	v_pk_add_f32 v[124:125], v[146:147], v[124:125]
	v_exp_f32_e32 v224, v207
	v_pk_add_f32 v[124:125], v[148:149], v[124:125]
	v_mov_b32_e32 v126, v225
	v_pk_add_f32 v[124:125], v[150:151], v[124:125]
	v_pk_mul_f32 v[118:119], v[118:119], v[126:127] op_sel_hi:[1,0]
	v_pk_add_f32 v[124:125], v[152:153], v[124:125]
	v_pk_mul_f32 v[116:117], v[116:117], v[126:127] op_sel_hi:[1,0]
	v_pk_add_f32 v[124:125], v[154:155], v[124:125]
	v_pk_mul_f32 v[122:123], v[122:123], v[126:127] op_sel_hi:[1,0]
	v_pk_mul_f32 v[120:121], v[120:121], v[126:127] op_sel_hi:[1,0]
	v_pk_mul_f32 v[114:115], v[114:115], v[126:127] op_sel_hi:[1,0]
	v_pk_mul_f32 v[112:113], v[112:113], v[126:127] op_sel_hi:[1,0]
	v_pk_mul_f32 v[110:111], v[110:111], v[126:127] op_sel_hi:[1,0]
	v_pk_mul_f32 v[108:109], v[108:109], v[126:127] op_sel_hi:[1,0]
	v_pk_fma_f32 v[176:177], v[176:177], v[224:225], v[124:125]
	v_pk_mul_f32 v[106:107], v[106:107], v[224:225] op_sel_hi:[1,0]
	v_pk_mul_f32 v[104:105], v[104:105], v[224:225] op_sel_hi:[1,0]
	v_pk_mul_f32 v[102:103], v[102:103], v[224:225] op_sel_hi:[1,0]
	v_pk_mul_f32 v[100:101], v[100:101], v[224:225] op_sel_hi:[1,0]
	v_pk_mul_f32 v[98:99], v[98:99], v[224:225] op_sel_hi:[1,0]
	v_pk_mul_f32 v[96:97], v[96:97], v[224:225] op_sel_hi:[1,0]
	v_pk_mul_f32 v[94:95], v[94:95], v[224:225] op_sel_hi:[1,0]
	v_pk_mul_f32 v[92:93], v[92:93], v[224:225] op_sel_hi:[1,0]
	s_nop 0
	ds_read2_b64 v[132:135], v226 offset1:4
	v_cvt_pk_bf16_f32 v124, v209, v211
	v_cvt_pk_bf16_f32 v125, v213, v215
	v_cvt_pk_bf16_f32 v126, v217, v219
	v_cvt_pk_bf16_f32 v127, v221, v223
	v_cvt_pk_bf16_f32 v128, v208, v210
	v_cvt_pk_bf16_f32 v129, v212, v214
	v_cvt_pk_bf16_f32 v130, v216, v218
	v_cvt_pk_bf16_f32 v131, v220, v222
	s_waitcnt lgkmcnt(0)
; #define LAS __attribute__((address_space(3)))
; __device__ __forceinline__ unsigned pk2(float lo, float hi) { f32x2 v = {lo, hi}; bf16x2_t b = __builtin_convertvector(v, bf16x2_t); return __builtin_bit_cast(unsigned, b); }
; #define MFMA16(a, b, c) __builtin_amdgcn_mfma_f32_16x16x32_bf16(a, b, c, 0, 0, 0)
; template <int MODE> ...
;     ...
; #pragma unroll
;     for (int kk = 0; kk < 2; ++kk) {
;         bf16x8 Pf[2];
; #pragma unroll
;         for (int qs = 0; qs < 2; ++qs) { u32x4 w; w.x = pk2(sc[2 * kk][qs][0], sc[2 * kk][qs][1]); w.y = pk2(sc[2 * kk][qs][2], sc[2 * kk][qs][3]);
;             w.z = pk2(sc[2 * kk + 1][qs][0], sc[2 * kk + 1][qs][1]); w.w = pk2(sc[2 * kk + 1][qs][2], sc[2 * kk + 1][qs][3]); Pf[qs] = __builtin_bit_cast(bf16x8, w); }
; #pragma unroll
;         for (int d = 0; d < 4; ++d) {
;             const LAS unsigned char* vp = VT + (d * 16) * 144 + (kk * 32) * 2;
;             const s16x4 lo = *(const LAS s16x4*)vp, hi = *(const LAS s16x4*)(vp + 32);
;             const bf16x8 Vf = {lo[0], lo[1], lo[2], lo[3], hi[0], hi[1], hi[2], hi[3]};
; #pragma unroll
;             for (int qs = 0; qs < 2; ++qs) O[d][qs] = MFMA16(Vf, Pf[qs], O[d][qs]);
;             __builtin_amdgcn_sched_barrier(0);
;         }
;     }
;     __builtin_amdgcn_s_setprio(0);
; __device__ __forceinline__ void nsa_phase(LAS unsigned char* lds, const Args& a, const bf16_t* z, const bf16_t* KC, const bf16_t* VCT, const bf16_t* VST, const bf16_t* VWT, bf16_t* A2, int ldo, bool merged) {
;     ...
;             for (; j <= cur; ++j) {
;                 __syncthreads();
;                 nsa_commit(lds, pkv, pvv, tidv);
;                 __syncthreads();
;                 if (j < cur) nsa_fetch(pkv, pvv, z + ((size_t)b * SEQ + (j + 1) * 64) * ZLD + ZKW + g * 64, ZLD, VWT + ((size_t)(b * 128 + g * 64)) * SEQ + (j + 1) * 64, SEQ, tidv);
;                 flash_tile<2>(lds, kt_off, vt_off, Qf, O, mrun, lrun, slope, tq, j * 64, selb, l15, g4, (j < cur) && (j > cur - 8));
;             }
	v_mfma_f32_16x16x32_bf16 v[116:119], v[132:135], v[124:127], v[116:119]
	v_mfma_f32_16x16x32_bf16 v[104:107], v[132:135], v[128:131], v[104:107]
	v_add_u32_e32 v140, 0x800, v226
	ds_read2_b64 v[132:135], v140 offset0:32 offset1:36
	s_waitcnt lgkmcnt(0)
	v_mfma_f32_16x16x32_bf16 v[120:123], v[132:135], v[124:127], v[120:123]
	v_mfma_f32_16x16x32_bf16 v[100:103], v[132:135], v[128:131], v[100:103]
	v_add_u32_e32 v141, 0x1000, v226
	ds_read2_b64 v[132:135], v141 offset0:64 offset1:68
	s_waitcnt lgkmcnt(0)
	v_mfma_f32_16x16x32_bf16 v[112:115], v[132:135], v[124:127], v[112:115]
	v_mfma_f32_16x16x32_bf16 v[96:99], v[132:135], v[128:131], v[96:99]
	v_add_u32_e32 v142, 0x1800, v226
	ds_read2_b64 v[132:135], v142 offset0:96 offset1:100
	s_waitcnt lgkmcnt(0)
	v_mfma_f32_16x16x32_bf16 v[108:111], v[132:135], v[124:127], v[108:111]
	v_mfma_f32_16x16x32_bf16 v[92:95], v[132:135], v[128:131], v[92:95]
	ds_read2_b64 v[132:135], v226 offset0:8 offset1:12
	v_cvt_pk_bf16_f32 v124, v137, v139
	v_cvt_pk_bf16_f32 v125, v145, v147
	v_cvt_pk_bf16_f32 v126, v149, v151
	v_cvt_pk_bf16_f32 v127, v153, v155
	v_cvt_pk_bf16_f32 v128, v136, v138
	v_cvt_pk_bf16_f32 v129, v144, v146
	v_cvt_pk_bf16_f32 v130, v148, v150
	v_cvt_pk_bf16_f32 v131, v152, v154
	s_waitcnt lgkmcnt(0)
	v_mfma_f32_16x16x32_bf16 v[116:119], v[132:135], v[124:127], v[116:119]
	v_mfma_f32_16x16x32_bf16 v[104:107], v[132:135], v[128:131], v[104:107]
	ds_read2_b64 v[132:135], v140 offset0:40 offset1:44
	s_waitcnt lgkmcnt(0)
	v_mfma_f32_16x16x32_bf16 v[120:123], v[132:135], v[124:127], v[120:123]
	v_mfma_f32_16x16x32_bf16 v[100:103], v[132:135], v[128:131], v[100:103]
	ds_read2_b64 v[132:135], v141 offset0:72 offset1:76
	s_waitcnt lgkmcnt(0)
	v_mfma_f32_16x16x32_bf16 v[112:115], v[132:135], v[124:127], v[112:115]
	v_mfma_f32_16x16x32_bf16 v[96:99], v[132:135], v[128:131], v[96:99]
	ds_read2_b64 v[132:135], v142 offset0:104 offset1:108
	s_waitcnt lgkmcnt(0)
	v_mfma_f32_16x16x32_bf16 v[108:111], v[132:135], v[124:127], v[108:111]
	v_mfma_f32_16x16x32_bf16 v[92:95], v[132:135], v[128:131], v[92:95]
	s_nop 0
	s_add_i32 s77, s77, 1
	s_add_i32 s79, s79, 64
	v_subrev_u32_e32 v3, 64, v3
	s_and_b64 vcc, exec, s[74:75]
	v_mov_b32_e32 v208, v161
	v_mov_b32_e32 v207, v227
	s_cbranch_vccnz .LBB0_912

; #define LAS __attribute__((address_space(3)))
; #define MFMA16(a, b, c) __builtin_amdgcn_mfma_f32_16x16x32_bf16(a, b, c, 0, 0, 0)
; template <int MODE> ...
;     ...
;     for (int qs = 0; qs < 2; ++qs) cb[qs] = slope * (float)(key0 + 4 * g4 - tq[qs]) + ((MODE == 1 && !selb[qs]) ? -1e30f : 0.f);
;     __builtin_amdgcn_s_setprio(1);
; #pragma unroll
;     for (int s = 0; s < 4; ++s) {
;         const LAS unsigned char* kp = KT + (s * 16) * 144;
;         const bf16x8 k0 = *(const LAS bf16x8*)kp, k1 = *(const LAS bf16x8*)(kp + 64);
; #pragma unroll
;         for (int qs = 0; qs < 2; ++qs) {
;             f32x4 zz;
; #pragma unroll
;             for (int i = 0; i < 4; ++i) zz[i] = fmaf(slope, (float)(s * 16 + i), cb[qs]);
;             zz = MFMA16(k0, Qf[qs][0], zz);
;             sc[s][qs] = MFMA16(k1, Qf[qs][1], zz);
;         }
;         __builtin_amdgcn_sched_barrier(0);
;     }
;     __builtin_amdgcn_s_setprio(0);
;     if (!full) {
; #pragma unroll
;         for (int qs = 0; qs < 2; ++qs)
; #pragma unroll
;             for (int s = 0; s < 4; ++s)
; #pragma unroll
;                 for (int i = 0; i < 4; ++i) {
;                     const int dist = (tq[qs] - key0 - 4 * g4) - (s * 16 + i);
;                     const bool ok = (MODE == 1) ? (dist >= 0) : (dist >= 0 && dist < 512);
;                     sc[s][qs][i] = ok ? sc[s][qs][i] : -1e30f;
;                 }
; __device__ __forceinline__ void nsa_phase(LAS unsigned char* lds, const Args& a, const bf16_t* z, const bf16_t* KC, const bf16_t* VCT, const bf16_t* VST, const bf16_t* VWT, bf16_t* A2, int ldo, bool merged) {
;     ...
;             for (; j <= cur; ++j) {
;                 __syncthreads();
;                 nsa_commit(lds, pkv, pvv, tidv);
;                 __syncthreads();
;                 if (j < cur) nsa_fetch(pkv, pvv, z + ((size_t)b * SEQ + (j + 1) * 64) * ZLD + ZKW + g * 64, ZLD, VWT + ((size_t)(b * 128 + g * 64)) * SEQ + (j + 1) * 64, SEQ, tidv);
;                 flash_tile<2>(lds, kt_off, vt_off, Qf, O, mrun, lrun, slope, tq, j * 64, selb, l15, g4, (j < cur) && (j > cur - 8));
.LBB0_1118:
	v_add_u32_e32 v125, s79, v204
	v_cvt_f32_i32_e32 v126, v125
	v_add_u32_e32 v125, -16, v125
	v_cvt_f32_i32_e32 v125, v125
	s_cmp_gt_i32 s77, s69
	s_cselect_b64 s[6:7], -1, 0
	v_mov_b32_e32 v124, v1
	v_mov_b32_e32 v209, v203
	s_and_b64 s[0:1], s[0:1], s[6:7]
	v_fma_f32 v210, v160, v126, 0
	v_add_u32_e32 v215, 0, v124
	v_fma_f32 v214, v160, v125, 0
	s_nop 0
	ds_read_b128 v[124:127], v215
	v_fma_f32 v128, 0, v160, v210
	v_add_f32_e32 v129, v160, v210
	v_pk_fma_f32 v[130:131], v[162:163], s[56:57], v[210:211] op_sel_hi:[1,1,0]
	v_fma_f32 v132, 0, v160, v214
	v_add_f32_e32 v133, v160, v214
	v_pk_fma_f32 v[134:135], v[162:163], s[56:57], v[214:215] op_sel_hi:[1,1,0]
	s_waitcnt lgkmcnt(0)
	v_mfma_f32_16x16x32_bf16 v[128:131], v[124:127], v[4:7], v[128:131]
	v_mfma_f32_16x16x32_bf16 v[124:127], v[124:127], v[12:15], v[132:135]
	s_nop 2
	ds_read_b128 v[132:135], v215 offset:64
	s_waitcnt lgkmcnt(0)
	v_mfma_f32_16x16x32_bf16 v[136:139], v[132:135], v[8:11], v[128:131]
	v_mfma_f32_16x16x32_bf16 v[124:127], v[132:135], v[16:19], v[124:127]
	s_nop 1
	ds_read_b128 v[128:131], v215 offset:2304
	v_mov_b32_e32 v161, v160
	v_pk_fma_f32 v[132:133], v[164:165], s[88:89], v[210:211] op_sel_hi:[1,1,0]
	v_pk_fma_f32 v[134:135], v[160:161], s[20:21], v[210:211] op_sel_hi:[1,1,0]
	v_pk_fma_f32 v[140:141], v[164:165], s[88:89], v[214:215] op_sel_hi:[1,1,0]
	v_pk_fma_f32 v[142:143], v[160:161], s[20:21], v[214:215] op_sel_hi:[1,1,0]
	s_waitcnt lgkmcnt(0)
	v_mfma_f32_16x16x32_bf16 v[132:135], v[128:131], v[4:7], v[132:135]
	v_mfma_f32_16x16x32_bf16 v[128:131], v[128:131], v[12:15], v[140:143]
	s_nop 2
	ds_read_b128 v[140:143], v215 offset:2368
	s_waitcnt lgkmcnt(0)
	v_mfma_f32_16x16x32_bf16 v[144:147], v[140:143], v[8:11], v[132:135]
	v_mfma_f32_16x16x32_bf16 v[128:131], v[140:143], v[16:19], v[128:131]
	s_nop 1
	ds_read_b128 v[132:135], v215 offset:4608
	ds_read_b128 v[152:155], v215 offset:4672
	v_pk_fma_f32 v[142:143], v[160:161], s[54:55], v[210:211] op_sel_hi:[1,1,0]
	v_pk_fma_f32 v[140:141], v[164:165], s[80:81], v[210:211] op_sel_hi:[1,1,0]
	v_pk_fma_f32 v[150:151], v[160:161], s[54:55], v[214:215] op_sel_hi:[1,1,0]
	v_pk_fma_f32 v[148:149], v[164:165], s[80:81], v[214:215] op_sel_hi:[1,1,0]
	s_waitcnt lgkmcnt(1)
	v_mfma_f32_16x16x32_bf16 v[140:143], v[132:135], v[4:7], v[140:143]
	v_mfma_f32_16x16x32_bf16 v[132:135], v[132:135], v[12:15], v[148:151]
	s_waitcnt lgkmcnt(0)
	v_mfma_f32_16x16x32_bf16 v[148:151], v[152:155], v[8:11], v[140:143]
	v_mfma_f32_16x16x32_bf16 v[132:135], v[152:155], v[16:19], v[132:135]
	s_nop 3
	ds_read_b128 v[140:143], v215 offset:6912
	v_pk_fma_f32 v[154:155], v[160:161], s[44:45], v[210:211] op_sel_hi:[1,1,0]
	v_pk_fma_f32 v[152:153], v[164:165], s[40:41], v[210:211] op_sel_hi:[1,1,0]
	v_pk_fma_f32 v[212:213], v[160:161], s[44:45], v[214:215] op_sel_hi:[1,1,0]
	v_pk_fma_f32 v[210:211], v[164:165], s[40:41], v[214:215] op_sel_hi:[1,1,0]
	s_waitcnt lgkmcnt(0)
	v_mfma_f32_16x16x32_bf16 v[152:155], v[140:143], v[4:7], v[152:155]
	v_mfma_f32_16x16x32_bf16 v[140:143], v[140:143], v[12:15], v[210:213]
	s_nop 2
	ds_read_b128 v[210:213], v215 offset:6976
	s_waitcnt lgkmcnt(0)
	v_mfma_f32_16x16x32_bf16 v[152:155], v[210:213], v[8:11], v[152:155]
	v_mfma_f32_16x16x32_bf16 v[140:143], v[210:213], v[16:19], v[140:143]
	s_nop 0
	s_and_b64 vcc, exec, s[0:1]
	s_cbranch_vccnz .LBB0_1115
	v_add_u32_e32 v161, 51, v3
	v_cmp_gt_u32_e32 vcc, s35, v161
	v_add_u32_e32 v161, 50, v3
	v_cmp_gt_u32_e64 s[0:1], s35, v161
	v_add_u32_e32 v161, 49, v3
	v_cmp_gt_u32_e64 s[6:7], s35, v161
	v_add_u32_e32 v161, 48, v3
	v_cmp_gt_u32_e64 s[8:9], s35, v161
	v_add_u32_e32 v161, 35, v3
	v_cmp_gt_u32_e64 s[10:11], s35, v161
	v_add_u32_e32 v161, 34, v3
	v_cmp_gt_u32_e64 s[12:13], s35, v161
	v_add_u32_e32 v161, 33, v3
	v_cmp_gt_u32_e64 s[14:15], s35, v161
	v_add_u32_e32 v161, 32, v3
	v_cmp_gt_u32_e64 s[16:17], s35, v161
	v_add_u32_e32 v161, 19, v3
	v_cmp_gt_u32_e64 s[18:19], s35, v161
	v_add_u32_e32 v161, 18, v3
	v_cmp_gt_u32_e64 s[22:23], s35, v161
	v_add_u32_e32 v161, 17, v3
	v_cmp_gt_u32_e64 s[24:25], s35, v161
	v_add_u32_e32 v161, 16, v3
	v_cmp_gt_u32_e64 s[26:27], s35, v161
	v_add_u32_e32 v161, 3, v3
	v_cmp_gt_u32_e64 s[28:29], s35, v161
	v_add_u32_e32 v161, 2, v3
	v_cndmask_b32_e32 v136, v194, v136, vcc
	v_cndmask_b32_e64 v152, v194, v152, s[28:29]
	v_cmp_gt_u32_e64 s[28:29], s35, v161
	v_add_u32_e32 v161, 1, v3
	v_cndmask_b32_e64 v137, v194, v137, s[0:1]
	v_cndmask_b32_e64 v153, v194, v153, s[28:29]
	v_cmp_gt_u32_e64 s[28:29], s35, v161
	v_add_u32_e32 v161, 0x43, v3
	v_cndmask_b32_e64 v138, v194, v138, s[6:7]
	v_cndmask_b32_e64 v154, v194, v154, s[28:29]
	v_cmp_gt_u32_e64 s[28:29], s35, v3
	v_cndmask_b32_e64 v139, v194, v139, s[8:9]
	v_cndmask_b32_e64 v144, v194, v144, s[10:11]
	v_cndmask_b32_e64 v155, v194, v155, s[28:29]
	v_cmp_gt_u32_e64 s[28:29], s35, v161
	v_add_u32_e32 v161, 0x42, v3
	v_cndmask_b32_e64 v145, v194, v145, s[12:13]
	v_cndmask_b32_e64 v124, v194, v124, s[28:29]
	v_cmp_gt_u32_e64 s[28:29], s35, v161
	v_add_u32_e32 v161, 0x41, v3
	v_cndmask_b32_e64 v146, v194, v146, s[14:15]
	v_cndmask_b32_e64 v125, v194, v125, s[28:29]
	v_cmp_gt_u32_e64 s[28:29], s35, v161
	v_add_u32_e32 v161, 64, v3
	v_cndmask_b32_e64 v147, v194, v147, s[16:17]
	v_cndmask_b32_e64 v126, v194, v126, s[28:29]
	v_cmp_gt_u32_e64 s[28:29], s35, v161
	v_cndmask_b32_e64 v148, v194, v148, s[18:19]
	v_cndmask_b32_e64 v149, v194, v149, s[22:23]
	v_cndmask_b32_e64 v150, v194, v150, s[24:25]
	v_cndmask_b32_e64 v151, v194, v151, s[26:27]
	v_cndmask_b32_e64 v127, v194, v127, s[28:29]
	v_cndmask_b32_e32 v128, v194, v128, vcc
	v_cndmask_b32_e64 v129, v194, v129, s[0:1]
	v_cndmask_b32_e64 v130, v194, v130, s[6:7]
	v_cndmask_b32_e64 v131, v194, v131, s[8:9]
	v_cndmask_b32_e64 v132, v194, v132, s[10:11]
	v_cndmask_b32_e64 v133, v194, v133, s[12:13]
	v_cndmask_b32_e64 v134, v194, v134, s[14:15]
	v_cndmask_b32_e64 v135, v194, v135, s[16:17]
	v_cndmask_b32_e64 v140, v194, v140, s[18:19]
	v_cndmask_b32_e64 v141, v194, v141, s[22:23]
	v_cndmask_b32_e64 v142, v194, v142, s[24:25]
	v_cndmask_b32_e64 v143, v194, v143, s[26:27]
	s_branch .LBB0_1115

; __device__ __forceinline__ u32x4 pack8(const float (&f)[8]) { u32x4 w; w.x = pk2(f[0], f[1]); w.y = pk2(f[2], f[3]); w.z = pk2(f[4], f[5]); w.w = pk2(f[6], f[7]); return w; }
;     __device__ __forceinline__ void operator()(const f32x4 (&acc)[2][2][4][2], const pg8::Unit& u, int wr, int wc, int fr, int fq) const {
;     ...
;             for (int m = 0; m < 4; ++m) {
;                 const int r = u.pm * 256 + ai * 128 + wr * 64 + m * 16 + fr;
;                 float rs = 1.f;
;                 if (MODE == 0 || MODE == 5) rs = rowscale[r];
;     ...
;                     } else if (MODE == 5) {
; #pragma unroll
;                         for (int j = 0; j < 8; ++j) { const float x = fmaxf(v[j] * rs, 0.f); v[j] = x * x; }
;                         *(u32x4*)(O + (size_t)r * ldc + c0) = pack8(v);
.LBB0_1647:
	v_lshl_add_u32 v146, s24, 8, v148
	v_ashrrev_i32_e32 v147, 31, v146
	v_lshl_add_u64 v[144:145], v[146:147], 2, s[10:11]
	global_load_dword v248, v[144:145], off
	global_load_dword v249, v[144:145], off offset:64
	global_load_dword v250, v[144:145], off offset:128
	global_load_dword v251, v[144:145], off offset:192
	global_load_dword v252, v[144:145], off offset:512
	global_load_dword v253, v[144:145], off offset:576
	global_load_dword v254, v[144:145], off offset:640
	global_load_dword v255, v[144:145], off offset:704
	v_lshl_or_b32 v144, s50, 8, v150
	v_ashrrev_i32_e32 v145, 31, v144
	v_lshlrev_b64 v[160:161], 13, v[146:147]
	v_lshlrev_b64 v[144:145], 1, v[144:145]
	v_lshl_add_u64 v[160:161], s[38:39], 0, v[160:161]
	v_or_b32_e32 v154, 16, v146
	v_lshl_add_u64 v[160:161], v[160:161], 0, v[144:145]
	v_ashrrev_i32_e32 v155, 31, v154
	v_lshl_add_u64 v[162:163], v[154:155], 2, s[10:11]
	s_andn2_b64 vcc, exec, s[4:5]
	s_mov_b64 s[4:5], -1
	s_waitcnt vmcnt(7)
	v_mul_f32_e32 v124, v124, v248
	v_mul_f32_e32 v125, v125, v248
	v_mul_f32_e32 v126, v126, v248
	v_mul_f32_e32 v127, v127, v248
	v_mul_f32_e32 v120, v120, v248
	v_mul_f32_e32 v121, v121, v248
	v_mul_f32_e32 v122, v122, v248
	v_mul_f32_e32 v123, v123, v248
	v_mul_f32_e32 v147, v116, v248
	v_mul_f32_e32 v159, v117, v248
	v_mul_f32_e32 v164, v118, v248
	v_mul_f32_e32 v165, v119, v248
	v_mul_f32_e32 v166, v112, v248
	v_mul_f32_e32 v167, v113, v248
	v_mul_f32_e32 v168, v114, v248
	v_mul_f32_e32 v157, v115, v248
	v_max_f32_e32 v112, 0, v124
	v_max_f32_e32 v113, 0, v125
	v_max_f32_e32 v114, 0, v126
	v_max_f32_e32 v115, 0, v127
	v_max_f32_e32 v116, 0, v120
	v_max_f32_e32 v117, 0, v121
	v_max_f32_e32 v118, 0, v122
	v_max_f32_e32 v119, 0, v123
	v_max_f32_e32 v120, 0, v147
	v_max_f32_e32 v121, 0, v159
	v_max_f32_e32 v122, 0, v164
	v_max_f32_e32 v123, 0, v165
	v_max_f32_e32 v124, 0, v166
	v_max_f32_e32 v125, 0, v167
	v_max_f32_e32 v126, 0, v168
	v_max_f32_e32 v127, 0, v157
	v_pk_mul_f32 v[112:113], v[112:113], v[112:113]
	v_pk_mul_f32 v[114:115], v[114:115], v[114:115]
	v_pk_mul_f32 v[116:117], v[116:117], v[116:117]
	v_pk_mul_f32 v[118:119], v[118:119], v[118:119]
	v_pk_mul_f32 v[120:121], v[120:121], v[120:121]
	v_pk_mul_f32 v[122:123], v[122:123], v[122:123]
	v_pk_mul_f32 v[124:125], v[124:125], v[124:125]
	v_pk_mul_f32 v[126:127], v[126:127], v[126:127]
	v_cvt_pk_bf16_f32 v112, v112, v113
	v_cvt_pk_bf16_f32 v113, v114, v115
	v_cvt_pk_bf16_f32 v114, v116, v117
	v_cvt_pk_bf16_f32 v115, v118, v119
	v_cvt_pk_bf16_f32 v116, v120, v121
	v_cvt_pk_bf16_f32 v117, v122, v123
	v_cvt_pk_bf16_f32 v118, v124, v125
	v_cvt_pk_bf16_f32 v119, v126, v127
	global_store_dwordx4 v[160:161], v[112:115], off
	global_store_dwordx4 v[160:161], v[116:119], off offset:256
	s_nop 0
	v_lshlrev_b64 v[114:115], 13, v[154:155]
	v_lshl_add_u64 v[114:115], s[38:39], 0, v[114:115]
	v_or_b32_e32 v112, 32, v146
	v_lshl_add_u64 v[114:115], v[114:115], 0, v[144:145]
	v_ashrrev_i32_e32 v113, 31, v112
	v_lshl_add_u64 v[116:117], v[112:113], 2, s[10:11]
	s_waitcnt vmcnt(8)
	v_mul_f32_e32 v108, v108, v249
	v_mul_f32_e32 v109, v109, v249
	v_mul_f32_e32 v110, v110, v249
	v_mul_f32_e32 v111, v111, v249
	v_mul_f32_e32 v104, v104, v249
	v_mul_f32_e32 v105, v105, v249
	v_mul_f32_e32 v106, v106, v249
	v_mul_f32_e32 v107, v107, v249
	v_mul_f32_e32 v119, v100, v249
	v_mul_f32_e32 v120, v101, v249
	v_mul_f32_e32 v121, v102, v249
	v_mul_f32_e32 v122, v103, v249
	v_mul_f32_e32 v123, v96, v249
	v_mul_f32_e32 v124, v97, v249
	v_mul_f32_e32 v125, v98, v249
	v_mul_f32_e32 v118, v99, v249
	v_max_f32_e32 v96, 0, v108
	v_max_f32_e32 v97, 0, v109
	v_max_f32_e32 v98, 0, v110
	v_max_f32_e32 v99, 0, v111
	v_max_f32_e32 v100, 0, v104
	v_max_f32_e32 v101, 0, v105
	v_max_f32_e32 v102, 0, v106
	v_max_f32_e32 v103, 0, v107
	v_max_f32_e32 v104, 0, v119
	v_max_f32_e32 v105, 0, v120
	v_max_f32_e32 v106, 0, v121
	v_max_f32_e32 v107, 0, v122
	v_max_f32_e32 v108, 0, v123
	v_max_f32_e32 v109, 0, v124
	v_max_f32_e32 v110, 0, v125
	v_max_f32_e32 v111, 0, v118
	v_pk_mul_f32 v[96:97], v[96:97], v[96:97]
	v_pk_mul_f32 v[98:99], v[98:99], v[98:99]
	v_pk_mul_f32 v[100:101], v[100:101], v[100:101]
	v_pk_mul_f32 v[102:103], v[102:103], v[102:103]
	v_pk_mul_f32 v[104:105], v[104:105], v[104:105]
	v_pk_mul_f32 v[106:107], v[106:107], v[106:107]
	v_pk_mul_f32 v[108:109], v[108:109], v[108:109]
	v_pk_mul_f32 v[110:111], v[110:111], v[110:111]
	v_cvt_pk_bf16_f32 v96, v96, v97
	v_cvt_pk_bf16_f32 v97, v98, v99
	v_cvt_pk_bf16_f32 v98, v100, v101
	v_cvt_pk_bf16_f32 v99, v102, v103
	v_cvt_pk_bf16_f32 v100, v104, v105
	v_cvt_pk_bf16_f32 v101, v106, v107
	v_cvt_pk_bf16_f32 v102, v108, v109
	v_cvt_pk_bf16_f32 v103, v110, v111
	global_store_dwordx4 v[114:115], v[96:99], off
	global_store_dwordx4 v[114:115], v[100:103], off offset:256
	s_nop 0
	v_lshlrev_b64 v[98:99], 13, v[112:113]
	v_lshl_add_u64 v[98:99], s[38:39], 0, v[98:99]
	v_or_b32_e32 v96, 48, v146
	v_lshl_add_u64 v[98:99], v[98:99], 0, v[144:145]
	v_ashrrev_i32_e32 v97, 31, v96
	v_lshl_add_u64 v[100:101], v[96:97], 2, s[10:11]
	s_waitcnt vmcnt(9)
; __device__ __forceinline__ u32x4 pack8(const float (&f)[8]) { u32x4 w; w.x = pk2(f[0], f[1]); w.y = pk2(f[2], f[3]); w.z = pk2(f[4], f[5]); w.w = pk2(f[6], f[7]); return w; }
;     __device__ __forceinline__ void operator()(const f32x4 (&acc)[2][2][4][2], const pg8::Unit& u, int wr, int wc, int fr, int fq) const {
;     ...
;             for (int m = 0; m < 4; ++m) {
;                 const int r = u.pm * 256 + ai * 128 + wr * 64 + m * 16 + fr;
;                 float rs = 1.f;
;                 if (MODE == 0 || MODE == 5) rs = rowscale[r];
;     ...
;                     } else if (MODE == 5) {
; #pragma unroll
;                         for (int j = 0; j < 8; ++j) { const float x = fmaxf(v[j] * rs, 0.f); v[j] = x * x; }
;                         *(u32x4*)(O + (size_t)r * ldc + c0) = pack8(v);
	v_mul_f32_e32 v92, v92, v250
	v_mul_f32_e32 v93, v93, v250
	v_mul_f32_e32 v94, v94, v250
	v_mul_f32_e32 v95, v95, v250
	v_mul_f32_e32 v88, v88, v250
	v_mul_f32_e32 v89, v89, v250
	v_mul_f32_e32 v90, v90, v250
	v_mul_f32_e32 v91, v91, v250
	v_mul_f32_e32 v103, v84, v250
	v_mul_f32_e32 v104, v85, v250
	v_mul_f32_e32 v105, v86, v250
	v_mul_f32_e32 v106, v87, v250
	v_mul_f32_e32 v107, v80, v250
	v_mul_f32_e32 v108, v81, v250
	v_mul_f32_e32 v109, v82, v250
	v_mul_f32_e32 v102, v83, v250
	v_max_f32_e32 v80, 0, v92
	v_max_f32_e32 v81, 0, v93
	v_max_f32_e32 v82, 0, v94
	v_max_f32_e32 v83, 0, v95
	v_max_f32_e32 v84, 0, v88
	v_max_f32_e32 v85, 0, v89
	v_max_f32_e32 v86, 0, v90
	v_max_f32_e32 v87, 0, v91
	v_max_f32_e32 v88, 0, v103
	v_max_f32_e32 v89, 0, v104
	v_max_f32_e32 v90, 0, v105
	v_max_f32_e32 v91, 0, v106
	v_max_f32_e32 v92, 0, v107
	v_max_f32_e32 v93, 0, v108
	v_max_f32_e32 v94, 0, v109
	v_max_f32_e32 v95, 0, v102
	v_pk_mul_f32 v[80:81], v[80:81], v[80:81]
	v_pk_mul_f32 v[82:83], v[82:83], v[82:83]
	v_pk_mul_f32 v[84:85], v[84:85], v[84:85]
	v_pk_mul_f32 v[86:87], v[86:87], v[86:87]
	v_pk_mul_f32 v[88:89], v[88:89], v[88:89]
	v_pk_mul_f32 v[90:91], v[90:91], v[90:91]
	v_pk_mul_f32 v[92:93], v[92:93], v[92:93]
	v_pk_mul_f32 v[94:95], v[94:95], v[94:95]
	v_cvt_pk_bf16_f32 v80, v80, v81
	v_cvt_pk_bf16_f32 v81, v82, v83
	v_cvt_pk_bf16_f32 v82, v84, v85
	v_cvt_pk_bf16_f32 v83, v86, v87
	v_cvt_pk_bf16_f32 v84, v88, v89
	v_cvt_pk_bf16_f32 v85, v90, v91
	v_cvt_pk_bf16_f32 v86, v92, v93
	v_cvt_pk_bf16_f32 v87, v94, v95
	global_store_dwordx4 v[98:99], v[80:83], off
	global_store_dwordx4 v[98:99], v[84:87], off offset:256
	s_nop 0
	v_lshlrev_b64 v[82:83], 13, v[96:97]
	v_lshl_add_u64 v[82:83], s[38:39], 0, v[82:83]
	v_add_u32_e32 v80, 0x80, v146
	v_lshl_add_u64 v[82:83], v[82:83], 0, v[144:145]
	v_ashrrev_i32_e32 v81, 31, v80
	v_lshl_add_u64 v[84:85], v[80:81], 2, s[10:11]
	s_waitcnt vmcnt(10)
	v_mul_f32_e32 v76, v76, v251
	v_mul_f32_e32 v77, v77, v251
	v_mul_f32_e32 v78, v78, v251
	v_mul_f32_e32 v79, v79, v251
	v_mul_f32_e32 v72, v72, v251
	v_mul_f32_e32 v73, v73, v251
	v_mul_f32_e32 v74, v74, v251
	v_mul_f32_e32 v75, v75, v251
	v_mul_f32_e32 v87, v68, v251
	v_mul_f32_e32 v88, v69, v251
	v_mul_f32_e32 v89, v70, v251
	v_mul_f32_e32 v90, v71, v251
	v_mul_f32_e32 v91, v64, v251
	v_mul_f32_e32 v92, v65, v251
	v_mul_f32_e32 v93, v66, v251
	v_mul_f32_e32 v86, v67, v251
	v_max_f32_e32 v64, 0, v76
	v_max_f32_e32 v65, 0, v77
	v_max_f32_e32 v66, 0, v78
	v_max_f32_e32 v67, 0, v79
	v_max_f32_e32 v68, 0, v72
	v_max_f32_e32 v69, 0, v73
	v_max_f32_e32 v70, 0, v74
	v_max_f32_e32 v71, 0, v75
	v_max_f32_e32 v72, 0, v87
	v_max_f32_e32 v73, 0, v88
	v_max_f32_e32 v74, 0, v89
	v_max_f32_e32 v75, 0, v90
	v_max_f32_e32 v76, 0, v91
	v_max_f32_e32 v77, 0, v92
	v_max_f32_e32 v78, 0, v93
	v_max_f32_e32 v79, 0, v86
	v_pk_mul_f32 v[64:65], v[64:65], v[64:65]
	v_pk_mul_f32 v[66:67], v[66:67], v[66:67]
	v_pk_mul_f32 v[68:69], v[68:69], v[68:69]
	v_pk_mul_f32 v[70:71], v[70:71], v[70:71]
	v_pk_mul_f32 v[72:73], v[72:73], v[72:73]
	v_pk_mul_f32 v[74:75], v[74:75], v[74:75]
	v_pk_mul_f32 v[76:77], v[76:77], v[76:77]
	v_pk_mul_f32 v[78:79], v[78:79], v[78:79]
	v_cvt_pk_bf16_f32 v64, v64, v65
	v_cvt_pk_bf16_f32 v65, v66, v67
	v_cvt_pk_bf16_f32 v66, v68, v69
	v_cvt_pk_bf16_f32 v67, v70, v71
	v_cvt_pk_bf16_f32 v68, v72, v73
	v_cvt_pk_bf16_f32 v69, v74, v75
	v_cvt_pk_bf16_f32 v70, v76, v77
	v_cvt_pk_bf16_f32 v71, v78, v79
	global_store_dwordx4 v[82:83], v[64:67], off
	global_store_dwordx4 v[82:83], v[68:71], off offset:256
	s_nop 0
	v_lshlrev_b64 v[66:67], 13, v[80:81]
	v_lshl_add_u64 v[66:67], s[38:39], 0, v[66:67]
	v_add_u32_e32 v64, 0x90, v146
	v_lshl_add_u64 v[66:67], v[66:67], 0, v[144:145]
	v_ashrrev_i32_e32 v65, 31, v64
	v_lshl_add_u64 v[68:69], v[64:65], 2, s[10:11]
	s_waitcnt vmcnt(11)
	v_mul_f32_e32 v60, v60, v252
	v_mul_f32_e32 v61, v61, v252
	v_mul_f32_e32 v62, v62, v252
	v_mul_f32_e32 v63, v63, v252
	v_mul_f32_e32 v56, v56, v252
	v_mul_f32_e32 v57, v57, v252
	v_mul_f32_e32 v58, v58, v252
	v_mul_f32_e32 v59, v59, v252
	v_mul_f32_e32 v71, v52, v252
	v_mul_f32_e32 v72, v53, v252
	v_mul_f32_e32 v73, v54, v252
	v_mul_f32_e32 v74, v55, v252
	v_mul_f32_e32 v75, v48, v252
	v_mul_f32_e32 v76, v49, v252
	v_mul_f32_e32 v77, v50, v252
	v_mul_f32_e32 v70, v51, v252
	v_max_f32_e32 v48, 0, v60
	v_max_f32_e32 v49, 0, v61
	v_max_f32_e32 v50, 0, v62
	v_max_f32_e32 v51, 0, v63
	v_max_f32_e32 v52, 0, v56
	v_max_f32_e32 v53, 0, v57
	v_max_f32_e32 v54, 0, v58
	v_max_f32_e32 v55, 0, v59
	v_max_f32_e32 v56, 0, v71
	v_max_f32_e32 v57, 0, v72
	v_max_f32_e32 v58, 0, v73
	v_max_f32_e32 v59, 0, v74
	v_max_f32_e32 v60, 0, v75
	v_max_f32_e32 v61, 0, v76
	v_max_f32_e32 v62, 0, v77
	v_max_f32_e32 v63, 0, v70
	v_pk_mul_f32 v[48:49], v[48:49], v[48:49]
	v_pk_mul_f32 v[50:51], v[50:51], v[50:51]
	v_pk_mul_f32 v[52:53], v[52:53], v[52:53]
	v_pk_mul_f32 v[54:55], v[54:55], v[54:55]
	v_pk_mul_f32 v[56:57], v[56:57], v[56:57]
	v_pk_mul_f32 v[58:59], v[58:59], v[58:59]
	v_pk_mul_f32 v[60:61], v[60:61], v[60:61]
	v_pk_mul_f32 v[62:63], v[62:63], v[62:63]
	v_cvt_pk_bf16_f32 v48, v48, v49
	v_cvt_pk_bf16_f32 v49, v50, v51
	v_cvt_pk_bf16_f32 v50, v52, v53
	v_cvt_pk_bf16_f32 v51, v54, v55
	v_cvt_pk_bf16_f32 v52, v56, v57
	v_cvt_pk_bf16_f32 v53, v58, v59
	v_cvt_pk_bf16_f32 v54, v60, v61
	v_cvt_pk_bf16_f32 v55, v62, v63
	global_store_dwordx4 v[66:67], v[48:51], off
	global_store_dwordx4 v[66:67], v[52:55], off offset:256
	s_nop 0
	v_lshlrev_b64 v[50:51], 13, v[64:65]
	v_lshl_add_u64 v[50:51], s[38:39], 0, v[50:51]
	v_add_u32_e32 v48, 0xa0, v146
	v_lshl_add_u64 v[50:51], v[50:51], 0, v[144:145]
	v_ashrrev_i32_e32 v49, 31, v48
	v_lshl_add_u64 v[52:53], v[48:49], 2, s[10:11]
	s_waitcnt vmcnt(12)
; __device__ __forceinline__ u32x4 pack8(const float (&f)[8]) { u32x4 w; w.x = pk2(f[0], f[1]); w.y = pk2(f[2], f[3]); w.z = pk2(f[4], f[5]); w.w = pk2(f[6], f[7]); return w; }
;     __device__ __forceinline__ void operator()(const f32x4 (&acc)[2][2][4][2], const pg8::Unit& u, int wr, int wc, int fr, int fq) const {
;     ...
;             for (int m = 0; m < 4; ++m) {
;                 const int r = u.pm * 256 + ai * 128 + wr * 64 + m * 16 + fr;
;                 float rs = 1.f;
;                 if (MODE == 0 || MODE == 5) rs = rowscale[r];
;     ...
;                     } else if (MODE == 5) {
; #pragma unroll
;                         for (int j = 0; j < 8; ++j) { const float x = fmaxf(v[j] * rs, 0.f); v[j] = x * x; }
;                         *(u32x4*)(O + (size_t)r * ldc + c0) = pack8(v);
	v_mul_f32_e32 v44, v44, v253
	v_mul_f32_e32 v45, v45, v253
	v_mul_f32_e32 v46, v46, v253
	v_mul_f32_e32 v47, v47, v253
	v_mul_f32_e32 v40, v40, v253
	v_mul_f32_e32 v41, v41, v253
	v_mul_f32_e32 v42, v42, v253
	v_mul_f32_e32 v43, v43, v253
	v_mul_f32_e32 v55, v36, v253
	v_mul_f32_e32 v56, v37, v253
	v_mul_f32_e32 v57, v38, v253
	v_mul_f32_e32 v58, v39, v253
	v_mul_f32_e32 v59, v32, v253
	v_mul_f32_e32 v60, v33, v253
	v_mul_f32_e32 v61, v34, v253
	v_mul_f32_e32 v54, v35, v253
	v_max_f32_e32 v32, 0, v44
	v_max_f32_e32 v33, 0, v45
	v_max_f32_e32 v34, 0, v46
	v_max_f32_e32 v35, 0, v47
	v_max_f32_e32 v36, 0, v40
	v_max_f32_e32 v37, 0, v41
	v_max_f32_e32 v38, 0, v42
	v_max_f32_e32 v39, 0, v43
	v_max_f32_e32 v40, 0, v55
	v_max_f32_e32 v41, 0, v56
	v_max_f32_e32 v42, 0, v57
	v_max_f32_e32 v43, 0, v58
	v_max_f32_e32 v44, 0, v59
	v_max_f32_e32 v45, 0, v60
	v_max_f32_e32 v46, 0, v61
	v_max_f32_e32 v47, 0, v54
	v_pk_mul_f32 v[32:33], v[32:33], v[32:33]
	v_pk_mul_f32 v[34:35], v[34:35], v[34:35]
	v_pk_mul_f32 v[36:37], v[36:37], v[36:37]
	v_pk_mul_f32 v[38:39], v[38:39], v[38:39]
	v_pk_mul_f32 v[40:41], v[40:41], v[40:41]
	v_pk_mul_f32 v[42:43], v[42:43], v[42:43]
	v_pk_mul_f32 v[44:45], v[44:45], v[44:45]
	v_pk_mul_f32 v[46:47], v[46:47], v[46:47]
	v_cvt_pk_bf16_f32 v32, v32, v33
	v_cvt_pk_bf16_f32 v33, v34, v35
	v_cvt_pk_bf16_f32 v34, v36, v37
	v_cvt_pk_bf16_f32 v35, v38, v39
	v_cvt_pk_bf16_f32 v36, v40, v41
	v_cvt_pk_bf16_f32 v37, v42, v43
	v_cvt_pk_bf16_f32 v38, v44, v45
	v_cvt_pk_bf16_f32 v39, v46, v47
	global_store_dwordx4 v[50:51], v[32:35], off
	global_store_dwordx4 v[50:51], v[36:39], off offset:256
	s_nop 0
	v_lshlrev_b64 v[34:35], 13, v[48:49]
	v_lshl_add_u64 v[34:35], s[38:39], 0, v[34:35]
	v_add_u32_e32 v32, 0xb0, v146
	v_lshl_add_u64 v[34:35], v[34:35], 0, v[144:145]
	v_ashrrev_i32_e32 v33, 31, v32
	v_lshl_add_u64 v[36:37], v[32:33], 2, s[10:11]
	s_waitcnt vmcnt(13)
	v_mul_f32_e32 v28, v28, v254
	v_mul_f32_e32 v29, v29, v254
	v_mul_f32_e32 v30, v30, v254
	v_mul_f32_e32 v31, v31, v254
	v_mul_f32_e32 v24, v24, v254
	v_mul_f32_e32 v25, v25, v254
	v_mul_f32_e32 v26, v26, v254
	v_mul_f32_e32 v27, v27, v254
	v_mul_f32_e32 v39, v20, v254
	v_mul_f32_e32 v40, v21, v254
	v_mul_f32_e32 v41, v22, v254
	v_mul_f32_e32 v42, v23, v254
	v_mul_f32_e32 v43, v16, v254
	v_mul_f32_e32 v44, v17, v254
	v_mul_f32_e32 v45, v18, v254
	v_mul_f32_e32 v38, v19, v254
	v_max_f32_e32 v16, 0, v28
	v_max_f32_e32 v17, 0, v29
	v_max_f32_e32 v18, 0, v30
	v_max_f32_e32 v19, 0, v31
	v_max_f32_e32 v20, 0, v24
	v_max_f32_e32 v21, 0, v25
	v_max_f32_e32 v22, 0, v26
	v_max_f32_e32 v23, 0, v27
	v_max_f32_e32 v24, 0, v39
	v_max_f32_e32 v25, 0, v40
	v_max_f32_e32 v26, 0, v41
	v_max_f32_e32 v27, 0, v42
	v_max_f32_e32 v28, 0, v43
	v_max_f32_e32 v29, 0, v44
	v_max_f32_e32 v30, 0, v45
	v_max_f32_e32 v31, 0, v38
	v_pk_mul_f32 v[16:17], v[16:17], v[16:17]
	v_pk_mul_f32 v[18:19], v[18:19], v[18:19]
	v_pk_mul_f32 v[20:21], v[20:21], v[20:21]
	v_pk_mul_f32 v[22:23], v[22:23], v[22:23]
	v_pk_mul_f32 v[24:25], v[24:25], v[24:25]
	v_pk_mul_f32 v[26:27], v[26:27], v[26:27]
	v_pk_mul_f32 v[28:29], v[28:29], v[28:29]
	v_pk_mul_f32 v[30:31], v[30:31], v[30:31]
	v_cvt_pk_bf16_f32 v16, v16, v17
	v_cvt_pk_bf16_f32 v17, v18, v19
	v_cvt_pk_bf16_f32 v18, v20, v21
	v_cvt_pk_bf16_f32 v19, v22, v23
	v_cvt_pk_bf16_f32 v20, v24, v25
	v_cvt_pk_bf16_f32 v21, v26, v27
	v_cvt_pk_bf16_f32 v22, v28, v29
	v_cvt_pk_bf16_f32 v23, v30, v31
	global_store_dwordx4 v[34:35], v[16:19], off
	global_store_dwordx4 v[34:35], v[20:23], off offset:256
	s_nop 0
	v_lshlrev_b64 v[16:17], 13, v[32:33]
	v_lshl_add_u64 v[16:17], s[38:39], 0, v[16:17]
	v_lshl_add_u64 v[16:17], v[16:17], 0, v[144:145]
	s_waitcnt vmcnt(14)
	v_mul_f32_e32 v12, v12, v255
	v_mul_f32_e32 v13, v13, v255
	v_mul_f32_e32 v14, v14, v255
	v_mul_f32_e32 v15, v15, v255
	v_mul_f32_e32 v8, v8, v255
	v_mul_f32_e32 v9, v9, v255
	v_mul_f32_e32 v10, v10, v255
	v_mul_f32_e32 v11, v11, v255
	v_mul_f32_e32 v19, v4, v255
	v_mul_f32_e32 v20, v5, v255
	v_mul_f32_e32 v21, v6, v255
	v_mul_f32_e32 v22, v7, v255
	v_mul_f32_e32 v23, v0, v255
	v_mul_f32_e32 v24, v1, v255
	v_mul_f32_e32 v25, v2, v255
	v_mul_f32_e32 v18, v3, v255
	v_max_f32_e32 v0, 0, v12
	v_max_f32_e32 v1, 0, v13
	v_max_f32_e32 v2, 0, v14
	v_max_f32_e32 v3, 0, v15
	v_max_f32_e32 v4, 0, v8
	v_max_f32_e32 v5, 0, v9
	v_max_f32_e32 v6, 0, v10
	v_max_f32_e32 v7, 0, v11
	v_max_f32_e32 v8, 0, v19
	v_max_f32_e32 v9, 0, v20
	v_max_f32_e32 v10, 0, v21
	v_max_f32_e32 v11, 0, v22
	v_max_f32_e32 v12, 0, v23
	v_max_f32_e32 v13, 0, v24
	v_max_f32_e32 v14, 0, v25
	v_max_f32_e32 v15, 0, v18
	v_pk_mul_f32 v[0:1], v[0:1], v[0:1]
	v_pk_mul_f32 v[2:3], v[2:3], v[2:3]
	v_pk_mul_f32 v[4:5], v[4:5], v[4:5]
	v_pk_mul_f32 v[6:7], v[6:7], v[6:7]
	v_pk_mul_f32 v[8:9], v[8:9], v[8:9]
	v_pk_mul_f32 v[10:11], v[10:11], v[10:11]
	v_pk_mul_f32 v[12:13], v[12:13], v[12:13]
	v_pk_mul_f32 v[14:15], v[14:15], v[14:15]
	v_cvt_pk_bf16_f32 v0, v0, v1
	v_cvt_pk_bf16_f32 v1, v2, v3
	v_cvt_pk_bf16_f32 v2, v4, v5
	v_cvt_pk_bf16_f32 v3, v6, v7
	v_cvt_pk_bf16_f32 v4, v8, v9
	v_cvt_pk_bf16_f32 v5, v10, v11
	v_cvt_pk_bf16_f32 v6, v12, v13
	v_cvt_pk_bf16_f32 v7, v14, v15
	global_store_dwordx4 v[16:17], v[0:3], off
	global_store_dwordx4 v[16:17], v[4:7], off offset:256
	s_cbranch_vccnz .LBB0_1636
	s_andn2_b64 vcc, exec, s[8:9]
	s_cbranch_vccnz .LBB0_1635
	s_barrier
	s_branch .LBB0_1635

; __device__ __forceinline__ float sigm(float x) { return __builtin_amdgcn_rcpf(1.f + __expf(-x)); }
;     __device__ __forceinline__ void operator()(const f32x4 (&acc)[2][2][4][2], const pg8::Unit& u, int wr, int wc, int fr, int fq) const {
;     ...
;                     } else if (MODE == 6) {
;                         float* op = outf + (size_t)r * DM + c0;
;                         const u32x4 xw = *(const u32x4*)(O + (size_t)r * DM + c0);
;                         float xf[8]; unpack8(xw, xf);
;                         const u32x4 pw = *(const u32x4*)(pe + (size_t)r * DM + c0);
;                         float pf[8]; unpack8(pw, pf);
;                         f32x4 o0, o1;
; #pragma unroll
;                         for (int j = 0; j < 4; ++j) { o0[j] = xf[j] + sigm(v[j]) * pf[j]; o1[j] = xf[4 + j] + sigm(v[4 + j]) * pf[4 + j]; }
;                         *(f32x4*)op = o0; *(f32x4*)(op + 4) = o1;
.LBB0_1912:
	v_lshl_add_u32 v146, s18, 8, v148
	v_lshl_or_b32 v162, s37, 8, v150
	v_ashrrev_i32_e32 v147, 31, v146
	v_ashrrev_i32_e32 v163, 31, v162
	v_lshlrev_b64 v[158:159], 11, v[146:147]
	v_lshl_add_u64 v[154:155], s[48:49], 0, v[158:159]
	v_lshlrev_b64 v[144:145], 1, v[162:163]
	v_lshl_add_u64 v[158:159], s[38:39], 0, v[158:159]
	v_lshl_add_u64 v[164:165], v[154:155], 0, v[144:145]
	v_lshl_add_u64 v[166:167], v[158:159], 0, v[144:145]
	s_mov_b64 s[60:61], 0x8000
	s_mov_b64 s[62:63], 0x28000
	v_mov_b64_e32 v[244:245], v[164:165]
	v_mov_b64_e32 v[248:249], v[166:167]
	global_load_dwordx4 v[180:183], v[244:245], off
	global_load_dwordx4 v[184:187], v[248:249], off
	global_load_dwordx4 v[188:191], v[244:245], off offset:256
	global_load_dwordx4 v[192:195], v[248:249], off offset:256
	v_lshl_add_u64 v[244:245], v[244:245], 0, s[60:61]
	v_lshl_add_u64 v[248:249], v[248:249], 0, s[60:61]
	global_load_dwordx4 v[196:199], v[244:245], off
	global_load_dwordx4 v[200:203], v[248:249], off
	global_load_dwordx4 v[204:207], v[244:245], off offset:256
	global_load_dwordx4 v[208:211], v[248:249], off offset:256
	v_lshl_add_u64 v[244:245], v[244:245], 0, s[60:61]
	v_lshl_add_u64 v[248:249], v[248:249], 0, s[60:61]
	global_load_dwordx4 v[212:215], v[244:245], off
	global_load_dwordx4 v[216:219], v[248:249], off
	global_load_dwordx4 v[220:223], v[244:245], off offset:256
	global_load_dwordx4 v[224:227], v[248:249], off offset:256
	v_lshl_add_u64 v[244:245], v[244:245], 0, s[60:61]
	v_lshl_add_u64 v[248:249], v[248:249], 0, s[60:61]
	global_load_dwordx4 v[228:231], v[244:245], off
	global_load_dwordx4 v[232:235], v[248:249], off
	global_load_dwordx4 v[236:239], v[244:245], off offset:256
	global_load_dwordx4 v[240:243], v[248:249], off offset:256
	v_lshl_add_u64 v[244:245], v[244:245], 0, s[62:63]
	v_lshl_add_u64 v[248:249], v[248:249], 0, s[62:63]
	s_nop 0
	v_mul_f32_e32 v124, 0xbfb8aa3b, v124
	v_mul_f32_e32 v120, 0xbfb8aa3b, v120
	v_mul_f32_e32 v125, 0xbfb8aa3b, v125
	v_mul_f32_e32 v121, 0xbfb8aa3b, v121
	v_mul_f32_e32 v126, 0xbfb8aa3b, v126
	v_mul_f32_e32 v122, 0xbfb8aa3b, v122
	v_mul_f32_e32 v127, 0xbfb8aa3b, v127
	v_mul_f32_e32 v123, 0xbfb8aa3b, v123
	v_exp_f32_e32 v124, v124
	v_exp_f32_e32 v168, v120
	v_exp_f32_e32 v125, v125
	v_exp_f32_e32 v169, v121
	v_exp_f32_e32 v170, v126
	v_exp_f32_e32 v171, v122
	v_exp_f32_e32 v172, v127
	v_exp_f32_e32 v173, v123
	v_lshlrev_b64 v[122:123], 12, v[146:147]
	v_lshlrev_b64 v[120:121], 2, v[162:163]
	v_lshl_add_u64 v[122:123], s[84:85], 0, v[122:123]
	v_lshl_add_u64 v[126:127], v[122:123], 0, v[120:121]
	v_add_f32_e32 v122, 1.0, v124
	v_add_f32_e32 v123, 1.0, v168
	v_add_f32_e32 v125, 1.0, v125
	v_add_f32_e32 v147, 1.0, v169
	v_add_f32_e32 v162, 1.0, v170
	v_add_f32_e32 v163, 1.0, v171
	v_add_f32_e32 v169, 1.0, v172
	v_add_f32_e32 v170, 1.0, v173
	v_rcp_f32_e32 v122, v122
	v_rcp_f32_e32 v124, v123
	v_rcp_f32_e32 v123, v125
	v_rcp_f32_e32 v125, v147
	v_rcp_f32_e32 v162, v162
	v_rcp_f32_e32 v168, v163
	v_rcp_f32_e32 v163, v169
	v_rcp_f32_e32 v169, v170
	v_mul_f32_e32 v116, 0xbfb8aa3b, v116
	v_mul_f32_e32 v112, 0xbfb8aa3b, v112
	v_mul_f32_e32 v117, 0xbfb8aa3b, v117
	v_mul_f32_e32 v113, 0xbfb8aa3b, v113
	v_mul_f32_e32 v118, 0xbfb8aa3b, v118
	v_mul_f32_e32 v119, 0xbfb8aa3b, v119
	v_mul_f32_e32 v114, 0xbfb8aa3b, v114
	v_mul_f32_e32 v115, 0xbfb8aa3b, v115
	v_exp_f32_e32 v116, v116
	v_exp_f32_e32 v147, v112
	v_exp_f32_e32 v117, v117
	v_exp_f32_e32 v118, v118
	v_exp_f32_e32 v119, v119
	v_mul_f32_e32 v108, 0xbfb8aa3b, v108
	v_mul_f32_e32 v104, 0xbfb8aa3b, v104
	v_add_f32_e32 v118, 1.0, v118
	v_add_f32_e32 v119, 1.0, v119
	v_rcp_f32_e32 v118, v118
	v_rcp_f32_e32 v119, v119
	v_mul_f32_e32 v109, 0xbfb8aa3b, v109
	v_mul_f32_e32 v105, 0xbfb8aa3b, v105
	v_mul_f32_e32 v110, 0xbfb8aa3b, v110
	v_mul_f32_e32 v111, 0xbfb8aa3b, v111
	v_mul_f32_e32 v106, 0xbfb8aa3b, v106
	v_mul_f32_e32 v107, 0xbfb8aa3b, v107
	v_exp_f32_e32 v108, v108
	v_exp_f32_e32 v109, v109
	v_exp_f32_e32 v110, v110
	v_exp_f32_e32 v111, v111
	v_exp_f32_e32 v106, v106
	v_exp_f32_e32 v107, v107
	v_add_f32_e32 v108, 1.0, v108
	v_add_f32_e32 v109, 1.0, v109
	v_add_f32_e32 v110, 1.0, v110
	v_add_f32_e32 v111, 1.0, v111
	v_rcp_f32_e32 v110, v110
	v_rcp_f32_e32 v111, v111
	v_mul_f32_e32 v100, 0xbfb8aa3b, v100
	v_mul_f32_e32 v96, 0xbfb8aa3b, v96
	v_mul_f32_e32 v101, 0xbfb8aa3b, v101
	v_mul_f32_e32 v97, 0xbfb8aa3b, v97
	v_mul_f32_e32 v102, 0xbfb8aa3b, v102
	s_waitcnt vmcnt(14)
; __device__ __forceinline__ float sigm(float x) { return __builtin_amdgcn_rcpf(1.f + __expf(-x)); }
;     __device__ __forceinline__ void operator()(const f32x4 (&acc)[2][2][4][2], const pg8::Unit& u, int wr, int wc, int fr, int fq) const {
;     ...
;                     } else if (MODE == 6) {
;                         float* op = outf + (size_t)r * DM + c0;
;                         const u32x4 xw = *(const u32x4*)(O + (size_t)r * DM + c0);
;                         float xf[8]; unpack8(xw, xf);
;                         const u32x4 pw = *(const u32x4*)(pe + (size_t)r * DM + c0);
;                         float pf[8]; unpack8(pw, pf);
;                         f32x4 o0, o1;
; #pragma unroll
;                         for (int j = 0; j < 4; ++j) { o0[j] = xf[j] + sigm(v[j]) * pf[j]; o1[j] = xf[4 + j] + sigm(v[4 + j]) * pf[4 + j]; }
;                         *(f32x4*)op = o0; *(f32x4*)(op + 4) = o1;
	v_mov_b64_e32 v[154:155], v[180:181]
	v_mov_b64_e32 v[156:157], v[182:183]
	v_mov_b64_e32 v[158:159], v[184:185]
	v_mov_b64_e32 v[160:161], v[186:187]
	v_lshlrev_b32_e32 v170, 16, v154
	v_and_b32_e32 v171, 0xffff0000, v154
	v_lshlrev_b32_e32 v172, 16, v158
	v_and_b32_e32 v173, 0xffff0000, v158
	v_lshlrev_b32_e32 v174, 16, v156
	v_and_b32_e32 v175, 0xffff0000, v156
	v_lshlrev_b32_e32 v176, 16, v160
	v_and_b32_e32 v177, 0xffff0000, v160
	v_lshlrev_b32_e32 v178, 16, v155
	v_and_b32_e32 v179, 0xffff0000, v155
	v_lshlrev_b32_e32 v158, 16, v159
	v_and_b32_e32 v159, 0xffff0000, v159
	v_lshlrev_b32_e32 v156, 16, v157
	v_and_b32_e32 v157, 0xffff0000, v157
	v_lshlrev_b32_e32 v160, 16, v161
	v_and_b32_e32 v161, 0xffff0000, v161
	v_pk_fma_f32 v[122:123], v[122:123], v[172:173], v[170:171]
	v_pk_fma_f32 v[154:155], v[124:125], v[176:177], v[174:175]
	v_pk_fma_f32 v[124:125], v[162:163], v[158:159], v[178:179]
	v_pk_fma_f32 v[156:157], v[168:169], v[160:161], v[156:157]
	global_store_dwordx4 v[126:127], v[122:125], off
	global_store_dwordx4 v[126:127], v[154:157], off offset:16
	global_load_dwordx4 v[180:183], v[244:245], off
	global_load_dwordx4 v[184:187], v[248:249], off
	s_nop 0
	s_nop 0
	s_nop 0
	v_exp_f32_e32 v162, v113
	v_exp_f32_e32 v163, v114
	v_exp_f32_e32 v164, v115
	v_or_b32_e32 v158, 16, v146
	v_ashrrev_i32_e32 v159, 31, v158
	v_lshlrev_b64 v[112:113], 11, v[158:159]
	v_lshl_add_u64 v[114:115], s[48:49], 0, v[112:113]
	v_lshl_add_u64 v[160:161], s[38:39], 0, v[112:113]
	v_add_f32_e32 v112, 1.0, v116
	v_add_f32_e32 v113, 1.0, v147
	v_add_f32_e32 v116, 1.0, v117
	v_add_f32_e32 v117, 1.0, v162
	v_add_f32_e32 v147, 1.0, v163
	v_add_f32_e32 v165, 1.0, v164
	v_lshl_add_u64 v[162:163], v[114:115], 0, v[144:145]
	v_rcp_f32_e32 v112, v112
	v_rcp_f32_e32 v114, v113
	v_rcp_f32_e32 v113, v116
	v_rcp_f32_e32 v115, v117
	v_rcp_f32_e32 v164, v147
	v_rcp_f32_e32 v165, v165
	v_add_f32_e32 v147, 1.0, v106
	v_mul_f32_e32 v103, 0xbfb8aa3b, v103
	v_mul_f32_e32 v98, 0xbfb8aa3b, v98
	v_mul_f32_e32 v99, 0xbfb8aa3b, v99
	v_exp_f32_e32 v100, v100
	v_exp_f32_e32 v101, v101
	v_exp_f32_e32 v102, v102
	v_exp_f32_e32 v103, v103
	v_mul_f32_e32 v92, 0xbfb8aa3b, v92
	v_mul_f32_e32 v88, 0xbfb8aa3b, v88
	v_add_f32_e32 v102, 1.0, v102
	v_add_f32_e32 v103, 1.0, v103
	v_rcp_f32_e32 v102, v102
	v_rcp_f32_e32 v103, v103
	v_mul_f32_e32 v93, 0xbfb8aa3b, v93
	v_mul_f32_e32 v89, 0xbfb8aa3b, v89
	v_mul_f32_e32 v94, 0xbfb8aa3b, v94
	v_mul_f32_e32 v95, 0xbfb8aa3b, v95
	v_mul_f32_e32 v90, 0xbfb8aa3b, v90
	v_mul_f32_e32 v91, 0xbfb8aa3b, v91
	v_exp_f32_e32 v92, v92
	v_exp_f32_e32 v93, v93
	v_exp_f32_e32 v94, v94
	v_exp_f32_e32 v95, v95
	v_exp_f32_e32 v90, v90
	v_exp_f32_e32 v91, v91
	v_add_f32_e32 v92, 1.0, v92
	v_add_f32_e32 v93, 1.0, v93
	v_add_f32_e32 v94, 1.0, v94
	v_add_f32_e32 v95, 1.0, v95
	v_rcp_f32_e32 v94, v94
	v_rcp_f32_e32 v95, v95
	v_mul_f32_e32 v84, 0xbfb8aa3b, v84
	v_mul_f32_e32 v80, 0xbfb8aa3b, v80
	v_mul_f32_e32 v85, 0xbfb8aa3b, v85
	v_mul_f32_e32 v81, 0xbfb8aa3b, v81
	v_mul_f32_e32 v86, 0xbfb8aa3b, v86
	v_mul_f32_e32 v87, 0xbfb8aa3b, v87
	v_mul_f32_e32 v82, 0xbfb8aa3b, v82
	v_mul_f32_e32 v83, 0xbfb8aa3b, v83
	v_exp_f32_e32 v84, v84
	v_exp_f32_e32 v85, v85
	v_exp_f32_e32 v86, v86
	v_exp_f32_e32 v87, v87
	v_mul_f32_e32 v76, 0xbfb8aa3b, v76
	v_mul_f32_e32 v72, 0xbfb8aa3b, v72
	v_add_f32_e32 v86, 1.0, v86
	v_add_f32_e32 v87, 1.0, v87
	v_rcp_f32_e32 v86, v86
	v_rcp_f32_e32 v87, v87
	v_mul_f32_e32 v77, 0xbfb8aa3b, v77
	v_mul_f32_e32 v73, 0xbfb8aa3b, v73
	v_mul_f32_e32 v78, 0xbfb8aa3b, v78
	v_mul_f32_e32 v79, 0xbfb8aa3b, v79
	v_mul_f32_e32 v74, 0xbfb8aa3b, v74
	v_mul_f32_e32 v75, 0xbfb8aa3b, v75
	v_exp_f32_e32 v76, v76
	s_waitcnt vmcnt(16)
	v_mov_b64_e32 v[122:123], v[188:189]
	v_mov_b64_e32 v[124:125], v[190:191]
	v_mov_b64_e32 v[154:155], v[192:193]
	v_mov_b64_e32 v[156:157], v[194:195]
	v_lshlrev_b32_e32 v116, 16, v122
	v_and_b32_e32 v117, 0xffff0000, v122
	s_nop 0
	v_lshlrev_b32_e32 v166, 16, v154
	v_and_b32_e32 v167, 0xffff0000, v154
	v_lshlrev_b32_e32 v168, 16, v124
	v_and_b32_e32 v169, 0xffff0000, v124
	v_lshlrev_b32_e32 v170, 16, v156
	v_and_b32_e32 v171, 0xffff0000, v156
	v_lshlrev_b32_e32 v122, 16, v123
	v_and_b32_e32 v123, 0xffff0000, v123
	v_lshlrev_b32_e32 v154, 16, v155
	v_and_b32_e32 v155, 0xffff0000, v155
	v_lshlrev_b32_e32 v124, 16, v125
	v_and_b32_e32 v125, 0xffff0000, v125
	v_lshlrev_b32_e32 v156, 16, v157
	v_and_b32_e32 v157, 0xffff0000, v157
	v_pk_fma_f32 v[112:113], v[112:113], v[166:167], v[116:117]
	v_pk_fma_f32 v[116:117], v[114:115], v[170:171], v[168:169]
	v_pk_fma_f32 v[114:115], v[118:119], v[154:155], v[122:123]
	v_pk_fma_f32 v[118:119], v[164:165], v[156:157], v[124:125]
	global_store_dwordx4 v[126:127], v[112:115], off offset:512
	global_store_dwordx4 v[126:127], v[116:119], off offset:528
	global_load_dwordx4 v[188:191], v[244:245], off offset:256
	global_load_dwordx4 v[192:195], v[248:249], off offset:256
	v_lshl_add_u64 v[244:245], v[244:245], 0, s[60:61]
	v_lshl_add_u64 v[248:249], v[248:249], 0, s[60:61]
	v_lshl_add_u64 v[122:123], v[160:161], 0, v[144:145]
	s_nop 0
	s_nop 0
	v_exp_f32_e32 v124, v104
	v_exp_f32_e32 v125, v105
	v_lshlrev_b64 v[104:105], 12, v[158:159]
	v_lshl_add_u64 v[104:105], s[84:85], 0, v[104:105]
	v_add_f32_e32 v126, 1.0, v124
	v_add_f32_e32 v127, 1.0, v125
	v_add_f32_e32 v154, 1.0, v107
	v_lshl_add_u64 v[124:125], v[104:105], 0, v[120:121]
	v_rcp_f32_e32 v104, v108
	v_rcp_f32_e32 v106, v126
	v_rcp_f32_e32 v105, v109
	v_rcp_f32_e32 v107, v127
	v_rcp_f32_e32 v126, v147
	v_rcp_f32_e32 v127, v154
	v_exp_f32_e32 v77, v77
	v_exp_f32_e32 v78, v78
	v_exp_f32_e32 v79, v79
	v_exp_f32_e32 v74, v74
	v_exp_f32_e32 v75, v75
; __device__ __forceinline__ float sigm(float x) { return __builtin_amdgcn_rcpf(1.f + __expf(-x)); }
;     __device__ __forceinline__ void operator()(const f32x4 (&acc)[2][2][4][2], const pg8::Unit& u, int wr, int wc, int fr, int fq) const {
;     ...
;                     } else if (MODE == 6) {
;                         float* op = outf + (size_t)r * DM + c0;
;                         const u32x4 xw = *(const u32x4*)(O + (size_t)r * DM + c0);
;                         float xf[8]; unpack8(xw, xf);
;                         const u32x4 pw = *(const u32x4*)(pe + (size_t)r * DM + c0);
;                         float pf[8]; unpack8(pw, pf);
;                         f32x4 o0, o1;
; #pragma unroll
;                         for (int j = 0; j < 4; ++j) { o0[j] = xf[j] + sigm(v[j]) * pf[j]; o1[j] = xf[4 + j] + sigm(v[4 + j]) * pf[4 + j]; }
;                         *(f32x4*)op = o0; *(f32x4*)(op + 4) = o1;
	v_add_f32_e32 v76, 1.0, v76
	v_add_f32_e32 v77, 1.0, v77
	v_add_f32_e32 v78, 1.0, v78
	v_add_f32_e32 v79, 1.0, v79
	v_rcp_f32_e32 v78, v78
	v_rcp_f32_e32 v79, v79
	v_mul_f32_e32 v68, 0xbfb8aa3b, v68
	v_mul_f32_e32 v64, 0xbfb8aa3b, v64
	v_mul_f32_e32 v69, 0xbfb8aa3b, v69
	v_mul_f32_e32 v65, 0xbfb8aa3b, v65
	v_mul_f32_e32 v70, 0xbfb8aa3b, v70
	v_mul_f32_e32 v71, 0xbfb8aa3b, v71
	v_mul_f32_e32 v66, 0xbfb8aa3b, v66
	v_mul_f32_e32 v67, 0xbfb8aa3b, v67
	v_exp_f32_e32 v68, v68
	v_exp_f32_e32 v69, v69
	v_exp_f32_e32 v70, v70
	v_exp_f32_e32 v71, v71
	v_mul_f32_e32 v60, 0xbfb8aa3b, v60
	v_mul_f32_e32 v56, 0xbfb8aa3b, v56
	v_add_f32_e32 v70, 1.0, v70
	v_add_f32_e32 v71, 1.0, v71
	v_rcp_f32_e32 v70, v70
	v_rcp_f32_e32 v71, v71
	v_mul_f32_e32 v61, 0xbfb8aa3b, v61
	v_mul_f32_e32 v57, 0xbfb8aa3b, v57
	v_mul_f32_e32 v62, 0xbfb8aa3b, v62
	v_mul_f32_e32 v63, 0xbfb8aa3b, v63
	v_mul_f32_e32 v58, 0xbfb8aa3b, v58
	v_mul_f32_e32 v59, 0xbfb8aa3b, v59
	v_exp_f32_e32 v60, v60
	v_exp_f32_e32 v61, v61
	v_exp_f32_e32 v62, v62
	v_exp_f32_e32 v63, v63
	v_exp_f32_e32 v58, v58
	v_exp_f32_e32 v59, v59
	v_add_f32_e32 v60, 1.0, v60
	v_add_f32_e32 v61, 1.0, v61
	v_add_f32_e32 v62, 1.0, v62
	v_add_f32_e32 v63, 1.0, v63
	v_rcp_f32_e32 v62, v62
	v_rcp_f32_e32 v63, v63
	v_mul_f32_e32 v52, 0xbfb8aa3b, v52
	v_mul_f32_e32 v48, 0xbfb8aa3b, v48
	v_mul_f32_e32 v53, 0xbfb8aa3b, v53
	v_mul_f32_e32 v49, 0xbfb8aa3b, v49
	v_mul_f32_e32 v54, 0xbfb8aa3b, v54
	v_mul_f32_e32 v55, 0xbfb8aa3b, v55
	v_mul_f32_e32 v50, 0xbfb8aa3b, v50
	v_mul_f32_e32 v51, 0xbfb8aa3b, v51
	v_exp_f32_e32 v52, v52
	v_exp_f32_e32 v53, v53
	v_exp_f32_e32 v54, v54
	v_exp_f32_e32 v55, v55
	v_mul_f32_e32 v44, 0xbfb8aa3b, v44
	v_mul_f32_e32 v40, 0xbfb8aa3b, v40
	v_add_f32_e32 v54, 1.0, v54
	v_add_f32_e32 v55, 1.0, v55
	v_rcp_f32_e32 v54, v54
	s_waitcnt vmcnt(18)
	v_mov_b64_e32 v[112:113], v[196:197]
	v_mov_b64_e32 v[114:115], v[198:199]
	v_mov_b64_e32 v[116:117], v[200:201]
	v_mov_b64_e32 v[118:119], v[202:203]
	v_lshlrev_b32_e32 v108, 16, v112
	v_and_b32_e32 v109, 0xffff0000, v112
	s_nop 0
	v_lshlrev_b32_e32 v154, 16, v116
	v_and_b32_e32 v155, 0xffff0000, v116
	v_lshlrev_b32_e32 v156, 16, v114
	v_and_b32_e32 v157, 0xffff0000, v114
	v_lshlrev_b32_e32 v158, 16, v118
	v_and_b32_e32 v159, 0xffff0000, v118
	v_lshlrev_b32_e32 v112, 16, v113
	v_and_b32_e32 v113, 0xffff0000, v113
	v_lshlrev_b32_e32 v116, 16, v117
	v_and_b32_e32 v117, 0xffff0000, v117
	v_lshlrev_b32_e32 v114, 16, v115
	v_and_b32_e32 v115, 0xffff0000, v115
	v_lshlrev_b32_e32 v118, 16, v119
	v_and_b32_e32 v119, 0xffff0000, v119
	v_pk_fma_f32 v[104:105], v[104:105], v[154:155], v[108:109]
	v_pk_fma_f32 v[108:109], v[106:107], v[158:159], v[156:157]
	v_pk_fma_f32 v[106:107], v[110:111], v[116:117], v[112:113]
	v_pk_fma_f32 v[110:111], v[126:127], v[118:119], v[114:115]
	global_store_dwordx4 v[124:125], v[104:107], off
	global_store_dwordx4 v[124:125], v[108:111], off offset:16
	global_load_dwordx4 v[196:199], v[244:245], off
	global_load_dwordx4 v[200:203], v[248:249], off
	s_nop 0
	s_nop 0
	s_nop 0
	v_exp_f32_e32 v116, v96
	v_exp_f32_e32 v117, v97
	v_exp_f32_e32 v118, v98
	v_exp_f32_e32 v119, v99
	v_or_b32_e32 v112, 32, v146
	v_ashrrev_i32_e32 v113, 31, v112
	v_lshlrev_b64 v[96:97], 11, v[112:113]
	v_lshl_add_u64 v[98:99], s[48:49], 0, v[96:97]
	v_lshl_add_u64 v[114:115], s[38:39], 0, v[96:97]
	v_add_f32_e32 v96, 1.0, v100
	v_add_f32_e32 v97, 1.0, v116
	v_add_f32_e32 v100, 1.0, v101
	v_add_f32_e32 v101, 1.0, v117
	v_add_f32_e32 v118, 1.0, v118
	v_add_f32_e32 v119, 1.0, v119
	v_lshl_add_u64 v[116:117], v[98:99], 0, v[144:145]
	v_rcp_f32_e32 v96, v96
	v_rcp_f32_e32 v98, v97
	v_rcp_f32_e32 v97, v100
	v_rcp_f32_e32 v99, v101
	v_rcp_f32_e32 v118, v118
	v_rcp_f32_e32 v119, v119
	v_rcp_f32_e32 v55, v55
	v_mul_f32_e32 v45, 0xbfb8aa3b, v45
	v_mul_f32_e32 v41, 0xbfb8aa3b, v41
	v_mul_f32_e32 v46, 0xbfb8aa3b, v46
	v_mul_f32_e32 v47, 0xbfb8aa3b, v47
	v_mul_f32_e32 v42, 0xbfb8aa3b, v42
	v_mul_f32_e32 v43, 0xbfb8aa3b, v43
	v_exp_f32_e32 v44, v44
	v_exp_f32_e32 v45, v45
	v_exp_f32_e32 v46, v46
	v_exp_f32_e32 v47, v47
	v_exp_f32_e32 v42, v42
	v_exp_f32_e32 v43, v43
	v_add_f32_e32 v44, 1.0, v44
	v_add_f32_e32 v45, 1.0, v45
	v_add_f32_e32 v46, 1.0, v46
	v_add_f32_e32 v47, 1.0, v47
	v_rcp_f32_e32 v46, v46
	v_rcp_f32_e32 v47, v47
	v_mul_f32_e32 v36, 0xbfb8aa3b, v36
	v_mul_f32_e32 v32, 0xbfb8aa3b, v32
	v_mul_f32_e32 v37, 0xbfb8aa3b, v37
	v_mul_f32_e32 v33, 0xbfb8aa3b, v33
	v_mul_f32_e32 v38, 0xbfb8aa3b, v38
	v_mul_f32_e32 v39, 0xbfb8aa3b, v39
	v_mul_f32_e32 v34, 0xbfb8aa3b, v34
	v_mul_f32_e32 v35, 0xbfb8aa3b, v35
	v_exp_f32_e32 v36, v36
	v_exp_f32_e32 v37, v37
	v_exp_f32_e32 v38, v38
	v_exp_f32_e32 v39, v39
	v_mul_f32_e32 v28, 0xbfb8aa3b, v28
	v_mul_f32_e32 v24, 0xbfb8aa3b, v24
	v_add_f32_e32 v38, 1.0, v38
	v_add_f32_e32 v39, 1.0, v39
	v_rcp_f32_e32 v38, v38
	v_rcp_f32_e32 v39, v39
	v_mul_f32_e32 v29, 0xbfb8aa3b, v29
	v_mul_f32_e32 v25, 0xbfb8aa3b, v25
	v_mul_f32_e32 v30, 0xbfb8aa3b, v30
	v_mul_f32_e32 v31, 0xbfb8aa3b, v31
	v_mul_f32_e32 v26, 0xbfb8aa3b, v26
	v_mul_f32_e32 v27, 0xbfb8aa3b, v27
	v_exp_f32_e32 v28, v28
	v_exp_f32_e32 v29, v29
	v_exp_f32_e32 v30, v30
	v_exp_f32_e32 v31, v31
	v_exp_f32_e32 v26, v26
	v_exp_f32_e32 v27, v27
	v_add_f32_e32 v28, 1.0, v28
	v_add_f32_e32 v29, 1.0, v29
	v_add_f32_e32 v30, 1.0, v30
	v_add_f32_e32 v31, 1.0, v31
	v_rcp_f32_e32 v30, v30
	v_rcp_f32_e32 v31, v31
	v_mul_f32_e32 v20, 0xbfb8aa3b, v20
	s_waitcnt vmcnt(20)
; __device__ __forceinline__ float sigm(float x) { return __builtin_amdgcn_rcpf(1.f + __expf(-x)); }
;     __device__ __forceinline__ void operator()(const f32x4 (&acc)[2][2][4][2], const pg8::Unit& u, int wr, int wc, int fr, int fq) const {
;     ...
;                     } else if (MODE == 6) {
;                         float* op = outf + (size_t)r * DM + c0;
;                         const u32x4 xw = *(const u32x4*)(O + (size_t)r * DM + c0);
;                         float xf[8]; unpack8(xw, xf);
;                         const u32x4 pw = *(const u32x4*)(pe + (size_t)r * DM + c0);
;                         float pf[8]; unpack8(pw, pf);
;                         f32x4 o0, o1;
; #pragma unroll
;                         for (int j = 0; j < 4; ++j) { o0[j] = xf[j] + sigm(v[j]) * pf[j]; o1[j] = xf[4 + j] + sigm(v[4 + j]) * pf[4 + j]; }
;                         *(f32x4*)op = o0; *(f32x4*)(op + 4) = o1;
	v_mov_b64_e32 v[104:105], v[204:205]
	v_mov_b64_e32 v[106:107], v[206:207]
	v_mov_b64_e32 v[108:109], v[208:209]
	v_mov_b64_e32 v[110:111], v[210:211]
	v_lshlrev_b32_e32 v100, 16, v104
	v_and_b32_e32 v101, 0xffff0000, v104
	s_nop 0
	v_lshlrev_b32_e32 v122, 16, v108
	v_and_b32_e32 v123, 0xffff0000, v108
	v_lshlrev_b32_e32 v126, 16, v106
	v_and_b32_e32 v127, 0xffff0000, v106
	v_lshlrev_b32_e32 v154, 16, v110
	v_and_b32_e32 v155, 0xffff0000, v110
	v_lshlrev_b32_e32 v104, 16, v105
	v_and_b32_e32 v105, 0xffff0000, v105
	v_lshlrev_b32_e32 v108, 16, v109
	v_and_b32_e32 v109, 0xffff0000, v109
	v_lshlrev_b32_e32 v106, 16, v107
	v_and_b32_e32 v107, 0xffff0000, v107
	v_lshlrev_b32_e32 v110, 16, v111
	v_and_b32_e32 v111, 0xffff0000, v111
	v_pk_fma_f32 v[96:97], v[96:97], v[122:123], v[100:101]
	v_pk_fma_f32 v[100:101], v[98:99], v[154:155], v[126:127]
	v_pk_fma_f32 v[98:99], v[102:103], v[108:109], v[104:105]
	v_pk_fma_f32 v[102:103], v[118:119], v[110:111], v[106:107]
	global_store_dwordx4 v[124:125], v[96:99], off offset:512
	global_store_dwordx4 v[124:125], v[100:103], off offset:528
	global_load_dwordx4 v[204:207], v[244:245], off offset:256
	global_load_dwordx4 v[208:211], v[248:249], off offset:256
	v_lshl_add_u64 v[244:245], v[244:245], 0, s[60:61]
	v_lshl_add_u64 v[248:249], v[248:249], 0, s[60:61]
	v_lshl_add_u64 v[104:105], v[114:115], 0, v[144:145]
	s_nop 0
	s_nop 0
	v_exp_f32_e32 v106, v88
	v_exp_f32_e32 v107, v89
	v_lshlrev_b64 v[88:89], 12, v[112:113]
	v_lshl_add_u64 v[88:89], s[84:85], 0, v[88:89]
	v_add_f32_e32 v108, 1.0, v106
	v_add_f32_e32 v109, 1.0, v107
	v_add_f32_e32 v110, 1.0, v90
	v_add_f32_e32 v111, 1.0, v91
	v_lshl_add_u64 v[106:107], v[88:89], 0, v[120:121]
	v_rcp_f32_e32 v88, v92
	v_rcp_f32_e32 v90, v108
	v_rcp_f32_e32 v89, v93
	v_rcp_f32_e32 v91, v109
	v_rcp_f32_e32 v108, v110
	v_rcp_f32_e32 v109, v111
	v_mul_f32_e32 v16, 0xbfb8aa3b, v16
	v_mul_f32_e32 v21, 0xbfb8aa3b, v21
	v_mul_f32_e32 v17, 0xbfb8aa3b, v17
	v_mul_f32_e32 v22, 0xbfb8aa3b, v22
	v_mul_f32_e32 v23, 0xbfb8aa3b, v23
	v_mul_f32_e32 v18, 0xbfb8aa3b, v18
	v_mul_f32_e32 v19, 0xbfb8aa3b, v19
	v_exp_f32_e32 v20, v20
	v_exp_f32_e32 v21, v21
	v_exp_f32_e32 v22, v22
	v_exp_f32_e32 v23, v23
	v_mul_f32_e32 v12, 0xbfb8aa3b, v12
	v_mul_f32_e32 v8, 0xbfb8aa3b, v8
	v_add_f32_e32 v22, 1.0, v22
	v_add_f32_e32 v23, 1.0, v23
	v_rcp_f32_e32 v22, v22
	v_rcp_f32_e32 v23, v23
	v_mul_f32_e32 v13, 0xbfb8aa3b, v13
	v_mul_f32_e32 v9, 0xbfb8aa3b, v9
	v_mul_f32_e32 v14, 0xbfb8aa3b, v14
	v_mul_f32_e32 v15, 0xbfb8aa3b, v15
	v_mul_f32_e32 v10, 0xbfb8aa3b, v10
	v_mul_f32_e32 v11, 0xbfb8aa3b, v11
	v_exp_f32_e32 v12, v12
	v_exp_f32_e32 v13, v13
	v_exp_f32_e32 v14, v14
	v_exp_f32_e32 v15, v15
	v_exp_f32_e32 v10, v10
	v_exp_f32_e32 v11, v11
	v_add_f32_e32 v12, 1.0, v12
	v_add_f32_e32 v13, 1.0, v13
	v_add_f32_e32 v14, 1.0, v14
	v_add_f32_e32 v15, 1.0, v15
	v_rcp_f32_e32 v14, v14
	v_rcp_f32_e32 v15, v15
	v_mul_f32_e32 v4, 0xbfb8aa3b, v4
	v_mul_f32_e32 v0, 0xbfb8aa3b, v0
	v_mul_f32_e32 v5, 0xbfb8aa3b, v5
	v_mul_f32_e32 v1, 0xbfb8aa3b, v1
	v_mul_f32_e32 v6, 0xbfb8aa3b, v6
	v_mul_f32_e32 v7, 0xbfb8aa3b, v7
	v_mul_f32_e32 v2, 0xbfb8aa3b, v2
	v_mul_f32_e32 v3, 0xbfb8aa3b, v3
	v_exp_f32_e32 v4, v4
	v_exp_f32_e32 v0, v0
	v_exp_f32_e32 v5, v5
	v_exp_f32_e32 v1, v1
	v_exp_f32_e32 v6, v6
	v_exp_f32_e32 v7, v7
	v_exp_f32_e32 v2, v2
	v_exp_f32_e32 v3, v3
	v_add_f32_e32 v4, 1.0, v4
	v_add_f32_e32 v5, 1.0, v5
	v_add_f32_e32 v6, 1.0, v6
	v_add_f32_e32 v7, 1.0, v7
	v_rcp_f32_e32 v6, v6
	v_rcp_f32_e32 v7, v7
	s_andn2_b64 vcc, exec, s[0:1]
	s_mov_b64 s[0:1], -1
	s_waitcnt vmcnt(22)
	v_mov_b64_e32 v[96:97], v[212:213]
	v_mov_b64_e32 v[98:99], v[214:215]
	v_mov_b64_e32 v[100:101], v[216:217]
	v_mov_b64_e32 v[102:103], v[218:219]
	v_lshlrev_b32_e32 v92, 16, v96
	v_and_b32_e32 v93, 0xffff0000, v96
	s_nop 0
	v_lshlrev_b32_e32 v110, 16, v100
	v_and_b32_e32 v111, 0xffff0000, v100
	v_lshlrev_b32_e32 v112, 16, v98
	v_and_b32_e32 v113, 0xffff0000, v98
	v_lshlrev_b32_e32 v114, 16, v102
	v_and_b32_e32 v115, 0xffff0000, v102
	v_lshlrev_b32_e32 v96, 16, v97
	v_and_b32_e32 v97, 0xffff0000, v97
	v_lshlrev_b32_e32 v100, 16, v101
	v_and_b32_e32 v101, 0xffff0000, v101
	v_lshlrev_b32_e32 v98, 16, v99
	v_and_b32_e32 v99, 0xffff0000, v99
	v_lshlrev_b32_e32 v102, 16, v103
	v_and_b32_e32 v103, 0xffff0000, v103
	v_pk_fma_f32 v[88:89], v[88:89], v[110:111], v[92:93]
	v_pk_fma_f32 v[92:93], v[90:91], v[114:115], v[112:113]
	v_pk_fma_f32 v[90:91], v[94:95], v[100:101], v[96:97]
	v_pk_fma_f32 v[94:95], v[108:109], v[102:103], v[98:99]
	global_store_dwordx4 v[106:107], v[88:91], off
	global_store_dwordx4 v[106:107], v[92:95], off offset:16
	global_load_dwordx4 v[212:215], v[244:245], off
	global_load_dwordx4 v[216:219], v[248:249], off
	s_nop 0
	s_nop 0
	s_nop 0
	v_exp_f32_e32 v100, v80
	v_exp_f32_e32 v101, v81
	v_exp_f32_e32 v102, v82
	v_exp_f32_e32 v103, v83
	v_or_b32_e32 v96, 48, v146
	v_ashrrev_i32_e32 v97, 31, v96
	v_lshlrev_b64 v[80:81], 11, v[96:97]
	v_lshl_add_u64 v[82:83], s[48:49], 0, v[80:81]
	v_lshl_add_u64 v[98:99], s[38:39], 0, v[80:81]
	v_add_f32_e32 v80, 1.0, v84
	v_add_f32_e32 v81, 1.0, v100
	v_add_f32_e32 v84, 1.0, v85
	v_add_f32_e32 v85, 1.0, v101
	v_add_f32_e32 v102, 1.0, v102
	v_add_f32_e32 v103, 1.0, v103
	v_lshl_add_u64 v[100:101], v[82:83], 0, v[144:145]
	v_rcp_f32_e32 v80, v80
	v_rcp_f32_e32 v82, v81
	v_rcp_f32_e32 v81, v84
	v_rcp_f32_e32 v83, v85
	v_rcp_f32_e32 v102, v102
	v_rcp_f32_e32 v103, v103
	s_waitcnt vmcnt(24)
; __device__ __forceinline__ float sigm(float x) { return __builtin_amdgcn_rcpf(1.f + __expf(-x)); }
;     __device__ __forceinline__ void operator()(const f32x4 (&acc)[2][2][4][2], const pg8::Unit& u, int wr, int wc, int fr, int fq) const {
;     ...
;                     } else if (MODE == 6) {
;                         float* op = outf + (size_t)r * DM + c0;
;                         const u32x4 xw = *(const u32x4*)(O + (size_t)r * DM + c0);
;                         float xf[8]; unpack8(xw, xf);
;                         const u32x4 pw = *(const u32x4*)(pe + (size_t)r * DM + c0);
;                         float pf[8]; unpack8(pw, pf);
;                         f32x4 o0, o1;
; #pragma unroll
;                         for (int j = 0; j < 4; ++j) { o0[j] = xf[j] + sigm(v[j]) * pf[j]; o1[j] = xf[4 + j] + sigm(v[4 + j]) * pf[4 + j]; }
;                         *(f32x4*)op = o0; *(f32x4*)(op + 4) = o1;
	v_mov_b64_e32 v[88:89], v[220:221]
	v_mov_b64_e32 v[90:91], v[222:223]
	v_mov_b64_e32 v[92:93], v[224:225]
	v_mov_b64_e32 v[94:95], v[226:227]
	v_lshlrev_b32_e32 v84, 16, v88
	v_and_b32_e32 v85, 0xffff0000, v88
	s_nop 0
	v_lshlrev_b32_e32 v104, 16, v92
	v_and_b32_e32 v105, 0xffff0000, v92
	v_lshlrev_b32_e32 v108, 16, v90
	v_and_b32_e32 v109, 0xffff0000, v90
	v_lshlrev_b32_e32 v110, 16, v94
	v_and_b32_e32 v111, 0xffff0000, v94
	v_lshlrev_b32_e32 v88, 16, v89
	v_and_b32_e32 v89, 0xffff0000, v89
	v_lshlrev_b32_e32 v92, 16, v93
	v_and_b32_e32 v93, 0xffff0000, v93
	v_lshlrev_b32_e32 v90, 16, v91
	v_and_b32_e32 v91, 0xffff0000, v91
	v_lshlrev_b32_e32 v94, 16, v95
	v_and_b32_e32 v95, 0xffff0000, v95
	v_pk_fma_f32 v[80:81], v[80:81], v[104:105], v[84:85]
	v_pk_fma_f32 v[84:85], v[82:83], v[110:111], v[108:109]
	v_pk_fma_f32 v[82:83], v[86:87], v[92:93], v[88:89]
	v_pk_fma_f32 v[86:87], v[102:103], v[94:95], v[90:91]
	global_store_dwordx4 v[106:107], v[80:83], off offset:512
	global_store_dwordx4 v[106:107], v[84:87], off offset:528
	global_load_dwordx4 v[220:223], v[244:245], off offset:256
	global_load_dwordx4 v[224:227], v[248:249], off offset:256
	v_lshl_add_u64 v[244:245], v[244:245], 0, s[60:61]
	v_lshl_add_u64 v[248:249], v[248:249], 0, s[60:61]
	v_lshl_add_u64 v[88:89], v[98:99], 0, v[144:145]
	s_nop 0
	s_nop 0
	v_exp_f32_e32 v90, v72
	v_exp_f32_e32 v91, v73
	v_lshlrev_b64 v[72:73], 12, v[96:97]
	v_lshl_add_u64 v[72:73], s[84:85], 0, v[72:73]
	v_add_f32_e32 v92, 1.0, v90
	v_add_f32_e32 v93, 1.0, v91
	v_add_f32_e32 v94, 1.0, v74
	v_add_f32_e32 v95, 1.0, v75
	v_lshl_add_u64 v[90:91], v[72:73], 0, v[120:121]
	v_rcp_f32_e32 v72, v76
	v_rcp_f32_e32 v74, v92
	v_rcp_f32_e32 v73, v77
	v_rcp_f32_e32 v75, v93
	v_rcp_f32_e32 v92, v94
	v_rcp_f32_e32 v93, v95
	s_waitcnt vmcnt(26)
	v_mov_b64_e32 v[80:81], v[228:229]
	v_mov_b64_e32 v[82:83], v[230:231]
	v_mov_b64_e32 v[84:85], v[232:233]
	v_mov_b64_e32 v[86:87], v[234:235]
	v_lshlrev_b32_e32 v76, 16, v80
	v_and_b32_e32 v77, 0xffff0000, v80
	s_nop 0
	v_lshlrev_b32_e32 v94, 16, v84
	v_and_b32_e32 v95, 0xffff0000, v84
	v_lshlrev_b32_e32 v96, 16, v82
	v_and_b32_e32 v97, 0xffff0000, v82
	v_lshlrev_b32_e32 v98, 16, v86
	v_and_b32_e32 v99, 0xffff0000, v86
	v_lshlrev_b32_e32 v80, 16, v81
	v_and_b32_e32 v81, 0xffff0000, v81
	v_lshlrev_b32_e32 v84, 16, v85
	v_and_b32_e32 v85, 0xffff0000, v85
	v_lshlrev_b32_e32 v82, 16, v83
	v_and_b32_e32 v83, 0xffff0000, v83
	v_lshlrev_b32_e32 v86, 16, v87
	v_and_b32_e32 v87, 0xffff0000, v87
	v_pk_fma_f32 v[72:73], v[72:73], v[94:95], v[76:77]
	v_pk_fma_f32 v[76:77], v[74:75], v[98:99], v[96:97]
	v_pk_fma_f32 v[74:75], v[78:79], v[84:85], v[80:81]
	v_pk_fma_f32 v[78:79], v[92:93], v[86:87], v[82:83]
	global_store_dwordx4 v[90:91], v[72:75], off
	global_store_dwordx4 v[90:91], v[76:79], off offset:16
	global_load_dwordx4 v[228:231], v[244:245], off
	global_load_dwordx4 v[232:235], v[248:249], off
	s_nop 0
	s_nop 0
	s_nop 0
	v_exp_f32_e32 v84, v64
	v_exp_f32_e32 v85, v65
	v_exp_f32_e32 v86, v66
	v_exp_f32_e32 v87, v67
	v_add_u32_e32 v80, 0x80, v146
	v_ashrrev_i32_e32 v81, 31, v80
	v_lshlrev_b64 v[64:65], 11, v[80:81]
	v_lshl_add_u64 v[66:67], s[48:49], 0, v[64:65]
	v_lshl_add_u64 v[82:83], s[38:39], 0, v[64:65]
	v_add_f32_e32 v64, 1.0, v68
	v_add_f32_e32 v65, 1.0, v84
	v_add_f32_e32 v68, 1.0, v69
	v_add_f32_e32 v69, 1.0, v85
	v_add_f32_e32 v86, 1.0, v86
	v_add_f32_e32 v87, 1.0, v87
	v_lshl_add_u64 v[84:85], v[66:67], 0, v[144:145]
	v_rcp_f32_e32 v64, v64
	v_rcp_f32_e32 v66, v65
	v_rcp_f32_e32 v65, v68
	v_rcp_f32_e32 v67, v69
	v_rcp_f32_e32 v86, v86
	v_rcp_f32_e32 v87, v87
	s_waitcnt vmcnt(28)
	v_mov_b64_e32 v[72:73], v[236:237]
	v_mov_b64_e32 v[74:75], v[238:239]
	v_mov_b64_e32 v[76:77], v[240:241]
	v_mov_b64_e32 v[78:79], v[242:243]
	v_lshlrev_b32_e32 v68, 16, v72
	v_and_b32_e32 v69, 0xffff0000, v72
	s_nop 0
	v_lshlrev_b32_e32 v88, 16, v76
	v_and_b32_e32 v89, 0xffff0000, v76
	v_lshlrev_b32_e32 v92, 16, v74
	v_and_b32_e32 v93, 0xffff0000, v74
	v_lshlrev_b32_e32 v94, 16, v78
	v_and_b32_e32 v95, 0xffff0000, v78
	v_lshlrev_b32_e32 v72, 16, v73
	v_and_b32_e32 v73, 0xffff0000, v73
	v_lshlrev_b32_e32 v76, 16, v77
	v_and_b32_e32 v77, 0xffff0000, v77
	v_lshlrev_b32_e32 v74, 16, v75
	v_and_b32_e32 v75, 0xffff0000, v75
	v_lshlrev_b32_e32 v78, 16, v79
	v_and_b32_e32 v79, 0xffff0000, v79
	v_pk_fma_f32 v[64:65], v[64:65], v[88:89], v[68:69]
	v_pk_fma_f32 v[68:69], v[66:67], v[94:95], v[92:93]
	v_pk_fma_f32 v[66:67], v[70:71], v[76:77], v[72:73]
	v_pk_fma_f32 v[70:71], v[86:87], v[78:79], v[74:75]
	global_store_dwordx4 v[90:91], v[64:67], off offset:512
	global_store_dwordx4 v[90:91], v[68:71], off offset:528
	global_load_dwordx4 v[236:239], v[244:245], off offset:256
	global_load_dwordx4 v[240:243], v[248:249], off offset:256
	v_lshl_add_u64 v[72:73], v[82:83], 0, v[144:145]
	s_nop 0
	s_nop 0
	v_exp_f32_e32 v74, v56
	v_exp_f32_e32 v75, v57
	v_lshlrev_b64 v[56:57], 12, v[80:81]
	v_lshl_add_u64 v[56:57], s[84:85], 0, v[56:57]
	v_add_f32_e32 v76, 1.0, v74
	v_add_f32_e32 v77, 1.0, v75
	v_add_f32_e32 v78, 1.0, v58
	v_add_f32_e32 v79, 1.0, v59
	v_lshl_add_u64 v[74:75], v[56:57], 0, v[120:121]
	v_rcp_f32_e32 v56, v60
	v_rcp_f32_e32 v58, v76
	v_rcp_f32_e32 v57, v61
	v_rcp_f32_e32 v59, v77
	v_rcp_f32_e32 v76, v78
	v_rcp_f32_e32 v77, v79
	s_waitcnt vmcnt(28)
; __device__ __forceinline__ float sigm(float x) { return __builtin_amdgcn_rcpf(1.f + __expf(-x)); }
;     __device__ __forceinline__ void operator()(const f32x4 (&acc)[2][2][4][2], const pg8::Unit& u, int wr, int wc, int fr, int fq) const {
;     ...
;                     } else if (MODE == 6) {
;                         float* op = outf + (size_t)r * DM + c0;
;                         const u32x4 xw = *(const u32x4*)(O + (size_t)r * DM + c0);
;                         float xf[8]; unpack8(xw, xf);
;                         const u32x4 pw = *(const u32x4*)(pe + (size_t)r * DM + c0);
;                         float pf[8]; unpack8(pw, pf);
;                         f32x4 o0, o1;
; #pragma unroll
;                         for (int j = 0; j < 4; ++j) { o0[j] = xf[j] + sigm(v[j]) * pf[j]; o1[j] = xf[4 + j] + sigm(v[4 + j]) * pf[4 + j]; }
;                         *(f32x4*)op = o0; *(f32x4*)(op + 4) = o1;
	v_mov_b64_e32 v[64:65], v[180:181]
	v_mov_b64_e32 v[66:67], v[182:183]
	v_mov_b64_e32 v[68:69], v[184:185]
	v_mov_b64_e32 v[70:71], v[186:187]
	v_lshlrev_b32_e32 v60, 16, v64
	v_and_b32_e32 v61, 0xffff0000, v64
	s_nop 0
	v_lshlrev_b32_e32 v78, 16, v68
	v_and_b32_e32 v79, 0xffff0000, v68
	v_lshlrev_b32_e32 v80, 16, v66
	v_and_b32_e32 v81, 0xffff0000, v66
	v_lshlrev_b32_e32 v82, 16, v70
	v_and_b32_e32 v83, 0xffff0000, v70
	v_lshlrev_b32_e32 v64, 16, v65
	v_and_b32_e32 v65, 0xffff0000, v65
	v_lshlrev_b32_e32 v68, 16, v69
	v_and_b32_e32 v69, 0xffff0000, v69
	v_lshlrev_b32_e32 v66, 16, v67
	v_and_b32_e32 v67, 0xffff0000, v67
	v_lshlrev_b32_e32 v70, 16, v71
	v_and_b32_e32 v71, 0xffff0000, v71
	v_pk_fma_f32 v[56:57], v[56:57], v[78:79], v[60:61]
	v_pk_fma_f32 v[60:61], v[58:59], v[82:83], v[80:81]
	v_pk_fma_f32 v[58:59], v[62:63], v[68:69], v[64:65]
	v_pk_fma_f32 v[62:63], v[76:77], v[70:71], v[66:67]
	global_store_dwordx4 v[74:75], v[56:59], off
	global_store_dwordx4 v[74:75], v[60:63], off offset:16
	s_nop 0
	s_nop 0
	s_nop 0
	v_exp_f32_e32 v68, v48
	v_exp_f32_e32 v69, v49
	v_exp_f32_e32 v70, v50
	v_exp_f32_e32 v71, v51
	v_add_u32_e32 v64, 0x90, v146
	v_ashrrev_i32_e32 v65, 31, v64
	v_lshlrev_b64 v[48:49], 11, v[64:65]
	v_lshl_add_u64 v[50:51], s[48:49], 0, v[48:49]
	v_lshl_add_u64 v[66:67], s[38:39], 0, v[48:49]
	v_add_f32_e32 v48, 1.0, v52
	v_add_f32_e32 v49, 1.0, v68
	v_add_f32_e32 v52, 1.0, v53
	v_add_f32_e32 v53, 1.0, v69
	v_add_f32_e32 v70, 1.0, v70
	v_add_f32_e32 v71, 1.0, v71
	v_lshl_add_u64 v[68:69], v[50:51], 0, v[144:145]
	v_rcp_f32_e32 v48, v48
	v_rcp_f32_e32 v50, v49
	v_rcp_f32_e32 v49, v52
	v_rcp_f32_e32 v51, v53
	v_rcp_f32_e32 v70, v70
	v_rcp_f32_e32 v71, v71
	s_waitcnt vmcnt(26)
	v_mov_b64_e32 v[56:57], v[188:189]
	v_mov_b64_e32 v[58:59], v[190:191]
	v_mov_b64_e32 v[60:61], v[192:193]
	v_mov_b64_e32 v[62:63], v[194:195]
	v_lshlrev_b32_e32 v52, 16, v56
	v_and_b32_e32 v53, 0xffff0000, v56
	s_nop 0
	v_lshlrev_b32_e32 v72, 16, v60
	v_and_b32_e32 v73, 0xffff0000, v60
	v_lshlrev_b32_e32 v76, 16, v58
	v_and_b32_e32 v77, 0xffff0000, v58
	v_lshlrev_b32_e32 v78, 16, v62
	v_and_b32_e32 v79, 0xffff0000, v62
	v_lshlrev_b32_e32 v56, 16, v57
	v_and_b32_e32 v57, 0xffff0000, v57
	v_lshlrev_b32_e32 v60, 16, v61
	v_and_b32_e32 v61, 0xffff0000, v61
	v_lshlrev_b32_e32 v58, 16, v59
	v_and_b32_e32 v59, 0xffff0000, v59
	v_lshlrev_b32_e32 v62, 16, v63
	v_and_b32_e32 v63, 0xffff0000, v63
	v_pk_fma_f32 v[48:49], v[48:49], v[72:73], v[52:53]
	v_pk_fma_f32 v[52:53], v[50:51], v[78:79], v[76:77]
	v_pk_fma_f32 v[50:51], v[54:55], v[60:61], v[56:57]
	v_pk_fma_f32 v[54:55], v[70:71], v[62:63], v[58:59]
	global_store_dwordx4 v[74:75], v[48:51], off offset:512
	global_store_dwordx4 v[74:75], v[52:55], off offset:528
	v_lshl_add_u64 v[56:57], v[66:67], 0, v[144:145]
	s_nop 0
	s_nop 0
	v_exp_f32_e32 v58, v40
	v_exp_f32_e32 v59, v41
	v_lshlrev_b64 v[40:41], 12, v[64:65]
	v_lshl_add_u64 v[40:41], s[84:85], 0, v[40:41]
	v_add_f32_e32 v60, 1.0, v58
	v_add_f32_e32 v61, 1.0, v59
	v_add_f32_e32 v62, 1.0, v42
	v_add_f32_e32 v63, 1.0, v43
	v_lshl_add_u64 v[58:59], v[40:41], 0, v[120:121]
	v_rcp_f32_e32 v40, v44
	v_rcp_f32_e32 v42, v60
	v_rcp_f32_e32 v41, v45
	v_rcp_f32_e32 v43, v61
	v_rcp_f32_e32 v60, v62
	v_rcp_f32_e32 v61, v63
	s_waitcnt vmcnt(24)
	v_mov_b64_e32 v[48:49], v[196:197]
	v_mov_b64_e32 v[50:51], v[198:199]
	v_mov_b64_e32 v[52:53], v[200:201]
	v_mov_b64_e32 v[54:55], v[202:203]
	v_lshlrev_b32_e32 v44, 16, v48
	v_and_b32_e32 v45, 0xffff0000, v48
	s_nop 0
	v_lshlrev_b32_e32 v62, 16, v52
	v_and_b32_e32 v63, 0xffff0000, v52
	v_lshlrev_b32_e32 v64, 16, v50
	v_and_b32_e32 v65, 0xffff0000, v50
	v_lshlrev_b32_e32 v66, 16, v54
	v_and_b32_e32 v67, 0xffff0000, v54
	v_lshlrev_b32_e32 v48, 16, v49
	v_and_b32_e32 v49, 0xffff0000, v49
	v_lshlrev_b32_e32 v52, 16, v53
	v_and_b32_e32 v53, 0xffff0000, v53
	v_lshlrev_b32_e32 v50, 16, v51
	v_and_b32_e32 v51, 0xffff0000, v51
	v_lshlrev_b32_e32 v54, 16, v55
	v_and_b32_e32 v55, 0xffff0000, v55
	v_pk_fma_f32 v[40:41], v[40:41], v[62:63], v[44:45]
	v_pk_fma_f32 v[44:45], v[42:43], v[66:67], v[64:65]
	v_pk_fma_f32 v[42:43], v[46:47], v[52:53], v[48:49]
	v_pk_fma_f32 v[46:47], v[60:61], v[54:55], v[50:51]
	global_store_dwordx4 v[58:59], v[40:43], off
	global_store_dwordx4 v[58:59], v[44:47], off offset:16
	s_nop 0
	s_nop 0
	s_nop 0
	v_exp_f32_e32 v52, v32
	v_exp_f32_e32 v53, v33
	v_exp_f32_e32 v54, v34
	v_exp_f32_e32 v55, v35
	v_add_u32_e32 v48, 0xa0, v146
	v_ashrrev_i32_e32 v49, 31, v48
	v_lshlrev_b64 v[32:33], 11, v[48:49]
	v_lshl_add_u64 v[34:35], s[48:49], 0, v[32:33]
	v_lshl_add_u64 v[50:51], s[38:39], 0, v[32:33]
	v_add_f32_e32 v32, 1.0, v36
	v_add_f32_e32 v33, 1.0, v52
	v_add_f32_e32 v36, 1.0, v37
	v_add_f32_e32 v37, 1.0, v53
	v_add_f32_e32 v54, 1.0, v54
	v_add_f32_e32 v55, 1.0, v55
	v_lshl_add_u64 v[52:53], v[34:35], 0, v[144:145]
	v_rcp_f32_e32 v32, v32
	v_rcp_f32_e32 v34, v33
	v_rcp_f32_e32 v33, v36
	v_rcp_f32_e32 v35, v37
	v_rcp_f32_e32 v54, v54
	v_rcp_f32_e32 v55, v55
	s_waitcnt vmcnt(22)
; __device__ __forceinline__ float sigm(float x) { return __builtin_amdgcn_rcpf(1.f + __expf(-x)); }
;     __device__ __forceinline__ void operator()(const f32x4 (&acc)[2][2][4][2], const pg8::Unit& u, int wr, int wc, int fr, int fq) const {
;     ...
;                     } else if (MODE == 6) {
;                         float* op = outf + (size_t)r * DM + c0;
;                         const u32x4 xw = *(const u32x4*)(O + (size_t)r * DM + c0);
;                         float xf[8]; unpack8(xw, xf);
;                         const u32x4 pw = *(const u32x4*)(pe + (size_t)r * DM + c0);
;                         float pf[8]; unpack8(pw, pf);
;                         f32x4 o0, o1;
; #pragma unroll
;                         for (int j = 0; j < 4; ++j) { o0[j] = xf[j] + sigm(v[j]) * pf[j]; o1[j] = xf[4 + j] + sigm(v[4 + j]) * pf[4 + j]; }
;                         *(f32x4*)op = o0; *(f32x4*)(op + 4) = o1;
	v_mov_b64_e32 v[40:41], v[204:205]
	v_mov_b64_e32 v[42:43], v[206:207]
	v_mov_b64_e32 v[44:45], v[208:209]
	v_mov_b64_e32 v[46:47], v[210:211]
	v_lshlrev_b32_e32 v36, 16, v40
	v_and_b32_e32 v37, 0xffff0000, v40
	s_nop 0
	v_lshlrev_b32_e32 v56, 16, v44
	v_and_b32_e32 v57, 0xffff0000, v44
	v_lshlrev_b32_e32 v60, 16, v42
	v_and_b32_e32 v61, 0xffff0000, v42
	v_lshlrev_b32_e32 v62, 16, v46
	v_and_b32_e32 v63, 0xffff0000, v46
	v_lshlrev_b32_e32 v40, 16, v41
	v_and_b32_e32 v41, 0xffff0000, v41
	v_lshlrev_b32_e32 v44, 16, v45
	v_and_b32_e32 v45, 0xffff0000, v45
	v_lshlrev_b32_e32 v42, 16, v43
	v_and_b32_e32 v43, 0xffff0000, v43
	v_lshlrev_b32_e32 v46, 16, v47
	v_and_b32_e32 v47, 0xffff0000, v47
	v_pk_fma_f32 v[32:33], v[32:33], v[56:57], v[36:37]
	v_pk_fma_f32 v[36:37], v[34:35], v[62:63], v[60:61]
	v_pk_fma_f32 v[34:35], v[38:39], v[44:45], v[40:41]
	v_pk_fma_f32 v[38:39], v[54:55], v[46:47], v[42:43]
	global_store_dwordx4 v[58:59], v[32:35], off offset:512
	global_store_dwordx4 v[58:59], v[36:39], off offset:528
	v_lshl_add_u64 v[40:41], v[50:51], 0, v[144:145]
	s_nop 0
	s_nop 0
	v_exp_f32_e32 v42, v24
	v_exp_f32_e32 v43, v25
	v_lshlrev_b64 v[24:25], 12, v[48:49]
	v_lshl_add_u64 v[24:25], s[84:85], 0, v[24:25]
	v_add_f32_e32 v44, 1.0, v42
	v_add_f32_e32 v45, 1.0, v43
	v_add_f32_e32 v46, 1.0, v26
	v_add_f32_e32 v47, 1.0, v27
	v_lshl_add_u64 v[42:43], v[24:25], 0, v[120:121]
	v_rcp_f32_e32 v24, v28
	v_rcp_f32_e32 v26, v44
	v_rcp_f32_e32 v25, v29
	v_rcp_f32_e32 v27, v45
	v_rcp_f32_e32 v44, v46
	v_rcp_f32_e32 v45, v47
	s_waitcnt vmcnt(20)
	v_mov_b64_e32 v[32:33], v[212:213]
	v_mov_b64_e32 v[34:35], v[214:215]
	v_mov_b64_e32 v[36:37], v[216:217]
	v_mov_b64_e32 v[38:39], v[218:219]
	v_lshlrev_b32_e32 v28, 16, v32
	v_and_b32_e32 v29, 0xffff0000, v32
	s_nop 0
	v_lshlrev_b32_e32 v46, 16, v36
	v_and_b32_e32 v47, 0xffff0000, v36
	v_lshlrev_b32_e32 v48, 16, v34
	v_and_b32_e32 v49, 0xffff0000, v34
	v_lshlrev_b32_e32 v50, 16, v38
	v_and_b32_e32 v51, 0xffff0000, v38
	v_lshlrev_b32_e32 v32, 16, v33
	v_and_b32_e32 v33, 0xffff0000, v33
	v_lshlrev_b32_e32 v36, 16, v37
	v_and_b32_e32 v37, 0xffff0000, v37
	v_lshlrev_b32_e32 v34, 16, v35
	v_and_b32_e32 v35, 0xffff0000, v35
	v_lshlrev_b32_e32 v38, 16, v39
	v_and_b32_e32 v39, 0xffff0000, v39
	v_pk_fma_f32 v[24:25], v[24:25], v[46:47], v[28:29]
	v_pk_fma_f32 v[28:29], v[26:27], v[50:51], v[48:49]
	v_pk_fma_f32 v[26:27], v[30:31], v[36:37], v[32:33]
	v_pk_fma_f32 v[30:31], v[44:45], v[38:39], v[34:35]
	global_store_dwordx4 v[42:43], v[24:27], off
	global_store_dwordx4 v[42:43], v[28:31], off offset:16
	s_nop 0
	s_nop 0
	s_nop 0
	v_exp_f32_e32 v36, v16
	v_exp_f32_e32 v37, v17
	v_exp_f32_e32 v38, v18
	v_exp_f32_e32 v39, v19
	v_add_u32_e32 v32, 0xb0, v146
	v_ashrrev_i32_e32 v33, 31, v32
	v_lshlrev_b64 v[16:17], 11, v[32:33]
	v_lshl_add_u64 v[18:19], s[48:49], 0, v[16:17]
	v_lshl_add_u64 v[34:35], s[38:39], 0, v[16:17]
	v_add_f32_e32 v16, 1.0, v20
	v_add_f32_e32 v17, 1.0, v36
	v_add_f32_e32 v20, 1.0, v21
	v_add_f32_e32 v21, 1.0, v37
	v_add_f32_e32 v38, 1.0, v38
	v_add_f32_e32 v39, 1.0, v39
	v_lshl_add_u64 v[36:37], v[18:19], 0, v[144:145]
	v_rcp_f32_e32 v16, v16
	v_rcp_f32_e32 v18, v17
	v_rcp_f32_e32 v17, v20
	v_rcp_f32_e32 v19, v21
	v_rcp_f32_e32 v38, v38
	v_rcp_f32_e32 v39, v39
	s_waitcnt vmcnt(18)
; __device__ __forceinline__ float sigm(float x) { return __builtin_amdgcn_rcpf(1.f + __expf(-x)); }
;     __device__ __forceinline__ void operator()(const f32x4 (&acc)[2][2][4][2], const pg8::Unit& u, int wr, int wc, int fr, int fq) const {
;     ...
;                     } else if (MODE == 6) {
;                         float* op = outf + (size_t)r * DM + c0;
;                         const u32x4 xw = *(const u32x4*)(O + (size_t)r * DM + c0);
;                         float xf[8]; unpack8(xw, xf);
;                         const u32x4 pw = *(const u32x4*)(pe + (size_t)r * DM + c0);
;                         float pf[8]; unpack8(pw, pf);
;                         f32x4 o0, o1;
; #pragma unroll
;                         for (int j = 0; j < 4; ++j) { o0[j] = xf[j] + sigm(v[j]) * pf[j]; o1[j] = xf[4 + j] + sigm(v[4 + j]) * pf[4 + j]; }
;                         *(f32x4*)op = o0; *(f32x4*)(op + 4) = o1;
	v_mov_b64_e32 v[24:25], v[220:221]
	v_mov_b64_e32 v[26:27], v[222:223]
	v_mov_b64_e32 v[28:29], v[224:225]
	v_mov_b64_e32 v[30:31], v[226:227]
	v_lshlrev_b32_e32 v20, 16, v24
	v_and_b32_e32 v21, 0xffff0000, v24
	s_nop 0
	v_lshlrev_b32_e32 v40, 16, v28
	v_and_b32_e32 v41, 0xffff0000, v28
	v_lshlrev_b32_e32 v44, 16, v26
	v_and_b32_e32 v45, 0xffff0000, v26
	v_lshlrev_b32_e32 v46, 16, v30
	v_and_b32_e32 v47, 0xffff0000, v30
	v_lshlrev_b32_e32 v24, 16, v25
	v_and_b32_e32 v25, 0xffff0000, v25
	v_lshlrev_b32_e32 v28, 16, v29
	v_and_b32_e32 v29, 0xffff0000, v29
	v_lshlrev_b32_e32 v26, 16, v27
	v_and_b32_e32 v27, 0xffff0000, v27
	v_lshlrev_b32_e32 v30, 16, v31
	v_and_b32_e32 v31, 0xffff0000, v31
	v_pk_fma_f32 v[16:17], v[16:17], v[40:41], v[20:21]
	v_pk_fma_f32 v[20:21], v[18:19], v[46:47], v[44:45]
	v_pk_fma_f32 v[18:19], v[22:23], v[28:29], v[24:25]
	v_pk_fma_f32 v[22:23], v[38:39], v[30:31], v[26:27]
	global_store_dwordx4 v[42:43], v[16:19], off offset:512
	global_store_dwordx4 v[42:43], v[20:23], off offset:528
	v_lshl_add_u64 v[24:25], v[34:35], 0, v[144:145]
	s_nop 0
	s_nop 0
	v_exp_f32_e32 v26, v8
	v_exp_f32_e32 v27, v9
	v_lshlrev_b64 v[8:9], 12, v[32:33]
	v_lshl_add_u64 v[8:9], s[84:85], 0, v[8:9]
	v_add_f32_e32 v28, 1.0, v26
	v_add_f32_e32 v29, 1.0, v27
	v_add_f32_e32 v30, 1.0, v10
	v_add_f32_e32 v31, 1.0, v11
	v_lshl_add_u64 v[26:27], v[8:9], 0, v[120:121]
	v_rcp_f32_e32 v8, v12
	v_rcp_f32_e32 v10, v28
	v_rcp_f32_e32 v9, v13
	v_rcp_f32_e32 v11, v29
	v_rcp_f32_e32 v28, v30
	v_rcp_f32_e32 v29, v31
	s_waitcnt vmcnt(16)
	v_mov_b64_e32 v[16:17], v[228:229]
	v_mov_b64_e32 v[18:19], v[230:231]
	v_mov_b64_e32 v[20:21], v[232:233]
	v_mov_b64_e32 v[22:23], v[234:235]
	v_lshlrev_b32_e32 v12, 16, v16
	v_and_b32_e32 v13, 0xffff0000, v16
	s_nop 0
	v_lshlrev_b32_e32 v30, 16, v20
	v_and_b32_e32 v31, 0xffff0000, v20
	v_lshlrev_b32_e32 v32, 16, v18
	v_and_b32_e32 v33, 0xffff0000, v18
	v_lshlrev_b32_e32 v34, 16, v22
	v_and_b32_e32 v35, 0xffff0000, v22
	v_lshlrev_b32_e32 v16, 16, v17
	v_and_b32_e32 v17, 0xffff0000, v17
	v_lshlrev_b32_e32 v20, 16, v21
	v_and_b32_e32 v21, 0xffff0000, v21
	v_lshlrev_b32_e32 v18, 16, v19
	v_and_b32_e32 v19, 0xffff0000, v19
	v_lshlrev_b32_e32 v22, 16, v23
	v_and_b32_e32 v23, 0xffff0000, v23
	v_pk_fma_f32 v[8:9], v[8:9], v[30:31], v[12:13]
	v_pk_fma_f32 v[12:13], v[10:11], v[34:35], v[32:33]
	v_pk_fma_f32 v[10:11], v[14:15], v[20:21], v[16:17]
	v_pk_fma_f32 v[14:15], v[28:29], v[22:23], v[18:19]
	global_store_dwordx4 v[26:27], v[8:11], off
	global_store_dwordx4 v[26:27], v[12:15], off offset:16
	s_nop 0
	s_nop 0
	s_nop 0
	v_add_f32_e32 v16, 1.0, v0
	v_add_f32_e32 v17, 1.0, v1
	v_add_f32_e32 v18, 1.0, v2
	v_add_f32_e32 v19, 1.0, v3
	v_rcp_f32_e32 v0, v4
	v_rcp_f32_e32 v2, v16
	v_rcp_f32_e32 v1, v5
	v_rcp_f32_e32 v3, v17
	v_rcp_f32_e32 v16, v18
	v_rcp_f32_e32 v17, v19
	s_waitcnt vmcnt(14)
	v_mov_b64_e32 v[8:9], v[236:237]
	v_mov_b64_e32 v[10:11], v[238:239]
	v_mov_b64_e32 v[12:13], v[240:241]
	v_mov_b64_e32 v[14:15], v[242:243]
	v_lshlrev_b32_e32 v4, 16, v8
	v_and_b32_e32 v5, 0xffff0000, v8
	s_nop 0
	v_lshlrev_b32_e32 v18, 16, v12
	v_and_b32_e32 v19, 0xffff0000, v12
	v_lshlrev_b32_e32 v20, 16, v10
	v_and_b32_e32 v21, 0xffff0000, v10
	v_lshlrev_b32_e32 v22, 16, v14
	v_and_b32_e32 v23, 0xffff0000, v14
	v_lshlrev_b32_e32 v8, 16, v9
	v_and_b32_e32 v9, 0xffff0000, v9
	v_lshlrev_b32_e32 v12, 16, v13
	v_and_b32_e32 v13, 0xffff0000, v13
	v_lshlrev_b32_e32 v10, 16, v11
	v_and_b32_e32 v11, 0xffff0000, v11
	v_lshlrev_b32_e32 v14, 16, v15
	v_and_b32_e32 v15, 0xffff0000, v15
	v_pk_fma_f32 v[0:1], v[0:1], v[18:19], v[4:5]
	v_pk_fma_f32 v[4:5], v[2:3], v[22:23], v[20:21]
	v_pk_fma_f32 v[2:3], v[6:7], v[12:13], v[8:9]
	v_pk_fma_f32 v[6:7], v[16:17], v[14:15], v[10:11]
	global_store_dwordx4 v[26:27], v[0:3], off offset:512
	global_store_dwordx4 v[26:27], v[4:7], off offset:528
	s_cbranch_vccnz .LBB0_1901
	s_andn2_b64 vcc, exec, s[4:5]
	s_cbranch_vccnz .LBB0_1900
	s_barrier
	s_branch .LBB0_1900
